# v88 + K-loops: LDS-DMA address add placed between the M0 write and the load (67 pad nops gone); 42 counted vmcnt waits that directly follow a full vmcnt(0) removed
# speedup vs baseline: 1.0051x; 1.0031x over previous
.LBB0_198:
	s_add_u32 s48, s60, 0xfff80080
	s_addc_u32 s49, s61, -1
	s_add_i32 s87, 0, 0x10000
	s_cmp_eq_u32 s86, 28
	s_cselect_b32 s69, s25, s49
	s_cselect_b32 s68, s81, s48
	s_cselect_b32 s63, s15, s85
	s_cselect_b32 s62, s83, s84
	s_add_i32 s48, 0, 0x14000
	ds_read_b128 v[142:145], v251
	ds_read_b128 v[146:149], v251 offset:1024
	ds_read_b128 v[150:153], v251 offset:2048
	ds_read_b128 v[158:161], v251 offset:3072
	ds_read_b128 v[162:165], v251 offset:16384
	ds_read_b128 v[166:169], v251 offset:17408
	ds_read_b128 v[170:173], v251 offset:18432
	ds_read_b128 v[174:177], v251 offset:19456
	v_lshl_add_u64 v[198:199], s[60:61], 0, v[138:139]
	s_add_i32 m0, s20, 0xc000
	ds_read_b128 v[178:181], v156
	ds_read_b128 v[182:185], v156 offset:1024
	ds_read_b128 v[186:189], v156 offset:2048
	ds_read_b128 v[190:193], v156 offset:3072
	ds_read_b128 v[194:197], v156 offset:4096
	ds_read_b128 v[210:213], v156 offset:5120
	ds_read_b128 v[214:217], v156 offset:6144
	ds_read_b128 v[218:221], v156 offset:7168
	global_load_lds_dwordx4 v[198:199], off
	s_add_i32 m0, s20, 0xe000
	v_lshl_add_u64 v[198:199], s[60:61], 0, v[140:141]
	global_load_lds_dwordx4 v[198:199], off
	s_waitcnt vmcnt(8) lgkmcnt(0)
	s_setprio 1
	s_barrier
	v_mfma_f32_16x16x32_bf16 v[128:131], v[142:145], v[178:181], v[128:131]
	v_mfma_f32_16x16x32_bf16 v[124:127], v[150:153], v[178:181], v[124:127]
	v_mfma_f32_16x16x32_bf16 v[112:115], v[142:145], v[186:189], v[112:115]
	v_mfma_f32_16x16x32_bf16 v[108:111], v[150:153], v[186:189], v[108:111]
	v_mfma_f32_16x16x32_bf16 v[96:99], v[142:145], v[194:197], v[96:99]
	v_mfma_f32_16x16x32_bf16 v[92:95], v[150:153], v[194:197], v[92:95]
	v_mfma_f32_16x16x32_bf16 v[80:83], v[142:145], v[214:217], v[80:83]
	v_mfma_f32_16x16x32_bf16 v[76:79], v[150:153], v[214:217], v[76:79]
	v_mfma_f32_16x16x32_bf16 v[128:131], v[146:149], v[182:185], v[128:131]
	v_mfma_f32_16x16x32_bf16 v[124:127], v[158:161], v[182:185], v[124:127]
	v_mfma_f32_16x16x32_bf16 v[112:115], v[146:149], v[190:193], v[112:115]
	v_mfma_f32_16x16x32_bf16 v[108:111], v[158:161], v[190:193], v[108:111]
	v_mfma_f32_16x16x32_bf16 v[96:99], v[146:149], v[210:213], v[96:99]
	v_mfma_f32_16x16x32_bf16 v[92:95], v[158:161], v[210:213], v[92:95]
	v_mfma_f32_16x16x32_bf16 v[80:83], v[146:149], v[218:221], v[80:83]
	v_mfma_f32_16x16x32_bf16 v[76:79], v[158:161], v[218:221], v[76:79]
	v_mfma_f32_16x16x32_bf16 v[120:123], v[162:165], v[178:181], v[120:123]
	v_mfma_f32_16x16x32_bf16 v[116:119], v[170:173], v[178:181], v[116:119]
	v_mfma_f32_16x16x32_bf16 v[104:107], v[162:165], v[186:189], v[104:107]
	v_mfma_f32_16x16x32_bf16 v[100:103], v[170:173], v[186:189], v[100:103]
	v_mfma_f32_16x16x32_bf16 v[88:91], v[162:165], v[194:197], v[88:91]
	v_mfma_f32_16x16x32_bf16 v[84:87], v[170:173], v[194:197], v[84:87]
	v_mfma_f32_16x16x32_bf16 v[72:75], v[162:165], v[214:217], v[72:75]
	v_mfma_f32_16x16x32_bf16 v[68:71], v[170:173], v[214:217], v[68:71]
	v_mfma_f32_16x16x32_bf16 v[120:123], v[166:169], v[182:185], v[120:123]
	v_mfma_f32_16x16x32_bf16 v[116:119], v[174:177], v[182:185], v[116:119]
	v_mfma_f32_16x16x32_bf16 v[104:107], v[166:169], v[190:193], v[104:107]
	v_mfma_f32_16x16x32_bf16 v[100:103], v[174:177], v[190:193], v[100:103]
	v_mfma_f32_16x16x32_bf16 v[88:91], v[166:169], v[210:213], v[88:91]
	v_mfma_f32_16x16x32_bf16 v[84:87], v[174:177], v[210:213], v[84:87]
	v_mfma_f32_16x16x32_bf16 v[72:75], v[166:169], v[218:221], v[72:75]
	v_mfma_f32_16x16x32_bf16 v[68:71], v[174:177], v[218:221], v[68:71]
	s_barrier
	s_setprio 0
	s_add_i32 s49, s87, s1
	v_lshl_add_u64 v[198:199], s[62:63], 0, v[200:201]
	s_mov_b32 m0, s49
	ds_read_b128 v[178:181], v156 offset:16384
	ds_read_b128 v[182:185], v156 offset:17408
	ds_read_b128 v[186:189], v156 offset:18432
	ds_read_b128 v[190:193], v156 offset:19456
	ds_read_b128 v[194:197], v156 offset:20480
	ds_read_b128 v[210:213], v156 offset:21504
	ds_read_b128 v[214:217], v156 offset:22528
	ds_read_b128 v[218:221], v156 offset:23552
	global_load_lds_dwordx4 v[198:199], off
	s_add_i32 m0, s49, 0x2000
	s_add_u32 s88, s62, 0x80000
	v_lshl_add_u64 v[206:207], s[62:63], 0, v[132:133]
	s_addc_u32 s89, s63, 0
	s_add_i32 s48, s48, s1
	global_load_lds_dwordx4 v[206:207], off
	v_lshl_add_u64 v[208:209], s[88:89], 0, v[200:201]
	s_mov_b32 m0, s48
	v_lshl_add_u64 v[222:223], s[68:69], 0, v[134:135]
	global_load_lds_dwordx4 v[208:209], off
	s_add_i32 m0, s48, 0x2000
	v_lshl_add_u64 v[208:209], s[88:89], 0, v[132:133]
	global_load_lds_dwordx4 v[208:209], off
	s_mov_b32 m0, s20
	v_lshl_add_u64 v[208:209], s[68:69], 0, v[136:137]
	global_load_lds_dwordx4 v[208:209], off
	s_mov_b32 m0, s21
	s_nop 0
	global_load_lds_dwordx4 v[222:223], off
	s_waitcnt vmcnt(8) lgkmcnt(0)
	s_setprio 1
	s_barrier
	v_mfma_f32_16x16x32_bf16 v[64:67], v[142:145], v[178:181], v[64:67]
	v_mfma_f32_16x16x32_bf16 v[60:63], v[150:153], v[178:181], v[60:63]
	v_mfma_f32_16x16x32_bf16 v[48:51], v[142:145], v[186:189], v[48:51]
	v_mfma_f32_16x16x32_bf16 v[44:47], v[150:153], v[186:189], v[44:47]
	v_mfma_f32_16x16x32_bf16 v[32:35], v[142:145], v[194:197], v[32:35]
	v_mfma_f32_16x16x32_bf16 v[28:31], v[150:153], v[194:197], v[28:31]
	v_mfma_f32_16x16x32_bf16 v[16:19], v[142:145], v[214:217], v[16:19]
	v_mfma_f32_16x16x32_bf16 v[12:15], v[150:153], v[214:217], v[12:15]
	v_mfma_f32_16x16x32_bf16 v[64:67], v[146:149], v[182:185], v[64:67]
	v_mfma_f32_16x16x32_bf16 v[60:63], v[158:161], v[182:185], v[60:63]
	v_mfma_f32_16x16x32_bf16 v[48:51], v[146:149], v[190:193], v[48:51]
	v_mfma_f32_16x16x32_bf16 v[44:47], v[158:161], v[190:193], v[44:47]
	v_mfma_f32_16x16x32_bf16 v[32:35], v[146:149], v[210:213], v[32:35]
	v_mfma_f32_16x16x32_bf16 v[28:31], v[158:161], v[210:213], v[28:31]
	v_mfma_f32_16x16x32_bf16 v[16:19], v[146:149], v[218:221], v[16:19]
	v_mfma_f32_16x16x32_bf16 v[12:15], v[158:161], v[218:221], v[12:15]
	v_mfma_f32_16x16x32_bf16 v[56:59], v[162:165], v[178:181], v[56:59]
	v_mfma_f32_16x16x32_bf16 v[52:55], v[170:173], v[178:181], v[52:55]
	v_mfma_f32_16x16x32_bf16 v[40:43], v[162:165], v[186:189], v[40:43]
	v_mfma_f32_16x16x32_bf16 v[36:39], v[170:173], v[186:189], v[36:39]
	v_mfma_f32_16x16x32_bf16 v[24:27], v[162:165], v[194:197], v[24:27]
	v_mfma_f32_16x16x32_bf16 v[20:23], v[170:173], v[194:197], v[20:23]
	v_mfma_f32_16x16x32_bf16 v[8:11], v[162:165], v[214:217], v[8:11]
	v_mfma_f32_16x16x32_bf16 v[4:7], v[170:173], v[214:217], v[4:7]
	v_mfma_f32_16x16x32_bf16 v[56:59], v[166:169], v[182:185], v[56:59]
	v_mfma_f32_16x16x32_bf16 v[52:55], v[174:177], v[182:185], v[52:55]
	v_mfma_f32_16x16x32_bf16 v[40:43], v[166:169], v[190:193], v[40:43]
	v_mfma_f32_16x16x32_bf16 v[36:39], v[174:177], v[190:193], v[36:39]
	v_mfma_f32_16x16x32_bf16 v[24:27], v[166:169], v[210:213], v[24:27]
	v_mfma_f32_16x16x32_bf16 v[20:23], v[174:177], v[210:213], v[20:23]
	v_mfma_f32_16x16x32_bf16 v[8:11], v[166:169], v[218:221], v[8:11]
	v_mfma_f32_16x16x32_bf16 v[4:7], v[174:177], v[218:221], v[4:7]
	s_barrier
	s_setprio 0
	s_add_i32 s48, 0, 0x18000
	s_add_i32 s49, 0, 0x1c000
	ds_read_b128 v[142:145], v251 offset:32768
	ds_read_b128 v[146:149], v251 offset:33792
	ds_read_b128 v[150:153], v251 offset:34816
	ds_read_b128 v[158:161], v251 offset:35840
	ds_read_b128 v[162:165], v251 offset:49152
	ds_read_b128 v[166:169], v251 offset:50176
	ds_read_b128 v[170:173], v251 offset:51200
	ds_read_b128 v[174:177], v251 offset:52224
	s_add_u32 s68, s68, 0x80000
	s_addc_u32 s69, s69, 0
	s_mov_b32 m0, s23
	v_lshl_add_u64 v[224:225], s[68:69], 0, v[136:137]
	ds_read_b128 v[178:181], v156 offset:32768
	ds_read_b128 v[182:185], v156 offset:33792
	ds_read_b128 v[186:189], v156 offset:34816
	ds_read_b128 v[190:193], v156 offset:35840
	ds_read_b128 v[194:197], v156 offset:36864
	ds_read_b128 v[210:213], v156 offset:37888
	ds_read_b128 v[214:217], v156 offset:38912
	ds_read_b128 v[218:221], v156 offset:39936
	global_load_lds_dwordx4 v[224:225], off
	s_mov_b32 m0, s42
	v_lshl_add_u64 v[224:225], s[68:69], 0, v[134:135]
	global_load_lds_dwordx4 v[224:225], off
	s_waitcnt vmcnt(8) lgkmcnt(0)
	s_setprio 1
	s_barrier
	v_mfma_f32_16x16x32_bf16 v[128:131], v[142:145], v[178:181], v[128:131]
	v_mfma_f32_16x16x32_bf16 v[124:127], v[150:153], v[178:181], v[124:127]
	v_mfma_f32_16x16x32_bf16 v[112:115], v[142:145], v[186:189], v[112:115]
	v_mfma_f32_16x16x32_bf16 v[108:111], v[150:153], v[186:189], v[108:111]
	v_mfma_f32_16x16x32_bf16 v[96:99], v[142:145], v[194:197], v[96:99]
	v_mfma_f32_16x16x32_bf16 v[92:95], v[150:153], v[194:197], v[92:95]
	v_mfma_f32_16x16x32_bf16 v[80:83], v[142:145], v[214:217], v[80:83]
	v_mfma_f32_16x16x32_bf16 v[76:79], v[150:153], v[214:217], v[76:79]
	v_mfma_f32_16x16x32_bf16 v[128:131], v[146:149], v[182:185], v[128:131]
	v_mfma_f32_16x16x32_bf16 v[124:127], v[158:161], v[182:185], v[124:127]
	v_mfma_f32_16x16x32_bf16 v[112:115], v[146:149], v[190:193], v[112:115]
	v_mfma_f32_16x16x32_bf16 v[108:111], v[158:161], v[190:193], v[108:111]
	v_mfma_f32_16x16x32_bf16 v[96:99], v[146:149], v[210:213], v[96:99]
	v_mfma_f32_16x16x32_bf16 v[92:95], v[158:161], v[210:213], v[92:95]
	v_mfma_f32_16x16x32_bf16 v[80:83], v[146:149], v[218:221], v[80:83]
	v_mfma_f32_16x16x32_bf16 v[76:79], v[158:161], v[218:221], v[76:79]
	v_mfma_f32_16x16x32_bf16 v[120:123], v[162:165], v[178:181], v[120:123]
	v_mfma_f32_16x16x32_bf16 v[116:119], v[170:173], v[178:181], v[116:119]
	v_mfma_f32_16x16x32_bf16 v[104:107], v[162:165], v[186:189], v[104:107]
	v_mfma_f32_16x16x32_bf16 v[100:103], v[170:173], v[186:189], v[100:103]
	v_mfma_f32_16x16x32_bf16 v[88:91], v[162:165], v[194:197], v[88:91]
	v_mfma_f32_16x16x32_bf16 v[84:87], v[170:173], v[194:197], v[84:87]
	v_mfma_f32_16x16x32_bf16 v[72:75], v[162:165], v[214:217], v[72:75]
	v_mfma_f32_16x16x32_bf16 v[68:71], v[170:173], v[214:217], v[68:71]
	v_mfma_f32_16x16x32_bf16 v[120:123], v[166:169], v[182:185], v[120:123]
	v_mfma_f32_16x16x32_bf16 v[116:119], v[174:177], v[182:185], v[116:119]
	v_mfma_f32_16x16x32_bf16 v[104:107], v[166:169], v[190:193], v[104:107]
	v_mfma_f32_16x16x32_bf16 v[100:103], v[174:177], v[190:193], v[100:103]
	v_mfma_f32_16x16x32_bf16 v[88:91], v[166:169], v[210:213], v[88:91]
	v_mfma_f32_16x16x32_bf16 v[84:87], v[174:177], v[210:213], v[84:87]
	v_mfma_f32_16x16x32_bf16 v[72:75], v[166:169], v[218:221], v[72:75]
	v_mfma_f32_16x16x32_bf16 v[68:71], v[174:177], v[218:221], v[68:71]
	s_barrier
	s_setprio 0
	s_add_i32 s48, s48, s1
	v_lshl_add_u64 v[198:199], v[198:199], 0, s[66:67]
	s_mov_b32 m0, s48
	ds_read_b128 v[178:181], v156 offset:49152
	ds_read_b128 v[182:185], v156 offset:50176
	ds_read_b128 v[186:189], v156 offset:51200
	ds_read_b128 v[190:193], v156 offset:52224
	ds_read_b128 v[194:197], v156 offset:53248
	ds_read_b128 v[210:213], v156 offset:54272
	ds_read_b128 v[214:217], v156 offset:55296
	ds_read_b128 v[218:221], v156 offset:56320
	global_load_lds_dwordx4 v[198:199], off
	s_add_i32 m0, s48, 0x2000
	s_add_u32 s62, s62, 0x80080
	v_lshl_add_u64 v[198:199], v[206:207], 0, s[66:67]
	s_addc_u32 s63, s63, 0
	s_add_i32 s48, s49, s1
	global_load_lds_dwordx4 v[198:199], off
	s_mov_b32 m0, s48
	v_lshl_add_u64 v[198:199], s[62:63], 0, v[200:201]
	global_load_lds_dwordx4 v[198:199], off
	s_add_i32 m0, s48, 0x2000
	v_lshl_add_u64 v[198:199], s[62:63], 0, v[132:133]
	global_load_lds_dwordx4 v[198:199], off
	v_lshl_add_u64 v[198:199], v[208:209], 0, s[66:67]
	s_mov_b32 m0, s55
	s_nop 0
	global_load_lds_dwordx4 v[198:199], off
	v_lshl_add_u64 v[198:199], v[222:223], 0, s[66:67]
	s_mov_b32 m0, s56
	s_nop 0
	global_load_lds_dwordx4 v[198:199], off
	s_waitcnt vmcnt(8) lgkmcnt(0)
	s_setprio 1
	s_barrier
	v_mfma_f32_16x16x32_bf16 v[64:67], v[142:145], v[178:181], v[64:67]
	v_mfma_f32_16x16x32_bf16 v[60:63], v[150:153], v[178:181], v[60:63]
	v_mfma_f32_16x16x32_bf16 v[48:51], v[142:145], v[186:189], v[48:51]
	v_mfma_f32_16x16x32_bf16 v[44:47], v[150:153], v[186:189], v[44:47]
	v_mfma_f32_16x16x32_bf16 v[32:35], v[142:145], v[194:197], v[32:35]
	v_mfma_f32_16x16x32_bf16 v[28:31], v[150:153], v[194:197], v[28:31]
	v_mfma_f32_16x16x32_bf16 v[16:19], v[142:145], v[214:217], v[16:19]
	v_mfma_f32_16x16x32_bf16 v[12:15], v[150:153], v[214:217], v[12:15]
	v_mfma_f32_16x16x32_bf16 v[64:67], v[146:149], v[182:185], v[64:67]
	v_mfma_f32_16x16x32_bf16 v[60:63], v[158:161], v[182:185], v[60:63]
	v_mfma_f32_16x16x32_bf16 v[48:51], v[146:149], v[190:193], v[48:51]
	v_mfma_f32_16x16x32_bf16 v[44:47], v[158:161], v[190:193], v[44:47]
	v_mfma_f32_16x16x32_bf16 v[32:35], v[146:149], v[210:213], v[32:35]
	v_mfma_f32_16x16x32_bf16 v[28:31], v[158:161], v[210:213], v[28:31]
	v_mfma_f32_16x16x32_bf16 v[16:19], v[146:149], v[218:221], v[16:19]
	v_mfma_f32_16x16x32_bf16 v[12:15], v[158:161], v[218:221], v[12:15]
	v_mfma_f32_16x16x32_bf16 v[56:59], v[162:165], v[178:181], v[56:59]
	v_mfma_f32_16x16x32_bf16 v[52:55], v[170:173], v[178:181], v[52:55]
	v_mfma_f32_16x16x32_bf16 v[40:43], v[162:165], v[186:189], v[40:43]
	v_mfma_f32_16x16x32_bf16 v[36:39], v[170:173], v[186:189], v[36:39]
	v_mfma_f32_16x16x32_bf16 v[24:27], v[162:165], v[194:197], v[24:27]
	v_mfma_f32_16x16x32_bf16 v[20:23], v[170:173], v[194:197], v[20:23]
	v_mfma_f32_16x16x32_bf16 v[8:11], v[162:165], v[214:217], v[8:11]
	v_mfma_f32_16x16x32_bf16 v[4:7], v[170:173], v[214:217], v[4:7]
	v_mfma_f32_16x16x32_bf16 v[56:59], v[166:169], v[182:185], v[56:59]
	v_mfma_f32_16x16x32_bf16 v[52:55], v[174:177], v[182:185], v[52:55]
	v_mfma_f32_16x16x32_bf16 v[40:43], v[166:169], v[190:193], v[40:43]
	v_mfma_f32_16x16x32_bf16 v[36:39], v[174:177], v[190:193], v[36:39]
	v_mfma_f32_16x16x32_bf16 v[24:27], v[166:169], v[210:213], v[24:27]
	v_mfma_f32_16x16x32_bf16 v[20:23], v[174:177], v[210:213], v[20:23]
	v_mfma_f32_16x16x32_bf16 v[8:11], v[166:169], v[218:221], v[8:11]
	v_mfma_f32_16x16x32_bf16 v[4:7], v[174:177], v[218:221], v[4:7]
	s_barrier
	s_setprio 0
	s_add_i32 s86, s86, 2
	s_add_u32 s60, s60, 0x100
	s_addc_u32 s61, s61, 0
	s_add_u32 s84, s84, 0x100
	s_addc_u32 s85, s85, 0
	s_cmp_gt_u32 s86, 29
	s_cbranch_scc0 .LBB0_198
	s_and_b64 vcc, exec, s[12:13]
	s_cbranch_vccz .LBB0_201
	s_barrier

.LBB0_221:
	s_waitcnt vmcnt(0)
	s_barrier
	s_mov_b64 s[4:5], exec
	v_readlane_b32 s10, v254, 5
	v_readlane_b32 s11, v254, 6
	s_and_b64 s[10:11], s[4:5], s[10:11]
	s_mov_b64 exec, s[10:11]
	s_cbranch_execz .LBB0_273
	v_readlane_b32 s10, v254, 2
	v_readlane_b32 s12, v255, 20
	v_readlane_b32 s1, v254, 4
	v_readlane_b32 s11, v254, 3
	v_mov_b32_e32 v3, s12
	s_waitcnt vmcnt(0) expcnt(0) lgkmcnt(0)
	ds_read_b32 v5, v3
	v_readlane_b32 s12, v255, 21
	s_waitcnt lgkmcnt(0)
	v_cmp_ne_u32_e32 vcc, 0, v5
	v_mov_b32_e32 v3, s12
	ds_read_b32 v4, v3
	s_cbranch_vccnz .LBB0_237
	v_readlane_b32 s12, v254, 0
	v_readlane_b32 s13, v254, 1
	s_load_dwordx2 s[20:21], s[12:13], 0x4
	s_add_u32 s12, s10, 0x1000
	s_addc_u32 s13, s11, 0
	s_add_u32 s14, s10, 0x1100
	s_addc_u32 s15, s11, 0
	s_add_u32 s24, s10, 0x1200
	s_addc_u32 s25, s11, 0
	s_waitcnt lgkmcnt(0)
	s_mul_i32 s20, s20, s33
	s_add_u32 s50, s10, 0x1300
	s_mul_i32 s20, s20, s21
	s_addc_u32 s51, s11, 0
	s_mov_b32 s21, 1
	s_branch .LBB0_225

.LBB0_279:
	s_add_u32 s10, s56, s6
	s_addc_u32 s11, s73, s7
	s_add_u32 s10, s10, 0x1d800100
	s_addc_u32 s11, s11, 0
	s_add_u32 s48, s0, s6
	s_addc_u32 s49, s50, s7
	s_add_i32 s52, 0, 0x10000
	s_cmpk_eq_i32 s6, 0xf00
	s_cselect_b32 s13, s55, s11
	s_cselect_b32 s12, s54, s10
	s_cselect_b32 s11, s5, s49
	s_cselect_b32 s10, s4, s48
	s_add_i32 s48, 0, 0x14000
	ds_read_b128 v[146:149], v251
	ds_read_b128 v[150:153], v251 offset:1024
	ds_read_b128 v[154:157], v251 offset:2048
	ds_read_b128 v[158:161], v251 offset:3072
	ds_read_b128 v[162:165], v251 offset:16384
	ds_read_b128 v[166:169], v251 offset:17408
	ds_read_b128 v[170:173], v251 offset:18432
	ds_read_b128 v[174:177], v251 offset:19456
	v_lshl_add_u64 v[198:199], v[138:139], 0, s[6:7]
	s_add_i32 m0, s15, 0xc000
	ds_read_b128 v[178:181], v144
	ds_read_b128 v[182:185], v144 offset:1024
	ds_read_b128 v[186:189], v144 offset:2048
	ds_read_b128 v[190:193], v144 offset:3072
	ds_read_b128 v[194:197], v144 offset:4096
	ds_read_b128 v[210:213], v144 offset:5120
	ds_read_b128 v[214:217], v144 offset:6144
	ds_read_b128 v[218:221], v144 offset:7168
	global_load_lds_dwordx4 v[198:199], off
	v_lshl_add_u64 v[198:199], v[140:141], 0, s[6:7]
	s_add_i32 m0, s15, 0xe000
	s_nop 0
	global_load_lds_dwordx4 v[198:199], off
	s_waitcnt vmcnt(8) lgkmcnt(0)
	s_setprio 1
	s_barrier
	v_mfma_f32_16x16x32_bf16 v[128:131], v[146:149], v[178:181], v[128:131]
	v_mfma_f32_16x16x32_bf16 v[124:127], v[154:157], v[178:181], v[124:127]
	v_mfma_f32_16x16x32_bf16 v[112:115], v[146:149], v[186:189], v[112:115]
	v_mfma_f32_16x16x32_bf16 v[108:111], v[154:157], v[186:189], v[108:111]
	v_mfma_f32_16x16x32_bf16 v[96:99], v[146:149], v[194:197], v[96:99]
	v_mfma_f32_16x16x32_bf16 v[92:95], v[154:157], v[194:197], v[92:95]
	v_mfma_f32_16x16x32_bf16 v[80:83], v[146:149], v[214:217], v[80:83]
	v_mfma_f32_16x16x32_bf16 v[76:79], v[154:157], v[214:217], v[76:79]
	v_mfma_f32_16x16x32_bf16 v[128:131], v[150:153], v[182:185], v[128:131]
	v_mfma_f32_16x16x32_bf16 v[124:127], v[158:161], v[182:185], v[124:127]
	v_mfma_f32_16x16x32_bf16 v[112:115], v[150:153], v[190:193], v[112:115]
	v_mfma_f32_16x16x32_bf16 v[108:111], v[158:161], v[190:193], v[108:111]
	v_mfma_f32_16x16x32_bf16 v[96:99], v[150:153], v[210:213], v[96:99]
	v_mfma_f32_16x16x32_bf16 v[92:95], v[158:161], v[210:213], v[92:95]
	v_mfma_f32_16x16x32_bf16 v[80:83], v[150:153], v[218:221], v[80:83]
	v_mfma_f32_16x16x32_bf16 v[76:79], v[158:161], v[218:221], v[76:79]
	v_mfma_f32_16x16x32_bf16 v[120:123], v[162:165], v[178:181], v[120:123]
	v_mfma_f32_16x16x32_bf16 v[116:119], v[170:173], v[178:181], v[116:119]
	v_mfma_f32_16x16x32_bf16 v[104:107], v[162:165], v[186:189], v[104:107]
	v_mfma_f32_16x16x32_bf16 v[100:103], v[170:173], v[186:189], v[100:103]
	v_mfma_f32_16x16x32_bf16 v[88:91], v[162:165], v[194:197], v[88:91]
	v_mfma_f32_16x16x32_bf16 v[84:87], v[170:173], v[194:197], v[84:87]
	v_mfma_f32_16x16x32_bf16 v[72:75], v[162:165], v[214:217], v[72:75]
	v_mfma_f32_16x16x32_bf16 v[68:71], v[170:173], v[214:217], v[68:71]
	v_mfma_f32_16x16x32_bf16 v[120:123], v[166:169], v[182:185], v[120:123]
	v_mfma_f32_16x16x32_bf16 v[116:119], v[174:177], v[182:185], v[116:119]
	v_mfma_f32_16x16x32_bf16 v[104:107], v[166:169], v[190:193], v[104:107]
	v_mfma_f32_16x16x32_bf16 v[100:103], v[174:177], v[190:193], v[100:103]
	v_mfma_f32_16x16x32_bf16 v[88:91], v[166:169], v[210:213], v[88:91]
	v_mfma_f32_16x16x32_bf16 v[84:87], v[174:177], v[210:213], v[84:87]
	v_mfma_f32_16x16x32_bf16 v[72:75], v[166:169], v[218:221], v[72:75]
	v_mfma_f32_16x16x32_bf16 v[68:71], v[174:177], v[218:221], v[68:71]
	s_barrier
	s_setprio 0
	s_add_i32 s49, s52, s14
	v_lshl_add_u64 v[198:199], s[10:11], 0, v[200:201]
	s_mov_b32 m0, s49
	ds_read_b128 v[178:181], v144 offset:16384
	ds_read_b128 v[182:185], v144 offset:17408
	ds_read_b128 v[186:189], v144 offset:18432
	ds_read_b128 v[190:193], v144 offset:19456
	ds_read_b128 v[194:197], v144 offset:20480
	ds_read_b128 v[210:213], v144 offset:21504
	ds_read_b128 v[214:217], v144 offset:22528
	ds_read_b128 v[218:221], v144 offset:23552
	global_load_lds_dwordx4 v[198:199], off
	s_add_i32 m0, s49, 0x2000
	s_add_u32 s52, s10, 0x80000
	v_lshl_add_u64 v[206:207], s[10:11], 0, v[136:137]
	s_addc_u32 s53, s11, 0
	s_add_i32 s48, s48, s14
	global_load_lds_dwordx4 v[206:207], off
	v_lshl_add_u64 v[208:209], s[52:53], 0, v[200:201]
	s_mov_b32 m0, s48
	v_lshl_add_u64 v[222:223], s[12:13], 0, v[134:135]
	global_load_lds_dwordx4 v[208:209], off
	s_add_i32 m0, s48, 0x2000
	v_lshl_add_u64 v[208:209], s[52:53], 0, v[136:137]
	global_load_lds_dwordx4 v[208:209], off
	s_mov_b32 m0, s15
	v_lshl_add_u64 v[208:209], s[12:13], 0, v[132:133]
	global_load_lds_dwordx4 v[208:209], off
	s_mov_b32 m0, s20
	s_nop 0
	global_load_lds_dwordx4 v[222:223], off
	s_waitcnt vmcnt(8) lgkmcnt(0)
	s_setprio 1
	s_barrier
	v_mfma_f32_16x16x32_bf16 v[64:67], v[146:149], v[178:181], v[64:67]
	v_mfma_f32_16x16x32_bf16 v[60:63], v[154:157], v[178:181], v[60:63]
	v_mfma_f32_16x16x32_bf16 v[48:51], v[146:149], v[186:189], v[48:51]
	v_mfma_f32_16x16x32_bf16 v[44:47], v[154:157], v[186:189], v[44:47]
	v_mfma_f32_16x16x32_bf16 v[32:35], v[146:149], v[194:197], v[32:35]
	v_mfma_f32_16x16x32_bf16 v[28:31], v[154:157], v[194:197], v[28:31]
	v_mfma_f32_16x16x32_bf16 v[16:19], v[146:149], v[214:217], v[16:19]
	v_mfma_f32_16x16x32_bf16 v[12:15], v[154:157], v[214:217], v[12:15]
	v_mfma_f32_16x16x32_bf16 v[64:67], v[150:153], v[182:185], v[64:67]
	v_mfma_f32_16x16x32_bf16 v[60:63], v[158:161], v[182:185], v[60:63]
	v_mfma_f32_16x16x32_bf16 v[48:51], v[150:153], v[190:193], v[48:51]
	v_mfma_f32_16x16x32_bf16 v[44:47], v[158:161], v[190:193], v[44:47]
	v_mfma_f32_16x16x32_bf16 v[32:35], v[150:153], v[210:213], v[32:35]
	v_mfma_f32_16x16x32_bf16 v[28:31], v[158:161], v[210:213], v[28:31]
	v_mfma_f32_16x16x32_bf16 v[16:19], v[150:153], v[218:221], v[16:19]
	v_mfma_f32_16x16x32_bf16 v[12:15], v[158:161], v[218:221], v[12:15]
	v_mfma_f32_16x16x32_bf16 v[56:59], v[162:165], v[178:181], v[56:59]
	v_mfma_f32_16x16x32_bf16 v[52:55], v[170:173], v[178:181], v[52:55]
	v_mfma_f32_16x16x32_bf16 v[40:43], v[162:165], v[186:189], v[40:43]
	v_mfma_f32_16x16x32_bf16 v[36:39], v[170:173], v[186:189], v[36:39]
	v_mfma_f32_16x16x32_bf16 v[24:27], v[162:165], v[194:197], v[24:27]
	v_mfma_f32_16x16x32_bf16 v[20:23], v[170:173], v[194:197], v[20:23]
	v_mfma_f32_16x16x32_bf16 v[8:11], v[162:165], v[214:217], v[8:11]
	v_mfma_f32_16x16x32_bf16 v[4:7], v[170:173], v[214:217], v[4:7]
	v_mfma_f32_16x16x32_bf16 v[56:59], v[166:169], v[182:185], v[56:59]
	v_mfma_f32_16x16x32_bf16 v[52:55], v[174:177], v[182:185], v[52:55]
	v_mfma_f32_16x16x32_bf16 v[40:43], v[166:169], v[190:193], v[40:43]
	v_mfma_f32_16x16x32_bf16 v[36:39], v[174:177], v[190:193], v[36:39]
	v_mfma_f32_16x16x32_bf16 v[24:27], v[166:169], v[210:213], v[24:27]
	v_mfma_f32_16x16x32_bf16 v[20:23], v[174:177], v[210:213], v[20:23]
	v_mfma_f32_16x16x32_bf16 v[8:11], v[166:169], v[218:221], v[8:11]
	v_mfma_f32_16x16x32_bf16 v[4:7], v[174:177], v[218:221], v[4:7]
	s_barrier
	s_setprio 0
	s_add_i32 s48, 0, 0x18000
	s_add_i32 s49, 0, 0x1c000
	ds_read_b128 v[146:149], v251 offset:32768
	ds_read_b128 v[150:153], v251 offset:33792
	ds_read_b128 v[154:157], v251 offset:34816
	ds_read_b128 v[158:161], v251 offset:35840
	ds_read_b128 v[162:165], v251 offset:49152
	ds_read_b128 v[166:169], v251 offset:50176
	ds_read_b128 v[170:173], v251 offset:51200
	ds_read_b128 v[174:177], v251 offset:52224
	s_add_u32 s12, s12, 0x80000
	s_addc_u32 s13, s13, 0
	s_mov_b32 m0, s21
	v_lshl_add_u64 v[224:225], s[12:13], 0, v[132:133]
	ds_read_b128 v[178:181], v144 offset:32768
	ds_read_b128 v[182:185], v144 offset:33792
	ds_read_b128 v[186:189], v144 offset:34816
	ds_read_b128 v[190:193], v144 offset:35840
	ds_read_b128 v[194:197], v144 offset:36864
	ds_read_b128 v[210:213], v144 offset:37888
	ds_read_b128 v[214:217], v144 offset:38912
	ds_read_b128 v[218:221], v144 offset:39936
	global_load_lds_dwordx4 v[224:225], off
	s_mov_b32 m0, s23
	v_lshl_add_u64 v[224:225], s[12:13], 0, v[134:135]
	global_load_lds_dwordx4 v[224:225], off
	s_waitcnt vmcnt(8) lgkmcnt(0)
	s_setprio 1
	s_barrier
	v_mfma_f32_16x16x32_bf16 v[128:131], v[146:149], v[178:181], v[128:131]
	v_mfma_f32_16x16x32_bf16 v[124:127], v[154:157], v[178:181], v[124:127]
	v_mfma_f32_16x16x32_bf16 v[112:115], v[146:149], v[186:189], v[112:115]
	v_mfma_f32_16x16x32_bf16 v[108:111], v[154:157], v[186:189], v[108:111]
	v_mfma_f32_16x16x32_bf16 v[96:99], v[146:149], v[194:197], v[96:99]
	v_mfma_f32_16x16x32_bf16 v[92:95], v[154:157], v[194:197], v[92:95]
	v_mfma_f32_16x16x32_bf16 v[80:83], v[146:149], v[214:217], v[80:83]
	v_mfma_f32_16x16x32_bf16 v[76:79], v[154:157], v[214:217], v[76:79]
	v_mfma_f32_16x16x32_bf16 v[128:131], v[150:153], v[182:185], v[128:131]
	v_mfma_f32_16x16x32_bf16 v[124:127], v[158:161], v[182:185], v[124:127]
	v_mfma_f32_16x16x32_bf16 v[112:115], v[150:153], v[190:193], v[112:115]
	v_mfma_f32_16x16x32_bf16 v[108:111], v[158:161], v[190:193], v[108:111]
	v_mfma_f32_16x16x32_bf16 v[96:99], v[150:153], v[210:213], v[96:99]
	v_mfma_f32_16x16x32_bf16 v[92:95], v[158:161], v[210:213], v[92:95]
	v_mfma_f32_16x16x32_bf16 v[80:83], v[150:153], v[218:221], v[80:83]
	v_mfma_f32_16x16x32_bf16 v[76:79], v[158:161], v[218:221], v[76:79]
	v_mfma_f32_16x16x32_bf16 v[120:123], v[162:165], v[178:181], v[120:123]
	v_mfma_f32_16x16x32_bf16 v[116:119], v[170:173], v[178:181], v[116:119]
	v_mfma_f32_16x16x32_bf16 v[104:107], v[162:165], v[186:189], v[104:107]
	v_mfma_f32_16x16x32_bf16 v[100:103], v[170:173], v[186:189], v[100:103]
	v_mfma_f32_16x16x32_bf16 v[88:91], v[162:165], v[194:197], v[88:91]
	v_mfma_f32_16x16x32_bf16 v[84:87], v[170:173], v[194:197], v[84:87]
	v_mfma_f32_16x16x32_bf16 v[72:75], v[162:165], v[214:217], v[72:75]
	v_mfma_f32_16x16x32_bf16 v[68:71], v[170:173], v[214:217], v[68:71]
	v_mfma_f32_16x16x32_bf16 v[120:123], v[166:169], v[182:185], v[120:123]
	v_mfma_f32_16x16x32_bf16 v[116:119], v[174:177], v[182:185], v[116:119]
	v_mfma_f32_16x16x32_bf16 v[104:107], v[166:169], v[190:193], v[104:107]
	v_mfma_f32_16x16x32_bf16 v[100:103], v[174:177], v[190:193], v[100:103]
	v_mfma_f32_16x16x32_bf16 v[88:91], v[166:169], v[210:213], v[88:91]
	v_mfma_f32_16x16x32_bf16 v[84:87], v[174:177], v[210:213], v[84:87]
	v_mfma_f32_16x16x32_bf16 v[72:75], v[166:169], v[218:221], v[72:75]
	v_mfma_f32_16x16x32_bf16 v[68:71], v[174:177], v[218:221], v[68:71]
	s_barrier
	s_setprio 0
	s_add_i32 s12, s48, s14
	v_lshl_add_u64 v[198:199], v[198:199], 0, s[66:67]
	s_mov_b32 m0, s12
	ds_read_b128 v[178:181], v144 offset:49152
	ds_read_b128 v[182:185], v144 offset:50176
	ds_read_b128 v[186:189], v144 offset:51200
	ds_read_b128 v[190:193], v144 offset:52224
	ds_read_b128 v[194:197], v144 offset:53248
	ds_read_b128 v[210:213], v144 offset:54272
	ds_read_b128 v[214:217], v144 offset:55296
	ds_read_b128 v[218:221], v144 offset:56320
	global_load_lds_dwordx4 v[198:199], off
	s_add_i32 m0, s12, 0x2000
	s_add_u32 s10, s10, 0x80080
	v_lshl_add_u64 v[198:199], v[206:207], 0, s[66:67]
	s_addc_u32 s11, s11, 0
	s_add_i32 s12, s49, s14
	global_load_lds_dwordx4 v[198:199], off
	s_mov_b32 m0, s12
	v_lshl_add_u64 v[198:199], s[10:11], 0, v[200:201]
	global_load_lds_dwordx4 v[198:199], off
	s_add_i32 m0, s12, 0x2000
	v_lshl_add_u64 v[198:199], s[10:11], 0, v[136:137]
	global_load_lds_dwordx4 v[198:199], off
	v_lshl_add_u64 v[198:199], v[208:209], 0, s[66:67]
	s_mov_b32 m0, s42
	s_nop 0
	global_load_lds_dwordx4 v[198:199], off
	v_lshl_add_u64 v[198:199], v[222:223], 0, s[66:67]
	s_mov_b32 m0, s44
	s_nop 0
	global_load_lds_dwordx4 v[198:199], off
	s_waitcnt vmcnt(8) lgkmcnt(0)
	s_setprio 1
	s_barrier
	v_mfma_f32_16x16x32_bf16 v[64:67], v[146:149], v[178:181], v[64:67]
	v_mfma_f32_16x16x32_bf16 v[60:63], v[154:157], v[178:181], v[60:63]
	v_mfma_f32_16x16x32_bf16 v[48:51], v[146:149], v[186:189], v[48:51]
	v_mfma_f32_16x16x32_bf16 v[44:47], v[154:157], v[186:189], v[44:47]
	v_mfma_f32_16x16x32_bf16 v[32:35], v[146:149], v[194:197], v[32:35]
	v_mfma_f32_16x16x32_bf16 v[28:31], v[154:157], v[194:197], v[28:31]
	v_mfma_f32_16x16x32_bf16 v[16:19], v[146:149], v[214:217], v[16:19]
	v_mfma_f32_16x16x32_bf16 v[12:15], v[154:157], v[214:217], v[12:15]
	v_mfma_f32_16x16x32_bf16 v[64:67], v[150:153], v[182:185], v[64:67]
	v_mfma_f32_16x16x32_bf16 v[60:63], v[158:161], v[182:185], v[60:63]
	v_mfma_f32_16x16x32_bf16 v[48:51], v[150:153], v[190:193], v[48:51]
	v_mfma_f32_16x16x32_bf16 v[44:47], v[158:161], v[190:193], v[44:47]
	v_mfma_f32_16x16x32_bf16 v[32:35], v[150:153], v[210:213], v[32:35]
	v_mfma_f32_16x16x32_bf16 v[28:31], v[158:161], v[210:213], v[28:31]
	v_mfma_f32_16x16x32_bf16 v[16:19], v[150:153], v[218:221], v[16:19]
	v_mfma_f32_16x16x32_bf16 v[12:15], v[158:161], v[218:221], v[12:15]
	v_mfma_f32_16x16x32_bf16 v[56:59], v[162:165], v[178:181], v[56:59]
	v_mfma_f32_16x16x32_bf16 v[52:55], v[170:173], v[178:181], v[52:55]
	v_mfma_f32_16x16x32_bf16 v[40:43], v[162:165], v[186:189], v[40:43]
	v_mfma_f32_16x16x32_bf16 v[36:39], v[170:173], v[186:189], v[36:39]
	v_mfma_f32_16x16x32_bf16 v[24:27], v[162:165], v[194:197], v[24:27]
	v_mfma_f32_16x16x32_bf16 v[20:23], v[170:173], v[194:197], v[20:23]
	v_mfma_f32_16x16x32_bf16 v[8:11], v[162:165], v[214:217], v[8:11]
	v_mfma_f32_16x16x32_bf16 v[4:7], v[170:173], v[214:217], v[4:7]
	v_mfma_f32_16x16x32_bf16 v[56:59], v[166:169], v[182:185], v[56:59]
	v_mfma_f32_16x16x32_bf16 v[52:55], v[174:177], v[182:185], v[52:55]
	v_mfma_f32_16x16x32_bf16 v[40:43], v[166:169], v[190:193], v[40:43]
	v_mfma_f32_16x16x32_bf16 v[36:39], v[174:177], v[190:193], v[36:39]
	v_mfma_f32_16x16x32_bf16 v[24:27], v[166:169], v[210:213], v[24:27]
	v_mfma_f32_16x16x32_bf16 v[20:23], v[174:177], v[210:213], v[20:23]
	v_mfma_f32_16x16x32_bf16 v[8:11], v[166:169], v[218:221], v[8:11]
	v_mfma_f32_16x16x32_bf16 v[4:7], v[174:177], v[218:221], v[4:7]
	s_barrier
	s_setprio 0
	s_add_i32 s51, s51, 2
	s_add_u32 s6, s6, 0x100
	s_addc_u32 s7, s7, 0
	s_cmp_gt_u32 s51, 29
	s_cbranch_scc0 .LBB0_279
	s_cmpk_lt_u32 s1, 0x100
	s_cbranch_scc0 .LBB0_282
	s_barrier

.LBB0_290:
	s_add_u32 s48, s24, 0xfffe0080
	s_addc_u32 s49, s25, -1
	s_add_i32 s84, 0, 0x10000
	s_cmp_eq_u32 s83, 4
	s_cselect_b32 s61, s68, s49
	s_cselect_b32 s60, s69, s48
	s_cselect_b32 s51, s70, s81
	s_cselect_b32 s50, s71, s73
	s_add_i32 s48, 0, 0x14000
	ds_read_b128 v[142:145], v251
	ds_read_b128 v[152:155], v251 offset:1024
	ds_read_b128 v[156:159], v251 offset:2048
	ds_read_b128 v[160:163], v251 offset:3072
	ds_read_b128 v[164:167], v251 offset:16384
	ds_read_b128 v[168:171], v251 offset:17408
	ds_read_b128 v[172:175], v251 offset:18432
	ds_read_b128 v[176:179], v251 offset:19456
	v_lshl_add_u64 v[146:147], s[24:25], 0, v[140:141]
	s_add_i32 m0, s23, 0xc000
	ds_read_b128 v[180:183], v150
	ds_read_b128 v[184:187], v150 offset:1024
	ds_read_b128 v[188:191], v150 offset:2048
	ds_read_b128 v[192:195], v150 offset:3072
	ds_read_b128 v[196:199], v150 offset:4096
	ds_read_b128 v[210:213], v150 offset:5120
	ds_read_b128 v[214:217], v150 offset:6144
	ds_read_b128 v[218:221], v150 offset:7168
	global_load_lds_dwordx4 v[146:147], off
	s_add_i32 m0, s23, 0xe000
	v_lshl_add_u64 v[146:147], s[24:25], 0, v[138:139]
	global_load_lds_dwordx4 v[146:147], off
	s_waitcnt vmcnt(8) lgkmcnt(0)
	s_setprio 1
	s_barrier
	v_mfma_f32_16x16x32_bf16 v[128:131], v[142:145], v[180:183], v[128:131]
	v_mfma_f32_16x16x32_bf16 v[124:127], v[156:159], v[180:183], v[124:127]
	v_mfma_f32_16x16x32_bf16 v[112:115], v[142:145], v[188:191], v[112:115]
	v_mfma_f32_16x16x32_bf16 v[108:111], v[156:159], v[188:191], v[108:111]
	v_mfma_f32_16x16x32_bf16 v[96:99], v[142:145], v[196:199], v[96:99]
	v_mfma_f32_16x16x32_bf16 v[92:95], v[156:159], v[196:199], v[92:95]
	v_mfma_f32_16x16x32_bf16 v[80:83], v[142:145], v[214:217], v[80:83]
	v_mfma_f32_16x16x32_bf16 v[76:79], v[156:159], v[214:217], v[76:79]
	v_mfma_f32_16x16x32_bf16 v[128:131], v[152:155], v[184:187], v[128:131]
	v_mfma_f32_16x16x32_bf16 v[124:127], v[160:163], v[184:187], v[124:127]
	v_mfma_f32_16x16x32_bf16 v[112:115], v[152:155], v[192:195], v[112:115]
	v_mfma_f32_16x16x32_bf16 v[108:111], v[160:163], v[192:195], v[108:111]
	v_mfma_f32_16x16x32_bf16 v[96:99], v[152:155], v[210:213], v[96:99]
	v_mfma_f32_16x16x32_bf16 v[92:95], v[160:163], v[210:213], v[92:95]
	v_mfma_f32_16x16x32_bf16 v[80:83], v[152:155], v[218:221], v[80:83]
	v_mfma_f32_16x16x32_bf16 v[76:79], v[160:163], v[218:221], v[76:79]
	v_mfma_f32_16x16x32_bf16 v[120:123], v[164:167], v[180:183], v[120:123]
	v_mfma_f32_16x16x32_bf16 v[116:119], v[172:175], v[180:183], v[116:119]
	v_mfma_f32_16x16x32_bf16 v[104:107], v[164:167], v[188:191], v[104:107]
	v_mfma_f32_16x16x32_bf16 v[100:103], v[172:175], v[188:191], v[100:103]
	v_mfma_f32_16x16x32_bf16 v[88:91], v[164:167], v[196:199], v[88:91]
	v_mfma_f32_16x16x32_bf16 v[84:87], v[172:175], v[196:199], v[84:87]
	v_mfma_f32_16x16x32_bf16 v[72:75], v[164:167], v[214:217], v[72:75]
	v_mfma_f32_16x16x32_bf16 v[68:71], v[172:175], v[214:217], v[68:71]
	v_mfma_f32_16x16x32_bf16 v[120:123], v[168:171], v[184:187], v[120:123]
	v_mfma_f32_16x16x32_bf16 v[116:119], v[176:179], v[184:187], v[116:119]
	v_mfma_f32_16x16x32_bf16 v[104:107], v[168:171], v[192:195], v[104:107]
	v_mfma_f32_16x16x32_bf16 v[100:103], v[176:179], v[192:195], v[100:103]
	v_mfma_f32_16x16x32_bf16 v[88:91], v[168:171], v[210:213], v[88:91]
	v_mfma_f32_16x16x32_bf16 v[84:87], v[176:179], v[210:213], v[84:87]
	v_mfma_f32_16x16x32_bf16 v[72:75], v[168:171], v[218:221], v[72:75]
	v_mfma_f32_16x16x32_bf16 v[68:71], v[176:179], v[218:221], v[68:71]
	s_barrier
	s_setprio 0
	s_add_i32 s49, s84, s21
	v_lshl_add_u64 v[146:147], s[50:51], 0, v[200:201]
	s_mov_b32 m0, s49
	ds_read_b128 v[180:183], v150 offset:16384
	ds_read_b128 v[184:187], v150 offset:17408
	ds_read_b128 v[188:191], v150 offset:18432
	ds_read_b128 v[192:195], v150 offset:19456
	ds_read_b128 v[196:199], v150 offset:20480
	ds_read_b128 v[210:213], v150 offset:21504
	ds_read_b128 v[214:217], v150 offset:22528
	ds_read_b128 v[218:221], v150 offset:23552
	global_load_lds_dwordx4 v[146:147], off
	s_add_i32 m0, s49, 0x2000
	s_add_u32 s84, s50, 0x20000
	v_lshl_add_u64 v[206:207], s[50:51], 0, v[132:133]
	s_addc_u32 s85, s51, 0
	s_add_i32 s48, s48, s21
	global_load_lds_dwordx4 v[206:207], off
	v_lshl_add_u64 v[208:209], s[84:85], 0, v[200:201]
	s_mov_b32 m0, s48
	v_lshl_add_u64 v[222:223], s[60:61], 0, v[134:135]
	global_load_lds_dwordx4 v[208:209], off
	s_add_i32 m0, s48, 0x2000
	v_lshl_add_u64 v[208:209], s[84:85], 0, v[132:133]
	global_load_lds_dwordx4 v[208:209], off
	s_mov_b32 m0, s23
	v_lshl_add_u64 v[208:209], s[60:61], 0, v[136:137]
	global_load_lds_dwordx4 v[208:209], off
	s_mov_b32 m0, s42
	s_nop 0
	global_load_lds_dwordx4 v[222:223], off
	s_waitcnt vmcnt(8) lgkmcnt(0)
	s_setprio 1
	s_barrier
	v_mfma_f32_16x16x32_bf16 v[64:67], v[142:145], v[180:183], v[64:67]
	v_mfma_f32_16x16x32_bf16 v[60:63], v[156:159], v[180:183], v[60:63]
	v_mfma_f32_16x16x32_bf16 v[48:51], v[142:145], v[188:191], v[48:51]
	v_mfma_f32_16x16x32_bf16 v[44:47], v[156:159], v[188:191], v[44:47]
	v_mfma_f32_16x16x32_bf16 v[32:35], v[142:145], v[196:199], v[32:35]
	v_mfma_f32_16x16x32_bf16 v[28:31], v[156:159], v[196:199], v[28:31]
	v_mfma_f32_16x16x32_bf16 v[16:19], v[142:145], v[214:217], v[16:19]
	v_mfma_f32_16x16x32_bf16 v[12:15], v[156:159], v[214:217], v[12:15]
	v_mfma_f32_16x16x32_bf16 v[64:67], v[152:155], v[184:187], v[64:67]
	v_mfma_f32_16x16x32_bf16 v[60:63], v[160:163], v[184:187], v[60:63]
	v_mfma_f32_16x16x32_bf16 v[48:51], v[152:155], v[192:195], v[48:51]
	v_mfma_f32_16x16x32_bf16 v[44:47], v[160:163], v[192:195], v[44:47]
	v_mfma_f32_16x16x32_bf16 v[32:35], v[152:155], v[210:213], v[32:35]
	v_mfma_f32_16x16x32_bf16 v[28:31], v[160:163], v[210:213], v[28:31]
	v_mfma_f32_16x16x32_bf16 v[16:19], v[152:155], v[218:221], v[16:19]
	v_mfma_f32_16x16x32_bf16 v[12:15], v[160:163], v[218:221], v[12:15]
	v_mfma_f32_16x16x32_bf16 v[56:59], v[164:167], v[180:183], v[56:59]
	v_mfma_f32_16x16x32_bf16 v[52:55], v[172:175], v[180:183], v[52:55]
	v_mfma_f32_16x16x32_bf16 v[40:43], v[164:167], v[188:191], v[40:43]
	v_mfma_f32_16x16x32_bf16 v[36:39], v[172:175], v[188:191], v[36:39]
	v_mfma_f32_16x16x32_bf16 v[24:27], v[164:167], v[196:199], v[24:27]
	v_mfma_f32_16x16x32_bf16 v[20:23], v[172:175], v[196:199], v[20:23]
	v_mfma_f32_16x16x32_bf16 v[8:11], v[164:167], v[214:217], v[8:11]
	v_mfma_f32_16x16x32_bf16 v[4:7], v[172:175], v[214:217], v[4:7]
	v_mfma_f32_16x16x32_bf16 v[56:59], v[168:171], v[184:187], v[56:59]
	v_mfma_f32_16x16x32_bf16 v[52:55], v[176:179], v[184:187], v[52:55]
	v_mfma_f32_16x16x32_bf16 v[40:43], v[168:171], v[192:195], v[40:43]
	v_mfma_f32_16x16x32_bf16 v[36:39], v[176:179], v[192:195], v[36:39]
	v_mfma_f32_16x16x32_bf16 v[24:27], v[168:171], v[210:213], v[24:27]
	v_mfma_f32_16x16x32_bf16 v[20:23], v[176:179], v[210:213], v[20:23]
	v_mfma_f32_16x16x32_bf16 v[8:11], v[168:171], v[218:221], v[8:11]
	v_mfma_f32_16x16x32_bf16 v[4:7], v[176:179], v[218:221], v[4:7]
	s_barrier
	s_setprio 0
	s_add_i32 s48, 0, 0x18000
	s_add_i32 s49, 0, 0x1c000
	ds_read_b128 v[142:145], v251 offset:32768
	ds_read_b128 v[152:155], v251 offset:33792
	ds_read_b128 v[156:159], v251 offset:34816
	ds_read_b128 v[160:163], v251 offset:35840
	ds_read_b128 v[164:167], v251 offset:49152
	ds_read_b128 v[168:171], v251 offset:50176
	ds_read_b128 v[172:175], v251 offset:51200
	ds_read_b128 v[176:179], v251 offset:52224
	s_add_u32 s60, s60, 0x20000
	s_addc_u32 s61, s61, 0
	s_mov_b32 m0, s44
	v_lshl_add_u64 v[224:225], s[60:61], 0, v[136:137]
	ds_read_b128 v[180:183], v150 offset:32768
	ds_read_b128 v[184:187], v150 offset:33792
	ds_read_b128 v[188:191], v150 offset:34816
	ds_read_b128 v[192:195], v150 offset:35840
	ds_read_b128 v[196:199], v150 offset:36864
	ds_read_b128 v[210:213], v150 offset:37888
	ds_read_b128 v[214:217], v150 offset:38912
	ds_read_b128 v[218:221], v150 offset:39936
	global_load_lds_dwordx4 v[224:225], off
	s_mov_b32 m0, s52
	v_lshl_add_u64 v[224:225], s[60:61], 0, v[134:135]
	global_load_lds_dwordx4 v[224:225], off
	s_waitcnt vmcnt(8) lgkmcnt(0)
	s_setprio 1
	s_barrier
	v_mfma_f32_16x16x32_bf16 v[128:131], v[142:145], v[180:183], v[128:131]
	v_mfma_f32_16x16x32_bf16 v[124:127], v[156:159], v[180:183], v[124:127]
	v_mfma_f32_16x16x32_bf16 v[112:115], v[142:145], v[188:191], v[112:115]
	v_mfma_f32_16x16x32_bf16 v[108:111], v[156:159], v[188:191], v[108:111]
	v_mfma_f32_16x16x32_bf16 v[96:99], v[142:145], v[196:199], v[96:99]
	v_mfma_f32_16x16x32_bf16 v[92:95], v[156:159], v[196:199], v[92:95]
	v_mfma_f32_16x16x32_bf16 v[80:83], v[142:145], v[214:217], v[80:83]
	v_mfma_f32_16x16x32_bf16 v[76:79], v[156:159], v[214:217], v[76:79]
	v_mfma_f32_16x16x32_bf16 v[128:131], v[152:155], v[184:187], v[128:131]
	v_mfma_f32_16x16x32_bf16 v[124:127], v[160:163], v[184:187], v[124:127]
	v_mfma_f32_16x16x32_bf16 v[112:115], v[152:155], v[192:195], v[112:115]
	v_mfma_f32_16x16x32_bf16 v[108:111], v[160:163], v[192:195], v[108:111]
	v_mfma_f32_16x16x32_bf16 v[96:99], v[152:155], v[210:213], v[96:99]
	v_mfma_f32_16x16x32_bf16 v[92:95], v[160:163], v[210:213], v[92:95]
	v_mfma_f32_16x16x32_bf16 v[80:83], v[152:155], v[218:221], v[80:83]
	v_mfma_f32_16x16x32_bf16 v[76:79], v[160:163], v[218:221], v[76:79]
	v_mfma_f32_16x16x32_bf16 v[120:123], v[164:167], v[180:183], v[120:123]
	v_mfma_f32_16x16x32_bf16 v[116:119], v[172:175], v[180:183], v[116:119]
	v_mfma_f32_16x16x32_bf16 v[104:107], v[164:167], v[188:191], v[104:107]
	v_mfma_f32_16x16x32_bf16 v[100:103], v[172:175], v[188:191], v[100:103]
	v_mfma_f32_16x16x32_bf16 v[88:91], v[164:167], v[196:199], v[88:91]
	v_mfma_f32_16x16x32_bf16 v[84:87], v[172:175], v[196:199], v[84:87]
	v_mfma_f32_16x16x32_bf16 v[72:75], v[164:167], v[214:217], v[72:75]
	v_mfma_f32_16x16x32_bf16 v[68:71], v[172:175], v[214:217], v[68:71]
	v_mfma_f32_16x16x32_bf16 v[120:123], v[168:171], v[184:187], v[120:123]
	v_mfma_f32_16x16x32_bf16 v[116:119], v[176:179], v[184:187], v[116:119]
	v_mfma_f32_16x16x32_bf16 v[104:107], v[168:171], v[192:195], v[104:107]
	v_mfma_f32_16x16x32_bf16 v[100:103], v[176:179], v[192:195], v[100:103]
	v_mfma_f32_16x16x32_bf16 v[88:91], v[168:171], v[210:213], v[88:91]
	v_mfma_f32_16x16x32_bf16 v[84:87], v[176:179], v[210:213], v[84:87]
	v_mfma_f32_16x16x32_bf16 v[72:75], v[168:171], v[218:221], v[72:75]
	v_mfma_f32_16x16x32_bf16 v[68:71], v[176:179], v[218:221], v[68:71]
	s_barrier
	s_setprio 0
	s_add_i32 s48, s48, s21
	v_lshl_add_u64 v[146:147], v[146:147], 0, s[66:67]
	s_mov_b32 m0, s48
	ds_read_b128 v[180:183], v150 offset:49152
	ds_read_b128 v[184:187], v150 offset:50176
	ds_read_b128 v[188:191], v150 offset:51200
	ds_read_b128 v[192:195], v150 offset:52224
	ds_read_b128 v[196:199], v150 offset:53248
	ds_read_b128 v[210:213], v150 offset:54272
	ds_read_b128 v[214:217], v150 offset:55296
	ds_read_b128 v[218:221], v150 offset:56320
	global_load_lds_dwordx4 v[146:147], off
	s_add_i32 m0, s48, 0x2000
	s_add_u32 s50, s50, 0x20080
	v_lshl_add_u64 v[146:147], v[206:207], 0, s[66:67]
	s_addc_u32 s51, s51, 0
	s_add_i32 s48, s49, s21
	global_load_lds_dwordx4 v[146:147], off
	s_mov_b32 m0, s48
	v_lshl_add_u64 v[146:147], s[50:51], 0, v[200:201]
	global_load_lds_dwordx4 v[146:147], off
	s_add_i32 m0, s48, 0x2000
	v_lshl_add_u64 v[146:147], s[50:51], 0, v[132:133]
	global_load_lds_dwordx4 v[146:147], off
	v_lshl_add_u64 v[146:147], v[208:209], 0, s[66:67]
	s_mov_b32 m0, s54
	s_nop 0
	global_load_lds_dwordx4 v[146:147], off
	v_lshl_add_u64 v[146:147], v[222:223], 0, s[66:67]
	s_mov_b32 m0, s55
	s_nop 0
	global_load_lds_dwordx4 v[146:147], off
	s_waitcnt vmcnt(8) lgkmcnt(0)
	s_setprio 1
	s_barrier
	v_mfma_f32_16x16x32_bf16 v[64:67], v[142:145], v[180:183], v[64:67]
	v_mfma_f32_16x16x32_bf16 v[60:63], v[156:159], v[180:183], v[60:63]
	v_mfma_f32_16x16x32_bf16 v[48:51], v[142:145], v[188:191], v[48:51]
	v_mfma_f32_16x16x32_bf16 v[44:47], v[156:159], v[188:191], v[44:47]
	v_mfma_f32_16x16x32_bf16 v[32:35], v[142:145], v[196:199], v[32:35]
	v_mfma_f32_16x16x32_bf16 v[28:31], v[156:159], v[196:199], v[28:31]
	v_mfma_f32_16x16x32_bf16 v[16:19], v[142:145], v[214:217], v[16:19]
	v_mfma_f32_16x16x32_bf16 v[12:15], v[156:159], v[214:217], v[12:15]
	v_mfma_f32_16x16x32_bf16 v[64:67], v[152:155], v[184:187], v[64:67]
	v_mfma_f32_16x16x32_bf16 v[60:63], v[160:163], v[184:187], v[60:63]
	v_mfma_f32_16x16x32_bf16 v[48:51], v[152:155], v[192:195], v[48:51]
	v_mfma_f32_16x16x32_bf16 v[44:47], v[160:163], v[192:195], v[44:47]
	v_mfma_f32_16x16x32_bf16 v[32:35], v[152:155], v[210:213], v[32:35]
	v_mfma_f32_16x16x32_bf16 v[28:31], v[160:163], v[210:213], v[28:31]
	v_mfma_f32_16x16x32_bf16 v[16:19], v[152:155], v[218:221], v[16:19]
	v_mfma_f32_16x16x32_bf16 v[12:15], v[160:163], v[218:221], v[12:15]
	v_mfma_f32_16x16x32_bf16 v[56:59], v[164:167], v[180:183], v[56:59]
	v_mfma_f32_16x16x32_bf16 v[52:55], v[172:175], v[180:183], v[52:55]
	v_mfma_f32_16x16x32_bf16 v[40:43], v[164:167], v[188:191], v[40:43]
	v_mfma_f32_16x16x32_bf16 v[36:39], v[172:175], v[188:191], v[36:39]
	v_mfma_f32_16x16x32_bf16 v[24:27], v[164:167], v[196:199], v[24:27]
	v_mfma_f32_16x16x32_bf16 v[20:23], v[172:175], v[196:199], v[20:23]
	v_mfma_f32_16x16x32_bf16 v[8:11], v[164:167], v[214:217], v[8:11]
	v_mfma_f32_16x16x32_bf16 v[4:7], v[172:175], v[214:217], v[4:7]
	v_mfma_f32_16x16x32_bf16 v[56:59], v[168:171], v[184:187], v[56:59]
	v_mfma_f32_16x16x32_bf16 v[52:55], v[176:179], v[184:187], v[52:55]
	v_mfma_f32_16x16x32_bf16 v[40:43], v[168:171], v[192:195], v[40:43]
	v_mfma_f32_16x16x32_bf16 v[36:39], v[176:179], v[192:195], v[36:39]
	v_mfma_f32_16x16x32_bf16 v[24:27], v[168:171], v[210:213], v[24:27]
	v_mfma_f32_16x16x32_bf16 v[20:23], v[176:179], v[210:213], v[20:23]
	v_mfma_f32_16x16x32_bf16 v[8:11], v[168:171], v[218:221], v[8:11]
	v_mfma_f32_16x16x32_bf16 v[4:7], v[176:179], v[218:221], v[4:7]
	s_barrier
	s_setprio 0
	s_add_i32 s83, s83, 2
	s_add_u32 s73, s73, 0x100
	s_addc_u32 s81, s81, 0
	s_add_u32 s24, s24, 0x100
	s_addc_u32 s25, s25, 0
	s_cmp_gt_u32 s83, 5
	s_cbranch_scc0 .LBB0_290
	v_mov_b32_e32 v142, v148
	v_mov_b32_e32 v143, v3
	v_readlane_b32 s84, v255, 29
	s_add_i32 s24, s63, s84
	v_add_u32_e32 v151, s56, v143
	v_ashrrev_i32_e32 v156, 12, v151
	s_ashr_i32 s25, s24, 31
	v_ashrrev_i32_e32 v157, 31, v156
	s_lshl_b64 s[24:25], s[24:25], 12
	v_lshlrev_b64 v[156:157], 16, v[156:157]
	v_lshl_add_u32 v143, v143, 2, s58
	v_lshl_add_u64 v[156:157], v[156:157], 0, s[24:25]
	v_lshl_add_u32 v142, v142, 3, s53
	ds_read2_b32 v[152:153], v143 offset1:16
	ds_read2_b32 v[154:155], v143 offset0:32 offset1:48
	ds_read2_b32 v[146:147], v143 offset0:128 offset1:144
	ds_read2_b32 v[144:145], v143 offset0:160 offset1:176
	v_and_or_b32 v156, v151, s17, v156
	v_ashrrev_i32_e32 v143, 31, v142
	v_lshlrev_b64 v[156:157], 7, v[156:157]
	v_lshl_add_u64 v[156:157], v[156:157], 0, v[142:143]
	s_waitcnt lgkmcnt(0)
	v_pk_mul_f32 v[128:129], v[128:129], v[152:153] op_sel_hi:[1,0]
	v_pk_mul_f32 v[130:131], v[130:131], v[152:153] op_sel_hi:[1,0]
	v_pk_mul_f32 v[158:159], v[126:127], v[152:153] op_sel_hi:[1,0]
	v_pk_mul_f32 v[126:127], v[124:125], v[152:153] op_sel_hi:[1,0]
	v_cvt_pk_bf16_f32 v124, v128, v129
	v_lshlrev_b64 v[128:129], 1, v[156:157]
	v_cvt_pk_bf16_f32 v125, v130, v131
	v_lshl_add_u64 v[130:131], s[12:13], 0, v[128:129]
	v_cvt_pk_bf16_f32 v126, v126, v127
	v_cvt_pk_bf16_f32 v127, v158, v159
	global_store_dwordx4 v[130:131], v[124:127], off
	v_pk_mul_f32 v[120:121], v[120:121], v[152:153] op_sel_hi:[1,0]
	v_pk_mul_f32 v[122:123], v[122:123], v[152:153] op_sel_hi:[1,0]
	v_pk_mul_f32 v[124:125], v[118:119], v[152:153] op_sel_hi:[1,0]
	v_pk_mul_f32 v[118:119], v[116:117], v[152:153] op_sel_hi:[1,0]
	v_cvt_pk_bf16_f32 v116, v120, v121
	v_cvt_pk_bf16_f32 v117, v122, v123
	v_lshl_add_u64 v[120:121], s[14:15], 0, v[128:129]
	v_cvt_pk_bf16_f32 v118, v118, v119
	v_cvt_pk_bf16_f32 v119, v124, v125
	global_store_dwordx4 v[120:121], v[116:119], off
	v_pk_mul_f32 v[96:97], v[96:97], v[154:155] op_sel_hi:[1,0]
	v_pk_mul_f32 v[98:99], v[98:99], v[154:155] op_sel_hi:[1,0]
	v_add_u32_e32 v118, 16, v151
	v_ashrrev_i32_e32 v116, 12, v118
	v_ashrrev_i32_e32 v117, 31, v116
	v_lshlrev_b64 v[116:117], 16, v[116:117]
	v_lshl_add_u64 v[116:117], v[116:117], 0, s[24:25]
	v_and_or_b32 v116, v118, s17, v116
	v_lshlrev_b64 v[116:117], 7, v[116:117]
	v_mov_b32_e32 v118, v153
	v_lshl_add_u64 v[116:117], v[116:117], 0, v[142:143]
	v_pk_mul_f32 v[112:113], v[112:113], v[118:119] op_sel_hi:[1,0]
	v_pk_mul_f32 v[114:115], v[114:115], v[118:119] op_sel_hi:[1,0]
	v_pk_mul_f32 v[120:121], v[110:111], v[118:119] op_sel_hi:[1,0]
	v_pk_mul_f32 v[110:111], v[108:109], v[118:119] op_sel_hi:[1,0]
	v_cvt_pk_bf16_f32 v108, v112, v113
	v_lshlrev_b64 v[112:113], 1, v[116:117]
	v_cvt_pk_bf16_f32 v109, v114, v115
	v_lshl_add_u64 v[114:115], s[12:13], 0, v[112:113]
	v_cvt_pk_bf16_f32 v110, v110, v111
	v_cvt_pk_bf16_f32 v111, v120, v121
	global_store_dwordx4 v[114:115], v[108:111], off
	v_pk_mul_f32 v[104:105], v[104:105], v[118:119] op_sel_hi:[1,0]
	v_pk_mul_f32 v[106:107], v[106:107], v[118:119] op_sel_hi:[1,0]
	v_pk_mul_f32 v[108:109], v[102:103], v[118:119] op_sel_hi:[1,0]
	v_pk_mul_f32 v[102:103], v[100:101], v[118:119] op_sel_hi:[1,0]
	v_cvt_pk_bf16_f32 v100, v104, v105
	v_cvt_pk_bf16_f32 v101, v106, v107
	v_lshl_add_u64 v[104:105], s[14:15], 0, v[112:113]
	v_cvt_pk_bf16_f32 v102, v102, v103
	v_cvt_pk_bf16_f32 v103, v108, v109
	global_store_dwordx4 v[104:105], v[100:103], off
	v_pk_mul_f32 v[88:89], v[88:89], v[154:155] op_sel_hi:[1,0]
	v_pk_mul_f32 v[90:91], v[90:91], v[154:155] op_sel_hi:[1,0]
	v_add_u32_e32 v102, 32, v151
	v_ashrrev_i32_e32 v100, 12, v102
	v_ashrrev_i32_e32 v101, 31, v100
	v_lshlrev_b64 v[100:101], 16, v[100:101]
	v_lshl_add_u64 v[100:101], v[100:101], 0, s[24:25]
	v_and_or_b32 v100, v102, s17, v100
	v_lshlrev_b64 v[100:101], 7, v[100:101]
	v_lshl_add_u64 v[100:101], v[100:101], 0, v[142:143]
	v_pk_mul_f32 v[102:103], v[94:95], v[154:155] op_sel_hi:[1,0]
	v_pk_mul_f32 v[94:95], v[92:93], v[154:155] op_sel_hi:[1,0]
	v_cvt_pk_bf16_f32 v92, v96, v97
	v_lshlrev_b64 v[96:97], 1, v[100:101]
	v_cvt_pk_bf16_f32 v93, v98, v99
	v_lshl_add_u64 v[98:99], s[12:13], 0, v[96:97]
	v_cvt_pk_bf16_f32 v94, v94, v95
	v_cvt_pk_bf16_f32 v95, v102, v103
	global_store_dwordx4 v[98:99], v[92:95], off
	v_pk_mul_f32 v[64:65], v[64:65], v[146:147] op_sel_hi:[1,0]
	v_pk_mul_f32 v[66:67], v[66:67], v[146:147] op_sel_hi:[1,0]
	v_pk_mul_f32 v[92:93], v[86:87], v[154:155] op_sel_hi:[1,0]
	v_pk_mul_f32 v[86:87], v[84:85], v[154:155] op_sel_hi:[1,0]
	v_cvt_pk_bf16_f32 v84, v88, v89
	v_cvt_pk_bf16_f32 v85, v90, v91
	v_lshl_add_u64 v[88:89], s[14:15], 0, v[96:97]
	v_cvt_pk_bf16_f32 v86, v86, v87
	v_cvt_pk_bf16_f32 v87, v92, v93
	global_store_dwordx4 v[88:89], v[84:87], off
	v_pk_mul_f32 v[56:57], v[56:57], v[146:147] op_sel_hi:[1,0]
	v_pk_mul_f32 v[58:59], v[58:59], v[146:147] op_sel_hi:[1,0]
	v_add_u32_e32 v86, 48, v151
	v_ashrrev_i32_e32 v84, 12, v86
	v_ashrrev_i32_e32 v85, 31, v84
	v_lshlrev_b64 v[84:85], 16, v[84:85]
	v_lshl_add_u64 v[84:85], v[84:85], 0, s[24:25]
	v_and_or_b32 v84, v86, s17, v84
	v_lshlrev_b64 v[84:85], 7, v[84:85]
	v_mov_b32_e32 v86, v155
	v_lshl_add_u64 v[84:85], v[84:85], 0, v[142:143]
	v_pk_mul_f32 v[80:81], v[80:81], v[86:87] op_sel_hi:[1,0]
	v_pk_mul_f32 v[82:83], v[82:83], v[86:87] op_sel_hi:[1,0]
	v_pk_mul_f32 v[88:89], v[78:79], v[86:87] op_sel_hi:[1,0]
	v_pk_mul_f32 v[78:79], v[76:77], v[86:87] op_sel_hi:[1,0]
	v_cvt_pk_bf16_f32 v76, v80, v81
	v_lshlrev_b64 v[80:81], 1, v[84:85]
	v_cvt_pk_bf16_f32 v77, v82, v83
	v_lshl_add_u64 v[82:83], s[12:13], 0, v[80:81]
	v_cvt_pk_bf16_f32 v78, v78, v79
	v_cvt_pk_bf16_f32 v79, v88, v89
	global_store_dwordx4 v[82:83], v[76:79], off
	v_pk_mul_f32 v[72:73], v[72:73], v[86:87] op_sel_hi:[1,0]
	v_pk_mul_f32 v[74:75], v[74:75], v[86:87] op_sel_hi:[1,0]
	v_pk_mul_f32 v[76:77], v[70:71], v[86:87] op_sel_hi:[1,0]
	v_pk_mul_f32 v[70:71], v[68:69], v[86:87] op_sel_hi:[1,0]
	v_cvt_pk_bf16_f32 v68, v72, v73
	v_cvt_pk_bf16_f32 v69, v74, v75
	v_lshl_add_u64 v[72:73], s[14:15], 0, v[80:81]
	v_cvt_pk_bf16_f32 v70, v70, v71
	v_cvt_pk_bf16_f32 v71, v76, v77
	global_store_dwordx4 v[72:73], v[68:71], off
	v_pk_mul_f32 v[32:33], v[32:33], v[144:145] op_sel_hi:[1,0]
	v_pk_mul_f32 v[34:35], v[34:35], v[144:145] op_sel_hi:[1,0]
	v_add_u32_e32 v70, 0x80, v151
	v_ashrrev_i32_e32 v68, 12, v70
	v_ashrrev_i32_e32 v69, 31, v68
	v_lshlrev_b64 v[68:69], 16, v[68:69]
	v_lshl_add_u64 v[68:69], v[68:69], 0, s[24:25]
	v_and_or_b32 v68, v70, s17, v68
	v_lshlrev_b64 v[68:69], 7, v[68:69]
	v_lshl_add_u64 v[68:69], v[68:69], 0, v[142:143]
	v_pk_mul_f32 v[70:71], v[62:63], v[146:147] op_sel_hi:[1,0]
	v_pk_mul_f32 v[62:63], v[60:61], v[146:147] op_sel_hi:[1,0]
	v_cvt_pk_bf16_f32 v60, v64, v65
	v_lshlrev_b64 v[64:65], 1, v[68:69]
	v_cvt_pk_bf16_f32 v61, v66, v67
	v_lshl_add_u64 v[66:67], s[12:13], 0, v[64:65]
	v_cvt_pk_bf16_f32 v62, v62, v63
	v_cvt_pk_bf16_f32 v63, v70, v71
	global_store_dwordx4 v[66:67], v[60:63], off
	v_pk_mul_f32 v[24:25], v[24:25], v[144:145] op_sel_hi:[1,0]
	v_pk_mul_f32 v[26:27], v[26:27], v[144:145] op_sel_hi:[1,0]
	v_pk_mul_f32 v[60:61], v[54:55], v[146:147] op_sel_hi:[1,0]
	v_pk_mul_f32 v[54:55], v[52:53], v[146:147] op_sel_hi:[1,0]
	v_cvt_pk_bf16_f32 v52, v56, v57
	v_cvt_pk_bf16_f32 v53, v58, v59
	v_lshl_add_u64 v[56:57], s[14:15], 0, v[64:65]
	v_cvt_pk_bf16_f32 v54, v54, v55
	v_cvt_pk_bf16_f32 v55, v60, v61
	global_store_dwordx4 v[56:57], v[52:55], off
	s_cmp_eq_u32 s62, 8
	s_mov_b32 s63, s62
	v_add_u32_e32 v54, 0x90, v151
	v_ashrrev_i32_e32 v52, 12, v54
	v_ashrrev_i32_e32 v53, 31, v52
	v_lshlrev_b64 v[52:53], 16, v[52:53]
	v_lshl_add_u64 v[52:53], v[52:53], 0, s[24:25]
	v_and_or_b32 v52, v54, s17, v52
	v_lshlrev_b64 v[52:53], 7, v[52:53]
	v_mov_b32_e32 v54, v147
	v_lshl_add_u64 v[52:53], v[52:53], 0, v[142:143]
	v_pk_mul_f32 v[48:49], v[48:49], v[54:55] op_sel_hi:[1,0]
	v_pk_mul_f32 v[50:51], v[50:51], v[54:55] op_sel_hi:[1,0]
	v_pk_mul_f32 v[56:57], v[46:47], v[54:55] op_sel_hi:[1,0]
	v_pk_mul_f32 v[46:47], v[44:45], v[54:55] op_sel_hi:[1,0]
	v_cvt_pk_bf16_f32 v44, v48, v49
	v_lshlrev_b64 v[48:49], 1, v[52:53]
	v_cvt_pk_bf16_f32 v45, v50, v51
	v_lshl_add_u64 v[50:51], s[12:13], 0, v[48:49]
	v_cvt_pk_bf16_f32 v46, v46, v47
	v_cvt_pk_bf16_f32 v47, v56, v57
	global_store_dwordx4 v[50:51], v[44:47], off
	v_pk_mul_f32 v[40:41], v[40:41], v[54:55] op_sel_hi:[1,0]
	v_pk_mul_f32 v[42:43], v[42:43], v[54:55] op_sel_hi:[1,0]
	v_pk_mul_f32 v[44:45], v[38:39], v[54:55] op_sel_hi:[1,0]
	v_pk_mul_f32 v[38:39], v[36:37], v[54:55] op_sel_hi:[1,0]
	v_cvt_pk_bf16_f32 v36, v40, v41
	v_cvt_pk_bf16_f32 v37, v42, v43
	v_lshl_add_u64 v[40:41], s[14:15], 0, v[48:49]
	v_cvt_pk_bf16_f32 v38, v38, v39
	v_cvt_pk_bf16_f32 v39, v44, v45
	global_store_dwordx4 v[40:41], v[36:39], off
	v_readlane_b32 s85, v255, 30
	s_nop 0
	v_add_u32_e32 v38, 0xa0, v151
	v_ashrrev_i32_e32 v36, 12, v38
	v_ashrrev_i32_e32 v37, 31, v36
	v_lshlrev_b64 v[36:37], 16, v[36:37]
	v_lshl_add_u64 v[36:37], v[36:37], 0, s[24:25]
	v_and_or_b32 v36, v38, s17, v36
	v_lshlrev_b64 v[36:37], 7, v[36:37]
	v_lshl_add_u64 v[36:37], v[36:37], 0, v[142:143]
	v_pk_mul_f32 v[38:39], v[30:31], v[144:145] op_sel_hi:[1,0]
	v_pk_mul_f32 v[30:31], v[28:29], v[144:145] op_sel_hi:[1,0]
	v_cvt_pk_bf16_f32 v28, v32, v33
	v_lshlrev_b64 v[32:33], 1, v[36:37]
	v_cvt_pk_bf16_f32 v29, v34, v35
	v_lshl_add_u64 v[34:35], s[12:13], 0, v[32:33]
	v_cvt_pk_bf16_f32 v30, v30, v31
	v_cvt_pk_bf16_f32 v31, v38, v39
	global_store_dwordx4 v[34:35], v[28:31], off
	s_nop 1
	v_pk_mul_f32 v[28:29], v[22:23], v[144:145] op_sel_hi:[1,0]
	v_pk_mul_f32 v[22:23], v[20:21], v[144:145] op_sel_hi:[1,0]
	v_cvt_pk_bf16_f32 v20, v24, v25
	v_cvt_pk_bf16_f32 v21, v26, v27
	v_lshl_add_u64 v[24:25], s[14:15], 0, v[32:33]
	v_cvt_pk_bf16_f32 v22, v22, v23
	v_cvt_pk_bf16_f32 v23, v28, v29
	global_store_dwordx4 v[24:25], v[20:23], off
	s_nop 1
	v_add_u32_e32 v22, 0xb0, v151
	v_ashrrev_i32_e32 v20, 12, v22
	v_ashrrev_i32_e32 v21, 31, v20
	v_lshlrev_b64 v[20:21], 16, v[20:21]
	v_lshl_add_u64 v[20:21], v[20:21], 0, s[24:25]
	v_and_or_b32 v20, v22, s17, v20
	v_lshlrev_b64 v[20:21], 7, v[20:21]
	v_mov_b32_e32 v22, v145
	v_lshl_add_u64 v[20:21], v[20:21], 0, v[142:143]
	v_pk_mul_f32 v[16:17], v[16:17], v[22:23] op_sel_hi:[1,0]
	v_pk_mul_f32 v[18:19], v[18:19], v[22:23] op_sel_hi:[1,0]
	v_pk_mul_f32 v[24:25], v[14:15], v[22:23] op_sel_hi:[1,0]
	v_pk_mul_f32 v[14:15], v[12:13], v[22:23] op_sel_hi:[1,0]
	v_cvt_pk_bf16_f32 v12, v16, v17
	v_lshlrev_b64 v[16:17], 1, v[20:21]
	v_cvt_pk_bf16_f32 v13, v18, v19
	v_lshl_add_u64 v[18:19], s[12:13], 0, v[16:17]
	v_pk_mul_f32 v[8:9], v[8:9], v[22:23] op_sel_hi:[1,0]
	v_cvt_pk_bf16_f32 v14, v14, v15
	v_cvt_pk_bf16_f32 v15, v24, v25
	global_store_dwordx4 v[18:19], v[12:15], off
	v_pk_mul_f32 v[10:11], v[10:11], v[22:23] op_sel_hi:[1,0]
	s_nop 0
	v_pk_mul_f32 v[12:13], v[6:7], v[22:23] op_sel_hi:[1,0]
	v_pk_mul_f32 v[6:7], v[4:5], v[22:23] op_sel_hi:[1,0]
	v_cvt_pk_bf16_f32 v4, v8, v9
	v_lshl_add_u64 v[8:9], s[14:15], 0, v[16:17]
	v_cvt_pk_bf16_f32 v5, v10, v11
	v_cvt_pk_bf16_f32 v6, v6, v7
	v_cvt_pk_bf16_f32 v7, v12, v13
	global_store_dwordx4 v[8:9], v[4:7], off
	s_cbranch_scc0 .LBB0_289
	s_waitcnt vmcnt(0)
	s_cmpk_gt_u32 s20, 0xff
	s_cbranch_scc1 .LBB0_294
	s_barrier

.LBB0_301:
	s_add_u32 s24, s14, 0xfffe0080
	s_addc_u32 s25, s15, -1
	s_add_i32 s48, 0, 0x10000
	s_cmp_eq_u32 s54, 4
	s_cselect_b32 s51, s21, s25
	s_cselect_b32 s50, s23, s24
	s_cselect_b32 s25, s42, s53
	s_cselect_b32 s24, s44, s52
	s_add_i32 s49, 0, 0x14000
	ds_read_b128 v[132:135], v251
	ds_read_b128 v[146:149], v251 offset:1024
	ds_read_b128 v[150:153], v251 offset:2048
	ds_read_b128 v[154:157], v251 offset:3072
	ds_read_b128 v[158:161], v251 offset:16384
	ds_read_b128 v[162:165], v251 offset:17408
	ds_read_b128 v[166:169], v251 offset:18432
	ds_read_b128 v[176:179], v251 offset:19456
	v_lshl_add_u64 v[170:171], s[14:15], 0, v[144:145]
	s_add_i32 m0, s62, 0xc000
	ds_read_b128 v[180:183], v174
	ds_read_b128 v[184:187], v174 offset:1024
	ds_read_b128 v[188:191], v174 offset:2048
	ds_read_b128 v[192:195], v174 offset:3072
	ds_read_b128 v[196:199], v174 offset:4096
	ds_read_b128 v[210:213], v174 offset:5120
	ds_read_b128 v[214:217], v174 offset:6144
	ds_read_b128 v[218:221], v174 offset:7168
	global_load_lds_dwordx4 v[170:171], off
	s_add_i32 m0, s62, 0xe000
	v_lshl_add_u64 v[170:171], s[14:15], 0, v[142:143]
	global_load_lds_dwordx4 v[170:171], off
	s_waitcnt vmcnt(8) lgkmcnt(0)
	s_setprio 1
	s_barrier
	v_mfma_f32_16x16x32_bf16 v[128:131], v[132:135], v[180:183], v[128:131]
	v_mfma_f32_16x16x32_bf16 v[124:127], v[150:153], v[180:183], v[124:127]
	v_mfma_f32_16x16x32_bf16 v[116:119], v[132:135], v[188:191], v[116:119]
	v_mfma_f32_16x16x32_bf16 v[108:111], v[150:153], v[188:191], v[108:111]
	v_mfma_f32_16x16x32_bf16 v[100:103], v[132:135], v[196:199], v[100:103]
	v_mfma_f32_16x16x32_bf16 v[92:95], v[150:153], v[196:199], v[92:95]
	v_mfma_f32_16x16x32_bf16 v[84:87], v[132:135], v[214:217], v[84:87]
	v_mfma_f32_16x16x32_bf16 v[76:79], v[150:153], v[214:217], v[76:79]
	v_mfma_f32_16x16x32_bf16 v[128:131], v[146:149], v[184:187], v[128:131]
	v_mfma_f32_16x16x32_bf16 v[124:127], v[154:157], v[184:187], v[124:127]
	v_mfma_f32_16x16x32_bf16 v[116:119], v[146:149], v[192:195], v[116:119]
	v_mfma_f32_16x16x32_bf16 v[108:111], v[154:157], v[192:195], v[108:111]
	v_mfma_f32_16x16x32_bf16 v[100:103], v[146:149], v[210:213], v[100:103]
	v_mfma_f32_16x16x32_bf16 v[92:95], v[154:157], v[210:213], v[92:95]
	v_mfma_f32_16x16x32_bf16 v[84:87], v[146:149], v[218:221], v[84:87]
	v_mfma_f32_16x16x32_bf16 v[76:79], v[154:157], v[218:221], v[76:79]
	v_mfma_f32_16x16x32_bf16 v[120:123], v[158:161], v[180:183], v[120:123]
	v_mfma_f32_16x16x32_bf16 v[112:115], v[166:169], v[180:183], v[112:115]
	v_mfma_f32_16x16x32_bf16 v[104:107], v[158:161], v[188:191], v[104:107]
	v_mfma_f32_16x16x32_bf16 v[96:99], v[166:169], v[188:191], v[96:99]
	v_mfma_f32_16x16x32_bf16 v[88:91], v[158:161], v[196:199], v[88:91]
	v_mfma_f32_16x16x32_bf16 v[80:83], v[166:169], v[196:199], v[80:83]
	v_mfma_f32_16x16x32_bf16 v[72:75], v[158:161], v[214:217], v[72:75]
	v_mfma_f32_16x16x32_bf16 v[68:71], v[166:169], v[214:217], v[68:71]
	v_mfma_f32_16x16x32_bf16 v[120:123], v[162:165], v[184:187], v[120:123]
	v_mfma_f32_16x16x32_bf16 v[112:115], v[176:179], v[184:187], v[112:115]
	v_mfma_f32_16x16x32_bf16 v[104:107], v[162:165], v[192:195], v[104:107]
	v_mfma_f32_16x16x32_bf16 v[96:99], v[176:179], v[192:195], v[96:99]
	v_mfma_f32_16x16x32_bf16 v[88:91], v[162:165], v[210:213], v[88:91]
	v_mfma_f32_16x16x32_bf16 v[80:83], v[176:179], v[210:213], v[80:83]
	v_mfma_f32_16x16x32_bf16 v[72:75], v[162:165], v[218:221], v[72:75]
	v_mfma_f32_16x16x32_bf16 v[68:71], v[176:179], v[218:221], v[68:71]
	s_barrier
	s_setprio 0
	s_add_i32 s48, s48, s61
	v_lshl_add_u64 v[170:171], s[24:25], 0, v[200:201]
	s_mov_b32 m0, s48
	ds_read_b128 v[180:183], v174 offset:16384
	ds_read_b128 v[184:187], v174 offset:17408
	ds_read_b128 v[188:191], v174 offset:18432
	ds_read_b128 v[192:195], v174 offset:19456
	ds_read_b128 v[196:199], v174 offset:20480
	ds_read_b128 v[210:213], v174 offset:21504
	ds_read_b128 v[214:217], v174 offset:22528
	ds_read_b128 v[218:221], v174 offset:23552
	global_load_lds_dwordx4 v[170:171], off
	s_add_i32 m0, s48, 0x2000
	s_add_u32 s84, s24, 0x20000
	v_lshl_add_u64 v[206:207], s[24:25], 0, v[136:137]
	s_addc_u32 s85, s25, 0
	s_add_i32 s48, s49, s61
	global_load_lds_dwordx4 v[206:207], off
	v_lshl_add_u64 v[208:209], s[84:85], 0, v[200:201]
	s_mov_b32 m0, s48
	v_lshl_add_u64 v[222:223], s[50:51], 0, v[138:139]
	global_load_lds_dwordx4 v[208:209], off
	s_add_i32 m0, s48, 0x2000
	v_lshl_add_u64 v[208:209], s[84:85], 0, v[136:137]
	global_load_lds_dwordx4 v[208:209], off
	s_mov_b32 m0, s62
	v_lshl_add_u64 v[208:209], s[50:51], 0, v[140:141]
	global_load_lds_dwordx4 v[208:209], off
	s_mov_b32 m0, s63
	s_nop 0
	global_load_lds_dwordx4 v[222:223], off
	s_waitcnt vmcnt(8) lgkmcnt(0)
	s_setprio 1
	s_barrier
; #define PG8_STAGE(bufoff, gbase, voff) do { _Pragma("unroll") for (int _i = 0; _i < 2; ++_i) \
;         __builtin_amdgcn_global_load_lds((const unsigned*)((const char*)(gbase) + (voff)[_i]), (PG8_LAS unsigned*)(lds + (bufoff) + ldsw + _i * 8192), 16, 0, 0); } while (0)
; #define PG8_LDA(dst, b, h) do { _Pragma("unroll") for (int m = 0; m < 4; ++m) _Pragma("unroll") for (int k = 0; k < 2; ++k) dst[m][k] = *(const PG8_LAS bf16x8*)(lds + PG8_SA(b, h) + aoff + m * 2048 + k * 1024); } while (0)
; #define PG8_LDB(dst, b, h) do { _Pragma("unroll") for (int n = 0; n < 2; ++n) _Pragma("unroll") for (int k = 0; k < 2; ++k) dst[n][k] = *(const PG8_LAS bf16x8*)(lds + PG8_SB(b, h) + boff + n * 2048 + k * 1024); } while (0)
; #define PG8_MMA(ai, bj, At, Bt) do { __builtin_amdgcn_s_setprio(1); _Pragma("unroll") for (int m = 0; m < 4; ++m) _Pragma("unroll") for (int n = 0; n < 2; ++n) _Pragma("unroll") for (int k = 0; k < 2; ++k) \
;         acc[ai][bj][m][n] = __builtin_amdgcn_mfma_f32_16x16x32_bf16(Bt[n][k], At[m][k], acc[ai][bj][m][n], 0, 0, 0); __builtin_amdgcn_s_setprio(0); } while (0)
; #define PG8_WAIT_V(n) asm volatile("s_waitcnt vmcnt(" #n ")" ::: "memory")
; #define PG8_WAIT_L(n) asm volatile("s_waitcnt lgkmcnt(" #n ")" ::: "memory")
; #define PG8_BAR __builtin_amdgcn_s_barrier()
; #define PG8_SCHED __builtin_amdgcn_sched_barrier(0)
;     ...
;             PG8_WAIT_V(8); PG8_WAIT_L(0); PG8_BAR; PG8_MMA(1, 0, At, B0); PG8_MMA(1, 1, At, B1); PG8_BAR; PG8_SCHED;
;             PG8_LDB(B0, 1, 0); PG8_LDB(B1, 1, 1); PG8_SCHED; PG8_LDA(At, 1, 0); PG8_STAGE(PG8_SA(0, 1), a2 + hstep, voffA);
;             PG8_WAIT_V(8); PG8_WAIT_L(0); PG8_BAR; PG8_MMA(0, 0, At, B0); PG8_MMA(0, 1, At, B1); PG8_BAR; PG8_SCHED;
	v_mfma_f32_16x16x32_bf16 v[64:67], v[132:135], v[180:183], v[64:67]
	v_mfma_f32_16x16x32_bf16 v[60:63], v[150:153], v[180:183], v[60:63]
	v_mfma_f32_16x16x32_bf16 v[52:55], v[132:135], v[188:191], v[52:55]
	v_mfma_f32_16x16x32_bf16 v[44:47], v[150:153], v[188:191], v[44:47]
	v_mfma_f32_16x16x32_bf16 v[36:39], v[132:135], v[196:199], v[36:39]
	v_mfma_f32_16x16x32_bf16 v[28:31], v[150:153], v[196:199], v[28:31]
	v_mfma_f32_16x16x32_bf16 v[20:23], v[132:135], v[214:217], v[20:23]
	v_mfma_f32_16x16x32_bf16 v[12:15], v[150:153], v[214:217], v[12:15]
	v_mfma_f32_16x16x32_bf16 v[64:67], v[146:149], v[184:187], v[64:67]
	v_mfma_f32_16x16x32_bf16 v[60:63], v[154:157], v[184:187], v[60:63]
	v_mfma_f32_16x16x32_bf16 v[52:55], v[146:149], v[192:195], v[52:55]
	v_mfma_f32_16x16x32_bf16 v[44:47], v[154:157], v[192:195], v[44:47]
	v_mfma_f32_16x16x32_bf16 v[36:39], v[146:149], v[210:213], v[36:39]
	v_mfma_f32_16x16x32_bf16 v[28:31], v[154:157], v[210:213], v[28:31]
	v_mfma_f32_16x16x32_bf16 v[20:23], v[146:149], v[218:221], v[20:23]
	v_mfma_f32_16x16x32_bf16 v[12:15], v[154:157], v[218:221], v[12:15]
	v_mfma_f32_16x16x32_bf16 v[56:59], v[158:161], v[180:183], v[56:59]
	v_mfma_f32_16x16x32_bf16 v[48:51], v[166:169], v[180:183], v[48:51]
	v_mfma_f32_16x16x32_bf16 v[40:43], v[158:161], v[188:191], v[40:43]
	v_mfma_f32_16x16x32_bf16 v[32:35], v[166:169], v[188:191], v[32:35]
	v_mfma_f32_16x16x32_bf16 v[24:27], v[158:161], v[196:199], v[24:27]
	v_mfma_f32_16x16x32_bf16 v[16:19], v[166:169], v[196:199], v[16:19]
	v_mfma_f32_16x16x32_bf16 v[8:11], v[158:161], v[214:217], v[8:11]
	v_mfma_f32_16x16x32_bf16 v[4:7], v[166:169], v[214:217], v[4:7]
	v_mfma_f32_16x16x32_bf16 v[56:59], v[162:165], v[184:187], v[56:59]
	v_mfma_f32_16x16x32_bf16 v[48:51], v[176:179], v[184:187], v[48:51]
	v_mfma_f32_16x16x32_bf16 v[40:43], v[162:165], v[192:195], v[40:43]
	v_mfma_f32_16x16x32_bf16 v[32:35], v[176:179], v[192:195], v[32:35]
	v_mfma_f32_16x16x32_bf16 v[24:27], v[162:165], v[210:213], v[24:27]
	v_mfma_f32_16x16x32_bf16 v[16:19], v[176:179], v[210:213], v[16:19]
	v_mfma_f32_16x16x32_bf16 v[8:11], v[162:165], v[218:221], v[8:11]
	v_mfma_f32_16x16x32_bf16 v[4:7], v[176:179], v[218:221], v[4:7]
	s_barrier
	s_setprio 0
	s_add_i32 s48, 0, 0x18000
	s_add_i32 s49, 0, 0x1c000
	ds_read_b128 v[132:135], v251 offset:32768
	ds_read_b128 v[146:149], v251 offset:33792
	ds_read_b128 v[150:153], v251 offset:34816
	ds_read_b128 v[154:157], v251 offset:35840
	ds_read_b128 v[158:161], v251 offset:49152
	ds_read_b128 v[162:165], v251 offset:50176
	ds_read_b128 v[166:169], v251 offset:51200
	ds_read_b128 v[176:179], v251 offset:52224
	s_add_u32 s50, s50, 0x20000
	s_addc_u32 s51, s51, 0
	s_mov_b32 m0, s68
	v_lshl_add_u64 v[224:225], s[50:51], 0, v[140:141]
	ds_read_b128 v[180:183], v174 offset:32768
	ds_read_b128 v[184:187], v174 offset:33792
	ds_read_b128 v[188:191], v174 offset:34816
	ds_read_b128 v[192:195], v174 offset:35840
	ds_read_b128 v[196:199], v174 offset:36864
	ds_read_b128 v[210:213], v174 offset:37888
	ds_read_b128 v[214:217], v174 offset:38912
	ds_read_b128 v[218:221], v174 offset:39936
	global_load_lds_dwordx4 v[224:225], off
	s_mov_b32 m0, s69
	v_lshl_add_u64 v[224:225], s[50:51], 0, v[138:139]
	global_load_lds_dwordx4 v[224:225], off
	s_waitcnt vmcnt(8) lgkmcnt(0)
	s_setprio 1
	s_barrier
	v_mfma_f32_16x16x32_bf16 v[128:131], v[132:135], v[180:183], v[128:131]
	v_mfma_f32_16x16x32_bf16 v[124:127], v[150:153], v[180:183], v[124:127]
	v_mfma_f32_16x16x32_bf16 v[116:119], v[132:135], v[188:191], v[116:119]
	v_mfma_f32_16x16x32_bf16 v[108:111], v[150:153], v[188:191], v[108:111]
	v_mfma_f32_16x16x32_bf16 v[100:103], v[132:135], v[196:199], v[100:103]
	v_mfma_f32_16x16x32_bf16 v[92:95], v[150:153], v[196:199], v[92:95]
	v_mfma_f32_16x16x32_bf16 v[84:87], v[132:135], v[214:217], v[84:87]
	v_mfma_f32_16x16x32_bf16 v[76:79], v[150:153], v[214:217], v[76:79]
	v_mfma_f32_16x16x32_bf16 v[128:131], v[146:149], v[184:187], v[128:131]
	v_mfma_f32_16x16x32_bf16 v[124:127], v[154:157], v[184:187], v[124:127]
	v_mfma_f32_16x16x32_bf16 v[116:119], v[146:149], v[192:195], v[116:119]
	v_mfma_f32_16x16x32_bf16 v[108:111], v[154:157], v[192:195], v[108:111]
	v_mfma_f32_16x16x32_bf16 v[100:103], v[146:149], v[210:213], v[100:103]
	v_mfma_f32_16x16x32_bf16 v[92:95], v[154:157], v[210:213], v[92:95]
	v_mfma_f32_16x16x32_bf16 v[84:87], v[146:149], v[218:221], v[84:87]
	v_mfma_f32_16x16x32_bf16 v[76:79], v[154:157], v[218:221], v[76:79]
	v_mfma_f32_16x16x32_bf16 v[120:123], v[158:161], v[180:183], v[120:123]
	v_mfma_f32_16x16x32_bf16 v[112:115], v[166:169], v[180:183], v[112:115]
	v_mfma_f32_16x16x32_bf16 v[104:107], v[158:161], v[188:191], v[104:107]
	v_mfma_f32_16x16x32_bf16 v[96:99], v[166:169], v[188:191], v[96:99]
	v_mfma_f32_16x16x32_bf16 v[88:91], v[158:161], v[196:199], v[88:91]
	v_mfma_f32_16x16x32_bf16 v[80:83], v[166:169], v[196:199], v[80:83]
	v_mfma_f32_16x16x32_bf16 v[72:75], v[158:161], v[214:217], v[72:75]
	v_mfma_f32_16x16x32_bf16 v[68:71], v[166:169], v[214:217], v[68:71]
	v_mfma_f32_16x16x32_bf16 v[120:123], v[162:165], v[184:187], v[120:123]
	v_mfma_f32_16x16x32_bf16 v[112:115], v[176:179], v[184:187], v[112:115]
	v_mfma_f32_16x16x32_bf16 v[104:107], v[162:165], v[192:195], v[104:107]
	v_mfma_f32_16x16x32_bf16 v[96:99], v[176:179], v[192:195], v[96:99]
	v_mfma_f32_16x16x32_bf16 v[88:91], v[162:165], v[210:213], v[88:91]
	v_mfma_f32_16x16x32_bf16 v[80:83], v[176:179], v[210:213], v[80:83]
	v_mfma_f32_16x16x32_bf16 v[72:75], v[162:165], v[218:221], v[72:75]
	v_mfma_f32_16x16x32_bf16 v[68:71], v[176:179], v[218:221], v[68:71]
	s_barrier
; #define PG8_G __attribute__((address_space(1)))
; __device__ __forceinline__ u32x4 pack8bf(const f32x4 a, const f32x4 b) { u32x4 w; w.x = cvt_pk_bf16(a[0], a[1]); w.y = cvt_pk_bf16(a[2], a[3]); w.z = cvt_pk_bf16(b[0], b[1]); w.w = cvt_pk_bf16(b[2], b[3]); return w; }
; #define PG8_STAGE(bufoff, gbase, voff) do { _Pragma("unroll") for (int _i = 0; _i < 2; ++_i) \
;         __builtin_amdgcn_global_load_lds((const unsigned*)((const char*)(gbase) + (voff)[_i]), (PG8_LAS unsigned*)(lds + (bufoff) + ldsw + _i * 8192), 16, 0, 0); } while (0)
; #define PG8_LDA(dst, b, h) do { _Pragma("unroll") for (int m = 0; m < 4; ++m) _Pragma("unroll") for (int k = 0; k < 2; ++k) dst[m][k] = *(const PG8_LAS bf16x8*)(lds + PG8_SA(b, h) + aoff + m * 2048 + k * 1024); } while (0)
; #define PG8_MMA(ai, bj, At, Bt) do { __builtin_amdgcn_s_setprio(1); _Pragma("unroll") for (int m = 0; m < 4; ++m) _Pragma("unroll") for (int n = 0; n < 2; ++n) _Pragma("unroll") for (int k = 0; k < 2; ++k) \
;         acc[ai][bj][m][n] = __builtin_amdgcn_mfma_f32_16x16x32_bf16(Bt[n][k], At[m][k], acc[ai][bj][m][n], 0, 0, 0); __builtin_amdgcn_s_setprio(0); } while (0)
; #define PG8_WAIT_V(n) asm volatile("s_waitcnt vmcnt(" #n ")" ::: "memory")
; #define PG8_WAIT_L(n) asm volatile("s_waitcnt lgkmcnt(" #n ")" ::: "memory")
;     __device__ __forceinline__ void operator()(const f32x4 (&acc)[2][2][4][2], const Unit& u, int wr, int wc, int fr_, int fq_, int ui) const {
;     ...
;         const int row0 = u.pm * BM + wr * 64 + fr;
;         float r[2][4]; load_rs(r, rsl, wr, fr);
;         if (u.pn < 8) {
;             const int col0 = u.pn * BM + wc * 32 + 8 * fq;
; #pragma unroll
;             for (int ai = 0; ai < 2; ++ai)
; #pragma unroll
;                 for (int m = 0; m < 4; ++m) { bf16_t* rowp = Q + (size_t)(row0 + ai * HALF + m * 16) * 3072 + col0;
; #pragma unroll
;                     for (int bj = 0; bj < 2; ++bj) *(PG8_G u32x4*)(rowp + bj * HALF) = pack8bf(acc[ai][bj][m][0] * r[ai][m], acc[ai][bj][m][1] * r[ai][m]); }
;         } else {
;             const int head = 4 * (u.pn - 8) + wc, i0 = 8 * fq;
;     ...
;             PG8_LDA(At, 1, 1); PG8_STAGE(PG8_SB(1, 0), b3, voffB); PG8_STAGE(PG8_SB(1, 1), b3 + hstep, voffB); PG8_STAGE(PG8_SA(1, 0), a3, voffA);
;             PG8_WAIT_V(8); PG8_WAIT_L(0); PG8_BAR; PG8_MMA(1, 0, At, B0); PG8_MMA(1, 1, At, B1); PG8_BAR; PG8_SCHED;
	s_setprio 0
	s_add_i32 s48, s48, s61
	v_lshl_add_u64 v[170:171], v[170:171], 0, s[66:67]
	s_mov_b32 m0, s48
	ds_read_b128 v[180:183], v174 offset:49152
	ds_read_b128 v[184:187], v174 offset:50176
	ds_read_b128 v[188:191], v174 offset:51200
	ds_read_b128 v[192:195], v174 offset:52224
	ds_read_b128 v[196:199], v174 offset:53248
	ds_read_b128 v[210:213], v174 offset:54272
	ds_read_b128 v[214:217], v174 offset:55296
	ds_read_b128 v[218:221], v174 offset:56320
	global_load_lds_dwordx4 v[170:171], off
	s_add_i32 m0, s48, 0x2000
	s_add_u32 s24, s24, 0x20080
	v_lshl_add_u64 v[170:171], v[206:207], 0, s[66:67]
	s_addc_u32 s25, s25, 0
	s_add_i32 s48, s49, s61
	global_load_lds_dwordx4 v[170:171], off
	s_mov_b32 m0, s48
	v_lshl_add_u64 v[170:171], s[24:25], 0, v[200:201]
	global_load_lds_dwordx4 v[170:171], off
	s_add_i32 m0, s48, 0x2000
	v_lshl_add_u64 v[170:171], s[24:25], 0, v[136:137]
	global_load_lds_dwordx4 v[170:171], off
	v_lshl_add_u64 v[170:171], v[208:209], 0, s[66:67]
	s_mov_b32 m0, s71
	s_nop 0
	global_load_lds_dwordx4 v[170:171], off
	v_lshl_add_u64 v[170:171], v[222:223], 0, s[66:67]
	s_mov_b32 m0, s73
	s_nop 0
	global_load_lds_dwordx4 v[170:171], off
	s_waitcnt vmcnt(8) lgkmcnt(0)
	s_setprio 1
	s_barrier
	v_mfma_f32_16x16x32_bf16 v[64:67], v[132:135], v[180:183], v[64:67]
	v_mfma_f32_16x16x32_bf16 v[60:63], v[150:153], v[180:183], v[60:63]
	v_mfma_f32_16x16x32_bf16 v[52:55], v[132:135], v[188:191], v[52:55]
	v_mfma_f32_16x16x32_bf16 v[44:47], v[150:153], v[188:191], v[44:47]
	v_mfma_f32_16x16x32_bf16 v[36:39], v[132:135], v[196:199], v[36:39]
	v_mfma_f32_16x16x32_bf16 v[28:31], v[150:153], v[196:199], v[28:31]
	v_mfma_f32_16x16x32_bf16 v[20:23], v[132:135], v[214:217], v[20:23]
	v_mfma_f32_16x16x32_bf16 v[12:15], v[150:153], v[214:217], v[12:15]
	v_mfma_f32_16x16x32_bf16 v[64:67], v[146:149], v[184:187], v[64:67]
	v_mfma_f32_16x16x32_bf16 v[60:63], v[154:157], v[184:187], v[60:63]
	v_mfma_f32_16x16x32_bf16 v[52:55], v[146:149], v[192:195], v[52:55]
	v_mfma_f32_16x16x32_bf16 v[44:47], v[154:157], v[192:195], v[44:47]
	v_mfma_f32_16x16x32_bf16 v[36:39], v[146:149], v[210:213], v[36:39]
	v_mfma_f32_16x16x32_bf16 v[28:31], v[154:157], v[210:213], v[28:31]
	v_mfma_f32_16x16x32_bf16 v[20:23], v[146:149], v[218:221], v[20:23]
	v_mfma_f32_16x16x32_bf16 v[12:15], v[154:157], v[218:221], v[12:15]
	v_mfma_f32_16x16x32_bf16 v[56:59], v[158:161], v[180:183], v[56:59]
	v_mfma_f32_16x16x32_bf16 v[48:51], v[166:169], v[180:183], v[48:51]
	v_mfma_f32_16x16x32_bf16 v[40:43], v[158:161], v[188:191], v[40:43]
	v_mfma_f32_16x16x32_bf16 v[32:35], v[166:169], v[188:191], v[32:35]
	v_mfma_f32_16x16x32_bf16 v[24:27], v[158:161], v[196:199], v[24:27]
	v_mfma_f32_16x16x32_bf16 v[16:19], v[166:169], v[196:199], v[16:19]
	v_mfma_f32_16x16x32_bf16 v[8:11], v[158:161], v[214:217], v[8:11]
	v_mfma_f32_16x16x32_bf16 v[4:7], v[166:169], v[214:217], v[4:7]
	v_mfma_f32_16x16x32_bf16 v[56:59], v[162:165], v[184:187], v[56:59]
	v_mfma_f32_16x16x32_bf16 v[48:51], v[176:179], v[184:187], v[48:51]
	v_mfma_f32_16x16x32_bf16 v[40:43], v[162:165], v[192:195], v[40:43]
	v_mfma_f32_16x16x32_bf16 v[32:35], v[176:179], v[192:195], v[32:35]
	v_mfma_f32_16x16x32_bf16 v[24:27], v[162:165], v[210:213], v[24:27]
	v_mfma_f32_16x16x32_bf16 v[16:19], v[176:179], v[210:213], v[16:19]
	v_mfma_f32_16x16x32_bf16 v[8:11], v[162:165], v[218:221], v[8:11]
	v_mfma_f32_16x16x32_bf16 v[4:7], v[176:179], v[218:221], v[4:7]
	s_barrier
	s_setprio 0
	s_add_i32 s54, s54, 2
	s_add_u32 s52, s52, 0x100
	s_addc_u32 s53, s53, 0
	s_add_u32 s14, s14, 0x100
	s_addc_u32 s15, s15, 0
	s_cmp_gt_u32 s54, 5
	s_cbranch_scc0 .LBB0_301
	v_mov_b32_e32 v132, v3
	v_mov_b32_e32 v133, v172
	v_readlane_b32 s14, v254, 30
	v_add_u32_e32 v146, s1, v132
	v_lshl_add_u32 v132, v132, 2, s78
	ds_read2_b32 v[164:165], v132 offset1:16
	ds_read2_b32 v[158:159], v132 offset0:32 offset1:48
	ds_read2_b32 v[152:153], v132 offset0:128 offset1:144
	ds_read2_b32 v[148:149], v132 offset0:160 offset1:176
	s_add_i32 s14, s20, s14
	s_lshl_b32 s20, s14, 8
	s_cmp_gt_u32 s14, 7
	v_lshlrev_b32_e32 v168, 3, v133
	v_ashrrev_i32_e32 v147, 31, v146
	s_mov_b64 s[14:15], -1
	v_add_u32_e32 v166, 16, v146
	v_add_u32_e32 v162, 32, v146
	v_add_u32_e32 v160, 48, v146
	v_add_u32_e32 v156, 0x80, v146
	v_add_u32_e32 v154, 0x90, v146
	v_add_u32_e32 v150, 0xa0, v146
	s_cbranch_scc0 .LBB0_304
; #define PG8_G __attribute__((address_space(1)))
; __device__ __forceinline__ u32x4 pack8bf(const f32x4 a, const f32x4 b) { u32x4 w; w.x = cvt_pk_bf16(a[0], a[1]); w.y = cvt_pk_bf16(a[2], a[3]); w.z = cvt_pk_bf16(b[0], b[1]); w.w = cvt_pk_bf16(b[2], b[3]); return w; }
;     __device__ __forceinline__ void operator()(const f32x4 (&acc)[2][2][4][2], const Unit& u, int wr, int wc, int fr_, int fq_, int ui) const {
;     ...
;             const int head = 4 * (u.pn - 8) + wc, i0 = 8 * fq;
; #pragma unroll
;             for (int ai = 0; ai < 2; ++ai)
; #pragma unroll
;                 for (int m = 0; m < 4; ++m) { const int row = row0 + ai * HALF + m * 16;
;                     const f32x4 c0 = *(const PG8_G f32x4*)(cosT + (size_t)row * 32 + i0), c1 = *(const PG8_G f32x4*)(cosT + (size_t)row * 32 + i0 + 4);
;                     const f32x4 s0 = *(const PG8_G f32x4*)(sinT + (size_t)row * 32 + i0), s1 = *(const PG8_G f32x4*)(sinT + (size_t)row * 32 + i0 + 4);
;                     const f32x4 x1a = acc[ai][0][m][0] * r[ai][m], x1b = acc[ai][0][m][1] * r[ai][m], x2a = acc[ai][1][m][0] * r[ai][m], x2b = acc[ai][1][m][1] * r[ai][m];
;                     const f32x4 y1a = x1a * c0 - x2a * s0, y1b = x1b * c1 - x2b * s1, y2a = x2a * c0 + x1a * s0, y2b = x2b * c1 + x1b * s1;
;                     bf16_t* dst = Q + (size_t)row * 3072 + 2048 + head * 64 + i0;
;                     *(PG8_G u32x4*)dst = pack8bf(y1a, y1b); *(PG8_G u32x4*)(dst + 32) = pack8bf(y2a, y2b); }
	v_ashrrev_i32_e32 v169, 31, v168
	v_lshlrev_b64 v[180:181], 7, v[146:147]
	v_lshl_add_u64 v[132:133], s[38:39], 0, v[180:181]
	v_lshlrev_b64 v[170:171], 2, v[168:169]
	v_lshl_add_u64 v[180:181], s[40:41], 0, v[180:181]
	v_lshl_add_u64 v[176:177], v[132:133], 0, v[170:171]
	v_lshl_add_u64 v[184:185], v[180:181], 0, v[170:171]
	global_load_dwordx4 v[132:135], v[176:177], off offset:16
	s_nop 0
	global_load_dwordx4 v[176:179], v[176:177], off
	s_nop 0
	global_load_dwordx4 v[180:183], v[184:185], off offset:16
	s_nop 0
	global_load_dwordx4 v[184:187], v[184:185], off
	s_waitcnt lgkmcnt(0)
	v_pk_mul_f32 v[188:189], v[130:131], v[164:165] op_sel_hi:[1,0]
	v_pk_mul_f32 v[196:197], v[122:123], v[164:165] op_sel_hi:[1,0]
	v_pk_mul_f32 v[190:191], v[128:129], v[164:165] op_sel_hi:[1,0]
	v_pk_mul_f32 v[194:195], v[124:125], v[164:165] op_sel_hi:[1,0]
	v_pk_mul_f32 v[198:199], v[120:121], v[164:165] op_sel_hi:[1,0]
	v_pk_mul_f32 v[208:209], v[112:113], v[164:165] op_sel_hi:[1,0]
	v_pk_mul_f32 v[192:193], v[126:127], v[164:165] op_sel_hi:[1,0]
	v_pk_mul_f32 v[206:207], v[114:115], v[164:165] op_sel_hi:[1,0]
	s_add_i32 s44, s0, s20
	s_mov_b64 s[48:49], 0x1000
	v_ashrrev_i32_e32 v167, 31, v166
	v_ashrrev_i32_e32 v163, 31, v162
	v_ashrrev_i32_e32 v161, 31, v160
	v_ashrrev_i32_e32 v157, 31, v156
	v_ashrrev_i32_e32 v155, 31, v154
	v_ashrrev_i32_e32 v151, 31, v150
	s_waitcnt vmcnt(0)
	v_pk_mul_f32 v[216:217], v[208:209], v[180:181]
	v_pk_mul_f32 v[210:211], v[196:197], v[186:187]
	v_pk_mul_f32 v[186:187], v[188:189], v[186:187]
	v_pk_mul_f32 v[212:213], v[198:199], v[184:185]
	v_pk_fma_f32 v[210:211], v[188:189], v[178:179], v[210:211] neg_lo:[0,0,1] neg_hi:[0,0,1]
	v_pk_mul_f32 v[184:185], v[190:191], v[184:185]
	v_pk_fma_f32 v[186:187], v[196:197], v[178:179], v[186:187]
	v_pk_mul_f32 v[178:179], v[194:195], v[180:181]
	v_pk_fma_f32 v[212:213], v[190:191], v[176:177], v[212:213] neg_lo:[0,0,1] neg_hi:[0,0,1]
	v_pk_mul_f32 v[214:215], v[206:207], v[182:183]
	v_pk_fma_f32 v[216:217], v[194:195], v[132:133], v[216:217] neg_lo:[0,0,1] neg_hi:[0,0,1]
	v_pk_fma_f32 v[184:185], v[198:199], v[176:177], v[184:185]
	v_pk_mul_f32 v[176:177], v[192:193], v[182:183]
	v_pk_fma_f32 v[182:183], v[208:209], v[132:133], v[178:179]
	v_mov_b64_e32 v[132:133], s[10:11]
	v_pk_fma_f32 v[214:215], v[192:193], v[134:135], v[214:215] neg_lo:[0,0,1] neg_hi:[0,0,1]
	v_pk_fma_f32 v[180:181], v[206:207], v[134:135], v[176:177]
	v_mad_i64_i32 v[134:135], s[14:15], v146, s26, v[132:133]
	s_lshl_b64 s[14:15], s[44:45], 1
	s_nop 0
	v_lshl_add_u64 v[176:177], v[134:135], 0, s[14:15]
	v_lshlrev_b64 v[134:135], 1, v[168:169]
	v_lshl_add_u64 v[188:189], v[176:177], 0, v[134:135]
	v_lshl_add_u64 v[190:191], v[188:189], 0, s[48:49]
	v_add_co_u32_e32 v188, vcc, s27, v188
	v_cvt_pk_bf16_f32 v176, v212, v213
	v_cvt_pk_bf16_f32 v177, v210, v211
	v_cvt_pk_bf16_f32 v178, v216, v217
	v_cvt_pk_bf16_f32 v179, v214, v215
	s_nop 1
	v_addc_co_u32_e32 v189, vcc, 0, v189, vcc
	global_store_dwordx4 v[188:189], v[176:179], off
	v_mov_b32_e32 v192, v165
	v_pk_mul_f32 v[194:195], v[118:119], v[192:193] op_sel_hi:[1,0]
	v_cvt_pk_bf16_f32 v176, v184, v185
	v_cvt_pk_bf16_f32 v177, v186, v187
	v_lshlrev_b64 v[184:185], 7, v[166:167]
	v_cvt_pk_bf16_f32 v178, v182, v183
	v_cvt_pk_bf16_f32 v179, v180, v181
	global_store_dwordx4 v[190:191], v[176:179], off offset:64
	v_pk_mul_f32 v[196:197], v[116:117], v[192:193] op_sel_hi:[1,0]
	v_pk_mul_f32 v[198:199], v[110:111], v[192:193] op_sel_hi:[1,0]
	v_lshl_add_u64 v[176:177], s[38:39], 0, v[184:185]
	v_lshl_add_u64 v[184:185], s[40:41], 0, v[184:185]
	v_lshl_add_u64 v[180:181], v[176:177], 0, v[170:171]
	v_lshl_add_u64 v[188:189], v[184:185], 0, v[170:171]
	global_load_dwordx4 v[176:179], v[180:181], off offset:16
	s_nop 0
	global_load_dwordx4 v[180:183], v[180:181], off
	s_nop 0
	global_load_dwordx4 v[184:187], v[188:189], off offset:16
	s_nop 0
	global_load_dwordx4 v[188:191], v[188:189], off
	v_pk_mul_f32 v[206:207], v[108:109], v[192:193] op_sel_hi:[1,0]
	v_pk_mul_f32 v[208:209], v[106:107], v[192:193] op_sel_hi:[1,0]
	v_pk_mul_f32 v[210:211], v[104:105], v[192:193] op_sel_hi:[1,0]
	v_pk_mul_f32 v[212:213], v[98:99], v[192:193] op_sel_hi:[1,0]
	v_pk_mul_f32 v[192:193], v[96:97], v[192:193] op_sel_hi:[1,0]
	s_waitcnt vmcnt(1)
	v_pk_mul_f32 v[218:219], v[212:213], v[186:187]
	v_pk_mul_f32 v[220:221], v[192:193], v[184:185]
	v_pk_mul_f32 v[184:185], v[206:207], v[184:185]
	v_pk_fma_f32 v[220:221], v[206:207], v[176:177], v[220:221] neg_lo:[0,0,1] neg_hi:[0,0,1]
	v_pk_fma_f32 v[184:185], v[192:193], v[176:177], v[184:185]
	v_mad_i64_i32 v[176:177], s[24:25], v166, s26, v[132:133]
	s_waitcnt vmcnt(0)
; #define PG8_G __attribute__((address_space(1)))
; __device__ __forceinline__ u32x4 pack8bf(const f32x4 a, const f32x4 b) { u32x4 w; w.x = cvt_pk_bf16(a[0], a[1]); w.y = cvt_pk_bf16(a[2], a[3]); w.z = cvt_pk_bf16(b[0], b[1]); w.w = cvt_pk_bf16(b[2], b[3]); return w; }
;     __device__ __forceinline__ void operator()(const f32x4 (&acc)[2][2][4][2], const Unit& u, int wr, int wc, int fr_, int fq_, int ui) const {
;     ...
;                 for (int m = 0; m < 4; ++m) { const int row = row0 + ai * HALF + m * 16;
;                     const f32x4 c0 = *(const PG8_G f32x4*)(cosT + (size_t)row * 32 + i0), c1 = *(const PG8_G f32x4*)(cosT + (size_t)row * 32 + i0 + 4);
;                     const f32x4 s0 = *(const PG8_G f32x4*)(sinT + (size_t)row * 32 + i0), s1 = *(const PG8_G f32x4*)(sinT + (size_t)row * 32 + i0 + 4);
;                     const f32x4 x1a = acc[ai][0][m][0] * r[ai][m], x1b = acc[ai][0][m][1] * r[ai][m], x2a = acc[ai][1][m][0] * r[ai][m], x2b = acc[ai][1][m][1] * r[ai][m];
;                     const f32x4 y1a = x1a * c0 - x2a * s0, y1b = x1b * c1 - x2b * s1, y2a = x2a * c0 + x1a * s0, y2b = x2b * c1 + x1b * s1;
;                     bf16_t* dst = Q + (size_t)row * 3072 + 2048 + head * 64 + i0;
;                     *(PG8_G u32x4*)dst = pack8bf(y1a, y1b); *(PG8_G u32x4*)(dst + 32) = pack8bf(y2a, y2b); }
	v_pk_mul_f32 v[216:217], v[210:211], v[188:189]
	v_pk_mul_f32 v[188:189], v[196:197], v[188:189]
	v_lshl_add_u64 v[176:177], v[176:177], 0, s[14:15]
	v_pk_mul_f32 v[214:215], v[208:209], v[190:191]
	v_pk_fma_f32 v[216:217], v[196:197], v[180:181], v[216:217] neg_lo:[0,0,1] neg_hi:[0,0,1]
	v_pk_mul_f32 v[190:191], v[194:195], v[190:191]
	v_pk_fma_f32 v[180:181], v[210:211], v[180:181], v[188:189]
	v_lshl_add_u64 v[188:189], v[176:177], 0, v[134:135]
	v_pk_fma_f32 v[214:215], v[194:195], v[182:183], v[214:215] neg_lo:[0,0,1] neg_hi:[0,0,1]
	v_pk_fma_f32 v[182:183], v[208:209], v[182:183], v[190:191]
	v_pk_mul_f32 v[186:187], v[198:199], v[186:187]
	v_lshl_add_u64 v[190:191], v[188:189], 0, s[48:49]
	v_add_co_u32_e32 v188, vcc, s27, v188
	v_pk_fma_f32 v[218:219], v[198:199], v[178:179], v[218:219] neg_lo:[0,0,1] neg_hi:[0,0,1]
	v_pk_fma_f32 v[186:187], v[212:213], v[178:179], v[186:187]
	v_cvt_pk_bf16_f32 v176, v216, v217
	v_cvt_pk_bf16_f32 v177, v214, v215
	v_cvt_pk_bf16_f32 v178, v220, v221
	v_addc_co_u32_e32 v189, vcc, 0, v189, vcc
	v_cvt_pk_bf16_f32 v179, v218, v219
	global_store_dwordx4 v[188:189], v[176:179], off
	v_pk_mul_f32 v[198:199], v[92:93], v[158:159] op_sel_hi:[1,0]
	v_pk_mul_f32 v[212:213], v[80:81], v[158:159] op_sel_hi:[1,0]
	v_cvt_pk_bf16_f32 v176, v180, v181
	v_cvt_pk_bf16_f32 v177, v182, v183
	v_cvt_pk_bf16_f32 v178, v184, v185
	v_lshlrev_b64 v[184:185], 7, v[162:163]
	v_cvt_pk_bf16_f32 v179, v186, v187
	global_store_dwordx4 v[190:191], v[176:179], off offset:64
	v_pk_mul_f32 v[194:195], v[100:101], v[158:159] op_sel_hi:[1,0]
	v_pk_mul_f32 v[208:209], v[88:89], v[158:159] op_sel_hi:[1,0]
	v_lshl_add_u64 v[176:177], s[38:39], 0, v[184:185]
	v_lshl_add_u64 v[184:185], s[40:41], 0, v[184:185]
	v_lshl_add_u64 v[180:181], v[176:177], 0, v[170:171]
	v_lshl_add_u64 v[188:189], v[184:185], 0, v[170:171]
	global_load_dwordx4 v[176:179], v[180:181], off offset:16
	s_nop 0
	global_load_dwordx4 v[180:183], v[180:181], off
	s_nop 0
	global_load_dwordx4 v[184:187], v[188:189], off offset:16
	s_nop 0
	global_load_dwordx4 v[188:191], v[188:189], off
	v_pk_mul_f32 v[192:193], v[102:103], v[158:159] op_sel_hi:[1,0]
	v_pk_mul_f32 v[206:207], v[90:91], v[158:159] op_sel_hi:[1,0]
	v_pk_mul_f32 v[196:197], v[94:95], v[158:159] op_sel_hi:[1,0]
	v_pk_mul_f32 v[210:211], v[82:83], v[158:159] op_sel_hi:[1,0]
	s_waitcnt vmcnt(1)
	v_pk_mul_f32 v[220:221], v[212:213], v[184:185]
	v_pk_mul_f32 v[184:185], v[198:199], v[184:185]
	v_pk_fma_f32 v[220:221], v[198:199], v[176:177], v[220:221] neg_lo:[0,0,1] neg_hi:[0,0,1]
	v_pk_fma_f32 v[184:185], v[212:213], v[176:177], v[184:185]
	v_mad_i64_i32 v[176:177], s[24:25], v162, s26, v[132:133]
	s_waitcnt vmcnt(0)
	v_pk_mul_f32 v[216:217], v[208:209], v[188:189]
	v_pk_mul_f32 v[188:189], v[194:195], v[188:189]
	v_lshl_add_u64 v[176:177], v[176:177], 0, s[14:15]
	v_pk_mul_f32 v[214:215], v[206:207], v[190:191]
	v_pk_fma_f32 v[216:217], v[194:195], v[180:181], v[216:217] neg_lo:[0,0,1] neg_hi:[0,0,1]
	v_pk_mul_f32 v[190:191], v[192:193], v[190:191]
	v_pk_fma_f32 v[180:181], v[208:209], v[180:181], v[188:189]
	v_lshl_add_u64 v[188:189], v[176:177], 0, v[134:135]
	v_pk_fma_f32 v[214:215], v[192:193], v[182:183], v[214:215] neg_lo:[0,0,1] neg_hi:[0,0,1]
	v_pk_mul_f32 v[218:219], v[210:211], v[186:187]
	v_pk_fma_f32 v[182:183], v[206:207], v[182:183], v[190:191]
	v_pk_mul_f32 v[186:187], v[196:197], v[186:187]
	v_lshl_add_u64 v[190:191], v[188:189], 0, s[48:49]
	v_add_co_u32_e32 v188, vcc, s27, v188
	v_pk_fma_f32 v[218:219], v[196:197], v[178:179], v[218:219] neg_lo:[0,0,1] neg_hi:[0,0,1]
	v_pk_fma_f32 v[186:187], v[210:211], v[178:179], v[186:187]
	v_cvt_pk_bf16_f32 v176, v216, v217
	v_cvt_pk_bf16_f32 v177, v214, v215
	v_cvt_pk_bf16_f32 v178, v220, v221
	v_addc_co_u32_e32 v189, vcc, 0, v189, vcc
	v_cvt_pk_bf16_f32 v179, v218, v219
	global_store_dwordx4 v[188:189], v[176:179], off
	v_mov_b32_e32 v192, v159
	v_pk_mul_f32 v[194:195], v[86:87], v[192:193] op_sel_hi:[1,0]
	v_cvt_pk_bf16_f32 v176, v180, v181
	v_cvt_pk_bf16_f32 v177, v182, v183
	v_cvt_pk_bf16_f32 v178, v184, v185
	v_lshlrev_b64 v[184:185], 7, v[160:161]
	v_cvt_pk_bf16_f32 v179, v186, v187
	global_store_dwordx4 v[190:191], v[176:179], off offset:64
	v_pk_mul_f32 v[196:197], v[84:85], v[192:193] op_sel_hi:[1,0]
	v_pk_mul_f32 v[198:199], v[78:79], v[192:193] op_sel_hi:[1,0]
	v_lshl_add_u64 v[176:177], s[38:39], 0, v[184:185]
	v_lshl_add_u64 v[184:185], s[40:41], 0, v[184:185]
	v_lshl_add_u64 v[180:181], v[176:177], 0, v[170:171]
	v_lshl_add_u64 v[188:189], v[184:185], 0, v[170:171]
	global_load_dwordx4 v[176:179], v[180:181], off offset:16
	s_nop 0
	global_load_dwordx4 v[180:183], v[180:181], off
	s_nop 0
	global_load_dwordx4 v[184:187], v[188:189], off offset:16
	s_nop 0
	global_load_dwordx4 v[188:191], v[188:189], off
	v_pk_mul_f32 v[206:207], v[76:77], v[192:193] op_sel_hi:[1,0]
	v_pk_mul_f32 v[208:209], v[74:75], v[192:193] op_sel_hi:[1,0]
	v_pk_mul_f32 v[210:211], v[72:73], v[192:193] op_sel_hi:[1,0]
	v_pk_mul_f32 v[212:213], v[70:71], v[192:193] op_sel_hi:[1,0]
	v_pk_mul_f32 v[192:193], v[68:69], v[192:193] op_sel_hi:[1,0]
	s_waitcnt vmcnt(1)
	v_pk_mul_f32 v[218:219], v[212:213], v[186:187]
	v_pk_mul_f32 v[220:221], v[192:193], v[184:185]
	v_pk_mul_f32 v[184:185], v[206:207], v[184:185]
	v_pk_fma_f32 v[220:221], v[206:207], v[176:177], v[220:221] neg_lo:[0,0,1] neg_hi:[0,0,1]
	v_pk_fma_f32 v[184:185], v[192:193], v[176:177], v[184:185]
	v_mad_i64_i32 v[176:177], s[24:25], v160, s26, v[132:133]
	s_waitcnt vmcnt(0)
; #define PG8_G __attribute__((address_space(1)))
; __device__ __forceinline__ u32x4 pack8bf(const f32x4 a, const f32x4 b) { u32x4 w; w.x = cvt_pk_bf16(a[0], a[1]); w.y = cvt_pk_bf16(a[2], a[3]); w.z = cvt_pk_bf16(b[0], b[1]); w.w = cvt_pk_bf16(b[2], b[3]); return w; }
;     __device__ __forceinline__ void operator()(const f32x4 (&acc)[2][2][4][2], const Unit& u, int wr, int wc, int fr_, int fq_, int ui) const {
;     ...
;                 for (int m = 0; m < 4; ++m) { const int row = row0 + ai * HALF + m * 16;
;                     const f32x4 c0 = *(const PG8_G f32x4*)(cosT + (size_t)row * 32 + i0), c1 = *(const PG8_G f32x4*)(cosT + (size_t)row * 32 + i0 + 4);
;                     const f32x4 s0 = *(const PG8_G f32x4*)(sinT + (size_t)row * 32 + i0), s1 = *(const PG8_G f32x4*)(sinT + (size_t)row * 32 + i0 + 4);
;                     const f32x4 x1a = acc[ai][0][m][0] * r[ai][m], x1b = acc[ai][0][m][1] * r[ai][m], x2a = acc[ai][1][m][0] * r[ai][m], x2b = acc[ai][1][m][1] * r[ai][m];
;                     const f32x4 y1a = x1a * c0 - x2a * s0, y1b = x1b * c1 - x2b * s1, y2a = x2a * c0 + x1a * s0, y2b = x2b * c1 + x1b * s1;
;                     bf16_t* dst = Q + (size_t)row * 3072 + 2048 + head * 64 + i0;
;                     *(PG8_G u32x4*)dst = pack8bf(y1a, y1b); *(PG8_G u32x4*)(dst + 32) = pack8bf(y2a, y2b); }
	v_pk_mul_f32 v[216:217], v[210:211], v[188:189]
	v_pk_mul_f32 v[188:189], v[196:197], v[188:189]
	v_lshl_add_u64 v[176:177], v[176:177], 0, s[14:15]
	v_pk_mul_f32 v[214:215], v[208:209], v[190:191]
	v_pk_fma_f32 v[216:217], v[196:197], v[180:181], v[216:217] neg_lo:[0,0,1] neg_hi:[0,0,1]
	v_pk_mul_f32 v[190:191], v[194:195], v[190:191]
	v_pk_fma_f32 v[180:181], v[210:211], v[180:181], v[188:189]
	v_lshl_add_u64 v[188:189], v[176:177], 0, v[134:135]
	v_pk_fma_f32 v[214:215], v[194:195], v[182:183], v[214:215] neg_lo:[0,0,1] neg_hi:[0,0,1]
	v_pk_fma_f32 v[182:183], v[208:209], v[182:183], v[190:191]
	v_pk_mul_f32 v[186:187], v[198:199], v[186:187]
	v_lshl_add_u64 v[190:191], v[188:189], 0, s[48:49]
	v_add_co_u32_e32 v188, vcc, s27, v188
	v_pk_fma_f32 v[218:219], v[198:199], v[178:179], v[218:219] neg_lo:[0,0,1] neg_hi:[0,0,1]
	v_pk_fma_f32 v[186:187], v[212:213], v[178:179], v[186:187]
	v_cvt_pk_bf16_f32 v176, v216, v217
	v_cvt_pk_bf16_f32 v177, v214, v215
	v_cvt_pk_bf16_f32 v178, v220, v221
	v_addc_co_u32_e32 v189, vcc, 0, v189, vcc
	v_cvt_pk_bf16_f32 v179, v218, v219
	global_store_dwordx4 v[188:189], v[176:179], off
	v_pk_mul_f32 v[198:199], v[60:61], v[152:153] op_sel_hi:[1,0]
	v_pk_mul_f32 v[212:213], v[48:49], v[152:153] op_sel_hi:[1,0]
	v_cvt_pk_bf16_f32 v176, v180, v181
	v_cvt_pk_bf16_f32 v177, v182, v183
	v_cvt_pk_bf16_f32 v178, v184, v185
	v_lshlrev_b64 v[184:185], 7, v[156:157]
	v_cvt_pk_bf16_f32 v179, v186, v187
	global_store_dwordx4 v[190:191], v[176:179], off offset:64
	v_pk_mul_f32 v[194:195], v[64:65], v[152:153] op_sel_hi:[1,0]
	v_pk_mul_f32 v[208:209], v[56:57], v[152:153] op_sel_hi:[1,0]
	v_lshl_add_u64 v[176:177], s[38:39], 0, v[184:185]
	v_lshl_add_u64 v[184:185], s[40:41], 0, v[184:185]
	v_lshl_add_u64 v[180:181], v[176:177], 0, v[170:171]
	v_lshl_add_u64 v[188:189], v[184:185], 0, v[170:171]
	global_load_dwordx4 v[176:179], v[180:181], off offset:16
	s_nop 0
	global_load_dwordx4 v[180:183], v[180:181], off
	s_nop 0
	global_load_dwordx4 v[184:187], v[188:189], off offset:16
	s_nop 0
	global_load_dwordx4 v[188:191], v[188:189], off
	v_pk_mul_f32 v[192:193], v[66:67], v[152:153] op_sel_hi:[1,0]
	v_pk_mul_f32 v[206:207], v[58:59], v[152:153] op_sel_hi:[1,0]
	v_pk_mul_f32 v[196:197], v[62:63], v[152:153] op_sel_hi:[1,0]
	v_pk_mul_f32 v[210:211], v[50:51], v[152:153] op_sel_hi:[1,0]
	s_waitcnt vmcnt(1)
	v_pk_mul_f32 v[220:221], v[212:213], v[184:185]
	v_pk_mul_f32 v[184:185], v[198:199], v[184:185]
	v_pk_fma_f32 v[220:221], v[198:199], v[176:177], v[220:221] neg_lo:[0,0,1] neg_hi:[0,0,1]
	v_pk_fma_f32 v[184:185], v[212:213], v[176:177], v[184:185]
	v_mad_i64_i32 v[176:177], s[24:25], v156, s26, v[132:133]
	s_waitcnt vmcnt(0)
	v_pk_mul_f32 v[216:217], v[208:209], v[188:189]
	v_pk_mul_f32 v[188:189], v[194:195], v[188:189]
	v_lshl_add_u64 v[176:177], v[176:177], 0, s[14:15]
	v_pk_mul_f32 v[214:215], v[206:207], v[190:191]
	v_pk_fma_f32 v[216:217], v[194:195], v[180:181], v[216:217] neg_lo:[0,0,1] neg_hi:[0,0,1]
	v_pk_mul_f32 v[190:191], v[192:193], v[190:191]
	v_pk_fma_f32 v[180:181], v[208:209], v[180:181], v[188:189]
	v_lshl_add_u64 v[188:189], v[176:177], 0, v[134:135]
	v_pk_fma_f32 v[214:215], v[192:193], v[182:183], v[214:215] neg_lo:[0,0,1] neg_hi:[0,0,1]
	v_pk_mul_f32 v[218:219], v[210:211], v[186:187]
	v_pk_fma_f32 v[182:183], v[206:207], v[182:183], v[190:191]
	v_pk_mul_f32 v[186:187], v[196:197], v[186:187]
	v_lshl_add_u64 v[190:191], v[188:189], 0, s[48:49]
	v_add_co_u32_e32 v188, vcc, s27, v188
	v_pk_fma_f32 v[218:219], v[196:197], v[178:179], v[218:219] neg_lo:[0,0,1] neg_hi:[0,0,1]
	v_pk_fma_f32 v[186:187], v[210:211], v[178:179], v[186:187]
	v_cvt_pk_bf16_f32 v176, v216, v217
	v_cvt_pk_bf16_f32 v177, v214, v215
	v_cvt_pk_bf16_f32 v178, v220, v221
	v_addc_co_u32_e32 v189, vcc, 0, v189, vcc
	v_cvt_pk_bf16_f32 v179, v218, v219
	global_store_dwordx4 v[188:189], v[176:179], off
	v_mov_b32_e32 v192, v153
	v_pk_mul_f32 v[194:195], v[54:55], v[192:193] op_sel_hi:[1,0]
	v_cvt_pk_bf16_f32 v176, v180, v181
	v_cvt_pk_bf16_f32 v177, v182, v183
	v_cvt_pk_bf16_f32 v178, v184, v185
	v_lshlrev_b64 v[184:185], 7, v[154:155]
	v_cvt_pk_bf16_f32 v179, v186, v187
	global_store_dwordx4 v[190:191], v[176:179], off offset:64
	v_pk_mul_f32 v[196:197], v[52:53], v[192:193] op_sel_hi:[1,0]
	v_pk_mul_f32 v[198:199], v[46:47], v[192:193] op_sel_hi:[1,0]
	v_lshl_add_u64 v[176:177], s[38:39], 0, v[184:185]
	v_lshl_add_u64 v[184:185], s[40:41], 0, v[184:185]
	v_lshl_add_u64 v[180:181], v[176:177], 0, v[170:171]
	v_lshl_add_u64 v[188:189], v[184:185], 0, v[170:171]
	global_load_dwordx4 v[176:179], v[180:181], off offset:16
	s_nop 0
	global_load_dwordx4 v[180:183], v[180:181], off
	s_nop 0
	global_load_dwordx4 v[184:187], v[188:189], off offset:16
	s_nop 0
	global_load_dwordx4 v[188:191], v[188:189], off
	v_pk_mul_f32 v[206:207], v[44:45], v[192:193] op_sel_hi:[1,0]
	v_pk_mul_f32 v[208:209], v[42:43], v[192:193] op_sel_hi:[1,0]
	v_pk_mul_f32 v[210:211], v[40:41], v[192:193] op_sel_hi:[1,0]
	v_pk_mul_f32 v[212:213], v[34:35], v[192:193] op_sel_hi:[1,0]
	v_pk_mul_f32 v[192:193], v[32:33], v[192:193] op_sel_hi:[1,0]
	s_waitcnt vmcnt(1)
	v_pk_mul_f32 v[218:219], v[212:213], v[186:187]
	v_pk_mul_f32 v[220:221], v[192:193], v[184:185]
	v_pk_mul_f32 v[184:185], v[206:207], v[184:185]
	v_pk_fma_f32 v[220:221], v[206:207], v[176:177], v[220:221] neg_lo:[0,0,1] neg_hi:[0,0,1]
	v_pk_fma_f32 v[184:185], v[192:193], v[176:177], v[184:185]
	v_mad_i64_i32 v[176:177], s[24:25], v154, s26, v[132:133]
	s_waitcnt vmcnt(0)
; #define PG8_G __attribute__((address_space(1)))
; __device__ __forceinline__ u32x4 pack8bf(const f32x4 a, const f32x4 b) { u32x4 w; w.x = cvt_pk_bf16(a[0], a[1]); w.y = cvt_pk_bf16(a[2], a[3]); w.z = cvt_pk_bf16(b[0], b[1]); w.w = cvt_pk_bf16(b[2], b[3]); return w; }
;     __device__ __forceinline__ void operator()(const f32x4 (&acc)[2][2][4][2], const Unit& u, int wr, int wc, int fr_, int fq_, int ui) const {
;     ...
;                 for (int m = 0; m < 4; ++m) { const int row = row0 + ai * HALF + m * 16;
;                     const f32x4 c0 = *(const PG8_G f32x4*)(cosT + (size_t)row * 32 + i0), c1 = *(const PG8_G f32x4*)(cosT + (size_t)row * 32 + i0 + 4);
;                     const f32x4 s0 = *(const PG8_G f32x4*)(sinT + (size_t)row * 32 + i0), s1 = *(const PG8_G f32x4*)(sinT + (size_t)row * 32 + i0 + 4);
;                     const f32x4 x1a = acc[ai][0][m][0] * r[ai][m], x1b = acc[ai][0][m][1] * r[ai][m], x2a = acc[ai][1][m][0] * r[ai][m], x2b = acc[ai][1][m][1] * r[ai][m];
;                     const f32x4 y1a = x1a * c0 - x2a * s0, y1b = x1b * c1 - x2b * s1, y2a = x2a * c0 + x1a * s0, y2b = x2b * c1 + x1b * s1;
;                     bf16_t* dst = Q + (size_t)row * 3072 + 2048 + head * 64 + i0;
;                     *(PG8_G u32x4*)dst = pack8bf(y1a, y1b); *(PG8_G u32x4*)(dst + 32) = pack8bf(y2a, y2b); }
	v_pk_mul_f32 v[216:217], v[210:211], v[188:189]
	v_pk_mul_f32 v[188:189], v[196:197], v[188:189]
	v_lshl_add_u64 v[176:177], v[176:177], 0, s[14:15]
	v_pk_mul_f32 v[214:215], v[208:209], v[190:191]
	v_pk_fma_f32 v[216:217], v[196:197], v[180:181], v[216:217] neg_lo:[0,0,1] neg_hi:[0,0,1]
	v_pk_mul_f32 v[190:191], v[194:195], v[190:191]
	v_pk_fma_f32 v[180:181], v[210:211], v[180:181], v[188:189]
	v_lshl_add_u64 v[188:189], v[176:177], 0, v[134:135]
	v_pk_fma_f32 v[214:215], v[194:195], v[182:183], v[214:215] neg_lo:[0,0,1] neg_hi:[0,0,1]
	v_pk_fma_f32 v[182:183], v[208:209], v[182:183], v[190:191]
	v_pk_mul_f32 v[186:187], v[198:199], v[186:187]
	v_lshl_add_u64 v[190:191], v[188:189], 0, s[48:49]
	v_add_co_u32_e32 v188, vcc, s27, v188
	v_pk_fma_f32 v[218:219], v[198:199], v[178:179], v[218:219] neg_lo:[0,0,1] neg_hi:[0,0,1]
	v_pk_fma_f32 v[186:187], v[212:213], v[178:179], v[186:187]
	v_cvt_pk_bf16_f32 v176, v216, v217
	v_cvt_pk_bf16_f32 v177, v214, v215
	v_cvt_pk_bf16_f32 v178, v220, v221
	v_addc_co_u32_e32 v189, vcc, 0, v189, vcc
	v_cvt_pk_bf16_f32 v179, v218, v219
	global_store_dwordx4 v[188:189], v[176:179], off
	v_pk_mul_f32 v[198:199], v[28:29], v[148:149] op_sel_hi:[1,0]
	v_pk_mul_f32 v[212:213], v[16:17], v[148:149] op_sel_hi:[1,0]
	v_cvt_pk_bf16_f32 v176, v180, v181
	v_cvt_pk_bf16_f32 v177, v182, v183
	v_cvt_pk_bf16_f32 v178, v184, v185
	v_lshlrev_b64 v[184:185], 7, v[150:151]
	v_cvt_pk_bf16_f32 v179, v186, v187
	global_store_dwordx4 v[190:191], v[176:179], off offset:64
	v_pk_mul_f32 v[194:195], v[36:37], v[148:149] op_sel_hi:[1,0]
	v_pk_mul_f32 v[208:209], v[24:25], v[148:149] op_sel_hi:[1,0]
	v_lshl_add_u64 v[176:177], s[38:39], 0, v[184:185]
	v_lshl_add_u64 v[184:185], s[40:41], 0, v[184:185]
	v_lshl_add_u64 v[180:181], v[176:177], 0, v[170:171]
	v_lshl_add_u64 v[188:189], v[184:185], 0, v[170:171]
	global_load_dwordx4 v[176:179], v[180:181], off offset:16
	s_nop 0
	global_load_dwordx4 v[180:183], v[180:181], off
	s_nop 0
	global_load_dwordx4 v[184:187], v[188:189], off offset:16
	s_nop 0
	global_load_dwordx4 v[188:191], v[188:189], off
	v_pk_mul_f32 v[192:193], v[38:39], v[148:149] op_sel_hi:[1,0]
	v_pk_mul_f32 v[206:207], v[26:27], v[148:149] op_sel_hi:[1,0]
	v_pk_mul_f32 v[196:197], v[30:31], v[148:149] op_sel_hi:[1,0]
	v_pk_mul_f32 v[210:211], v[18:19], v[148:149] op_sel_hi:[1,0]
	s_waitcnt vmcnt(1)
	v_pk_mul_f32 v[220:221], v[212:213], v[184:185]
	v_pk_mul_f32 v[184:185], v[198:199], v[184:185]
	v_pk_fma_f32 v[220:221], v[198:199], v[176:177], v[220:221] neg_lo:[0,0,1] neg_hi:[0,0,1]
	v_pk_fma_f32 v[184:185], v[212:213], v[176:177], v[184:185]
	v_mad_i64_i32 v[176:177], s[24:25], v150, s26, v[132:133]
	s_waitcnt vmcnt(0)
	v_pk_mul_f32 v[216:217], v[208:209], v[188:189]
	v_pk_mul_f32 v[188:189], v[194:195], v[188:189]
	v_lshl_add_u64 v[176:177], v[176:177], 0, s[14:15]
	v_pk_mul_f32 v[214:215], v[206:207], v[190:191]
	v_pk_fma_f32 v[216:217], v[194:195], v[180:181], v[216:217] neg_lo:[0,0,1] neg_hi:[0,0,1]
	v_pk_mul_f32 v[190:191], v[192:193], v[190:191]
	v_pk_fma_f32 v[180:181], v[208:209], v[180:181], v[188:189]
	v_lshl_add_u64 v[188:189], v[176:177], 0, v[134:135]
	v_pk_fma_f32 v[214:215], v[192:193], v[182:183], v[214:215] neg_lo:[0,0,1] neg_hi:[0,0,1]
	v_pk_mul_f32 v[218:219], v[210:211], v[186:187]
	v_pk_fma_f32 v[182:183], v[206:207], v[182:183], v[190:191]
	v_pk_mul_f32 v[186:187], v[196:197], v[186:187]
	v_lshl_add_u64 v[190:191], v[188:189], 0, s[48:49]
	v_add_co_u32_e32 v188, vcc, s27, v188
	v_add_u32_e32 v192, 0xb0, v146
	v_pk_fma_f32 v[218:219], v[196:197], v[178:179], v[218:219] neg_lo:[0,0,1] neg_hi:[0,0,1]
	v_pk_fma_f32 v[186:187], v[210:211], v[178:179], v[186:187]
	v_cvt_pk_bf16_f32 v176, v216, v217
	v_cvt_pk_bf16_f32 v177, v214, v215
	v_cvt_pk_bf16_f32 v178, v220, v221
	v_addc_co_u32_e32 v189, vcc, 0, v189, vcc
	v_ashrrev_i32_e32 v193, 31, v192
	v_cvt_pk_bf16_f32 v179, v218, v219
	global_store_dwordx4 v[188:189], v[176:179], off
	v_mad_i64_i32 v[132:133], s[24:25], v192, s26, v[132:133]
	s_nop 0
	v_cvt_pk_bf16_f32 v176, v180, v181
	v_cvt_pk_bf16_f32 v177, v182, v183
	v_cvt_pk_bf16_f32 v178, v184, v185
	v_lshlrev_b64 v[184:185], 7, v[192:193]
	v_cvt_pk_bf16_f32 v179, v186, v187
	global_store_dwordx4 v[190:191], v[176:179], off offset:64
	v_lshl_add_u64 v[132:133], v[132:133], 0, s[14:15]
	s_mov_b64 s[14:15], 0x1040
	v_lshl_add_u64 v[176:177], s[38:39], 0, v[184:185]
	v_lshl_add_u64 v[184:185], s[40:41], 0, v[184:185]
	v_lshl_add_u64 v[180:181], v[176:177], 0, v[170:171]
	v_lshl_add_u64 v[170:171], v[184:185], 0, v[170:171]
	global_load_dwordx4 v[176:179], v[180:181], off offset:16
	s_nop 0
	global_load_dwordx4 v[180:183], v[180:181], off
	s_nop 0
	global_load_dwordx4 v[184:187], v[170:171], off offset:16
	global_load_dwordx4 v[188:191], v[170:171], off
	v_mov_b32_e32 v170, v149
	v_pk_mul_f32 v[194:195], v[22:23], v[170:171] op_sel_hi:[1,0]
	v_pk_mul_f32 v[196:197], v[20:21], v[170:171] op_sel_hi:[1,0]
	v_pk_mul_f32 v[198:199], v[14:15], v[170:171] op_sel_hi:[1,0]
	v_pk_mul_f32 v[206:207], v[12:13], v[170:171] op_sel_hi:[1,0]
	v_pk_mul_f32 v[208:209], v[10:11], v[170:171] op_sel_hi:[1,0]
	v_pk_mul_f32 v[210:211], v[8:9], v[170:171] op_sel_hi:[1,0]
	v_pk_mul_f32 v[212:213], v[6:7], v[170:171] op_sel_hi:[1,0]
	v_pk_mul_f32 v[170:171], v[4:5], v[170:171] op_sel_hi:[1,0]
	s_waitcnt vmcnt(1)
	v_pk_mul_f32 v[218:219], v[212:213], v[186:187]
	v_pk_mul_f32 v[220:221], v[170:171], v[184:185]
	v_pk_mul_f32 v[184:185], v[206:207], v[184:185]
	v_pk_fma_f32 v[220:221], v[206:207], v[176:177], v[220:221] neg_lo:[0,0,1] neg_hi:[0,0,1]
	v_pk_fma_f32 v[170:171], v[170:171], v[176:177], v[184:185]
	v_lshl_add_u64 v[176:177], v[132:133], 0, v[134:135]
	s_waitcnt vmcnt(0)
	v_pk_mul_f32 v[214:215], v[208:209], v[190:191]
	v_pk_mul_f32 v[216:217], v[210:211], v[188:189]
	v_add_co_u32_e32 v184, vcc, s27, v176
	v_pk_fma_f32 v[214:215], v[194:195], v[182:183], v[214:215] neg_lo:[0,0,1] neg_hi:[0,0,1]
	v_pk_fma_f32 v[216:217], v[196:197], v[180:181], v[216:217] neg_lo:[0,0,1] neg_hi:[0,0,1]
	v_pk_fma_f32 v[218:219], v[198:199], v[178:179], v[218:219] neg_lo:[0,0,1] neg_hi:[0,0,1]
	v_pk_mul_f32 v[190:191], v[194:195], v[190:191]
	v_pk_mul_f32 v[188:189], v[196:197], v[188:189]
	v_pk_mul_f32 v[186:187], v[198:199], v[186:187]
	v_cvt_pk_bf16_f32 v132, v216, v217
	v_cvt_pk_bf16_f32 v133, v214, v215
	v_cvt_pk_bf16_f32 v134, v220, v221
	v_cvt_pk_bf16_f32 v135, v218, v219
	v_addc_co_u32_e32 v185, vcc, 0, v177, vcc
	v_pk_fma_f32 v[182:183], v[208:209], v[182:183], v[190:191]
	v_pk_fma_f32 v[180:181], v[210:211], v[180:181], v[188:189]
	v_pk_fma_f32 v[178:179], v[212:213], v[178:179], v[186:187]
	global_store_dwordx4 v[184:185], v[132:135], off
	s_nop 1
	v_cvt_pk_bf16_f32 v132, v180, v181
	v_cvt_pk_bf16_f32 v133, v182, v183
	v_cvt_pk_bf16_f32 v134, v170, v171
	v_cvt_pk_bf16_f32 v135, v178, v179
	v_lshl_add_u64 v[170:171], v[176:177], 0, s[14:15]
	s_mov_b64 s[14:15], 0

; #define VMW() asm volatile("s_waitcnt vmcnt(0)" ::: "memory")
; #define SWRITE_HK(bf) do { *(bf16x8*)(K_lds + (bf) * SHM_K + kws) = S.st_k0; *(bf16x8*)(K_lds + (bf) * SHM_K + kws + 32 * 256) = S.st_k1; \
;                            if constexpr (PE) *(bf16x8*)(lds + OFF_KPE + (bf) * SHM_KPE + pws) = S.st_kp; } while (0)
; template <bool PE>
; __device__ __forceinline__ void swa_prime(const BlockRef& cur, const Prm& P, char* lds, Seam<PE>& S) {
;     int tid_ = threadIdx.x; asm volatile("" : "+v"(tid_));
;     const int tid = tid_, wid = __builtin_amdgcn_readfirstlane(tid >> 6), lane = tid & 63, r32 = lane & 31, hi = lane >> 5;
;     const int sr = tid >> 4, sc = (tid & 15) * 8, kws = KSWZ(sr, sc * 2); char* K_lds = lds + OFF_K;
;     const int pr = tid >> 3, pc = (tid & 7) * 8, pws = pr * KPE_ROW + (tid & 7) * 16;
;     const unsigned kvoff = (unsigned)(sr * P.kvs + sc) * 2u, kpoff = (unsigned)(pr * P.kpes + pc) * 2u, qoff = (unsigned)((wid * QBLK + r32) * P.qs + hi * 8) * 2u, qpoff = (unsigned)((wid * QBLK + r32) * P.qpes + hi * 8) * 2u;
;     const int kb0 = swa_jlo(cur.P0, P.W) * KVBLK;
; #pragma unroll
;     for (int d0 = 0; d0 < 8; ++d0) S.qr[d0] = LDG(cur.Q, qoff + d0 * 32);
;     if constexpr (PE) {
; #pragma unroll
;         for (int d0 = 0; d0 < 4; ++d0) *(bf16x8*)(lds + OFF_QPE + wid * 4096 + d0 * 1024 + lane * 16) = LDG(cur.Qpe, qpoff + d0 * 32);
;     }
;     SLOAD_H(cur, kb0); VMW(); SWRITE_HK(0);
;     __syncthreads();
; }
.LBB0_361:
	s_or_b64 exec, exec, s[4:5]
	v_readlane_b32 s4, v255, 25
	s_add_u32 s58, s28, 0x36a00000
	v_readlane_b32 s5, v255, 26
	s_addc_u32 s59, s29, 0
	s_waitcnt lgkmcnt(0)
	s_barrier
	v_readlane_b32 s6, v255, 27
	v_readlane_b32 s7, v255, 28
	s_lshl_b32 s14, s3, 8
	v_writelane_b32 v255, s4, 25
	s_and_b32 s68, s14, 0x700
	s_ashr_i32 s0, s3, 3
	v_writelane_b32 v255, s5, 26
	v_writelane_b32 v255, s6, 27
	v_writelane_b32 v255, s7, 28
	s_ashr_i32 s4, s3, 7
	s_ashr_i32 s5, s4, 31
	s_lshl_b64 s[6:7], s[4:5], 12
	s_or_b32 s6, s6, s68
	s_mul_i32 s14, s7, 0x1800
	s_mul_hi_u32 s15, s6, 0x1800
	s_and_b32 s1, s0, 15
	s_add_i32 s15, s15, s14
	s_mul_i32 s14, s6, 0x1800
	s_add_u32 s20, s10, s14
	s_addc_u32 s21, s11, s15
	s_lshl_b32 s23, s1, 7
	s_lshl_b32 s24, s1, 8
	s_add_u32 s14, s20, s24
	s_addc_u32 s15, s21, 0
	s_add_u32 s1, s20, s23
	s_addc_u32 s20, s21, 0
	s_add_u32 s50, s1, 0x1000
	s_addc_u32 s51, s20, 0
	s_ashr_i32 s1, s0, 31
	s_lshl_b64 s[0:1], s[0:1], 20
	s_add_u32 s86, s12, s0
	s_addc_u32 s87, s13, s1
	s_add_u32 s88, s86, 0x4000000
	s_addc_u32 s89, s87, 0
	s_lshl_b64 s[0:1], s[4:5], 19
	s_add_u32 s90, s8, s0
	s_addc_u32 s91, s9, s1
	s_lshl_b64 s[0:1], s[6:7], 12
	s_add_u32 s0, s58, s0
	s_addc_u32 s1, s59, s1
	v_mov_b32_e32 v3, v0
	s_add_u32 s78, s0, s24
	s_addc_u32 s79, s1, 0
	v_readfirstlane_b32 s0, v3
	s_ashr_i32 s0, s0, 6
	v_and_b32_e32 v4, 31, v3
	v_lshl_or_b32 v4, s0, 5, v4
	s_movk_i32 s1, 0xc00
	v_mul_lo_u32 v4, v4, s1
	v_lshrrev_b32_e32 v5, 2, v3
	v_and_or_b32 v4, v5, 8, v4
	s_lshl_b32 s0, s0, 12
	v_lshlrev_b32_e32 v9, 4, v3
	v_lshlrev_b32_e32 v8, 1, v4
	s_add_i32 s0, s0, 0
	v_and_b32_e32 v4, 0x3f0, v9
	v_add_u32_e32 v4, s0, v4
	global_load_dwordx4 v[160:163], v8, s[14:15]
	global_load_dwordx4 v[156:159], v8, s[14:15] offset:32
	global_load_dwordx4 v[152:155], v8, s[14:15] offset:64
	global_load_dwordx4 v[148:151], v8, s[14:15] offset:96
	global_load_dwordx4 v[144:147], v8, s[14:15] offset:128
	global_load_dwordx4 v[140:143], v8, s[14:15] offset:160
	global_load_dwordx4 v[136:139], v8, s[14:15] offset:192
	global_load_dwordx4 v[132:135], v8, s[14:15] offset:224
	v_add_u32_e32 v10, 0x15000, v4
	global_load_dwordx4 v[4:7], v8, s[50:51]
	s_movk_i32 s0, 0xff00
	v_bitop3_b32 v200, v9, s0, v228 bitop3:0xe0
	global_load_dwordx4 v[100:103], v200, s[88:89]
	s_movk_i32 s0, 0x90
	v_and_b32_e32 v16, 0x70, v9
	v_and_b32_e32 v17, 0xffffff00, v9
	s_mov_b32 s1, 0
	s_xor_b32 s69, s68, 0xf00
	s_mov_b32 s4, s68
	s_mov_b32 s73, s68
	s_mov_b64 s[84:85], s[90:91]
	s_mov_b64 s[62:63], s[78:79]
	s_mov_b64 s[70:71], s[88:89]
	s_mov_b64 s[60:61], s[86:87]
	s_waitcnt vmcnt(1)
	ds_write_b128 v10, v[4:7]
	global_load_dwordx4 v[4:7], v8, s[50:51] offset:32
	s_waitcnt vmcnt(0)
	ds_write_b128 v10, v[4:7] offset:1024
	global_load_dwordx4 v[4:7], v8, s[50:51] offset:64
	s_waitcnt vmcnt(0)
	ds_write_b128 v10, v[4:7] offset:2048
	global_load_dwordx4 v[4:7], v8, s[50:51] offset:96
	s_waitcnt vmcnt(0)
	ds_write_b128 v10, v[4:7] offset:3072
	v_ashrrev_i32_e32 v4, 3, v3
	v_mul_lo_u32 v18, v4, s0
	v_and_b32_e32 v3, 0xf0, v3
	s_movk_i32 s0, 0xf0
	v_bitop3_b32 v3, v9, v3, s0 bitop3:0x6c
	v_lshl_add_u64 v[8:9], s[86:87], 0, v[200:201]
	v_lshl_or_b32 v12, v4, 7, v16
	v_add_co_u32_e32 v4, vcc, 0x4002000, v8
	v_add3_u32 v3, 0, v17, v3
	s_nop 0
	v_addc_co_u32_e32 v5, vcc, 0, v9, vcc
	v_add_co_u32_e32 v8, vcc, 0x2000, v8
	global_load_dwordx4 v[104:107], v[4:5], off
	s_nop 0
	global_load_dwordx4 v[4:7], v200, s[86:87]
	v_addc_co_u32_e32 v9, vcc, 0, v9, vcc
	global_load_dwordx4 v[8:11], v[8:9], off
	s_nop 0
	global_load_dwordx4 v[12:15], v12, s[90:91]
	s_waitcnt vmcnt(0)
	ds_write_b128 v3, v[4:7] offset:32768
	ds_write_b128 v3, v[8:11] offset:40960
	v_add3_u32 v3, s34, v18, v16
	ds_write_b128 v3, v[12:15]
	s_waitcnt lgkmcnt(0)
	s_barrier
	s_branch .LBB0_364

; #define SBAR() __builtin_amdgcn_sched_barrier(0)
; __device__ __forceinline__ unsigned cvtpk(float lo, float hi) { unsigned r; asm volatile("v_cvt_pk_bf16_f32 %0, %1, %2" : "=v"(r) : "v"(lo), "v"(hi)); return r; }
; #define VMW() asm volatile("s_waitcnt vmcnt(0)" ::: "memory")
; #define ATT_G __attribute__((address_space(1)))
; #define SWRITE_HK(bf) do { *(bf16x8*)(K_lds + (bf) * SHM_K + kws) = S.st_k0; *(bf16x8*)(K_lds + (bf) * SHM_K + kws + 32 * 256) = S.st_k1; \
;                            if constexpr (PE) *(bf16x8*)(lds + OFF_KPE + (bf) * SHM_KPE + pws) = S.st_kp; } while (0)
; template <bool PE, bool SK, bool LSE, bool EARLY>
; __device__ __forceinline__ void swa_block(const BlockRef& cur, const BlockRef& nxt, const Prm& P, char* lds, Seam<PE>& S) {
;     ...
;     SBAR();
;     VMW(); SWRITE_HK(0);
;     if constexpr (PE) {
; #pragma unroll
;         for (int d0 = 0; d0 < 4; ++d0) *(bf16x8*)(lds + OFF_QPE + wid * 4096 + d0 * 1024 + lane * 16) = qpn[d0];
;     }
;     SBAR();
;     { const float rl = __builtin_amdgcn_rcpf(l_reg);
;       ATT_G char* ob = (ATT_G char*)cur.O + (unsigned)(((wid * QBLK + r32) * P.os + 8 * hi) * 2);
; #pragma unroll
;       for (int d0 = 0; d0 < 4; ++d0)
; #pragma unroll
;         for (int j = 0; j < 2; ++j) {
;             const unsigned ax = cvtpk(o[d0][8 * j + 0] * rl, o[d0][8 * j + 1] * rl), ay = cvtpk(o[d0][8 * j + 2] * rl, o[d0][8 * j + 3] * rl);
;             const unsigned bx = cvtpk(o[d0][8 * j + 4] * rl, o[d0][8 * j + 5] * rl), by = cvtpk(o[d0][8 * j + 6] * rl, o[d0][8 * j + 7] * rl);
;             auto rx = __builtin_amdgcn_permlane32_swap(ax, bx, false, false); auto ry = __builtin_amdgcn_permlane32_swap(ay, by, false, false);
;             const u32x4 w = {rx[0], ry[0], rx[1], ry[1]};
;             *(ATT_G u32x4*)(ob + d0 * 64 + j * 32) = w; } }
;     if constexpr (LSE) { if (hi == 0) *(ATT_G float*)((ATT_G char*)cur.Lse + (unsigned)((wid * QBLK + r32) * P.lses) * 4u) = m_reg * P.scale + __logf(l_reg); }
;     __syncthreads();
.LBB0_363:
	s_waitcnt vmcnt(0)
	ds_write_b128 v216, v[108:111] offset:32768
	ds_write_b128 v216, v[112:115] offset:40960
	ds_write_b128 v225, v[116:119]
	ds_write_b128 v215, v[120:123]
	ds_write_b128 v215, v[124:127] offset:1024
	ds_write_b128 v215, v[128:131] offset:2048
	ds_write_b128 v215, v[164:167] offset:3072
	v_rcp_f32_e32 v68, v169
	v_lshl_or_b32 v3, v190, 12, v3
	s_cmp_lg_u32 s0, 4
	s_mov_b32 s4, s73
	v_mul_f32_e32 v52, v52, v68
	v_mul_f32_e32 v53, v53, v68
	v_mul_f32_e32 v54, v54, v68
	v_cvt_pk_bf16_f32 v52, v52, v53
	v_mul_f32_e32 v53, v55, v68
	v_cvt_pk_bf16_f32 v53, v54, v53
	v_mul_f32_e32 v54, v56, v68
	v_mul_f32_e32 v55, v57, v68
	v_cvt_pk_bf16_f32 v54, v54, v55
	v_mul_f32_e32 v55, v58, v68
	v_mul_f32_e32 v56, v59, v68
	v_cvt_pk_bf16_f32 v55, v55, v56
	v_permlane32_swap_b32_e32 v52, v54
	v_permlane32_swap_b32_e32 v53, v55
	global_store_dwordx4 v3, v[52:55], s[78:79]
	v_mul_f32_e32 v56, v67, v68
	v_mul_f32_e32 v36, v36, v68
	v_mul_f32_e32 v52, v60, v68
	v_mul_f32_e32 v53, v61, v68
	v_cvt_pk_bf16_f32 v52, v52, v53
	v_mul_f32_e32 v53, v62, v68
	v_mul_f32_e32 v54, v63, v68
	v_cvt_pk_bf16_f32 v53, v53, v54
	v_mul_f32_e32 v54, v64, v68
	v_mul_f32_e32 v55, v65, v68
	v_cvt_pk_bf16_f32 v54, v54, v55
	v_mul_f32_e32 v55, v66, v68
	v_cvt_pk_bf16_f32 v55, v55, v56
	v_permlane32_swap_b32_e32 v52, v54
	s_nop 0
	v_permlane32_swap_b32_e32 v53, v55
	v_mul_f32_e32 v37, v37, v68
	global_store_dwordx4 v3, v[52:55], s[78:79] offset:32
	v_cvt_pk_bf16_f32 v36, v36, v37
	v_mul_f32_e32 v37, v38, v68
	v_mul_f32_e32 v38, v39, v68
	v_cvt_pk_bf16_f32 v37, v37, v38
	v_mul_f32_e32 v38, v40, v68
	v_mul_f32_e32 v39, v41, v68
	v_cvt_pk_bf16_f32 v38, v38, v39
	v_mul_f32_e32 v39, v42, v68
	v_mul_f32_e32 v40, v43, v68
	v_cvt_pk_bf16_f32 v39, v39, v40
	v_permlane32_swap_b32_e32 v36, v38
	v_permlane32_swap_b32_e32 v37, v39
	global_store_dwordx4 v3, v[36:39], s[78:79] offset:64
	v_mul_f32_e32 v40, v51, v68
	v_mul_f32_e32 v20, v20, v68
	v_mul_f32_e32 v36, v44, v68
	v_mul_f32_e32 v37, v45, v68
	v_cvt_pk_bf16_f32 v36, v36, v37
	v_mul_f32_e32 v37, v46, v68
	v_mul_f32_e32 v38, v47, v68
	v_cvt_pk_bf16_f32 v37, v37, v38
	v_mul_f32_e32 v38, v48, v68
	v_mul_f32_e32 v39, v49, v68
	v_cvt_pk_bf16_f32 v38, v38, v39
	v_mul_f32_e32 v39, v50, v68
	v_cvt_pk_bf16_f32 v39, v39, v40
	v_permlane32_swap_b32_e32 v36, v38
	s_nop 0
	v_permlane32_swap_b32_e32 v37, v39
	v_mul_f32_e32 v21, v21, v68
	global_store_dwordx4 v3, v[36:39], s[78:79] offset:96
	v_cvt_pk_bf16_f32 v20, v20, v21
	v_mul_f32_e32 v21, v22, v68
	v_mul_f32_e32 v22, v23, v68
	v_cvt_pk_bf16_f32 v21, v21, v22
	v_mul_f32_e32 v22, v24, v68
	v_mul_f32_e32 v23, v25, v68
	v_cvt_pk_bf16_f32 v22, v22, v23
	v_mul_f32_e32 v23, v26, v68
	v_mul_f32_e32 v24, v27, v68
	v_cvt_pk_bf16_f32 v23, v23, v24
	v_permlane32_swap_b32_e32 v20, v22
	v_permlane32_swap_b32_e32 v21, v23
	global_store_dwordx4 v3, v[20:23], s[78:79] offset:128
	v_mul_f32_e32 v24, v35, v68
	v_mul_f32_e32 v4, v4, v68
	v_mul_f32_e32 v20, v28, v68
	v_mul_f32_e32 v21, v29, v68
	v_cvt_pk_bf16_f32 v20, v20, v21
	v_mul_f32_e32 v21, v30, v68
	v_mul_f32_e32 v22, v31, v68
	v_cvt_pk_bf16_f32 v21, v21, v22
	v_mul_f32_e32 v22, v32, v68
	v_mul_f32_e32 v23, v33, v68
	v_cvt_pk_bf16_f32 v22, v22, v23
	v_mul_f32_e32 v23, v34, v68
	v_cvt_pk_bf16_f32 v23, v23, v24
	v_permlane32_swap_b32_e32 v20, v22
	s_nop 0
	v_permlane32_swap_b32_e32 v21, v23
	v_mul_f32_e32 v5, v5, v68
	global_store_dwordx4 v3, v[20:23], s[78:79] offset:160
	v_cvt_pk_bf16_f32 v4, v4, v5
	v_mul_f32_e32 v5, v6, v68
	v_mul_f32_e32 v6, v7, v68
	v_cvt_pk_bf16_f32 v5, v5, v6
	v_mul_f32_e32 v6, v8, v68
	v_mul_f32_e32 v7, v9, v68
	v_cvt_pk_bf16_f32 v6, v6, v7
	v_mul_f32_e32 v7, v10, v68
	v_mul_f32_e32 v8, v11, v68
	v_cvt_pk_bf16_f32 v7, v7, v8
	v_permlane32_swap_b32_e32 v4, v6
	v_permlane32_swap_b32_e32 v5, v7
	global_store_dwordx4 v3, v[4:7], s[78:79] offset:192
	v_mul_f32_e32 v8, v19, v68
	s_mov_b64 s[90:91], s[84:85]
	v_mul_f32_e32 v4, v12, v68
	v_mul_f32_e32 v5, v13, v68
	v_cvt_pk_bf16_f32 v4, v4, v5
	v_mul_f32_e32 v5, v14, v68
	v_mul_f32_e32 v6, v15, v68
	v_cvt_pk_bf16_f32 v5, v5, v6
	v_mul_f32_e32 v6, v16, v68
	v_mul_f32_e32 v7, v17, v68
	v_cvt_pk_bf16_f32 v6, v6, v7
	v_mul_f32_e32 v7, v18, v68
	v_cvt_pk_bf16_f32 v7, v7, v8
	v_permlane32_swap_b32_e32 v4, v6
	s_nop 0
	v_permlane32_swap_b32_e32 v5, v7
	global_store_dwordx4 v3, v[4:7], s[78:79] offset:224
	s_mov_b64 s[78:79], s[62:63]
	s_mov_b64 s[88:89], s[70:71]
	s_mov_b64 s[86:87], s[60:61]
	s_mov_b32 s1, s0
	s_waitcnt lgkmcnt(0)
	s_barrier
	s_cbranch_scc0 .LBB0_389

; __device__ __forceinline__ void partialSM(f32x16& p0, f32x16& p1, float& m_reg, float& mn, float& alpha, const float scale) {
;     float pmax = p0[0]; for (int r = 1; r < 16; ++r) pmax = fmaxf(pmax, p0[r]); for (int r = 0; r < 16; ++r) pmax = fmaxf(pmax, p1[r]);
;     { auto rr = __builtin_amdgcn_permlane32_swap(__float_as_uint(pmax), __float_as_uint(pmax), false, false);
;       pmax = fmaxf(__uint_as_float(rr[0]), __uint_as_float(rr[1])); }
;     const float C2 = 1.4426950408889634f * scale;
;     if (__builtin_expect(__all((pmax - m_reg) * scale <= THR), 1)) { mn = m_reg; alpha = 1.f; }
;     else { mn = fmaxf(m_reg, pmax); alpha = __builtin_amdgcn_exp2f((m_reg - mn) * C2); m_reg = mn; }
;     const float mnL = -mn * C2;
;     for (int r = 0; r < 16; ++r) p0[r] = fmaf(p0[r], C2, mnL); for (int r = 0; r < 16; ++r) p1[r] = fmaf(p1[r], C2, mnL);
;     for (int r = 0; r < 16; ++r) p0[r] = __builtin_amdgcn_exp2f(p0[r]);
; }
; template <bool PE, bool SK, bool LSE, bool EARLY>
; __device__ __forceinline__ void swa_block(const BlockRef& cur, const BlockRef& nxt, const Prm& P, char* lds, Seam<PE>& S) {
;     ...
;     const int j_lo = swa_jlo(cur.P0, W);
;     int j_hi = (cur.P0 + QB - 1) / KVBLK + 1; if (j_hi > P.skv / KVBLK) j_hi = P.skv / KVBLK;
;     const int NT = j_hi - j_lo;
;     const int kbn = swa_jlo(nxt.P0, W) * KVBLK;
;     const int qlo = cur.P0 + wid * QBLK, qm = qlo + r32 - 4 * hi;
;     char* V_lds = lds + OFF_V; char* K_lds = lds + OFF_K;
;     float* ws = (float*)(lds + OFF_WS) + wid * 64; float* li_l = ws, * al_l = ws + 32;
;     float m_reg = -1e30f, l_reg = 0; f32x16 o[4] = {};
;     const int sr = tid >> 4, sc = (tid & 15) * 8, vst0 = v_st(sr, sc), vst1 = v_st(32 + sr, sc), kws = KSWZ(sr, sc * 2);
;     const int pr = tid >> 3, pc = (tid & 7) * 8, pws = pr * KPE_ROW + (tid & 7) * 16;
;     const unsigned kvoff = (unsigned)(sr * P.kvs + sc) * 2u, kpoff = (unsigned)(pr * P.kpes + pc) * 2u;
;     const int vb0 = (int)(uintptr_t)lds + v_rd_base(lane);
;     ...
;     f32x16 pA0, pA1, pB0, pB1; float mnA, mnB, alA, alB; bf16x8 pa0, pa1, pa2, pa3;
;     SWRITE_HV(0); SBAR();
;     if (NT > 1) { SLOAD_H(cur, KBASE(1)); }
;     SBAR(); qkt<0, SK, PE>(pA0, pA1, lds, r32, hi, wid, lane, S.qr, ACT(0));
;     MASKT(pA0, pA1, 0); partialSM(pA0, pA1, m_reg, mnA, alA, P.scale);
;     if (NT > 1) { VMW(); SWRITE_H(1); }
;     __syncthreads();
.LBB0_368:
	s_add_i32 s5, s4, 0xff
	s_lshr_b32 s5, s5, 6
	s_add_i32 s5, s5, 1
	s_cmpk_lt_u32 s4, 0xf01
	v_and_b32_e32 v59, 0xf0, v59
	s_movk_i32 s4, 0x90
	s_cselect_b32 s21, s5, 64
	v_bitop3_b32 v59, v60, v62, v59 bitop3:0xde
	v_mad_u64_u32 v[212:213], s[4:5], v61, s4, v[56:57]
	v_lshlrev_b32_e32 v56, 3, v58
	v_and_b32_e32 v60, 0xc0, v63
	v_and_or_b32 v56, v56, 24, v60
	v_lshlrev_b32_e32 v60, 1, v58
	v_lshlrev_b32_e32 v58, 6, v58
	v_and_b32_e32 v60, 32, v60
	v_and_b32_e32 v58, 0x800, v58
	s_cmp_lg_u32 0, -1
	v_or3_b32 v56, v56, v60, v58
	s_cselect_b32 s4, 0, 0
	v_add_u32_e32 v213, s4, v56
	v_max_f32_e32 v56, v21, v21
	v_max_f32_e32 v58, v20, v20
	v_max_f32_e32 v56, v58, v56
	v_max3_f32 v56, v56, v22, v23
	v_max3_f32 v56, v56, v24, v25
	v_max3_f32 v56, v56, v26, v27
	v_max3_f32 v56, v56, v28, v29
	v_max3_f32 v56, v56, v30, v31
	v_max3_f32 v56, v56, v32, v33
	v_max3_f32 v56, v56, v34, v35
	v_max3_f32 v56, v56, v4, v5
	v_max3_f32 v56, v56, v6, v7
	v_max3_f32 v56, v56, v8, v9
	v_max3_f32 v56, v56, v10, v11
	v_max3_f32 v56, v56, v12, v13
	v_max3_f32 v56, v56, v14, v15
	v_max3_f32 v56, v56, v16, v17
	v_max3_f32 v56, v56, v18, v19
	v_mov_b32_e32 v58, v56
	s_nop 1
	v_permlane32_swap_b32_e32 v56, v58
	v_max_f32_e32 v58, v58, v58
	v_max_f32_e32 v56, v56, v56
	v_max_f32_e32 v56, v56, v58
	v_add_f32_e32 v58, 0x7149f2ca, v56
	v_mul_f32_e32 v58, 0x3d93cd3a, v58
	v_max_f32_e32 v56, 0xf149f2ca, v56
	v_cmp_ge_f32_e32 vcc, s35, v58
	v_sub_f32_e32 v58, 0xf149f2ca, v56
	s_add_i32 s23, s1, 0xfffff01f
	v_mul_f32_e32 v58, 0x3dd53b94, v58
	v_exp_f32_e32 v58, v58
	s_cmp_eq_u64 vcc, exec
	s_cselect_b64 vcc, -1, 0
	v_cndmask_b32_e32 v185, v56, v229, vcc
	v_mul_f32_e32 v56, 0xbdd53b94, v185
	v_cndmask_b32_e64 v184, v58, 1.0, vcc
	v_mov_b32_e32 v58, v56
	s_add_i32 s4, 0, 0x12c00
	v_mul_u32_u24_e32 v64, 0x90, v218
	v_fmamk_f32 v20, v20, 0x3dd53b94, v56
	v_fmamk_f32 v21, v21, 0x3dd53b94, v56
	v_fmamk_f32 v22, v22, 0x3dd53b94, v56
	v_fmamk_f32 v23, v23, 0x3dd53b94, v56
	v_fmamk_f32 v24, v24, 0x3dd53b94, v56
	v_fmamk_f32 v25, v25, 0x3dd53b94, v56
	v_fmamk_f32 v26, v26, 0x3dd53b94, v56
	v_fmamk_f32 v27, v27, 0x3dd53b94, v56
	v_fmamk_f32 v28, v28, 0x3dd53b94, v56
	v_fmamk_f32 v29, v29, 0x3dd53b94, v56
	v_fmamk_f32 v30, v30, 0x3dd53b94, v56
	v_fmamk_f32 v31, v31, 0x3dd53b94, v56
	v_fmamk_f32 v32, v32, 0x3dd53b94, v56
	v_fmamk_f32 v33, v33, 0x3dd53b94, v56
	v_fmamk_f32 v34, v34, 0x3dd53b94, v56
	v_fmac_f32_e32 v58, 0x3dd53b94, v35
	v_pk_fma_f32 v[182:183], v[4:5], s[46:47], v[56:57] op_sel_hi:[1,0,0]
	v_add_u32_e32 v216, 0, v59
	v_add_u32_e32 v4, s4, v212
	v_exp_f32_e32 v236, v20
	v_exp_f32_e32 v237, v21
	v_exp_f32_e32 v199, v22
	v_exp_f32_e32 v235, v23
	v_exp_f32_e32 v197, v24
	v_exp_f32_e32 v214, v25
	v_exp_f32_e32 v196, v26
	v_exp_f32_e32 v198, v27
	v_exp_f32_e32 v193, v28
	v_exp_f32_e32 v195, v29
	v_exp_f32_e32 v191, v30
	v_exp_f32_e32 v194, v31
	v_exp_f32_e32 v188, v32
	v_exp_f32_e32 v192, v33
	v_exp_f32_e32 v187, v34
	v_exp_f32_e32 v189, v58
	s_waitcnt vmcnt(0)
	ds_write_b128 v223, v[36:39] offset:16384
	ds_write_b128 v224, v[40:43] offset:16384
	ds_write_b128 v216, v[44:47] offset:49152
	ds_write_b128 v216, v[48:51] offset:57344
	ds_write_b128 v4, v[52:55]
	v_add_u32_e32 v4, s4, v64
	s_add_i32 s4, s1, 0xffffff45
	v_add_u32_e32 v5, s4, v218
	v_mov_b32_e32 v52, v201
	v_mov_b32_e32 v53, v201
	v_pk_fma_f32 v[168:169], v[18:19], s[46:47], v[56:57] op_sel_hi:[1,0,0]
	v_pk_fma_f32 v[170:171], v[16:17], s[46:47], v[56:57] op_sel_hi:[1,0,0]
	v_pk_fma_f32 v[172:173], v[14:15], s[46:47], v[56:57] op_sel_hi:[1,0,0]
	v_pk_fma_f32 v[174:175], v[12:13], s[46:47], v[56:57] op_sel_hi:[1,0,0]
	v_pk_fma_f32 v[176:177], v[10:11], s[46:47], v[56:57] op_sel_hi:[1,0,0]
	v_pk_fma_f32 v[178:179], v[8:9], s[46:47], v[56:57] op_sel_hi:[1,0,0]
	v_pk_fma_f32 v[180:181], v[6:7], s[46:47], v[56:57] op_sel_hi:[1,0,0]
	v_sub_u32_e32 v234, v5, v57
	v_mov_b32_e32 v54, v201
	v_mov_b32_e32 v55, v201
	v_mov_b32_e32 v56, v201
	v_mov_b32_e32 v57, v201
	v_mov_b32_e32 v58, v201
	v_mov_b32_e32 v59, v201
	v_mov_b32_e32 v60, v201
	v_mov_b32_e32 v61, v201
	v_mov_b32_e32 v62, v201
	v_mov_b32_e32 v63, v201
	v_mov_b32_e32 v64, v201
	v_mov_b32_e32 v65, v201
	v_mov_b32_e32 v66, v201
	v_mov_b32_e32 v67, v201
	v_add_u32_e32 v233, v4, v3
	v_mov_b64_e32 v[36:37], v[52:53]
	v_mov_b64_e32 v[20:21], v[52:53]
	v_mov_b64_e32 v[4:5], v[52:53]
	v_mov_b32_e32 v186, 0
	s_movk_i32 s42, 0xbf
	s_mov_b32 s52, 2
	s_movk_i32 s24, 0x180
	v_mov_b64_e32 v[38:39], v[54:55]
	v_mov_b64_e32 v[40:41], v[56:57]
	v_mov_b64_e32 v[42:43], v[58:59]
	v_mov_b64_e32 v[44:45], v[60:61]
	v_mov_b64_e32 v[46:47], v[62:63]
	v_mov_b64_e32 v[48:49], v[64:65]
	v_mov_b64_e32 v[50:51], v[66:67]
	v_mov_b64_e32 v[22:23], v[54:55]
	v_mov_b64_e32 v[24:25], v[56:57]
	v_mov_b64_e32 v[26:27], v[58:59]
	v_mov_b64_e32 v[28:29], v[60:61]
	v_mov_b64_e32 v[30:31], v[62:63]
	v_mov_b64_e32 v[32:33], v[64:65]
	v_mov_b64_e32 v[34:35], v[66:67]
	v_mov_b64_e32 v[6:7], v[54:55]
	v_mov_b64_e32 v[8:9], v[56:57]
	v_mov_b64_e32 v[10:11], v[58:59]
	v_mov_b64_e32 v[12:13], v[60:61]
	v_mov_b64_e32 v[14:15], v[62:63]
	v_mov_b64_e32 v[16:17], v[64:65]
	v_mov_b64_e32 v[18:19], v[66:67]
	s_waitcnt lgkmcnt(0)
	s_barrier
	s_branch .LBB0_370

; __device__ __forceinline__ void partialSM(f32x16& p0, f32x16& p1, float& m_reg, float& mn, float& alpha, const float scale) {
;     float pmax = p0[0]; for (int r = 1; r < 16; ++r) pmax = fmaxf(pmax, p0[r]); for (int r = 0; r < 16; ++r) pmax = fmaxf(pmax, p1[r]);
;     { auto rr = __builtin_amdgcn_permlane32_swap(__float_as_uint(pmax), __float_as_uint(pmax), false, false);
;       pmax = fmaxf(__uint_as_float(rr[0]), __uint_as_float(rr[1])); }
;     const float C2 = 1.4426950408889634f * scale;
;     if (__builtin_expect(__all((pmax - m_reg) * scale <= THR), 1)) { mn = m_reg; alpha = 1.f; }
;     else { mn = fmaxf(m_reg, pmax); alpha = __builtin_amdgcn_exp2f((m_reg - mn) * C2); m_reg = mn; }
.LBB0_372:
	v_max_f32_e32 v100, v85, v85
	v_max_f32_e32 v101, v84, v84
	v_max_f32_e32 v100, v101, v100
	v_max3_f32 v100, v100, v86, v87
	v_max3_f32 v100, v100, v88, v89
	v_max3_f32 v100, v100, v90, v91
	v_max3_f32 v100, v100, v92, v93
	v_max3_f32 v100, v100, v94, v95
	v_max3_f32 v100, v100, v96, v97
	v_max3_f32 v100, v100, v98, v99
	v_max3_f32 v100, v100, v68, v69
	v_max3_f32 v100, v100, v70, v71
	v_max3_f32 v100, v100, v72, v73
	v_max3_f32 v100, v100, v74, v75
	v_max3_f32 v100, v100, v76, v77
	v_max3_f32 v100, v100, v78, v79
	v_max3_f32 v100, v100, v80, v81
	v_max3_f32 v100, v100, v82, v83
	v_mov_b32_e32 v101, v100
	s_nop 1
	v_permlane32_swap_b32_e32 v100, v101
	v_max_f32_e32 v101, v101, v101
	v_max_f32_e32 v100, v100, v100
	v_max_f32_e32 v100, v100, v101
	v_max_f32_e32 v102, v185, v185
	v_sub_f32_e32 v101, v100, v185
	v_max_f32_e32 v100, v102, v100
	v_sub_f32_e32 v102, v185, v100
	v_mul_f32_e32 v102, 0x3dd53b94, v102
	v_mul_f32_e32 v101, 0x3d93cd3a, v101
	v_exp_f32_e32 v102, v102
	v_cmp_ge_f32_e32 vcc, s35, v101
	s_cmp_eq_u64 vcc, exec
	v_add_f32_e32 v235, v104, v105
	s_cselect_b64 s[4:5], -1, 0
	v_fmac_f32_e32 v235, v184, v186
	v_cndmask_b32_e64 v214, v102, 1.0, s[4:5]
	s_barrier
	s_waitcnt vmcnt(0)
	v_add_u32_e32 v237, 0, v212
	v_cmp_gt_f32_e32 vcc, 1.0, v214
	v_cmp_neq_f32_e64 s[6:7], 0, v235
	v_add_u32_e32 v225, 0x10800, v237
	s_and_b64 vcc, vcc, s[6:7]
	ds_write_b128 v223, v[164:167]
	ds_write_b128 v224, v[168:171]
	ds_write_b128 v216, v[172:175] offset:32768
	ds_write_b128 v216, v[176:179] offset:40960
	ds_write_b128 v225, v[180:183]
	s_cbranch_vccz .LBB0_374
	v_pk_mul_f32 v[66:67], v[66:67], v[214:215] op_sel_hi:[1,0]
	v_pk_mul_f32 v[64:65], v[64:65], v[214:215] op_sel_hi:[1,0]
	v_pk_mul_f32 v[62:63], v[62:63], v[214:215] op_sel_hi:[1,0]
	v_pk_mul_f32 v[60:61], v[60:61], v[214:215] op_sel_hi:[1,0]
	v_pk_mul_f32 v[58:59], v[58:59], v[214:215] op_sel_hi:[1,0]
	v_pk_mul_f32 v[56:57], v[56:57], v[214:215] op_sel_hi:[1,0]
	v_pk_mul_f32 v[54:55], v[54:55], v[214:215] op_sel_hi:[1,0]
	v_pk_mul_f32 v[52:53], v[52:53], v[214:215] op_sel_hi:[1,0]
	v_pk_mul_f32 v[50:51], v[50:51], v[214:215] op_sel_hi:[1,0]
	v_pk_mul_f32 v[48:49], v[48:49], v[214:215] op_sel_hi:[1,0]
	v_pk_mul_f32 v[46:47], v[46:47], v[214:215] op_sel_hi:[1,0]
	v_pk_mul_f32 v[44:45], v[44:45], v[214:215] op_sel_hi:[1,0]
	v_pk_mul_f32 v[42:43], v[42:43], v[214:215] op_sel_hi:[1,0]
	v_pk_mul_f32 v[40:41], v[40:41], v[214:215] op_sel_hi:[1,0]
	v_pk_mul_f32 v[38:39], v[38:39], v[214:215] op_sel_hi:[1,0]
	v_pk_mul_f32 v[36:37], v[36:37], v[214:215] op_sel_hi:[1,0]
	v_pk_mul_f32 v[34:35], v[34:35], v[214:215] op_sel_hi:[1,0]
	v_pk_mul_f32 v[32:33], v[32:33], v[214:215] op_sel_hi:[1,0]
	v_pk_mul_f32 v[30:31], v[30:31], v[214:215] op_sel_hi:[1,0]
	v_pk_mul_f32 v[28:29], v[28:29], v[214:215] op_sel_hi:[1,0]
	v_pk_mul_f32 v[26:27], v[26:27], v[214:215] op_sel_hi:[1,0]
	v_pk_mul_f32 v[24:25], v[24:25], v[214:215] op_sel_hi:[1,0]
	v_pk_mul_f32 v[22:23], v[22:23], v[214:215] op_sel_hi:[1,0]
	v_pk_mul_f32 v[20:21], v[20:21], v[214:215] op_sel_hi:[1,0]
	v_pk_mul_f32 v[18:19], v[18:19], v[214:215] op_sel_hi:[1,0]
	v_pk_mul_f32 v[16:17], v[16:17], v[214:215] op_sel_hi:[1,0]
	v_pk_mul_f32 v[14:15], v[14:15], v[214:215] op_sel_hi:[1,0]
	v_pk_mul_f32 v[12:13], v[12:13], v[214:215] op_sel_hi:[1,0]
	v_pk_mul_f32 v[10:11], v[10:11], v[214:215] op_sel_hi:[1,0]
	v_pk_mul_f32 v[8:9], v[8:9], v[214:215] op_sel_hi:[1,0]
	v_pk_mul_f32 v[6:7], v[6:7], v[214:215] op_sel_hi:[1,0]
	v_pk_mul_f32 v[4:5], v[4:5], v[214:215] op_sel_hi:[1,0]

.LBB0_378:
	v_max_f32_e32 v184, v117, v117
	v_max_f32_e32 v185, v116, v116
	v_max_f32_e32 v184, v185, v184
	v_max3_f32 v184, v184, v118, v119
	v_max3_f32 v184, v184, v120, v121
	v_max3_f32 v184, v184, v122, v123
	v_max3_f32 v184, v184, v124, v125
	v_max3_f32 v184, v184, v126, v127
	v_max3_f32 v184, v184, v128, v129
	v_max3_f32 v184, v184, v130, v131
	v_max3_f32 v184, v184, v100, v101
	v_max3_f32 v184, v184, v102, v103
	v_max3_f32 v184, v184, v104, v105
	v_max3_f32 v184, v184, v106, v107
	v_max3_f32 v184, v184, v108, v109
	v_max3_f32 v184, v184, v110, v111
	v_max3_f32 v184, v184, v112, v113
	v_max3_f32 v184, v184, v114, v115
	v_mov_b32_e32 v185, v184
	s_nop 1
	v_permlane32_swap_b32_e32 v184, v185
	v_max_f32_e32 v185, v185, v185
	v_max_f32_e32 v184, v184, v184
	v_max_f32_e32 v184, v184, v185
	v_sub_f32_e32 v185, v184, v236
	v_mul_f32_e32 v185, 0x3d93cd3a, v185
	v_cmp_ge_f32_e32 vcc, s35, v185
	s_cmp_eq_u64 vcc, exec
	s_cselect_b64 s[4:5], -1, 0
	s_andn2_b64 vcc, exec, s[6:7]
	s_barrier
	s_cbranch_vccnz .LBB0_380
	s_waitcnt vmcnt(0)
	ds_write_b128 v223, v[164:167] offset:16384
	ds_write_b128 v224, v[168:171] offset:16384
	ds_write_b128 v216, v[172:175] offset:49152
	ds_write_b128 v216, v[176:179] offset:57344
	v_add_u32_e32 v164, 0x12c00, v237
	ds_write_b128 v164, v[180:183]

;     __device__ __forceinline__ bool next(int i, Unit& u) const { if (i >= n) return false; u.pm = pm; u.pn = pn0 + i; return true; }
;     __device__ __forceinline__ bool next(int i, Unit& u) const { if (i) return false; u.pm = pm; u.pn = pn; return true; }
; #define PG8_STAGE(bufoff, gbase, voff) do { _Pragma("unroll") for (int _i = 0; _i < 2; ++_i) \
;         __builtin_amdgcn_global_load_lds((const unsigned*)((const char*)(gbase) + (voff)[_i]), (PG8_LAS unsigned*)(lds + (bufoff) + ldsw + _i * 8192), 16, 0, 0); } while (0)
; #define PG8_LDA(dst, b, h) do { _Pragma("unroll") for (int m = 0; m < 4; ++m) _Pragma("unroll") for (int k = 0; k < 2; ++k) dst[m][k] = *(const PG8_LAS bf16x8*)(lds + PG8_SA(b, h) + aoff + m * 2048 + k * 1024); } while (0)
; #define PG8_LDB(dst, b, h) do { _Pragma("unroll") for (int n = 0; n < 2; ++n) _Pragma("unroll") for (int k = 0; k < 2; ++k) dst[n][k] = *(const PG8_LAS bf16x8*)(lds + PG8_SB(b, h) + boff + n * 2048 + k * 1024); } while (0)
; #define PG8_WAIT_V(n) asm volatile("s_waitcnt vmcnt(" #n ")" ::: "memory")
; #define PG8_BAR __builtin_amdgcn_s_barrier()
;     ...
;         const bool has_next = S.next(ui + 1, nxt);
;         const char* nA = has_next ? (const char*)g.A + (size_t)nxt.pm * tstep : cA; const char* nB = has_next ? (const char*)g.Bt + (size_t)nxt.pn * tstep : cB;
;         for (int t = 0; t < nt; t += 2) {
;             const bool last = (t == nt - 2);
;             const char* a1 = cA + (size_t)(t + 1) * kstep;
;             const char* a2 = last ? nA : cA + (size_t)(t + 2) * kstep; const char* b2 = last ? nB : cB + (size_t)(t + 2) * kstep;
;             const char* a3 = a2 + kstep; const char* b3 = b2 + kstep;
;             if (last && has_next) S.a_ready(nxt);
;             if (t == 0) E.pre_issue(pre, cur, tid, ui); else if (t == 2) E.pre_finish(pre, tid, ui);
;             if constexpr (SP2) {
;             PG8_LDB(B0, 0, 0); PG8_LDB(B1, 0, 1); PG8_SCHED; PG8_LDA(At, 0, 0); PG8_STAGE(PG8_SA(1, 1), a1 + hstep, voffA);
;             PG8_WAIT_V(8); PG8_WAIT_L(0); PG8_BAR; PG8_MMA(0, 0, At, B0); PG8_MMA(0, 1, At, B1); PG8_BAR; PG8_SCHED;
;             PG8_LDA(At, 0, 1); PG8_STAGE(PG8_SB(0, 0), b2, voffB); PG8_STAGE(PG8_SB(0, 1), b2 + hstep, voffB); PG8_STAGE(PG8_SA(0, 0), a2, voffA);
;             PG8_WAIT_V(8); PG8_WAIT_L(0); PG8_BAR; PG8_MMA(1, 0, At, B0); PG8_MMA(1, 1, At, B1); PG8_BAR; PG8_SCHED;
.LBB0_454:
	s_add_u32 s48, s62, 0xfff80080
	s_addc_u32 s49, s63, -1
	s_add_i32 s82, 0, 0x10000
	s_cmp_eq_u32 s81, 28
	s_cselect_b32 s71, s25, s49
	s_cselect_b32 s70, s76, s48
	s_cselect_b32 s69, s15, s79
	s_cselect_b32 s68, s77, s78
	s_add_i32 s48, 0, 0x14000
	ds_read_b128 v[108:111], v251
	ds_read_b128 v[112:115], v251 offset:1024
	ds_read_b128 v[128:131], v251 offset:2048
	ds_read_b128 v[136:139], v251 offset:3072
	ds_read_b128 v[148:151], v251 offset:16384
	ds_read_b128 v[152:155], v251 offset:17408
	ds_read_b128 v[156:159], v251 offset:18432
	ds_read_b128 v[160:163], v251 offset:19456
	v_lshl_add_u64 v[198:199], s[62:63], 0, v[196:197]
	s_add_i32 m0, s20, 0xc000
	ds_read_b128 v[164:167], v234
	ds_read_b128 v[168:171], v234 offset:1024
	ds_read_b128 v[172:175], v234 offset:2048
	ds_read_b128 v[176:179], v234 offset:3072
	ds_read_b128 v[180:183], v234 offset:4096
	ds_read_b128 v[184:187], v234 offset:5120
	ds_read_b128 v[206:209], v234 offset:6144
	ds_read_b128 v[210:213], v234 offset:7168
	global_load_lds_dwordx4 v[198:199], off
	s_add_i32 m0, s20, 0xe000
	v_lshl_add_u64 v[198:199], s[62:63], 0, v[194:195]
	global_load_lds_dwordx4 v[198:199], off
	s_waitcnt vmcnt(8) lgkmcnt(0)
	s_setprio 1
	s_barrier
	v_mfma_f32_16x16x32_bf16 v[144:147], v[108:111], v[164:167], v[144:147]
	v_mfma_f32_16x16x32_bf16 v[140:143], v[128:131], v[164:167], v[140:143]
	v_mfma_f32_16x16x32_bf16 v[120:123], v[108:111], v[172:175], v[120:123]
	v_mfma_f32_16x16x32_bf16 v[116:119], v[128:131], v[172:175], v[116:119]
	v_mfma_f32_16x16x32_bf16 v[96:99], v[108:111], v[180:183], v[96:99]
	v_mfma_f32_16x16x32_bf16 v[92:95], v[128:131], v[180:183], v[92:95]
	v_mfma_f32_16x16x32_bf16 v[80:83], v[108:111], v[206:209], v[80:83]
	v_mfma_f32_16x16x32_bf16 v[76:79], v[128:131], v[206:209], v[76:79]
	v_mfma_f32_16x16x32_bf16 v[144:147], v[112:115], v[168:171], v[144:147]
	v_mfma_f32_16x16x32_bf16 v[140:143], v[136:139], v[168:171], v[140:143]
	v_mfma_f32_16x16x32_bf16 v[120:123], v[112:115], v[176:179], v[120:123]
	v_mfma_f32_16x16x32_bf16 v[116:119], v[136:139], v[176:179], v[116:119]
	v_mfma_f32_16x16x32_bf16 v[96:99], v[112:115], v[184:187], v[96:99]
	v_mfma_f32_16x16x32_bf16 v[92:95], v[136:139], v[184:187], v[92:95]
	v_mfma_f32_16x16x32_bf16 v[80:83], v[112:115], v[210:213], v[80:83]
	v_mfma_f32_16x16x32_bf16 v[76:79], v[136:139], v[210:213], v[76:79]
	v_mfma_f32_16x16x32_bf16 v[132:135], v[148:151], v[164:167], v[132:135]
	v_mfma_f32_16x16x32_bf16 v[124:127], v[156:159], v[164:167], v[124:127]
	v_mfma_f32_16x16x32_bf16 v[104:107], v[148:151], v[172:175], v[104:107]
	v_mfma_f32_16x16x32_bf16 v[100:103], v[156:159], v[172:175], v[100:103]
	v_mfma_f32_16x16x32_bf16 v[88:91], v[148:151], v[180:183], v[88:91]
	v_mfma_f32_16x16x32_bf16 v[84:87], v[156:159], v[180:183], v[84:87]
	v_mfma_f32_16x16x32_bf16 v[72:75], v[148:151], v[206:209], v[72:75]
	v_mfma_f32_16x16x32_bf16 v[68:71], v[156:159], v[206:209], v[68:71]
	v_mfma_f32_16x16x32_bf16 v[132:135], v[152:155], v[168:171], v[132:135]
	v_mfma_f32_16x16x32_bf16 v[124:127], v[160:163], v[168:171], v[124:127]
	v_mfma_f32_16x16x32_bf16 v[104:107], v[152:155], v[176:179], v[104:107]
	v_mfma_f32_16x16x32_bf16 v[100:103], v[160:163], v[176:179], v[100:103]
	v_mfma_f32_16x16x32_bf16 v[88:91], v[152:155], v[184:187], v[88:91]
	v_mfma_f32_16x16x32_bf16 v[84:87], v[160:163], v[184:187], v[84:87]
	v_mfma_f32_16x16x32_bf16 v[72:75], v[152:155], v[210:213], v[72:75]
	v_mfma_f32_16x16x32_bf16 v[68:71], v[160:163], v[210:213], v[68:71]
	s_barrier
	s_setprio 0
	s_add_i32 s49, s82, s5
	v_lshl_add_u64 v[198:199], s[68:69], 0, v[200:201]
	s_mov_b32 m0, s49
	ds_read_b128 v[164:167], v234 offset:16384
	ds_read_b128 v[168:171], v234 offset:17408
	ds_read_b128 v[172:175], v234 offset:18432
	ds_read_b128 v[176:179], v234 offset:19456
	ds_read_b128 v[180:183], v234 offset:20480
	ds_read_b128 v[184:187], v234 offset:21504
	ds_read_b128 v[206:209], v234 offset:22528
	ds_read_b128 v[210:213], v234 offset:23552
	global_load_lds_dwordx4 v[198:199], off
	s_add_i32 m0, s49, 0x2000
	s_add_u32 s82, s68, 0x80000
	v_lshl_add_u64 v[214:215], s[68:69], 0, v[188:189]
	s_addc_u32 s83, s69, 0
	s_add_i32 s48, s48, s5
	global_load_lds_dwordx4 v[214:215], off
	v_lshl_add_u64 v[216:217], s[82:83], 0, v[200:201]
	s_mov_b32 m0, s48
	v_lshl_add_u64 v[218:219], s[70:71], 0, v[190:191]
	global_load_lds_dwordx4 v[216:217], off
	s_add_i32 m0, s48, 0x2000
	v_lshl_add_u64 v[216:217], s[82:83], 0, v[188:189]
	global_load_lds_dwordx4 v[216:217], off
	s_mov_b32 m0, s20
	v_lshl_add_u64 v[216:217], s[70:71], 0, v[192:193]
	global_load_lds_dwordx4 v[216:217], off
	s_mov_b32 m0, s21
	s_nop 0
	global_load_lds_dwordx4 v[218:219], off
	s_waitcnt vmcnt(8) lgkmcnt(0)
	s_setprio 1
	s_barrier
; #define PG8_STAGE(bufoff, gbase, voff) do { _Pragma("unroll") for (int _i = 0; _i < 2; ++_i) \
;         __builtin_amdgcn_global_load_lds((const unsigned*)((const char*)(gbase) + (voff)[_i]), (PG8_LAS unsigned*)(lds + (bufoff) + ldsw + _i * 8192), 16, 0, 0); } while (0)
; #define PG8_LDA(dst, b, h) do { _Pragma("unroll") for (int m = 0; m < 4; ++m) _Pragma("unroll") for (int k = 0; k < 2; ++k) dst[m][k] = *(const PG8_LAS bf16x8*)(lds + PG8_SA(b, h) + aoff + m * 2048 + k * 1024); } while (0)
; #define PG8_LDB(dst, b, h) do { _Pragma("unroll") for (int n = 0; n < 2; ++n) _Pragma("unroll") for (int k = 0; k < 2; ++k) dst[n][k] = *(const PG8_LAS bf16x8*)(lds + PG8_SB(b, h) + boff + n * 2048 + k * 1024); } while (0)
; #define PG8_MMA(ai, bj, At, Bt) do { __builtin_amdgcn_s_setprio(1); _Pragma("unroll") for (int m = 0; m < 4; ++m) _Pragma("unroll") for (int n = 0; n < 2; ++n) _Pragma("unroll") for (int k = 0; k < 2; ++k) \
;         acc[ai][bj][m][n] = __builtin_amdgcn_mfma_f32_16x16x32_bf16(Bt[n][k], At[m][k], acc[ai][bj][m][n], 0, 0, 0); __builtin_amdgcn_s_setprio(0); } while (0)
; #define PG8_WAIT_V(n) asm volatile("s_waitcnt vmcnt(" #n ")" ::: "memory")
; #define PG8_WAIT_L(n) asm volatile("s_waitcnt lgkmcnt(" #n ")" ::: "memory")
; #define PG8_BAR __builtin_amdgcn_s_barrier()
; #define PG8_SCHED __builtin_amdgcn_sched_barrier(0)
;     ...
;             PG8_WAIT_V(8); PG8_WAIT_L(0); PG8_BAR; PG8_MMA(1, 0, At, B0); PG8_MMA(1, 1, At, B1); PG8_BAR; PG8_SCHED;
;             PG8_LDB(B0, 1, 0); PG8_LDB(B1, 1, 1); PG8_SCHED; PG8_LDA(At, 1, 0); PG8_STAGE(PG8_SA(0, 1), a2 + hstep, voffA);
;             PG8_WAIT_V(8); PG8_WAIT_L(0); PG8_BAR; PG8_MMA(0, 0, At, B0); PG8_MMA(0, 1, At, B1); PG8_BAR; PG8_SCHED;
	v_mfma_f32_16x16x32_bf16 v[64:67], v[108:111], v[164:167], v[64:67]
	v_mfma_f32_16x16x32_bf16 v[60:63], v[128:131], v[164:167], v[60:63]
	v_mfma_f32_16x16x32_bf16 v[48:51], v[108:111], v[172:175], v[48:51]
	v_mfma_f32_16x16x32_bf16 v[44:47], v[128:131], v[172:175], v[44:47]
	v_mfma_f32_16x16x32_bf16 v[32:35], v[108:111], v[180:183], v[32:35]
	v_mfma_f32_16x16x32_bf16 v[28:31], v[128:131], v[180:183], v[28:31]
	v_mfma_f32_16x16x32_bf16 v[16:19], v[108:111], v[206:209], v[16:19]
	v_mfma_f32_16x16x32_bf16 v[12:15], v[128:131], v[206:209], v[12:15]
	v_mfma_f32_16x16x32_bf16 v[64:67], v[112:115], v[168:171], v[64:67]
	v_mfma_f32_16x16x32_bf16 v[60:63], v[136:139], v[168:171], v[60:63]
	v_mfma_f32_16x16x32_bf16 v[48:51], v[112:115], v[176:179], v[48:51]
	v_mfma_f32_16x16x32_bf16 v[44:47], v[136:139], v[176:179], v[44:47]
	v_mfma_f32_16x16x32_bf16 v[32:35], v[112:115], v[184:187], v[32:35]
	v_mfma_f32_16x16x32_bf16 v[28:31], v[136:139], v[184:187], v[28:31]
	v_mfma_f32_16x16x32_bf16 v[16:19], v[112:115], v[210:213], v[16:19]
	v_mfma_f32_16x16x32_bf16 v[12:15], v[136:139], v[210:213], v[12:15]
	v_mfma_f32_16x16x32_bf16 v[56:59], v[148:151], v[164:167], v[56:59]
	v_mfma_f32_16x16x32_bf16 v[52:55], v[156:159], v[164:167], v[52:55]
	v_mfma_f32_16x16x32_bf16 v[40:43], v[148:151], v[172:175], v[40:43]
	v_mfma_f32_16x16x32_bf16 v[36:39], v[156:159], v[172:175], v[36:39]
	v_mfma_f32_16x16x32_bf16 v[24:27], v[148:151], v[180:183], v[24:27]
	v_mfma_f32_16x16x32_bf16 v[20:23], v[156:159], v[180:183], v[20:23]
	v_mfma_f32_16x16x32_bf16 v[8:11], v[148:151], v[206:209], v[8:11]
	v_mfma_f32_16x16x32_bf16 v[4:7], v[156:159], v[206:209], v[4:7]
	v_mfma_f32_16x16x32_bf16 v[56:59], v[152:155], v[168:171], v[56:59]
	v_mfma_f32_16x16x32_bf16 v[52:55], v[160:163], v[168:171], v[52:55]
	v_mfma_f32_16x16x32_bf16 v[40:43], v[152:155], v[176:179], v[40:43]
	v_mfma_f32_16x16x32_bf16 v[36:39], v[160:163], v[176:179], v[36:39]
	v_mfma_f32_16x16x32_bf16 v[24:27], v[152:155], v[184:187], v[24:27]
	v_mfma_f32_16x16x32_bf16 v[20:23], v[160:163], v[184:187], v[20:23]
	v_mfma_f32_16x16x32_bf16 v[8:11], v[152:155], v[210:213], v[8:11]
	v_mfma_f32_16x16x32_bf16 v[4:7], v[160:163], v[210:213], v[4:7]
	s_barrier
	s_setprio 0
	s_add_i32 s48, 0, 0x18000
	s_add_i32 s49, 0, 0x1c000
	ds_read_b128 v[108:111], v251 offset:32768
	ds_read_b128 v[112:115], v251 offset:33792
	ds_read_b128 v[128:131], v251 offset:34816
	ds_read_b128 v[136:139], v251 offset:35840
	ds_read_b128 v[148:151], v251 offset:49152
	ds_read_b128 v[152:155], v251 offset:50176
	ds_read_b128 v[156:159], v251 offset:51200
	ds_read_b128 v[160:163], v251 offset:52224
	s_add_u32 s70, s70, 0x80000
	s_addc_u32 s71, s71, 0
	s_mov_b32 m0, s23
	v_lshl_add_u64 v[220:221], s[70:71], 0, v[192:193]
	ds_read_b128 v[164:167], v234 offset:32768
	ds_read_b128 v[168:171], v234 offset:33792
	ds_read_b128 v[172:175], v234 offset:34816
	ds_read_b128 v[176:179], v234 offset:35840
	ds_read_b128 v[180:183], v234 offset:36864
	ds_read_b128 v[184:187], v234 offset:37888
	ds_read_b128 v[206:209], v234 offset:38912
	ds_read_b128 v[210:213], v234 offset:39936
	global_load_lds_dwordx4 v[220:221], off
	s_mov_b32 m0, s42
	v_lshl_add_u64 v[220:221], s[70:71], 0, v[190:191]
	global_load_lds_dwordx4 v[220:221], off
	s_waitcnt vmcnt(8) lgkmcnt(0)
	s_setprio 1
	s_barrier
	v_mfma_f32_16x16x32_bf16 v[144:147], v[108:111], v[164:167], v[144:147]
	v_mfma_f32_16x16x32_bf16 v[140:143], v[128:131], v[164:167], v[140:143]
	v_mfma_f32_16x16x32_bf16 v[120:123], v[108:111], v[172:175], v[120:123]
	v_mfma_f32_16x16x32_bf16 v[116:119], v[128:131], v[172:175], v[116:119]
	v_mfma_f32_16x16x32_bf16 v[96:99], v[108:111], v[180:183], v[96:99]
	v_mfma_f32_16x16x32_bf16 v[92:95], v[128:131], v[180:183], v[92:95]
	v_mfma_f32_16x16x32_bf16 v[80:83], v[108:111], v[206:209], v[80:83]
	v_mfma_f32_16x16x32_bf16 v[76:79], v[128:131], v[206:209], v[76:79]
	v_mfma_f32_16x16x32_bf16 v[144:147], v[112:115], v[168:171], v[144:147]
	v_mfma_f32_16x16x32_bf16 v[140:143], v[136:139], v[168:171], v[140:143]
	v_mfma_f32_16x16x32_bf16 v[120:123], v[112:115], v[176:179], v[120:123]
	v_mfma_f32_16x16x32_bf16 v[116:119], v[136:139], v[176:179], v[116:119]
	v_mfma_f32_16x16x32_bf16 v[96:99], v[112:115], v[184:187], v[96:99]
	v_mfma_f32_16x16x32_bf16 v[92:95], v[136:139], v[184:187], v[92:95]
	v_mfma_f32_16x16x32_bf16 v[80:83], v[112:115], v[210:213], v[80:83]
	v_mfma_f32_16x16x32_bf16 v[76:79], v[136:139], v[210:213], v[76:79]
	v_mfma_f32_16x16x32_bf16 v[132:135], v[148:151], v[164:167], v[132:135]
	v_mfma_f32_16x16x32_bf16 v[124:127], v[156:159], v[164:167], v[124:127]
	v_mfma_f32_16x16x32_bf16 v[104:107], v[148:151], v[172:175], v[104:107]
	v_mfma_f32_16x16x32_bf16 v[100:103], v[156:159], v[172:175], v[100:103]
	v_mfma_f32_16x16x32_bf16 v[88:91], v[148:151], v[180:183], v[88:91]
	v_mfma_f32_16x16x32_bf16 v[84:87], v[156:159], v[180:183], v[84:87]
	v_mfma_f32_16x16x32_bf16 v[72:75], v[148:151], v[206:209], v[72:75]
	v_mfma_f32_16x16x32_bf16 v[68:71], v[156:159], v[206:209], v[68:71]
	v_mfma_f32_16x16x32_bf16 v[132:135], v[152:155], v[168:171], v[132:135]
	v_mfma_f32_16x16x32_bf16 v[124:127], v[160:163], v[168:171], v[124:127]
	v_mfma_f32_16x16x32_bf16 v[104:107], v[152:155], v[176:179], v[104:107]
	v_mfma_f32_16x16x32_bf16 v[100:103], v[160:163], v[176:179], v[100:103]
	v_mfma_f32_16x16x32_bf16 v[88:91], v[152:155], v[184:187], v[88:91]
	v_mfma_f32_16x16x32_bf16 v[84:87], v[160:163], v[184:187], v[84:87]
	v_mfma_f32_16x16x32_bf16 v[72:75], v[152:155], v[210:213], v[72:75]
	v_mfma_f32_16x16x32_bf16 v[68:71], v[160:163], v[210:213], v[68:71]
	s_barrier
; #define PG8_STAGE(bufoff, gbase, voff) do { _Pragma("unroll") for (int _i = 0; _i < 2; ++_i) \
;         __builtin_amdgcn_global_load_lds((const unsigned*)((const char*)(gbase) + (voff)[_i]), (PG8_LAS unsigned*)(lds + (bufoff) + ldsw + _i * 8192), 16, 0, 0); } while (0)
; #define PG8_LDA(dst, b, h) do { _Pragma("unroll") for (int m = 0; m < 4; ++m) _Pragma("unroll") for (int k = 0; k < 2; ++k) dst[m][k] = *(const PG8_LAS bf16x8*)(lds + PG8_SA(b, h) + aoff + m * 2048 + k * 1024); } while (0)
; #define PG8_MMA(ai, bj, At, Bt) do { __builtin_amdgcn_s_setprio(1); _Pragma("unroll") for (int m = 0; m < 4; ++m) _Pragma("unroll") for (int n = 0; n < 2; ++n) _Pragma("unroll") for (int k = 0; k < 2; ++k) \
;         acc[ai][bj][m][n] = __builtin_amdgcn_mfma_f32_16x16x32_bf16(Bt[n][k], At[m][k], acc[ai][bj][m][n], 0, 0, 0); __builtin_amdgcn_s_setprio(0); } while (0)
; #define PG8_WAIT_V(n) asm volatile("s_waitcnt vmcnt(" #n ")" ::: "memory")
; #define PG8_WAIT_L(n) asm volatile("s_waitcnt lgkmcnt(" #n ")" ::: "memory")
; #define PG8_BAR __builtin_amdgcn_s_barrier()
; #define PG8_SCHED __builtin_amdgcn_sched_barrier(0)
;     ...
;             PG8_LDA(At, 1, 1); PG8_STAGE(PG8_SB(1, 0), b3, voffB); PG8_STAGE(PG8_SB(1, 1), b3 + hstep, voffB); PG8_STAGE(PG8_SA(1, 0), a3, voffA);
;             PG8_WAIT_V(8); PG8_WAIT_L(0); PG8_BAR; PG8_MMA(1, 0, At, B0); PG8_MMA(1, 1, At, B1); PG8_BAR; PG8_SCHED;
	s_setprio 0
	s_add_i32 s48, s48, s5
	v_lshl_add_u64 v[198:199], v[198:199], 0, s[66:67]
	s_mov_b32 m0, s48
	ds_read_b128 v[164:167], v234 offset:49152
	ds_read_b128 v[168:171], v234 offset:50176
	ds_read_b128 v[172:175], v234 offset:51200
	ds_read_b128 v[176:179], v234 offset:52224
	ds_read_b128 v[180:183], v234 offset:53248
	ds_read_b128 v[184:187], v234 offset:54272
	ds_read_b128 v[206:209], v234 offset:55296
	ds_read_b128 v[210:213], v234 offset:56320
	global_load_lds_dwordx4 v[198:199], off
	s_add_i32 m0, s48, 0x2000
	s_add_u32 s68, s68, 0x80080
	v_lshl_add_u64 v[198:199], v[214:215], 0, s[66:67]
	s_addc_u32 s69, s69, 0
	s_add_i32 s48, s49, s5
	global_load_lds_dwordx4 v[198:199], off
	s_mov_b32 m0, s48
	v_lshl_add_u64 v[198:199], s[68:69], 0, v[200:201]
	global_load_lds_dwordx4 v[198:199], off
	s_add_i32 m0, s48, 0x2000
	v_lshl_add_u64 v[198:199], s[68:69], 0, v[188:189]
	global_load_lds_dwordx4 v[198:199], off
	v_lshl_add_u64 v[198:199], v[216:217], 0, s[66:67]
	s_mov_b32 m0, s55
	s_nop 0
	global_load_lds_dwordx4 v[198:199], off
	v_lshl_add_u64 v[198:199], v[218:219], 0, s[66:67]
	s_mov_b32 m0, s56
	s_nop 0
	global_load_lds_dwordx4 v[198:199], off
	s_waitcnt vmcnt(8) lgkmcnt(0)
	s_setprio 1
	s_barrier
	v_mfma_f32_16x16x32_bf16 v[64:67], v[108:111], v[164:167], v[64:67]
	v_mfma_f32_16x16x32_bf16 v[60:63], v[128:131], v[164:167], v[60:63]
	v_mfma_f32_16x16x32_bf16 v[48:51], v[108:111], v[172:175], v[48:51]
	v_mfma_f32_16x16x32_bf16 v[44:47], v[128:131], v[172:175], v[44:47]
	v_mfma_f32_16x16x32_bf16 v[32:35], v[108:111], v[180:183], v[32:35]
	v_mfma_f32_16x16x32_bf16 v[28:31], v[128:131], v[180:183], v[28:31]
	v_mfma_f32_16x16x32_bf16 v[16:19], v[108:111], v[206:209], v[16:19]
	v_mfma_f32_16x16x32_bf16 v[12:15], v[128:131], v[206:209], v[12:15]
	v_mfma_f32_16x16x32_bf16 v[64:67], v[112:115], v[168:171], v[64:67]
	v_mfma_f32_16x16x32_bf16 v[60:63], v[136:139], v[168:171], v[60:63]
	v_mfma_f32_16x16x32_bf16 v[48:51], v[112:115], v[176:179], v[48:51]
	v_mfma_f32_16x16x32_bf16 v[44:47], v[136:139], v[176:179], v[44:47]
	v_mfma_f32_16x16x32_bf16 v[32:35], v[112:115], v[184:187], v[32:35]
	v_mfma_f32_16x16x32_bf16 v[28:31], v[136:139], v[184:187], v[28:31]
	v_mfma_f32_16x16x32_bf16 v[16:19], v[112:115], v[210:213], v[16:19]
	v_mfma_f32_16x16x32_bf16 v[12:15], v[136:139], v[210:213], v[12:15]
	v_mfma_f32_16x16x32_bf16 v[56:59], v[148:151], v[164:167], v[56:59]
	v_mfma_f32_16x16x32_bf16 v[52:55], v[156:159], v[164:167], v[52:55]
	v_mfma_f32_16x16x32_bf16 v[40:43], v[148:151], v[172:175], v[40:43]
	v_mfma_f32_16x16x32_bf16 v[36:39], v[156:159], v[172:175], v[36:39]
	v_mfma_f32_16x16x32_bf16 v[24:27], v[148:151], v[180:183], v[24:27]
	v_mfma_f32_16x16x32_bf16 v[20:23], v[156:159], v[180:183], v[20:23]
	v_mfma_f32_16x16x32_bf16 v[8:11], v[148:151], v[206:209], v[8:11]
	v_mfma_f32_16x16x32_bf16 v[4:7], v[156:159], v[206:209], v[4:7]
	v_mfma_f32_16x16x32_bf16 v[56:59], v[152:155], v[168:171], v[56:59]
	v_mfma_f32_16x16x32_bf16 v[52:55], v[160:163], v[168:171], v[52:55]
	v_mfma_f32_16x16x32_bf16 v[40:43], v[152:155], v[176:179], v[40:43]
	v_mfma_f32_16x16x32_bf16 v[36:39], v[160:163], v[176:179], v[36:39]
	v_mfma_f32_16x16x32_bf16 v[24:27], v[152:155], v[184:187], v[24:27]
	v_mfma_f32_16x16x32_bf16 v[20:23], v[160:163], v[184:187], v[20:23]
	v_mfma_f32_16x16x32_bf16 v[8:11], v[152:155], v[210:213], v[8:11]
	v_mfma_f32_16x16x32_bf16 v[4:7], v[160:163], v[210:213], v[4:7]
	s_barrier
	s_setprio 0
	s_add_i32 s81, s81, 2
	s_add_u32 s78, s78, 0x100
	s_addc_u32 s79, s79, 0
	s_add_u32 s62, s62, 0x100
	s_addc_u32 s63, s63, 0
	s_cmp_gt_u32 s81, 29
	s_cbranch_scc0 .LBB0_454
	s_and_b64 vcc, exec, s[12:13]
	s_cbranch_vccz .LBB0_457
	s_barrier

;     __device__ __forceinline__ bool next(int i, Unit& u) const { if (i >= n) return false; u.pm = pm; u.pn = pn0 + i; return true; }
;     __device__ __forceinline__ bool next(int i, Unit& u) const { if (i) return false; u.pm = pm; u.pn = pn; return true; }
; #define PG8_STAGE(bufoff, gbase, voff) do { _Pragma("unroll") for (int _i = 0; _i < 2; ++_i) \
;         __builtin_amdgcn_global_load_lds((const unsigned*)((const char*)(gbase) + (voff)[_i]), (PG8_LAS unsigned*)(lds + (bufoff) + ldsw + _i * 8192), 16, 0, 0); } while (0)
; #define PG8_LDA(dst, b, h) do { _Pragma("unroll") for (int m = 0; m < 4; ++m) _Pragma("unroll") for (int k = 0; k < 2; ++k) dst[m][k] = *(const PG8_LAS bf16x8*)(lds + PG8_SA(b, h) + aoff + m * 2048 + k * 1024); } while (0)
; #define PG8_LDB(dst, b, h) do { _Pragma("unroll") for (int n = 0; n < 2; ++n) _Pragma("unroll") for (int k = 0; k < 2; ++k) dst[n][k] = *(const PG8_LAS bf16x8*)(lds + PG8_SB(b, h) + boff + n * 2048 + k * 1024); } while (0)
; #define PG8_WAIT_V(n) asm volatile("s_waitcnt vmcnt(" #n ")" ::: "memory")
; #define PG8_BAR __builtin_amdgcn_s_barrier()
;     ...
;         const bool has_next = S.next(ui + 1, nxt);
;         const char* nA = has_next ? (const char*)g.A + (size_t)nxt.pm * tstep : cA; const char* nB = has_next ? (const char*)g.Bt + (size_t)nxt.pn * tstep : cB;
;         for (int t = 0; t < nt; t += 2) {
;             const bool last = (t == nt - 2);
;             const char* a1 = cA + (size_t)(t + 1) * kstep;
;             const char* a2 = last ? nA : cA + (size_t)(t + 2) * kstep; const char* b2 = last ? nB : cB + (size_t)(t + 2) * kstep;
;             const char* a3 = a2 + kstep; const char* b3 = b2 + kstep;
;             if (last && has_next) S.a_ready(nxt);
;             if (t == 0) E.pre_issue(pre, cur, tid, ui); else if (t == 2) E.pre_finish(pre, tid, ui);
;             if constexpr (SP2) {
;             PG8_LDB(B0, 0, 0); PG8_LDB(B1, 0, 1); PG8_SCHED; PG8_LDA(At, 0, 0); PG8_STAGE(PG8_SA(1, 1), a1 + hstep, voffA);
;             PG8_WAIT_V(8); PG8_WAIT_L(0); PG8_BAR; PG8_MMA(0, 0, At, B0); PG8_MMA(0, 1, At, B1); PG8_BAR; PG8_SCHED;
;             PG8_LDA(At, 0, 1); PG8_STAGE(PG8_SB(0, 0), b2, voffB); PG8_STAGE(PG8_SB(0, 1), b2 + hstep, voffB); PG8_STAGE(PG8_SA(0, 0), a2, voffA);
;             PG8_WAIT_V(8); PG8_WAIT_L(0); PG8_BAR; PG8_MMA(1, 0, At, B0); PG8_MMA(1, 1, At, B1); PG8_BAR; PG8_SCHED;
.LBB0_542:
	s_add_u32 s12, s10, 0xfff80080
	s_addc_u32 s13, s11, -1
	s_add_i32 s48, 0, 0x10000
	s_cmp_eq_u32 s89, 28
	s_cselect_b32 s15, s25, s13
	s_cselect_b32 s14, s69, s12
	s_cselect_b32 s13, s76, s83
	s_cselect_b32 s12, s77, s82
	s_add_i32 s49, 0, 0x14000
	ds_read_b128 v[106:109], v251
	ds_read_b128 v[110:113], v251 offset:1024
	ds_read_b128 v[114:117], v251 offset:2048
	ds_read_b128 v[118:121], v251 offset:3072
	ds_read_b128 v[122:125], v251 offset:16384
	ds_read_b128 v[126:129], v251 offset:17408
	ds_read_b128 v[130:133], v251 offset:18432
	ds_read_b128 v[134:137], v251 offset:19456
	v_lshl_add_u64 v[100:101], s[10:11], 0, v[190:191]
	s_add_i32 m0, s1, 0xc000
	ds_read_b128 v[166:169], v222
	ds_read_b128 v[170:173], v222 offset:1024
	ds_read_b128 v[174:177], v222 offset:2048
	ds_read_b128 v[178:181], v222 offset:3072
	ds_read_b128 v[194:197], v222 offset:4096
	ds_read_b128 v[206:209], v222 offset:5120
	ds_read_b128 v[210:213], v222 offset:6144
	ds_read_b128 v[214:217], v222 offset:7168
	global_load_lds_dwordx4 v[100:101], off
	s_add_i32 m0, s1, 0xe000
	v_lshl_add_u64 v[100:101], s[10:11], 0, v[192:193]
	global_load_lds_dwordx4 v[100:101], off
	s_waitcnt vmcnt(8) lgkmcnt(0)
	s_setprio 1
	s_barrier
	v_mfma_f32_16x16x32_bf16 v[4:7], v[106:109], v[166:169], v[4:7]
	v_mfma_f32_16x16x32_bf16 v[72:75], v[114:117], v[166:169], v[72:75]
	v_mfma_f32_16x16x32_bf16 v[162:165], v[106:109], v[174:177], v[162:165]
	v_mfma_f32_16x16x32_bf16 v[60:63], v[114:117], v[174:177], v[60:63]
	v_mfma_f32_16x16x32_bf16 v[158:161], v[106:109], v[194:197], v[158:161]
	v_mfma_f32_16x16x32_bf16 v[56:59], v[114:117], v[194:197], v[56:59]
	v_mfma_f32_16x16x32_bf16 v[96:99], v[106:109], v[210:213], v[96:99]
	v_mfma_f32_16x16x32_bf16 v[76:79], v[114:117], v[210:213], v[76:79]
	v_mfma_f32_16x16x32_bf16 v[4:7], v[110:113], v[170:173], v[4:7]
	v_mfma_f32_16x16x32_bf16 v[72:75], v[118:121], v[170:173], v[72:75]
	v_mfma_f32_16x16x32_bf16 v[162:165], v[110:113], v[178:181], v[162:165]
	v_mfma_f32_16x16x32_bf16 v[60:63], v[118:121], v[178:181], v[60:63]
	v_mfma_f32_16x16x32_bf16 v[158:161], v[110:113], v[206:209], v[158:161]
	v_mfma_f32_16x16x32_bf16 v[56:59], v[118:121], v[206:209], v[56:59]
	v_mfma_f32_16x16x32_bf16 v[96:99], v[110:113], v[214:217], v[96:99]
	v_mfma_f32_16x16x32_bf16 v[76:79], v[118:121], v[214:217], v[76:79]
	v_mfma_f32_16x16x32_bf16 v[8:11], v[122:125], v[166:169], v[8:11]
	v_mfma_f32_16x16x32_bf16 v[64:67], v[130:133], v[166:169], v[64:67]
	v_mfma_f32_16x16x32_bf16 v[154:157], v[122:125], v[174:177], v[154:157]
	v_mfma_f32_16x16x32_bf16 v[52:55], v[130:133], v[174:177], v[52:55]
	v_mfma_f32_16x16x32_bf16 v[150:153], v[122:125], v[194:197], v[150:153]
	v_mfma_f32_16x16x32_bf16 v[48:51], v[130:133], v[194:197], v[48:51]
	v_mfma_f32_16x16x32_bf16 v[92:95], v[122:125], v[210:213], v[92:95]
	v_mfma_f32_16x16x32_bf16 v[68:71], v[130:133], v[210:213], v[68:71]
	v_mfma_f32_16x16x32_bf16 v[8:11], v[126:129], v[170:173], v[8:11]
	v_mfma_f32_16x16x32_bf16 v[64:67], v[134:137], v[170:173], v[64:67]
	v_mfma_f32_16x16x32_bf16 v[154:157], v[126:129], v[178:181], v[154:157]
	v_mfma_f32_16x16x32_bf16 v[52:55], v[134:137], v[178:181], v[52:55]
	v_mfma_f32_16x16x32_bf16 v[150:153], v[126:129], v[206:209], v[150:153]
	v_mfma_f32_16x16x32_bf16 v[48:51], v[134:137], v[206:209], v[48:51]
	v_mfma_f32_16x16x32_bf16 v[92:95], v[126:129], v[214:217], v[92:95]
	v_mfma_f32_16x16x32_bf16 v[68:71], v[134:137], v[214:217], v[68:71]
	s_barrier
	s_setprio 0
	s_add_i32 s48, s48, s0
	v_lshl_add_u64 v[198:199], s[12:13], 0, v[186:187]
	s_mov_b32 m0, s48
	ds_read_b128 v[166:169], v222 offset:16384
	ds_read_b128 v[170:173], v222 offset:17408
	ds_read_b128 v[174:177], v222 offset:18432
	ds_read_b128 v[178:181], v222 offset:19456
	ds_read_b128 v[194:197], v222 offset:20480
	ds_read_b128 v[206:209], v222 offset:21504
	ds_read_b128 v[210:213], v222 offset:22528
	ds_read_b128 v[214:217], v222 offset:23552
	global_load_lds_dwordx4 v[198:199], off
	s_add_i32 m0, s48, 0x2000
	s_add_u32 vcc_lo, s12, 0x80000
	v_lshl_add_u64 v[218:219], s[12:13], 0, v[182:183]
	s_addc_u32 vcc_hi, s13, 0
	s_add_i32 s48, s49, s0
	global_load_lds_dwordx4 v[218:219], off
	v_lshl_add_u64 v[100:101], vcc, 0, v[186:187]
	s_mov_b32 m0, s48
	v_lshl_add_u64 v[224:225], s[14:15], 0, v[188:189]
	global_load_lds_dwordx4 v[100:101], off
	v_lshl_add_u64 v[100:101], vcc, 0, v[182:183]
	s_add_i32 m0, s48, 0x2000
	v_lshl_add_u64 v[232:233], s[14:15], 0, v[184:185]
	global_load_lds_dwordx4 v[100:101], off
	s_mov_b32 m0, s1
	s_nop 0
	global_load_lds_dwordx4 v[224:225], off
	s_mov_b32 m0, s4
	s_nop 0
	global_load_lds_dwordx4 v[232:233], off
	s_waitcnt vmcnt(8) lgkmcnt(0)
	s_setprio 1
	s_barrier
; #define PG8_STAGE(bufoff, gbase, voff) do { _Pragma("unroll") for (int _i = 0; _i < 2; ++_i) \
;         __builtin_amdgcn_global_load_lds((const unsigned*)((const char*)(gbase) + (voff)[_i]), (PG8_LAS unsigned*)(lds + (bufoff) + ldsw + _i * 8192), 16, 0, 0); } while (0)
; #define PG8_LDA(dst, b, h) do { _Pragma("unroll") for (int m = 0; m < 4; ++m) _Pragma("unroll") for (int k = 0; k < 2; ++k) dst[m][k] = *(const PG8_LAS bf16x8*)(lds + PG8_SA(b, h) + aoff + m * 2048 + k * 1024); } while (0)
; #define PG8_LDB(dst, b, h) do { _Pragma("unroll") for (int n = 0; n < 2; ++n) _Pragma("unroll") for (int k = 0; k < 2; ++k) dst[n][k] = *(const PG8_LAS bf16x8*)(lds + PG8_SB(b, h) + boff + n * 2048 + k * 1024); } while (0)
; #define PG8_MMA(ai, bj, At, Bt) do { __builtin_amdgcn_s_setprio(1); _Pragma("unroll") for (int m = 0; m < 4; ++m) _Pragma("unroll") for (int n = 0; n < 2; ++n) _Pragma("unroll") for (int k = 0; k < 2; ++k) \
;         acc[ai][bj][m][n] = __builtin_amdgcn_mfma_f32_16x16x32_bf16(Bt[n][k], At[m][k], acc[ai][bj][m][n], 0, 0, 0); __builtin_amdgcn_s_setprio(0); } while (0)
; #define PG8_WAIT_V(n) asm volatile("s_waitcnt vmcnt(" #n ")" ::: "memory")
; #define PG8_WAIT_L(n) asm volatile("s_waitcnt lgkmcnt(" #n ")" ::: "memory")
; #define PG8_BAR __builtin_amdgcn_s_barrier()
; #define PG8_SCHED __builtin_amdgcn_sched_barrier(0)
;     ...
;             PG8_WAIT_V(8); PG8_WAIT_L(0); PG8_BAR; PG8_MMA(1, 0, At, B0); PG8_MMA(1, 1, At, B1); PG8_BAR; PG8_SCHED;
;             PG8_LDB(B0, 1, 0); PG8_LDB(B1, 1, 1); PG8_SCHED; PG8_LDA(At, 1, 0); PG8_STAGE(PG8_SA(0, 1), a2 + hstep, voffA);
;             PG8_WAIT_V(8); PG8_WAIT_L(0); PG8_BAR; PG8_MMA(0, 0, At, B0); PG8_MMA(0, 1, At, B1); PG8_BAR; PG8_SCHED;
	v_mfma_f32_16x16x32_bf16 v[146:149], v[106:109], v[166:169], v[146:149]
	v_mfma_f32_16x16x32_bf16 v[44:47], v[114:117], v[166:169], v[44:47]
	v_mfma_f32_16x16x32_bf16 v[142:145], v[106:109], v[174:177], v[142:145]
	v_mfma_f32_16x16x32_bf16 v[40:43], v[114:117], v[174:177], v[40:43]
	v_mfma_f32_16x16x32_bf16 v[138:141], v[106:109], v[194:197], v[138:141]
	v_mfma_f32_16x16x32_bf16 v[36:39], v[114:117], v[194:197], v[36:39]
	v_mfma_f32_16x16x32_bf16 v[80:83], v[106:109], v[210:213], v[80:83]
	v_mfma_f32_16x16x32_bf16 v[20:23], v[114:117], v[210:213], v[20:23]
	v_mfma_f32_16x16x32_bf16 v[146:149], v[110:113], v[170:173], v[146:149]
	v_mfma_f32_16x16x32_bf16 v[44:47], v[118:121], v[170:173], v[44:47]
	v_mfma_f32_16x16x32_bf16 v[142:145], v[110:113], v[178:181], v[142:145]
	v_mfma_f32_16x16x32_bf16 v[40:43], v[118:121], v[178:181], v[40:43]
	v_mfma_f32_16x16x32_bf16 v[138:141], v[110:113], v[206:209], v[138:141]
	v_mfma_f32_16x16x32_bf16 v[36:39], v[118:121], v[206:209], v[36:39]
	v_mfma_f32_16x16x32_bf16 v[80:83], v[110:113], v[214:217], v[80:83]
	v_mfma_f32_16x16x32_bf16 v[20:23], v[118:121], v[214:217], v[20:23]
	v_mfma_f32_16x16x32_bf16 v[100:103], v[122:125], v[166:169], v[102:105]
	v_mfma_f32_16x16x32_bf16 v[32:35], v[130:133], v[166:169], v[32:35]
	v_mfma_f32_16x16x32_bf16 v[88:91], v[122:125], v[174:177], v[88:91]
	v_mfma_f32_16x16x32_bf16 v[28:31], v[130:133], v[174:177], v[28:31]
	v_mfma_f32_16x16x32_bf16 v[84:87], v[122:125], v[194:197], v[84:87]
	v_mfma_f32_16x16x32_bf16 v[24:27], v[130:133], v[194:197], v[24:27]
	v_mfma_f32_16x16x32_bf16 v[16:19], v[122:125], v[210:213], v[16:19]
	v_mfma_f32_16x16x32_bf16 v[12:15], v[130:133], v[210:213], v[12:15]
	v_mfma_f32_16x16x32_bf16 v[100:103], v[126:129], v[170:173], v[100:103]
	v_mfma_f32_16x16x32_bf16 v[32:35], v[134:137], v[170:173], v[32:35]
	v_mfma_f32_16x16x32_bf16 v[88:91], v[126:129], v[178:181], v[88:91]
	v_mfma_f32_16x16x32_bf16 v[28:31], v[134:137], v[178:181], v[28:31]
	v_mfma_f32_16x16x32_bf16 v[84:87], v[126:129], v[206:209], v[84:87]
	v_mfma_f32_16x16x32_bf16 v[24:27], v[134:137], v[206:209], v[24:27]
	v_mfma_f32_16x16x32_bf16 v[16:19], v[126:129], v[214:217], v[16:19]
	v_mfma_f32_16x16x32_bf16 v[12:15], v[134:137], v[214:217], v[12:15]
	s_barrier
	s_setprio 0
	s_add_i32 s48, 0, 0x18000
	s_add_i32 s49, 0, 0x1c000
	ds_read_b128 v[104:107], v251 offset:32768
	ds_read_b128 v[108:111], v251 offset:33792
	ds_read_b128 v[112:115], v251 offset:34816
	ds_read_b128 v[116:119], v251 offset:35840
	ds_read_b128 v[120:123], v251 offset:49152
	ds_read_b128 v[124:127], v251 offset:50176
	ds_read_b128 v[128:131], v251 offset:51200
	ds_read_b128 v[132:135], v251 offset:52224
	s_add_u32 s14, s14, 0x80000
	s_addc_u32 s15, s15, 0
	s_mov_b32 m0, s5
	v_lshl_add_u64 v[136:137], s[14:15], 0, v[188:189]
	ds_read_b128 v[166:169], v222 offset:32768
	ds_read_b128 v[170:173], v222 offset:33792
	ds_read_b128 v[174:177], v222 offset:34816
	ds_read_b128 v[178:181], v222 offset:35840
	ds_read_b128 v[194:197], v222 offset:36864
	ds_read_b128 v[206:209], v222 offset:37888
	ds_read_b128 v[210:213], v222 offset:38912
	ds_read_b128 v[214:217], v222 offset:39936
	global_load_lds_dwordx4 v[136:137], off
	s_mov_b32 m0, s44
	v_lshl_add_u64 v[136:137], s[14:15], 0, v[184:185]
	global_load_lds_dwordx4 v[136:137], off
	s_waitcnt vmcnt(8) lgkmcnt(0)
	s_setprio 1
	s_barrier
	v_mfma_f32_16x16x32_bf16 v[4:7], v[104:107], v[166:169], v[4:7]
	v_mfma_f32_16x16x32_bf16 v[72:75], v[112:115], v[166:169], v[72:75]
	v_mfma_f32_16x16x32_bf16 v[162:165], v[104:107], v[174:177], v[162:165]
	v_mfma_f32_16x16x32_bf16 v[60:63], v[112:115], v[174:177], v[60:63]
	v_mfma_f32_16x16x32_bf16 v[158:161], v[104:107], v[194:197], v[158:161]
	v_mfma_f32_16x16x32_bf16 v[56:59], v[112:115], v[194:197], v[56:59]
	v_mfma_f32_16x16x32_bf16 v[96:99], v[104:107], v[210:213], v[96:99]
	v_mfma_f32_16x16x32_bf16 v[76:79], v[112:115], v[210:213], v[76:79]
	v_mfma_f32_16x16x32_bf16 v[4:7], v[108:111], v[170:173], v[4:7]
	v_mfma_f32_16x16x32_bf16 v[72:75], v[116:119], v[170:173], v[72:75]
	v_mfma_f32_16x16x32_bf16 v[162:165], v[108:111], v[178:181], v[162:165]
	v_mfma_f32_16x16x32_bf16 v[60:63], v[116:119], v[178:181], v[60:63]
	v_mfma_f32_16x16x32_bf16 v[158:161], v[108:111], v[206:209], v[158:161]
	v_mfma_f32_16x16x32_bf16 v[56:59], v[116:119], v[206:209], v[56:59]
	v_mfma_f32_16x16x32_bf16 v[96:99], v[108:111], v[214:217], v[96:99]
	v_mfma_f32_16x16x32_bf16 v[76:79], v[116:119], v[214:217], v[76:79]
	v_mfma_f32_16x16x32_bf16 v[8:11], v[120:123], v[166:169], v[8:11]
	v_mfma_f32_16x16x32_bf16 v[64:67], v[128:131], v[166:169], v[64:67]
	v_mfma_f32_16x16x32_bf16 v[154:157], v[120:123], v[174:177], v[154:157]
	v_mfma_f32_16x16x32_bf16 v[52:55], v[128:131], v[174:177], v[52:55]
	v_mfma_f32_16x16x32_bf16 v[150:153], v[120:123], v[194:197], v[150:153]
	v_mfma_f32_16x16x32_bf16 v[48:51], v[128:131], v[194:197], v[48:51]
	v_mfma_f32_16x16x32_bf16 v[92:95], v[120:123], v[210:213], v[92:95]
	v_mfma_f32_16x16x32_bf16 v[68:71], v[128:131], v[210:213], v[68:71]
	v_mfma_f32_16x16x32_bf16 v[8:11], v[124:127], v[170:173], v[8:11]
	v_mfma_f32_16x16x32_bf16 v[64:67], v[132:135], v[170:173], v[64:67]
	v_mfma_f32_16x16x32_bf16 v[154:157], v[124:127], v[178:181], v[154:157]
	v_mfma_f32_16x16x32_bf16 v[52:55], v[132:135], v[178:181], v[52:55]
	v_mfma_f32_16x16x32_bf16 v[150:153], v[124:127], v[206:209], v[150:153]
	v_mfma_f32_16x16x32_bf16 v[48:51], v[132:135], v[206:209], v[48:51]
	v_mfma_f32_16x16x32_bf16 v[92:95], v[124:127], v[214:217], v[92:95]
	v_mfma_f32_16x16x32_bf16 v[68:71], v[132:135], v[214:217], v[68:71]
	s_barrier
; #define PG8_STAGE(bufoff, gbase, voff) do { _Pragma("unroll") for (int _i = 0; _i < 2; ++_i) \
;         __builtin_amdgcn_global_load_lds((const unsigned*)((const char*)(gbase) + (voff)[_i]), (PG8_LAS unsigned*)(lds + (bufoff) + ldsw + _i * 8192), 16, 0, 0); } while (0)
; #define PG8_LDA(dst, b, h) do { _Pragma("unroll") for (int m = 0; m < 4; ++m) _Pragma("unroll") for (int k = 0; k < 2; ++k) dst[m][k] = *(const PG8_LAS bf16x8*)(lds + PG8_SA(b, h) + aoff + m * 2048 + k * 1024); } while (0)
; #define PG8_MMA(ai, bj, At, Bt) do { __builtin_amdgcn_s_setprio(1); _Pragma("unroll") for (int m = 0; m < 4; ++m) _Pragma("unroll") for (int n = 0; n < 2; ++n) _Pragma("unroll") for (int k = 0; k < 2; ++k) \
;         acc[ai][bj][m][n] = __builtin_amdgcn_mfma_f32_16x16x32_bf16(Bt[n][k], At[m][k], acc[ai][bj][m][n], 0, 0, 0); __builtin_amdgcn_s_setprio(0); } while (0)
; #define PG8_WAIT_V(n) asm volatile("s_waitcnt vmcnt(" #n ")" ::: "memory")
; #define PG8_WAIT_L(n) asm volatile("s_waitcnt lgkmcnt(" #n ")" ::: "memory")
; #define PG8_BAR __builtin_amdgcn_s_barrier()
; #define PG8_SCHED __builtin_amdgcn_sched_barrier(0)
;     ...
;             PG8_LDA(At, 1, 1); PG8_STAGE(PG8_SB(1, 0), b3, voffB); PG8_STAGE(PG8_SB(1, 1), b3 + hstep, voffB); PG8_STAGE(PG8_SA(1, 0), a3, voffA);
;             PG8_WAIT_V(8); PG8_WAIT_L(0); PG8_BAR; PG8_MMA(1, 0, At, B0); PG8_MMA(1, 1, At, B1); PG8_BAR; PG8_SCHED;
	s_setprio 0
	s_add_i32 s14, s48, s0
	v_lshl_add_u64 v[136:137], v[198:199], 0, s[66:67]
	s_mov_b32 m0, s14
	ds_read_b128 v[166:169], v222 offset:49152
	ds_read_b128 v[170:173], v222 offset:50176
	ds_read_b128 v[174:177], v222 offset:51200
	ds_read_b128 v[178:181], v222 offset:52224
	ds_read_b128 v[194:197], v222 offset:53248
	ds_read_b128 v[206:209], v222 offset:54272
	ds_read_b128 v[210:213], v222 offset:55296
	ds_read_b128 v[214:217], v222 offset:56320
	global_load_lds_dwordx4 v[136:137], off
	s_add_i32 m0, s14, 0x2000
	s_add_u32 s12, s12, 0x80080
	v_lshl_add_u64 v[136:137], v[218:219], 0, s[66:67]
	s_addc_u32 s13, s13, 0
	s_add_i32 s14, s49, s0
	global_load_lds_dwordx4 v[136:137], off
	s_mov_b32 m0, s14
	v_lshl_add_u64 v[136:137], s[12:13], 0, v[186:187]
	global_load_lds_dwordx4 v[136:137], off
	s_add_i32 m0, s14, 0x2000
	v_lshl_add_u64 v[136:137], s[12:13], 0, v[182:183]
	global_load_lds_dwordx4 v[136:137], off
	v_lshl_add_u64 v[136:137], v[224:225], 0, s[66:67]
	s_mov_b32 m0, s81
	s_nop 0
	global_load_lds_dwordx4 v[136:137], off
	v_lshl_add_u64 v[136:137], v[232:233], 0, s[66:67]
	s_mov_b32 m0, s42
	s_nop 0
	global_load_lds_dwordx4 v[136:137], off
	s_waitcnt vmcnt(8) lgkmcnt(0)
	s_setprio 1
	s_barrier
	v_mfma_f32_16x16x32_bf16 v[146:149], v[104:107], v[166:169], v[146:149]
	v_mfma_f32_16x16x32_bf16 v[44:47], v[112:115], v[166:169], v[44:47]
	v_mfma_f32_16x16x32_bf16 v[142:145], v[104:107], v[174:177], v[142:145]
	v_mfma_f32_16x16x32_bf16 v[40:43], v[112:115], v[174:177], v[40:43]
	v_mfma_f32_16x16x32_bf16 v[136:139], v[104:107], v[194:197], v[138:141]
	v_mfma_f32_16x16x32_bf16 v[36:39], v[112:115], v[194:197], v[36:39]
	v_mfma_f32_16x16x32_bf16 v[80:83], v[104:107], v[210:213], v[80:83]
	v_mfma_f32_16x16x32_bf16 v[20:23], v[112:115], v[210:213], v[20:23]
	v_mfma_f32_16x16x32_bf16 v[146:149], v[108:111], v[170:173], v[146:149]
	v_mfma_f32_16x16x32_bf16 v[44:47], v[116:119], v[170:173], v[44:47]
	v_mfma_f32_16x16x32_bf16 v[142:145], v[108:111], v[178:181], v[142:145]
	v_mfma_f32_16x16x32_bf16 v[40:43], v[116:119], v[178:181], v[40:43]
	v_mfma_f32_16x16x32_bf16 v[138:141], v[108:111], v[206:209], v[136:139]
	v_mfma_f32_16x16x32_bf16 v[36:39], v[116:119], v[206:209], v[36:39]
	v_mfma_f32_16x16x32_bf16 v[80:83], v[108:111], v[214:217], v[80:83]
	v_mfma_f32_16x16x32_bf16 v[20:23], v[116:119], v[214:217], v[20:23]
	v_mfma_f32_16x16x32_bf16 v[100:103], v[120:123], v[166:169], v[100:103]
	v_mfma_f32_16x16x32_bf16 v[32:35], v[128:131], v[166:169], v[32:35]
	v_mfma_f32_16x16x32_bf16 v[88:91], v[120:123], v[174:177], v[88:91]
	v_mfma_f32_16x16x32_bf16 v[28:31], v[128:131], v[174:177], v[28:31]
	v_mfma_f32_16x16x32_bf16 v[84:87], v[120:123], v[194:197], v[84:87]
	v_mfma_f32_16x16x32_bf16 v[24:27], v[128:131], v[194:197], v[24:27]
	v_mfma_f32_16x16x32_bf16 v[16:19], v[120:123], v[210:213], v[16:19]
	v_mfma_f32_16x16x32_bf16 v[12:15], v[128:131], v[210:213], v[12:15]
	v_mfma_f32_16x16x32_bf16 v[102:105], v[124:127], v[170:173], v[100:103]
	v_mfma_f32_16x16x32_bf16 v[32:35], v[132:135], v[170:173], v[32:35]
	v_mfma_f32_16x16x32_bf16 v[88:91], v[124:127], v[178:181], v[88:91]
	v_mfma_f32_16x16x32_bf16 v[28:31], v[132:135], v[178:181], v[28:31]
	v_mfma_f32_16x16x32_bf16 v[84:87], v[124:127], v[206:209], v[84:87]
	v_mfma_f32_16x16x32_bf16 v[24:27], v[132:135], v[206:209], v[24:27]
	v_mfma_f32_16x16x32_bf16 v[16:19], v[124:127], v[214:217], v[16:19]
	v_mfma_f32_16x16x32_bf16 v[12:15], v[132:135], v[214:217], v[12:15]
	s_barrier
	s_setprio 0
	s_add_i32 s89, s89, 2
	s_add_u32 s10, s10, 0x100
	s_addc_u32 s11, s11, 0
	s_add_u32 s82, s82, 0x100
	s_addc_u32 s83, s83, 0
	s_cmp_gt_u32 s89, 29
	s_cbranch_scc0 .LBB0_542
	s_and_b64 vcc, exec, s[70:71]
	s_cbranch_vccz .LBB0_545
	s_barrier

;     __device__ __forceinline__ bool next(int i, Unit& u) const { if (i >= n) return false; u.pm = pm; u.pn = pn0 + i; return true; }
;     __device__ __forceinline__ bool next(int i, Unit& u) const { if (i) return false; u.pm = pm; u.pn = pn; return true; }
; #define PG8_STAGE(bufoff, gbase, voff) do { _Pragma("unroll") for (int _i = 0; _i < 2; ++_i) \
;         __builtin_amdgcn_global_load_lds((const unsigned*)((const char*)(gbase) + (voff)[_i]), (PG8_LAS unsigned*)(lds + (bufoff) + ldsw + _i * 8192), 16, 0, 0); } while (0)
; #define PG8_LDA(dst, b, h) do { _Pragma("unroll") for (int m = 0; m < 4; ++m) _Pragma("unroll") for (int k = 0; k < 2; ++k) dst[m][k] = *(const PG8_LAS bf16x8*)(lds + PG8_SA(b, h) + aoff + m * 2048 + k * 1024); } while (0)
; #define PG8_LDB(dst, b, h) do { _Pragma("unroll") for (int n = 0; n < 2; ++n) _Pragma("unroll") for (int k = 0; k < 2; ++k) dst[n][k] = *(const PG8_LAS bf16x8*)(lds + PG8_SB(b, h) + boff + n * 2048 + k * 1024); } while (0)
; #define PG8_WAIT_V(n) asm volatile("s_waitcnt vmcnt(" #n ")" ::: "memory")
; #define PG8_BAR __builtin_amdgcn_s_barrier()
;     ...
;         const bool has_next = S.next(ui + 1, nxt);
;         const char* nA = has_next ? (const char*)g.A + (size_t)nxt.pm * tstep : cA; const char* nB = has_next ? (const char*)g.Bt + (size_t)nxt.pn * tstep : cB;
;         for (int t = 0; t < nt; t += 2) {
;             const bool last = (t == nt - 2);
;             const char* a1 = cA + (size_t)(t + 1) * kstep;
;             const char* a2 = last ? nA : cA + (size_t)(t + 2) * kstep; const char* b2 = last ? nB : cB + (size_t)(t + 2) * kstep;
;             const char* a3 = a2 + kstep; const char* b3 = b2 + kstep;
;             if (last && has_next) S.a_ready(nxt);
;             if (t == 0) E.pre_issue(pre, cur, tid, ui); else if (t == 2) E.pre_finish(pre, tid, ui);
;             if constexpr (SP2) {
;             PG8_LDB(B0, 0, 0); PG8_LDB(B1, 0, 1); PG8_SCHED; PG8_LDA(At, 0, 0); PG8_STAGE(PG8_SA(1, 1), a1 + hstep, voffA);
;             PG8_WAIT_V(8); PG8_WAIT_L(0); PG8_BAR; PG8_MMA(0, 0, At, B0); PG8_MMA(0, 1, At, B1); PG8_BAR; PG8_SCHED;
;             PG8_LDA(At, 0, 1); PG8_STAGE(PG8_SB(0, 0), b2, voffB); PG8_STAGE(PG8_SB(0, 1), b2 + hstep, voffB); PG8_STAGE(PG8_SA(0, 0), a2, voffA);
;             PG8_WAIT_V(8); PG8_WAIT_L(0); PG8_BAR; PG8_MMA(1, 0, At, B0); PG8_MMA(1, 1, At, B1); PG8_BAR; PG8_SCHED;
.LBB0_667:
	s_add_u32 s68, s62, 0x100
	s_addc_u32 s69, s63, 0
	s_add_i32 s48, 0, 0x10000
	s_cmpk_eq_i32 s78, 0x54
	s_cselect_b32 s77, s11, s69
	s_cselect_b32 s76, s10, s68
	s_cselect_b32 s71, s61, s75
	s_cselect_b32 s70, s60, s73
	s_add_i32 s49, 0, 0x14000
	ds_read_b128 v[108:111], v251
	ds_read_b128 v[112:115], v251 offset:1024
	ds_read_b128 v[128:131], v251 offset:2048
	ds_read_b128 v[136:139], v251 offset:3072
	ds_read_b128 v[148:151], v251 offset:16384
	ds_read_b128 v[152:155], v251 offset:17408
	ds_read_b128 v[156:159], v251 offset:18432
	ds_read_b128 v[160:163], v251 offset:19456
	v_lshl_add_u64 v[198:199], s[62:63], 0, v[196:197]
	s_add_i32 m0, s6, 0xc000
	ds_read_b128 v[164:167], v234
	ds_read_b128 v[168:171], v234 offset:1024
	ds_read_b128 v[172:175], v234 offset:2048
	ds_read_b128 v[176:179], v234 offset:3072
	ds_read_b128 v[180:183], v234 offset:4096
	ds_read_b128 v[184:187], v234 offset:5120
	ds_read_b128 v[206:209], v234 offset:6144
	ds_read_b128 v[210:213], v234 offset:7168
	global_load_lds_dwordx4 v[198:199], off
	s_add_i32 m0, s6, 0xe000
	v_lshl_add_u64 v[198:199], s[62:63], 0, v[194:195]
	global_load_lds_dwordx4 v[198:199], off
	s_waitcnt vmcnt(8) lgkmcnt(0)
	s_setprio 1
	s_barrier
	v_mfma_f32_16x16x32_bf16 v[144:147], v[108:111], v[164:167], v[144:147]
	v_mfma_f32_16x16x32_bf16 v[140:143], v[128:131], v[164:167], v[140:143]
	v_mfma_f32_16x16x32_bf16 v[120:123], v[108:111], v[172:175], v[120:123]
	v_mfma_f32_16x16x32_bf16 v[116:119], v[128:131], v[172:175], v[116:119]
	v_mfma_f32_16x16x32_bf16 v[96:99], v[108:111], v[180:183], v[96:99]
	v_mfma_f32_16x16x32_bf16 v[92:95], v[128:131], v[180:183], v[92:95]
	v_mfma_f32_16x16x32_bf16 v[80:83], v[108:111], v[206:209], v[80:83]
	v_mfma_f32_16x16x32_bf16 v[76:79], v[128:131], v[206:209], v[76:79]
	v_mfma_f32_16x16x32_bf16 v[144:147], v[112:115], v[168:171], v[144:147]
	v_mfma_f32_16x16x32_bf16 v[140:143], v[136:139], v[168:171], v[140:143]
	v_mfma_f32_16x16x32_bf16 v[120:123], v[112:115], v[176:179], v[120:123]
	v_mfma_f32_16x16x32_bf16 v[116:119], v[136:139], v[176:179], v[116:119]
	v_mfma_f32_16x16x32_bf16 v[96:99], v[112:115], v[184:187], v[96:99]
	v_mfma_f32_16x16x32_bf16 v[92:95], v[136:139], v[184:187], v[92:95]
	v_mfma_f32_16x16x32_bf16 v[80:83], v[112:115], v[210:213], v[80:83]
	v_mfma_f32_16x16x32_bf16 v[76:79], v[136:139], v[210:213], v[76:79]
	v_mfma_f32_16x16x32_bf16 v[132:135], v[148:151], v[164:167], v[132:135]
	v_mfma_f32_16x16x32_bf16 v[124:127], v[156:159], v[164:167], v[124:127]
	v_mfma_f32_16x16x32_bf16 v[104:107], v[148:151], v[172:175], v[104:107]
	v_mfma_f32_16x16x32_bf16 v[100:103], v[156:159], v[172:175], v[100:103]
	v_mfma_f32_16x16x32_bf16 v[88:91], v[148:151], v[180:183], v[88:91]
	v_mfma_f32_16x16x32_bf16 v[84:87], v[156:159], v[180:183], v[84:87]
	v_mfma_f32_16x16x32_bf16 v[72:75], v[148:151], v[206:209], v[72:75]
	v_mfma_f32_16x16x32_bf16 v[68:71], v[156:159], v[206:209], v[68:71]
	v_mfma_f32_16x16x32_bf16 v[132:135], v[152:155], v[168:171], v[132:135]
	v_mfma_f32_16x16x32_bf16 v[124:127], v[160:163], v[168:171], v[124:127]
	v_mfma_f32_16x16x32_bf16 v[104:107], v[152:155], v[176:179], v[104:107]
	v_mfma_f32_16x16x32_bf16 v[100:103], v[160:163], v[176:179], v[100:103]
	v_mfma_f32_16x16x32_bf16 v[88:91], v[152:155], v[184:187], v[88:91]
	v_mfma_f32_16x16x32_bf16 v[84:87], v[160:163], v[184:187], v[84:87]
	v_mfma_f32_16x16x32_bf16 v[72:75], v[152:155], v[210:213], v[72:75]
	v_mfma_f32_16x16x32_bf16 v[68:71], v[160:163], v[210:213], v[68:71]
	s_barrier
	s_setprio 0
	s_add_i32 s48, s48, s5
	v_lshl_add_u64 v[198:199], s[70:71], 0, v[200:201]
	s_mov_b32 m0, s48
	ds_read_b128 v[164:167], v234 offset:16384
	ds_read_b128 v[168:171], v234 offset:17408
	ds_read_b128 v[172:175], v234 offset:18432
	ds_read_b128 v[176:179], v234 offset:19456
	ds_read_b128 v[180:183], v234 offset:20480
	ds_read_b128 v[184:187], v234 offset:21504
	ds_read_b128 v[206:209], v234 offset:22528
	ds_read_b128 v[210:213], v234 offset:23552
	global_load_lds_dwordx4 v[198:199], off
	s_add_i32 m0, s48, 0x2000
	s_add_u32 s62, s70, 0x160000
	v_lshl_add_u64 v[214:215], s[70:71], 0, v[188:189]
	s_addc_u32 s63, s71, 0
	s_add_i32 s48, s49, s5
	global_load_lds_dwordx4 v[214:215], off
	v_lshl_add_u64 v[216:217], s[62:63], 0, v[200:201]
	s_mov_b32 m0, s48
	v_lshl_add_u64 v[218:219], s[76:77], 0, v[190:191]
	global_load_lds_dwordx4 v[216:217], off
	s_add_i32 m0, s48, 0x2000
	v_lshl_add_u64 v[216:217], s[62:63], 0, v[188:189]
	global_load_lds_dwordx4 v[216:217], off
	s_mov_b32 m0, s6
	v_lshl_add_u64 v[216:217], s[76:77], 0, v[192:193]
	global_load_lds_dwordx4 v[216:217], off
	s_mov_b32 m0, s7
	s_nop 0
	global_load_lds_dwordx4 v[218:219], off
	s_waitcnt vmcnt(8) lgkmcnt(0)
	s_setprio 1
	s_barrier
; #define PG8_STAGE(bufoff, gbase, voff) do { _Pragma("unroll") for (int _i = 0; _i < 2; ++_i) \
;         __builtin_amdgcn_global_load_lds((const unsigned*)((const char*)(gbase) + (voff)[_i]), (PG8_LAS unsigned*)(lds + (bufoff) + ldsw + _i * 8192), 16, 0, 0); } while (0)
; #define PG8_LDA(dst, b, h) do { _Pragma("unroll") for (int m = 0; m < 4; ++m) _Pragma("unroll") for (int k = 0; k < 2; ++k) dst[m][k] = *(const PG8_LAS bf16x8*)(lds + PG8_SA(b, h) + aoff + m * 2048 + k * 1024); } while (0)
; #define PG8_LDB(dst, b, h) do { _Pragma("unroll") for (int n = 0; n < 2; ++n) _Pragma("unroll") for (int k = 0; k < 2; ++k) dst[n][k] = *(const PG8_LAS bf16x8*)(lds + PG8_SB(b, h) + boff + n * 2048 + k * 1024); } while (0)
; #define PG8_MMA(ai, bj, At, Bt) do { __builtin_amdgcn_s_setprio(1); _Pragma("unroll") for (int m = 0; m < 4; ++m) _Pragma("unroll") for (int n = 0; n < 2; ++n) _Pragma("unroll") for (int k = 0; k < 2; ++k) \
;         acc[ai][bj][m][n] = __builtin_amdgcn_mfma_f32_16x16x32_bf16(Bt[n][k], At[m][k], acc[ai][bj][m][n], 0, 0, 0); __builtin_amdgcn_s_setprio(0); } while (0)
; #define PG8_WAIT_V(n) asm volatile("s_waitcnt vmcnt(" #n ")" ::: "memory")
; #define PG8_WAIT_L(n) asm volatile("s_waitcnt lgkmcnt(" #n ")" ::: "memory")
; #define PG8_BAR __builtin_amdgcn_s_barrier()
; #define PG8_SCHED __builtin_amdgcn_sched_barrier(0)
;     ...
;             PG8_WAIT_V(8); PG8_WAIT_L(0); PG8_BAR; PG8_MMA(1, 0, At, B0); PG8_MMA(1, 1, At, B1); PG8_BAR; PG8_SCHED;
;             PG8_LDB(B0, 1, 0); PG8_LDB(B1, 1, 1); PG8_SCHED; PG8_LDA(At, 1, 0); PG8_STAGE(PG8_SA(0, 1), a2 + hstep, voffA);
;             PG8_WAIT_V(8); PG8_WAIT_L(0); PG8_BAR; PG8_MMA(0, 0, At, B0); PG8_MMA(0, 1, At, B1); PG8_BAR; PG8_SCHED;
	v_mfma_f32_16x16x32_bf16 v[64:67], v[108:111], v[164:167], v[64:67]
	v_mfma_f32_16x16x32_bf16 v[60:63], v[128:131], v[164:167], v[60:63]
	v_mfma_f32_16x16x32_bf16 v[48:51], v[108:111], v[172:175], v[48:51]
	v_mfma_f32_16x16x32_bf16 v[44:47], v[128:131], v[172:175], v[44:47]
	v_mfma_f32_16x16x32_bf16 v[32:35], v[108:111], v[180:183], v[32:35]
	v_mfma_f32_16x16x32_bf16 v[28:31], v[128:131], v[180:183], v[28:31]
	v_mfma_f32_16x16x32_bf16 v[16:19], v[108:111], v[206:209], v[16:19]
	v_mfma_f32_16x16x32_bf16 v[12:15], v[128:131], v[206:209], v[12:15]
	v_mfma_f32_16x16x32_bf16 v[64:67], v[112:115], v[168:171], v[64:67]
	v_mfma_f32_16x16x32_bf16 v[60:63], v[136:139], v[168:171], v[60:63]
	v_mfma_f32_16x16x32_bf16 v[48:51], v[112:115], v[176:179], v[48:51]
	v_mfma_f32_16x16x32_bf16 v[44:47], v[136:139], v[176:179], v[44:47]
	v_mfma_f32_16x16x32_bf16 v[32:35], v[112:115], v[184:187], v[32:35]
	v_mfma_f32_16x16x32_bf16 v[28:31], v[136:139], v[184:187], v[28:31]
	v_mfma_f32_16x16x32_bf16 v[16:19], v[112:115], v[210:213], v[16:19]
	v_mfma_f32_16x16x32_bf16 v[12:15], v[136:139], v[210:213], v[12:15]
	v_mfma_f32_16x16x32_bf16 v[56:59], v[148:151], v[164:167], v[56:59]
	v_mfma_f32_16x16x32_bf16 v[52:55], v[156:159], v[164:167], v[52:55]
	v_mfma_f32_16x16x32_bf16 v[40:43], v[148:151], v[172:175], v[40:43]
	v_mfma_f32_16x16x32_bf16 v[36:39], v[156:159], v[172:175], v[36:39]
	v_mfma_f32_16x16x32_bf16 v[24:27], v[148:151], v[180:183], v[24:27]
	v_mfma_f32_16x16x32_bf16 v[20:23], v[156:159], v[180:183], v[20:23]
	v_mfma_f32_16x16x32_bf16 v[8:11], v[148:151], v[206:209], v[8:11]
	v_mfma_f32_16x16x32_bf16 v[4:7], v[156:159], v[206:209], v[4:7]
	v_mfma_f32_16x16x32_bf16 v[56:59], v[152:155], v[168:171], v[56:59]
	v_mfma_f32_16x16x32_bf16 v[52:55], v[160:163], v[168:171], v[52:55]
	v_mfma_f32_16x16x32_bf16 v[40:43], v[152:155], v[176:179], v[40:43]
	v_mfma_f32_16x16x32_bf16 v[36:39], v[160:163], v[176:179], v[36:39]
	v_mfma_f32_16x16x32_bf16 v[24:27], v[152:155], v[184:187], v[24:27]
	v_mfma_f32_16x16x32_bf16 v[20:23], v[160:163], v[184:187], v[20:23]
	v_mfma_f32_16x16x32_bf16 v[8:11], v[152:155], v[210:213], v[8:11]
	v_mfma_f32_16x16x32_bf16 v[4:7], v[160:163], v[210:213], v[4:7]
	s_barrier
	s_setprio 0
	s_add_i32 s48, 0, 0x18000
	s_add_i32 s49, 0, 0x1c000
	ds_read_b128 v[108:111], v251 offset:32768
	ds_read_b128 v[112:115], v251 offset:33792
	ds_read_b128 v[128:131], v251 offset:34816
	ds_read_b128 v[136:139], v251 offset:35840
	ds_read_b128 v[148:151], v251 offset:49152
	ds_read_b128 v[152:155], v251 offset:50176
	ds_read_b128 v[156:159], v251 offset:51200
	ds_read_b128 v[160:163], v251 offset:52224
	s_add_u32 s62, s76, 0x160000
	s_addc_u32 s63, s77, 0
	s_mov_b32 m0, s20
	v_lshl_add_u64 v[220:221], s[62:63], 0, v[192:193]
	ds_read_b128 v[164:167], v234 offset:32768
	ds_read_b128 v[168:171], v234 offset:33792
	ds_read_b128 v[172:175], v234 offset:34816
	ds_read_b128 v[176:179], v234 offset:35840
	ds_read_b128 v[180:183], v234 offset:36864
	ds_read_b128 v[184:187], v234 offset:37888
	ds_read_b128 v[206:209], v234 offset:38912
	ds_read_b128 v[210:213], v234 offset:39936
	global_load_lds_dwordx4 v[220:221], off
	s_mov_b32 m0, s21
	v_lshl_add_u64 v[220:221], s[62:63], 0, v[190:191]
	global_load_lds_dwordx4 v[220:221], off
	s_waitcnt vmcnt(8) lgkmcnt(0)
	s_setprio 1
	s_barrier
	v_mfma_f32_16x16x32_bf16 v[144:147], v[108:111], v[164:167], v[144:147]
	v_mfma_f32_16x16x32_bf16 v[140:143], v[128:131], v[164:167], v[140:143]
	v_mfma_f32_16x16x32_bf16 v[120:123], v[108:111], v[172:175], v[120:123]
	v_mfma_f32_16x16x32_bf16 v[116:119], v[128:131], v[172:175], v[116:119]
	v_mfma_f32_16x16x32_bf16 v[96:99], v[108:111], v[180:183], v[96:99]
	v_mfma_f32_16x16x32_bf16 v[92:95], v[128:131], v[180:183], v[92:95]
	v_mfma_f32_16x16x32_bf16 v[80:83], v[108:111], v[206:209], v[80:83]
	v_mfma_f32_16x16x32_bf16 v[76:79], v[128:131], v[206:209], v[76:79]
	v_mfma_f32_16x16x32_bf16 v[144:147], v[112:115], v[168:171], v[144:147]
	v_mfma_f32_16x16x32_bf16 v[140:143], v[136:139], v[168:171], v[140:143]
	v_mfma_f32_16x16x32_bf16 v[120:123], v[112:115], v[176:179], v[120:123]
	v_mfma_f32_16x16x32_bf16 v[116:119], v[136:139], v[176:179], v[116:119]
	v_mfma_f32_16x16x32_bf16 v[96:99], v[112:115], v[184:187], v[96:99]
	v_mfma_f32_16x16x32_bf16 v[92:95], v[136:139], v[184:187], v[92:95]
	v_mfma_f32_16x16x32_bf16 v[80:83], v[112:115], v[210:213], v[80:83]
	v_mfma_f32_16x16x32_bf16 v[76:79], v[136:139], v[210:213], v[76:79]
	v_mfma_f32_16x16x32_bf16 v[132:135], v[148:151], v[164:167], v[132:135]
	v_mfma_f32_16x16x32_bf16 v[124:127], v[156:159], v[164:167], v[124:127]
	v_mfma_f32_16x16x32_bf16 v[104:107], v[148:151], v[172:175], v[104:107]
	v_mfma_f32_16x16x32_bf16 v[100:103], v[156:159], v[172:175], v[100:103]
	v_mfma_f32_16x16x32_bf16 v[88:91], v[148:151], v[180:183], v[88:91]
	v_mfma_f32_16x16x32_bf16 v[84:87], v[156:159], v[180:183], v[84:87]
	v_mfma_f32_16x16x32_bf16 v[72:75], v[148:151], v[206:209], v[72:75]
	v_mfma_f32_16x16x32_bf16 v[68:71], v[156:159], v[206:209], v[68:71]
	v_mfma_f32_16x16x32_bf16 v[132:135], v[152:155], v[168:171], v[132:135]
	v_mfma_f32_16x16x32_bf16 v[124:127], v[160:163], v[168:171], v[124:127]
	v_mfma_f32_16x16x32_bf16 v[104:107], v[152:155], v[176:179], v[104:107]
	v_mfma_f32_16x16x32_bf16 v[100:103], v[160:163], v[176:179], v[100:103]
	v_mfma_f32_16x16x32_bf16 v[88:91], v[152:155], v[184:187], v[88:91]
	v_mfma_f32_16x16x32_bf16 v[84:87], v[160:163], v[184:187], v[84:87]
	v_mfma_f32_16x16x32_bf16 v[72:75], v[152:155], v[210:213], v[72:75]
	v_mfma_f32_16x16x32_bf16 v[68:71], v[160:163], v[210:213], v[68:71]
	s_barrier
; #define PG8_STAGE(bufoff, gbase, voff) do { _Pragma("unroll") for (int _i = 0; _i < 2; ++_i) \
;         __builtin_amdgcn_global_load_lds((const unsigned*)((const char*)(gbase) + (voff)[_i]), (PG8_LAS unsigned*)(lds + (bufoff) + ldsw + _i * 8192), 16, 0, 0); } while (0)
; #define PG8_LDA(dst, b, h) do { _Pragma("unroll") for (int m = 0; m < 4; ++m) _Pragma("unroll") for (int k = 0; k < 2; ++k) dst[m][k] = *(const PG8_LAS bf16x8*)(lds + PG8_SA(b, h) + aoff + m * 2048 + k * 1024); } while (0)
; #define PG8_MMA(ai, bj, At, Bt) do { __builtin_amdgcn_s_setprio(1); _Pragma("unroll") for (int m = 0; m < 4; ++m) _Pragma("unroll") for (int n = 0; n < 2; ++n) _Pragma("unroll") for (int k = 0; k < 2; ++k) \
;         acc[ai][bj][m][n] = __builtin_amdgcn_mfma_f32_16x16x32_bf16(Bt[n][k], At[m][k], acc[ai][bj][m][n], 0, 0, 0); __builtin_amdgcn_s_setprio(0); } while (0)
; #define PG8_WAIT_V(n) asm volatile("s_waitcnt vmcnt(" #n ")" ::: "memory")
; #define PG8_WAIT_L(n) asm volatile("s_waitcnt lgkmcnt(" #n ")" ::: "memory")
; #define PG8_BAR __builtin_amdgcn_s_barrier()
; #define PG8_SCHED __builtin_amdgcn_sched_barrier(0)
;     ...
;             PG8_LDA(At, 1, 1); PG8_STAGE(PG8_SB(1, 0), b3, voffB); PG8_STAGE(PG8_SB(1, 1), b3 + hstep, voffB); PG8_STAGE(PG8_SA(1, 0), a3, voffA);
;             PG8_WAIT_V(8); PG8_WAIT_L(0); PG8_BAR; PG8_MMA(1, 0, At, B0); PG8_MMA(1, 1, At, B1); PG8_BAR; PG8_SCHED;
	s_setprio 0
	s_add_i32 s48, s48, s5
	v_lshl_add_u64 v[198:199], v[198:199], 0, s[66:67]
	s_mov_b32 m0, s48
	ds_read_b128 v[164:167], v234 offset:49152
	ds_read_b128 v[168:171], v234 offset:50176
	ds_read_b128 v[172:175], v234 offset:51200
	ds_read_b128 v[176:179], v234 offset:52224
	ds_read_b128 v[180:183], v234 offset:53248
	ds_read_b128 v[184:187], v234 offset:54272
	ds_read_b128 v[206:209], v234 offset:55296
	ds_read_b128 v[210:213], v234 offset:56320
	global_load_lds_dwordx4 v[198:199], off
	s_add_i32 m0, s48, 0x2000
	s_add_u32 s62, s70, 0x160080
	v_lshl_add_u64 v[198:199], v[214:215], 0, s[66:67]
	s_addc_u32 s63, s71, 0
	s_add_i32 s48, s49, s5
	global_load_lds_dwordx4 v[198:199], off
	s_mov_b32 m0, s48
	v_lshl_add_u64 v[198:199], s[62:63], 0, v[200:201]
	global_load_lds_dwordx4 v[198:199], off
	s_add_i32 m0, s48, 0x2000
	v_lshl_add_u64 v[198:199], s[62:63], 0, v[188:189]
	global_load_lds_dwordx4 v[198:199], off
	v_lshl_add_u64 v[198:199], v[216:217], 0, s[66:67]
	s_mov_b32 m0, s53
	s_nop 0
	global_load_lds_dwordx4 v[198:199], off
	v_lshl_add_u64 v[198:199], v[218:219], 0, s[66:67]
	s_mov_b32 m0, s54
	s_nop 0
	global_load_lds_dwordx4 v[198:199], off
	s_waitcnt vmcnt(8) lgkmcnt(0)
	s_setprio 1
	s_barrier
	v_mfma_f32_16x16x32_bf16 v[64:67], v[108:111], v[164:167], v[64:67]
	v_mfma_f32_16x16x32_bf16 v[60:63], v[128:131], v[164:167], v[60:63]
	v_mfma_f32_16x16x32_bf16 v[48:51], v[108:111], v[172:175], v[48:51]
	v_mfma_f32_16x16x32_bf16 v[44:47], v[128:131], v[172:175], v[44:47]
	v_mfma_f32_16x16x32_bf16 v[32:35], v[108:111], v[180:183], v[32:35]
	v_mfma_f32_16x16x32_bf16 v[28:31], v[128:131], v[180:183], v[28:31]
	v_mfma_f32_16x16x32_bf16 v[16:19], v[108:111], v[206:209], v[16:19]
	v_mfma_f32_16x16x32_bf16 v[12:15], v[128:131], v[206:209], v[12:15]
	v_mfma_f32_16x16x32_bf16 v[64:67], v[112:115], v[168:171], v[64:67]
	v_mfma_f32_16x16x32_bf16 v[60:63], v[136:139], v[168:171], v[60:63]
	v_mfma_f32_16x16x32_bf16 v[48:51], v[112:115], v[176:179], v[48:51]
	v_mfma_f32_16x16x32_bf16 v[44:47], v[136:139], v[176:179], v[44:47]
	v_mfma_f32_16x16x32_bf16 v[32:35], v[112:115], v[184:187], v[32:35]
	v_mfma_f32_16x16x32_bf16 v[28:31], v[136:139], v[184:187], v[28:31]
	v_mfma_f32_16x16x32_bf16 v[16:19], v[112:115], v[210:213], v[16:19]
	v_mfma_f32_16x16x32_bf16 v[12:15], v[136:139], v[210:213], v[12:15]
	v_mfma_f32_16x16x32_bf16 v[56:59], v[148:151], v[164:167], v[56:59]
	v_mfma_f32_16x16x32_bf16 v[52:55], v[156:159], v[164:167], v[52:55]
	v_mfma_f32_16x16x32_bf16 v[40:43], v[148:151], v[172:175], v[40:43]
	v_mfma_f32_16x16x32_bf16 v[36:39], v[156:159], v[172:175], v[36:39]
	v_mfma_f32_16x16x32_bf16 v[24:27], v[148:151], v[180:183], v[24:27]
	v_mfma_f32_16x16x32_bf16 v[20:23], v[156:159], v[180:183], v[20:23]
	v_mfma_f32_16x16x32_bf16 v[8:11], v[148:151], v[206:209], v[8:11]
	v_mfma_f32_16x16x32_bf16 v[4:7], v[156:159], v[206:209], v[4:7]
	v_mfma_f32_16x16x32_bf16 v[56:59], v[152:155], v[168:171], v[56:59]
	v_mfma_f32_16x16x32_bf16 v[52:55], v[160:163], v[168:171], v[52:55]
	v_mfma_f32_16x16x32_bf16 v[40:43], v[152:155], v[176:179], v[40:43]
	v_mfma_f32_16x16x32_bf16 v[36:39], v[160:163], v[176:179], v[36:39]
	v_mfma_f32_16x16x32_bf16 v[24:27], v[152:155], v[184:187], v[24:27]
	v_mfma_f32_16x16x32_bf16 v[20:23], v[160:163], v[184:187], v[20:23]
	v_mfma_f32_16x16x32_bf16 v[8:11], v[152:155], v[210:213], v[8:11]
	v_mfma_f32_16x16x32_bf16 v[4:7], v[160:163], v[210:213], v[4:7]
	s_barrier
	s_setprio 0
	s_add_i32 s78, s78, 2
	s_add_u32 s73, s73, 0x100
	s_addc_u32 s75, s75, 0
	s_cmpk_gt_u32 s78, 0x55
	s_mov_b64 s[62:63], s[68:69]
	s_cbranch_scc0 .LBB0_667
	s_and_b64 vcc, exec, s[24:25]
	s_cbranch_vccz .LBB0_670
	s_barrier

;     __device__ __forceinline__ bool next(int i, Unit& u) const { if (i >= n) return false; u.pm = pm; u.pn = pn0 + i; return true; }
;     __device__ __forceinline__ bool next(int i, Unit& u) const { if (i) return false; u.pm = pm; u.pn = pn; return true; }
; #define PG8_STAGE(bufoff, gbase, voff) do { _Pragma("unroll") for (int _i = 0; _i < 2; ++_i) \
;         __builtin_amdgcn_global_load_lds((const unsigned*)((const char*)(gbase) + (voff)[_i]), (PG8_LAS unsigned*)(lds + (bufoff) + ldsw + _i * 8192), 16, 0, 0); } while (0)
; #define PG8_LDA(dst, b, h) do { _Pragma("unroll") for (int m = 0; m < 4; ++m) _Pragma("unroll") for (int k = 0; k < 2; ++k) dst[m][k] = *(const PG8_LAS bf16x8*)(lds + PG8_SA(b, h) + aoff + m * 2048 + k * 1024); } while (0)
; #define PG8_LDB(dst, b, h) do { _Pragma("unroll") for (int n = 0; n < 2; ++n) _Pragma("unroll") for (int k = 0; k < 2; ++k) dst[n][k] = *(const PG8_LAS bf16x8*)(lds + PG8_SB(b, h) + boff + n * 2048 + k * 1024); } while (0)
; #define PG8_WAIT_V(n) asm volatile("s_waitcnt vmcnt(" #n ")" ::: "memory")
; #define PG8_BAR __builtin_amdgcn_s_barrier()
;     ...
;         const bool has_next = S.next(ui + 1, nxt);
;         const char* nA = has_next ? (const char*)g.A + (size_t)nxt.pm * tstep : cA; const char* nB = has_next ? (const char*)g.Bt + (size_t)nxt.pn * tstep : cB;
;         for (int t = 0; t < nt; t += 2) {
;             const bool last = (t == nt - 2);
;             const char* a1 = cA + (size_t)(t + 1) * kstep;
;             const char* a2 = last ? nA : cA + (size_t)(t + 2) * kstep; const char* b2 = last ? nB : cB + (size_t)(t + 2) * kstep;
;             const char* a3 = a2 + kstep; const char* b3 = b2 + kstep;
;             if (last && has_next) S.a_ready(nxt);
;             if (t == 0) E.pre_issue(pre, cur, tid, ui); else if (t == 2) E.pre_finish(pre, tid, ui);
;             if constexpr (SP2) {
;             PG8_LDB(B0, 0, 0); PG8_LDB(B1, 0, 1); PG8_SCHED; PG8_LDA(At, 0, 0); PG8_STAGE(PG8_SA(1, 1), a1 + hstep, voffA);
;             PG8_WAIT_V(8); PG8_WAIT_L(0); PG8_BAR; PG8_MMA(0, 0, At, B0); PG8_MMA(0, 1, At, B1); PG8_BAR; PG8_SCHED;
;             PG8_LDA(At, 0, 1); PG8_STAGE(PG8_SB(0, 0), b2, voffB); PG8_STAGE(PG8_SB(0, 1), b2 + hstep, voffB); PG8_STAGE(PG8_SA(0, 0), a2, voffA);
;             PG8_WAIT_V(8); PG8_WAIT_L(0); PG8_BAR; PG8_MMA(1, 0, At, B0); PG8_MMA(1, 1, At, B1); PG8_BAR; PG8_SCHED;
.LBB0_753:
	s_add_u32 s48, s68, 0xfff80080
	s_addc_u32 s49, s69, -1
	s_add_i32 s61, 0, 0x10000
	s_cmp_eq_u32 s59, 28
	s_cselect_b32 s79, s53, s49
	s_cselect_b32 s78, s54, s48
	s_cselect_b32 s77, s25, s58
	s_cselect_b32 s76, s55, s56
	s_add_i32 s48, 0, 0x14000
	ds_read_b128 v[132:135], v251
	ds_read_b128 v[158:161], v251 offset:1024
	ds_read_b128 v[162:165], v251 offset:2048
	ds_read_b128 v[166:169], v251 offset:3072
	ds_read_b128 v[170:173], v251 offset:16384
	ds_read_b128 v[176:179], v251 offset:17408
	ds_read_b128 v[180:183], v251 offset:18432
	ds_read_b128 v[184:187], v251 offset:19456
	v_lshl_add_u64 v[232:233], s[68:69], 0, v[150:151]
	s_add_i32 m0, s1, 0xc000
	ds_read_b128 v[188:191], v175
	ds_read_b128 v[192:195], v175 offset:1024
	ds_read_b128 v[196:199], v175 offset:2048
	ds_read_b128 v[206:209], v175 offset:3072
	ds_read_b128 v[210:213], v175 offset:4096
	ds_read_b128 v[214:217], v175 offset:5120
	ds_read_b128 v[218:221], v175 offset:6144
	ds_read_b128 v[222:225], v175 offset:7168
	global_load_lds_dwordx4 v[232:233], off
	s_add_i32 m0, s1, 0xe000
	v_lshl_add_u64 v[232:233], s[68:69], 0, v[152:153]
	global_load_lds_dwordx4 v[232:233], off
	s_waitcnt vmcnt(8) lgkmcnt(0)
	s_setprio 1
	s_barrier
	v_mfma_f32_16x16x32_bf16 v[128:131], v[132:135], v[188:191], v[128:131]
	v_mfma_f32_16x16x32_bf16 v[124:127], v[162:165], v[188:191], v[124:127]
	v_mfma_f32_16x16x32_bf16 v[116:119], v[132:135], v[196:199], v[116:119]
	v_mfma_f32_16x16x32_bf16 v[108:111], v[162:165], v[196:199], v[108:111]
	v_mfma_f32_16x16x32_bf16 v[100:103], v[132:135], v[210:213], v[100:103]
	v_mfma_f32_16x16x32_bf16 v[92:95], v[162:165], v[210:213], v[92:95]
	v_mfma_f32_16x16x32_bf16 v[84:87], v[132:135], v[218:221], v[84:87]
	v_mfma_f32_16x16x32_bf16 v[76:79], v[162:165], v[218:221], v[76:79]
	v_mfma_f32_16x16x32_bf16 v[128:131], v[158:161], v[192:195], v[128:131]
	v_mfma_f32_16x16x32_bf16 v[124:127], v[166:169], v[192:195], v[124:127]
	v_mfma_f32_16x16x32_bf16 v[116:119], v[158:161], v[206:209], v[116:119]
	v_mfma_f32_16x16x32_bf16 v[108:111], v[166:169], v[206:209], v[108:111]
	v_mfma_f32_16x16x32_bf16 v[100:103], v[158:161], v[214:217], v[100:103]
	v_mfma_f32_16x16x32_bf16 v[92:95], v[166:169], v[214:217], v[92:95]
	v_mfma_f32_16x16x32_bf16 v[84:87], v[158:161], v[222:225], v[84:87]
	v_mfma_f32_16x16x32_bf16 v[76:79], v[166:169], v[222:225], v[76:79]
	v_mfma_f32_16x16x32_bf16 v[120:123], v[170:173], v[188:191], v[120:123]
	v_mfma_f32_16x16x32_bf16 v[112:115], v[180:183], v[188:191], v[112:115]
	v_mfma_f32_16x16x32_bf16 v[104:107], v[170:173], v[196:199], v[104:107]
	v_mfma_f32_16x16x32_bf16 v[96:99], v[180:183], v[196:199], v[96:99]
	v_mfma_f32_16x16x32_bf16 v[88:91], v[170:173], v[210:213], v[88:91]
	v_mfma_f32_16x16x32_bf16 v[80:83], v[180:183], v[210:213], v[80:83]
	v_mfma_f32_16x16x32_bf16 v[72:75], v[170:173], v[218:221], v[72:75]
	v_mfma_f32_16x16x32_bf16 v[68:71], v[180:183], v[218:221], v[68:71]
	v_mfma_f32_16x16x32_bf16 v[120:123], v[176:179], v[192:195], v[120:123]
	v_mfma_f32_16x16x32_bf16 v[112:115], v[184:187], v[192:195], v[112:115]
	v_mfma_f32_16x16x32_bf16 v[104:107], v[176:179], v[206:209], v[104:107]
	v_mfma_f32_16x16x32_bf16 v[96:99], v[184:187], v[206:209], v[96:99]
	v_mfma_f32_16x16x32_bf16 v[88:91], v[176:179], v[214:217], v[88:91]
	v_mfma_f32_16x16x32_bf16 v[80:83], v[184:187], v[214:217], v[80:83]
	v_mfma_f32_16x16x32_bf16 v[72:75], v[176:179], v[222:225], v[72:75]
	v_mfma_f32_16x16x32_bf16 v[68:71], v[184:187], v[222:225], v[68:71]
	s_barrier
	s_setprio 0
	s_add_i32 s49, s61, s0
	v_lshl_add_u64 v[232:233], s[76:77], 0, v[140:141]
	s_mov_b32 m0, s49
	ds_read_b128 v[188:191], v175 offset:16384
	ds_read_b128 v[192:195], v175 offset:17408
	ds_read_b128 v[196:199], v175 offset:18432
	ds_read_b128 v[206:209], v175 offset:19456
	ds_read_b128 v[210:213], v175 offset:20480
	ds_read_b128 v[214:217], v175 offset:21504
	ds_read_b128 v[218:221], v175 offset:22528
	ds_read_b128 v[222:225], v175 offset:23552
	global_load_lds_dwordx4 v[232:233], off
	s_add_i32 m0, s49, 0x2000
	s_add_u32 s82, s76, 0x80000
	v_lshl_add_u64 v[234:235], s[76:77], 0, v[136:137]
	s_addc_u32 s83, s77, 0
	s_add_i32 s48, s48, s0
	global_load_lds_dwordx4 v[234:235], off
	v_lshl_add_u64 v[236:237], s[82:83], 0, v[140:141]
	s_mov_b32 m0, s48
	v_lshl_add_u64 v[238:239], s[78:79], 0, v[138:139]
	global_load_lds_dwordx4 v[236:237], off
	s_add_i32 m0, s48, 0x2000
	v_lshl_add_u64 v[236:237], s[82:83], 0, v[136:137]
	global_load_lds_dwordx4 v[236:237], off
	s_mov_b32 m0, s1
	v_lshl_add_u64 v[236:237], s[78:79], 0, v[142:143]
	global_load_lds_dwordx4 v[236:237], off
	s_mov_b32 m0, s4
	s_nop 0
	global_load_lds_dwordx4 v[238:239], off
	s_waitcnt vmcnt(8) lgkmcnt(0)
	s_setprio 1
	s_barrier
; #define PG8_STAGE(bufoff, gbase, voff) do { _Pragma("unroll") for (int _i = 0; _i < 2; ++_i) \
;         __builtin_amdgcn_global_load_lds((const unsigned*)((const char*)(gbase) + (voff)[_i]), (PG8_LAS unsigned*)(lds + (bufoff) + ldsw + _i * 8192), 16, 0, 0); } while (0)
; #define PG8_LDA(dst, b, h) do { _Pragma("unroll") for (int m = 0; m < 4; ++m) _Pragma("unroll") for (int k = 0; k < 2; ++k) dst[m][k] = *(const PG8_LAS bf16x8*)(lds + PG8_SA(b, h) + aoff + m * 2048 + k * 1024); } while (0)
; #define PG8_LDB(dst, b, h) do { _Pragma("unroll") for (int n = 0; n < 2; ++n) _Pragma("unroll") for (int k = 0; k < 2; ++k) dst[n][k] = *(const PG8_LAS bf16x8*)(lds + PG8_SB(b, h) + boff + n * 2048 + k * 1024); } while (0)
; #define PG8_MMA(ai, bj, At, Bt) do { __builtin_amdgcn_s_setprio(1); _Pragma("unroll") for (int m = 0; m < 4; ++m) _Pragma("unroll") for (int n = 0; n < 2; ++n) _Pragma("unroll") for (int k = 0; k < 2; ++k) \
;         acc[ai][bj][m][n] = __builtin_amdgcn_mfma_f32_16x16x32_bf16(Bt[n][k], At[m][k], acc[ai][bj][m][n], 0, 0, 0); __builtin_amdgcn_s_setprio(0); } while (0)
; #define PG8_WAIT_V(n) asm volatile("s_waitcnt vmcnt(" #n ")" ::: "memory")
; #define PG8_WAIT_L(n) asm volatile("s_waitcnt lgkmcnt(" #n ")" ::: "memory")
; #define PG8_BAR __builtin_amdgcn_s_barrier()
; #define PG8_SCHED __builtin_amdgcn_sched_barrier(0)
;     ...
;             PG8_WAIT_V(8); PG8_WAIT_L(0); PG8_BAR; PG8_MMA(1, 0, At, B0); PG8_MMA(1, 1, At, B1); PG8_BAR; PG8_SCHED;
;             PG8_LDB(B0, 1, 0); PG8_LDB(B1, 1, 1); PG8_SCHED; PG8_LDA(At, 1, 0); PG8_STAGE(PG8_SA(0, 1), a2 + hstep, voffA);
;             PG8_WAIT_V(8); PG8_WAIT_L(0); PG8_BAR; PG8_MMA(0, 0, At, B0); PG8_MMA(0, 1, At, B1); PG8_BAR; PG8_SCHED;
	v_mfma_f32_16x16x32_bf16 v[64:67], v[132:135], v[188:191], v[64:67]
	v_mfma_f32_16x16x32_bf16 v[60:63], v[162:165], v[188:191], v[60:63]
	v_mfma_f32_16x16x32_bf16 v[52:55], v[132:135], v[196:199], v[52:55]
	v_mfma_f32_16x16x32_bf16 v[44:47], v[162:165], v[196:199], v[44:47]
	v_mfma_f32_16x16x32_bf16 v[36:39], v[132:135], v[210:213], v[36:39]
	v_mfma_f32_16x16x32_bf16 v[28:31], v[162:165], v[210:213], v[28:31]
	v_mfma_f32_16x16x32_bf16 v[20:23], v[132:135], v[218:221], v[20:23]
	v_mfma_f32_16x16x32_bf16 v[12:15], v[162:165], v[218:221], v[12:15]
	v_mfma_f32_16x16x32_bf16 v[64:67], v[158:161], v[192:195], v[64:67]
	v_mfma_f32_16x16x32_bf16 v[60:63], v[166:169], v[192:195], v[60:63]
	v_mfma_f32_16x16x32_bf16 v[52:55], v[158:161], v[206:209], v[52:55]
	v_mfma_f32_16x16x32_bf16 v[44:47], v[166:169], v[206:209], v[44:47]
	v_mfma_f32_16x16x32_bf16 v[36:39], v[158:161], v[214:217], v[36:39]
	v_mfma_f32_16x16x32_bf16 v[28:31], v[166:169], v[214:217], v[28:31]
	v_mfma_f32_16x16x32_bf16 v[20:23], v[158:161], v[222:225], v[20:23]
	v_mfma_f32_16x16x32_bf16 v[12:15], v[166:169], v[222:225], v[12:15]
	v_mfma_f32_16x16x32_bf16 v[56:59], v[170:173], v[188:191], v[56:59]
	v_mfma_f32_16x16x32_bf16 v[48:51], v[180:183], v[188:191], v[48:51]
	v_mfma_f32_16x16x32_bf16 v[40:43], v[170:173], v[196:199], v[40:43]
	v_mfma_f32_16x16x32_bf16 v[32:35], v[180:183], v[196:199], v[32:35]
	v_mfma_f32_16x16x32_bf16 v[24:27], v[170:173], v[210:213], v[24:27]
	v_mfma_f32_16x16x32_bf16 v[16:19], v[180:183], v[210:213], v[16:19]
	v_mfma_f32_16x16x32_bf16 v[8:11], v[170:173], v[218:221], v[8:11]
	v_mfma_f32_16x16x32_bf16 v[4:7], v[180:183], v[218:221], v[4:7]
	v_mfma_f32_16x16x32_bf16 v[56:59], v[176:179], v[192:195], v[56:59]
	v_mfma_f32_16x16x32_bf16 v[48:51], v[184:187], v[192:195], v[48:51]
	v_mfma_f32_16x16x32_bf16 v[40:43], v[176:179], v[206:209], v[40:43]
	v_mfma_f32_16x16x32_bf16 v[32:35], v[184:187], v[206:209], v[32:35]
	v_mfma_f32_16x16x32_bf16 v[24:27], v[176:179], v[214:217], v[24:27]
	v_mfma_f32_16x16x32_bf16 v[16:19], v[184:187], v[214:217], v[16:19]
	v_mfma_f32_16x16x32_bf16 v[8:11], v[176:179], v[222:225], v[8:11]
	v_mfma_f32_16x16x32_bf16 v[4:7], v[184:187], v[222:225], v[4:7]
	s_barrier
	s_setprio 0
	s_add_i32 s48, 0, 0x18000
	s_add_i32 s49, 0, 0x1c000
	ds_read_b128 v[132:135], v251 offset:32768
	ds_read_b128 v[158:161], v251 offset:33792
	ds_read_b128 v[162:165], v251 offset:34816
	ds_read_b128 v[166:169], v251 offset:35840
	ds_read_b128 v[170:173], v251 offset:49152
	ds_read_b128 v[176:179], v251 offset:50176
	ds_read_b128 v[180:183], v251 offset:51200
	ds_read_b128 v[184:187], v251 offset:52224
	s_add_u32 s78, s78, 0x80000
	s_addc_u32 s79, s79, 0
	s_mov_b32 m0, s5
	v_lshl_add_u64 v[240:241], s[78:79], 0, v[142:143]
	ds_read_b128 v[188:191], v175 offset:32768
	ds_read_b128 v[192:195], v175 offset:33792
	ds_read_b128 v[196:199], v175 offset:34816
	ds_read_b128 v[206:209], v175 offset:35840
	ds_read_b128 v[210:213], v175 offset:36864
	ds_read_b128 v[214:217], v175 offset:37888
	ds_read_b128 v[218:221], v175 offset:38912
	ds_read_b128 v[222:225], v175 offset:39936
	global_load_lds_dwordx4 v[240:241], off
	s_mov_b32 m0, s7
	v_lshl_add_u64 v[240:241], s[78:79], 0, v[138:139]
	global_load_lds_dwordx4 v[240:241], off
	s_waitcnt vmcnt(8) lgkmcnt(0)
	s_setprio 1
	s_barrier
	v_mfma_f32_16x16x32_bf16 v[128:131], v[132:135], v[188:191], v[128:131]
	v_mfma_f32_16x16x32_bf16 v[124:127], v[162:165], v[188:191], v[124:127]
	v_mfma_f32_16x16x32_bf16 v[116:119], v[132:135], v[196:199], v[116:119]
	v_mfma_f32_16x16x32_bf16 v[108:111], v[162:165], v[196:199], v[108:111]
	v_mfma_f32_16x16x32_bf16 v[100:103], v[132:135], v[210:213], v[100:103]
	v_mfma_f32_16x16x32_bf16 v[92:95], v[162:165], v[210:213], v[92:95]
	v_mfma_f32_16x16x32_bf16 v[84:87], v[132:135], v[218:221], v[84:87]
	v_mfma_f32_16x16x32_bf16 v[76:79], v[162:165], v[218:221], v[76:79]
	v_mfma_f32_16x16x32_bf16 v[128:131], v[158:161], v[192:195], v[128:131]
	v_mfma_f32_16x16x32_bf16 v[124:127], v[166:169], v[192:195], v[124:127]
	v_mfma_f32_16x16x32_bf16 v[116:119], v[158:161], v[206:209], v[116:119]
	v_mfma_f32_16x16x32_bf16 v[108:111], v[166:169], v[206:209], v[108:111]
	v_mfma_f32_16x16x32_bf16 v[100:103], v[158:161], v[214:217], v[100:103]
	v_mfma_f32_16x16x32_bf16 v[92:95], v[166:169], v[214:217], v[92:95]
	v_mfma_f32_16x16x32_bf16 v[84:87], v[158:161], v[222:225], v[84:87]
	v_mfma_f32_16x16x32_bf16 v[76:79], v[166:169], v[222:225], v[76:79]
	v_mfma_f32_16x16x32_bf16 v[120:123], v[170:173], v[188:191], v[120:123]
	v_mfma_f32_16x16x32_bf16 v[112:115], v[180:183], v[188:191], v[112:115]
	v_mfma_f32_16x16x32_bf16 v[104:107], v[170:173], v[196:199], v[104:107]
	v_mfma_f32_16x16x32_bf16 v[96:99], v[180:183], v[196:199], v[96:99]
	v_mfma_f32_16x16x32_bf16 v[88:91], v[170:173], v[210:213], v[88:91]
	v_mfma_f32_16x16x32_bf16 v[80:83], v[180:183], v[210:213], v[80:83]
	v_mfma_f32_16x16x32_bf16 v[72:75], v[170:173], v[218:221], v[72:75]
	v_mfma_f32_16x16x32_bf16 v[68:71], v[180:183], v[218:221], v[68:71]
	v_mfma_f32_16x16x32_bf16 v[120:123], v[176:179], v[192:195], v[120:123]
	v_mfma_f32_16x16x32_bf16 v[112:115], v[184:187], v[192:195], v[112:115]
	v_mfma_f32_16x16x32_bf16 v[104:107], v[176:179], v[206:209], v[104:107]
	v_mfma_f32_16x16x32_bf16 v[96:99], v[184:187], v[206:209], v[96:99]
	v_mfma_f32_16x16x32_bf16 v[88:91], v[176:179], v[214:217], v[88:91]
	v_mfma_f32_16x16x32_bf16 v[80:83], v[184:187], v[214:217], v[80:83]
	v_mfma_f32_16x16x32_bf16 v[72:75], v[176:179], v[222:225], v[72:75]
	v_mfma_f32_16x16x32_bf16 v[68:71], v[184:187], v[222:225], v[68:71]
	s_barrier
; #define PG8_STAGE(bufoff, gbase, voff) do { _Pragma("unroll") for (int _i = 0; _i < 2; ++_i) \
;         __builtin_amdgcn_global_load_lds((const unsigned*)((const char*)(gbase) + (voff)[_i]), (PG8_LAS unsigned*)(lds + (bufoff) + ldsw + _i * 8192), 16, 0, 0); } while (0)
; #define PG8_LDA(dst, b, h) do { _Pragma("unroll") for (int m = 0; m < 4; ++m) _Pragma("unroll") for (int k = 0; k < 2; ++k) dst[m][k] = *(const PG8_LAS bf16x8*)(lds + PG8_SA(b, h) + aoff + m * 2048 + k * 1024); } while (0)
; #define PG8_MMA(ai, bj, At, Bt) do { __builtin_amdgcn_s_setprio(1); _Pragma("unroll") for (int m = 0; m < 4; ++m) _Pragma("unroll") for (int n = 0; n < 2; ++n) _Pragma("unroll") for (int k = 0; k < 2; ++k) \
;         acc[ai][bj][m][n] = __builtin_amdgcn_mfma_f32_16x16x32_bf16(Bt[n][k], At[m][k], acc[ai][bj][m][n], 0, 0, 0); __builtin_amdgcn_s_setprio(0); } while (0)
; #define PG8_WAIT_V(n) asm volatile("s_waitcnt vmcnt(" #n ")" ::: "memory")
; #define PG8_WAIT_L(n) asm volatile("s_waitcnt lgkmcnt(" #n ")" ::: "memory")
; #define PG8_BAR __builtin_amdgcn_s_barrier()
; #define PG8_SCHED __builtin_amdgcn_sched_barrier(0)
;     ...
;             PG8_LDA(At, 1, 1); PG8_STAGE(PG8_SB(1, 0), b3, voffB); PG8_STAGE(PG8_SB(1, 1), b3 + hstep, voffB); PG8_STAGE(PG8_SA(1, 0), a3, voffA);
;             PG8_WAIT_V(8); PG8_WAIT_L(0); PG8_BAR; PG8_MMA(1, 0, At, B0); PG8_MMA(1, 1, At, B1); PG8_BAR; PG8_SCHED;
	s_setprio 0
	s_add_i32 s48, s48, s0
	v_lshl_add_u64 v[232:233], v[232:233], 0, s[66:67]
	s_mov_b32 m0, s48
	ds_read_b128 v[188:191], v175 offset:49152
	ds_read_b128 v[192:195], v175 offset:50176
	ds_read_b128 v[196:199], v175 offset:51200
	ds_read_b128 v[206:209], v175 offset:52224
	ds_read_b128 v[210:213], v175 offset:53248
	ds_read_b128 v[214:217], v175 offset:54272
	ds_read_b128 v[218:221], v175 offset:55296
	ds_read_b128 v[222:225], v175 offset:56320
	global_load_lds_dwordx4 v[232:233], off
	s_add_i32 m0, s48, 0x2000
	s_add_u32 s76, s76, 0x80080
	v_lshl_add_u64 v[232:233], v[234:235], 0, s[66:67]
	s_addc_u32 s77, s77, 0
	s_add_i32 s48, s49, s0
	global_load_lds_dwordx4 v[232:233], off
	s_mov_b32 m0, s48
	v_lshl_add_u64 v[232:233], s[76:77], 0, v[140:141]
	global_load_lds_dwordx4 v[232:233], off
	s_add_i32 m0, s48, 0x2000
	v_lshl_add_u64 v[232:233], s[76:77], 0, v[136:137]
	global_load_lds_dwordx4 v[232:233], off
	v_lshl_add_u64 v[232:233], v[236:237], 0, s[66:67]
	s_mov_b32 m0, s21
	s_nop 0
	global_load_lds_dwordx4 v[232:233], off
	v_lshl_add_u64 v[232:233], v[238:239], 0, s[66:67]
	s_mov_b32 m0, s23
	s_nop 0
	global_load_lds_dwordx4 v[232:233], off
	s_waitcnt vmcnt(8) lgkmcnt(0)
	s_setprio 1
	s_barrier
	v_mfma_f32_16x16x32_bf16 v[64:67], v[132:135], v[188:191], v[64:67]
	v_mfma_f32_16x16x32_bf16 v[60:63], v[162:165], v[188:191], v[60:63]
	v_mfma_f32_16x16x32_bf16 v[52:55], v[132:135], v[196:199], v[52:55]
	v_mfma_f32_16x16x32_bf16 v[44:47], v[162:165], v[196:199], v[44:47]
	v_mfma_f32_16x16x32_bf16 v[36:39], v[132:135], v[210:213], v[36:39]
	v_mfma_f32_16x16x32_bf16 v[28:31], v[162:165], v[210:213], v[28:31]
	v_mfma_f32_16x16x32_bf16 v[20:23], v[132:135], v[218:221], v[20:23]
	v_mfma_f32_16x16x32_bf16 v[12:15], v[162:165], v[218:221], v[12:15]
	v_mfma_f32_16x16x32_bf16 v[64:67], v[158:161], v[192:195], v[64:67]
	v_mfma_f32_16x16x32_bf16 v[60:63], v[166:169], v[192:195], v[60:63]
	v_mfma_f32_16x16x32_bf16 v[52:55], v[158:161], v[206:209], v[52:55]
	v_mfma_f32_16x16x32_bf16 v[44:47], v[166:169], v[206:209], v[44:47]
	v_mfma_f32_16x16x32_bf16 v[36:39], v[158:161], v[214:217], v[36:39]
	v_mfma_f32_16x16x32_bf16 v[28:31], v[166:169], v[214:217], v[28:31]
	v_mfma_f32_16x16x32_bf16 v[20:23], v[158:161], v[222:225], v[20:23]
	v_mfma_f32_16x16x32_bf16 v[12:15], v[166:169], v[222:225], v[12:15]
	v_mfma_f32_16x16x32_bf16 v[56:59], v[170:173], v[188:191], v[56:59]
	v_mfma_f32_16x16x32_bf16 v[48:51], v[180:183], v[188:191], v[48:51]
	v_mfma_f32_16x16x32_bf16 v[40:43], v[170:173], v[196:199], v[40:43]
	v_mfma_f32_16x16x32_bf16 v[32:35], v[180:183], v[196:199], v[32:35]
	v_mfma_f32_16x16x32_bf16 v[24:27], v[170:173], v[210:213], v[24:27]
	v_mfma_f32_16x16x32_bf16 v[16:19], v[180:183], v[210:213], v[16:19]
	v_mfma_f32_16x16x32_bf16 v[8:11], v[170:173], v[218:221], v[8:11]
	v_mfma_f32_16x16x32_bf16 v[4:7], v[180:183], v[218:221], v[4:7]
	v_mfma_f32_16x16x32_bf16 v[56:59], v[176:179], v[192:195], v[56:59]
	v_mfma_f32_16x16x32_bf16 v[48:51], v[184:187], v[192:195], v[48:51]
	v_mfma_f32_16x16x32_bf16 v[40:43], v[176:179], v[206:209], v[40:43]
	v_mfma_f32_16x16x32_bf16 v[32:35], v[184:187], v[206:209], v[32:35]
	v_mfma_f32_16x16x32_bf16 v[24:27], v[176:179], v[214:217], v[24:27]
	v_mfma_f32_16x16x32_bf16 v[16:19], v[184:187], v[214:217], v[16:19]
	v_mfma_f32_16x16x32_bf16 v[8:11], v[176:179], v[222:225], v[8:11]
	v_mfma_f32_16x16x32_bf16 v[4:7], v[184:187], v[222:225], v[4:7]
	s_barrier
	s_setprio 0
	s_add_i32 s59, s59, 2
	s_add_u32 s68, s68, 0x100
	s_addc_u32 s69, s69, 0
	s_add_u32 s56, s56, 0x100
	s_addc_u32 s58, s58, 0
	s_cmp_gt_u32 s59, 29
	s_cbranch_scc0 .LBB0_753
	s_and_b64 vcc, exec, s[12:13]
	s_cbranch_vccz .LBB0_756
	s_barrier

; #define VMW() asm volatile("s_waitcnt vmcnt(0)" ::: "memory")
; #define SWRITE_HK(bf) do { *(bf16x8*)(K_lds + (bf) * SHM_K + kws) = S.st_k0; *(bf16x8*)(K_lds + (bf) * SHM_K + kws + 32 * 256) = S.st_k1; \
;                            if constexpr (PE) *(bf16x8*)(lds + OFF_KPE + (bf) * SHM_KPE + pws) = S.st_kp; } while (0)
; template <bool PE>
; __device__ __forceinline__ void swa_prime(const BlockRef& cur, const Prm& P, char* lds, Seam<PE>& S) {
;     int tid_ = threadIdx.x; asm volatile("" : "+v"(tid_));
;     const int tid = tid_, wid = __builtin_amdgcn_readfirstlane(tid >> 6), lane = tid & 63, r32 = lane & 31, hi = lane >> 5;
;     const int sr = tid >> 4, sc = (tid & 15) * 8, kws = KSWZ(sr, sc * 2); char* K_lds = lds + OFF_K;
;     const int pr = tid >> 3, pc = (tid & 7) * 8, pws = pr * KPE_ROW + (tid & 7) * 16;
;     const unsigned kvoff = (unsigned)(sr * P.kvs + sc) * 2u, kpoff = (unsigned)(pr * P.kpes + pc) * 2u, qoff = (unsigned)((wid * QBLK + r32) * P.qs + hi * 8) * 2u, qpoff = (unsigned)((wid * QBLK + r32) * P.qpes + hi * 8) * 2u;
;     const int kb0 = swa_jlo(cur.P0, P.W) * KVBLK;
; #pragma unroll
;     for (int d0 = 0; d0 < 8; ++d0) S.qr[d0] = LDG(cur.Q, qoff + d0 * 32);
;     if constexpr (PE) {
; #pragma unroll
;         for (int d0 = 0; d0 < 4; ++d0) *(bf16x8*)(lds + OFF_QPE + wid * 4096 + d0 * 1024 + lane * 16) = LDG(cur.Qpe, qpoff + d0 * 32);
;     }
;     SLOAD_H(cur, kb0); VMW(); SWRITE_HK(0);
;     __syncthreads();
; }
.LBB0_818:
	s_lshl_b32 s77, s76, 1
	s_sub_i32 s82, 4, s77
	s_ashr_i32 s0, s3, s82
	s_lshl_b32 s1, -1, s82
	s_not_b32 s83, s1
	s_andn2_b32 s9, s3, s1
	s_ashr_i32 s1, s0, 4
	s_sub_i32 s4, 12, s77
	s_ashr_i32 s12, s1, s77
	s_lshl_b32 s1, s1, s4
	s_lshl_b32 s0, s0, 2
	s_and_b32 s13, s1, 0xffe
	s_lshl_b32 s8, s9, 8
	s_mul_i32 s5, s76, 0xc0
	s_and_b32 s21, s0, 60
	s_add_i32 s20, s13, s8
	s_or_b32 s0, s21, s5
	s_ashr_i32 s23, s12, 31
	s_add_u32 s0, s0, s12
	s_addc_u32 s1, 0, s23
	s_lshl_b64 s[0:1], s[0:1], 12
	s_add_u32 s10, s0, s20
	s_addc_u32 s11, s1, 0
	s_lshl_b64 s[10:11], s[10:11], 8
	s_add_u32 s84, s50, s10
	s_addc_u32 s85, s51, s11
	s_or_b32 s0, s0, s13
	s_lshl_b64 s[0:1], s[0:1], 8
	s_add_u32 s90, s7, s0
	s_addc_u32 s91, s73, s1
	s_add_u32 s94, s90, 0x4000000
	s_addc_u32 s95, s91, 0
	s_lshl_b32 s59, s76, 6
	s_or_b32 s0, s21, s59
	s_add_u32 s0, s0, s12
	s_addc_u32 s1, 0, s23
	s_lshl_b64 s[10:11], s[0:1], 12
	s_add_u32 s10, s10, s20
	s_addc_u32 s11, s11, 0
	s_lshl_b64 s[10:11], s[10:11], 8
	s_add_u32 s62, s78, s10
	s_addc_u32 s63, s79, s11
	s_lshl_b64 s[0:1], s[0:1], 14
	s_add_u32 s0, s14, s0
	s_addc_u32 s1, s15, s1
	s_lshl_b32 s10, s20, 2
	v_mov_b32_e32 v3, v0
	s_add_u32 s96, s0, s10
	s_addc_u32 s97, s1, 0
	v_readfirstlane_b32 s0, v3
	s_lshr_b32 s0, s0, 1
	s_and_b32 s0, s0, 0xffffe0
	v_and_or_b32 v4, v3, 31, s0
	s_add_i32 s0, s8, 0xffffff80
	s_cmp_lg_u32 s9, 0
	s_cselect_b32 s44, s0, 0
	v_lshlrev_b32_e32 v9, 4, v3
	s_movk_i32 s0, 0xff00
	v_bitop3_b32 v200, v9, s0, v228 bitop3:0xe0
	s_lshl_b64 s[0:1], s[44:45], 8
	s_add_u32 s10, s90, s0
	v_lshrrev_b32_e32 v5, 1, v3
	s_addc_u32 s11, s91, s1
	v_and_b32_e32 v5, 16, v5
	s_add_u32 s0, s94, s0
	v_lshl_or_b32 v8, v4, 8, v5
	s_addc_u32 s1, s95, s1
	global_load_dwordx4 v[166:169], v8, s[84:85]
	global_load_dwordx4 v[162:165], v8, s[84:85] offset:32
	global_load_dwordx4 v[114:117], v200, s[0:1]
	global_load_dwordx4 v[122:125], v200, s[10:11]
	v_lshl_add_u64 v[4:5], s[0:1], 0, v[200:201]
	v_add_co_u32_e32 v4, vcc, s43, v4
	v_lshl_add_u64 v[6:7], s[10:11], 0, v[200:201]
	s_nop 0
	v_addc_co_u32_e32 v5, vcc, 0, v5, vcc
	v_add_co_u32_e32 v6, vcc, 0x2000, v6
	v_and_b32_e32 v3, 0xf0, v3
	s_nop 0
	v_addc_co_u32_e32 v7, vcc, 0, v7, vcc
	global_load_dwordx4 v[118:121], v[4:5], off
	global_load_dwordx4 v[126:129], v[6:7], off
	global_load_dwordx4 v[174:177], v8, s[84:85] offset:64
	global_load_dwordx4 v[170:173], v8, s[84:85] offset:96
	global_load_dwordx4 v[158:161], v8, s[84:85] offset:128
	global_load_dwordx4 v[154:157], v8, s[84:85] offset:160
	global_load_dwordx4 v[150:153], v8, s[84:85] offset:192
	global_load_dwordx4 v[146:149], v8, s[84:85] offset:224
	s_movk_i32 s0, 0xf0
	s_waitcnt vmcnt(0)
	v_and_b32_e32 v4, 0xffffff00, v9
	v_bitop3_b32 v3, v9, v3, s0 bitop3:0x6c
	s_mov_b32 s75, 0
	v_add3_u32 v3, 0, v4, v3
	s_mov_b32 s0, s8
	s_mov_b64 s[70:71], s[94:95]
	s_mov_b64 s[88:89], s[62:63]
	s_mov_b64 s[86:87], s[96:97]
	s_lshr_b32 s58, 64, s77
	s_mov_b64 s[60:61], s[90:91]
	ds_write_b128 v3, v[122:125] offset:32768
	ds_write_b128 v3, v[126:129] offset:40960
	s_waitcnt lgkmcnt(0)
	s_barrier
	s_branch .LBB0_820

; #define SBAR() __builtin_amdgcn_sched_barrier(0)
; #define VMW() asm volatile("s_waitcnt vmcnt(0)" ::: "memory")
; #define SWRITE_H(bf) do { SWRITE_HV(bf); SWRITE_HK(bf); } while (0)
; #define ACT(t) (KBASE(t) <= qlo + QBLK - 1 && KBASE(t) + KVBLK - 1 >= qlo - W + 1)
; #define MASKT(P0_, P1_, t) do { const int kb_ = KBASE(t); if ((!SK || ACT(t)) && (kb_ + KVBLK - 1 > qlo || kb_ <= qlo + QBLK - 1 - W)) mask_tile(P0_, P1_, qm - kb_, (unsigned)W); } while (0)
; __device__ __forceinline__ void partialSM(f32x16& p0, f32x16& p1, float& m_reg, float& mn, float& alpha, const float scale) {
;     float pmax = p0[0]; for (int r = 1; r < 16; ++r) pmax = fmaxf(pmax, p0[r]); for (int r = 0; r < 16; ++r) pmax = fmaxf(pmax, p1[r]);
;     { auto rr = __builtin_amdgcn_permlane32_swap(__float_as_uint(pmax), __float_as_uint(pmax), false, false);
;       pmax = fmaxf(__uint_as_float(rr[0]), __uint_as_float(rr[1])); }
;     const float C2 = 1.4426950408889634f * scale;
;     if (__builtin_expect(__all((pmax - m_reg) * scale <= THR), 1)) { mn = m_reg; alpha = 1.f; }
;     else { mn = fmaxf(m_reg, pmax); alpha = __builtin_amdgcn_exp2f((m_reg - mn) * C2); m_reg = mn; }
; template <bool PE, bool SK, bool LSE, bool EARLY>
; __device__ __forceinline__ void swa_block(const BlockRef& cur, const BlockRef& nxt, const Prm& P, char* lds, Seam<PE>& S) {
;     ...
;     SBAR(); qkt<0, SK, PE>(pA0, pA1, lds, r32, hi, wid, lane, S.qr, ACT(0));
;     MASKT(pA0, pA1, 0); partialSM(pA0, pA1, m_reg, mnA, alA, P.scale);
;     if (NT > 1) { VMW(); SWRITE_H(1); }
.LBB0_830:
	v_and_b32_e32 v4, 0xf0, v50
	v_bitop3_b32 v5, v51, v52, v4 bitop3:0xde
	v_max_f32_e32 v4, v35, v35
	v_max_f32_e32 v6, v34, v34
	v_max_f32_e32 v4, v6, v4
	v_max3_f32 v4, v4, v36, v37
	v_max3_f32 v4, v4, v38, v39
	v_max3_f32 v4, v4, v40, v41
	v_max3_f32 v4, v4, v42, v43
	v_max3_f32 v4, v4, v44, v45
	v_max3_f32 v4, v4, v46, v47
	v_max3_f32 v4, v4, v48, v49
	v_max3_f32 v4, v4, v18, v19
	v_max3_f32 v4, v4, v20, v21
	v_max3_f32 v4, v4, v22, v23
	v_max3_f32 v4, v4, v24, v25
	v_max3_f32 v4, v4, v26, v27
	v_max3_f32 v4, v4, v28, v29
	v_max3_f32 v4, v4, v30, v31
	v_max3_f32 v4, v4, v32, v33
	v_mov_b32_e32 v6, v4
	s_nop 1
	v_permlane32_swap_b32_e32 v4, v6
	v_max_f32_e32 v6, v6, v6
	v_max_f32_e32 v4, v4, v4
	v_max_f32_e32 v4, v4, v6
	v_add_f32_e32 v6, 0x7149f2ca, v4
	v_mul_f32_e32 v6, 0x3db504f3, v6
	v_cmp_ge_f32_e32 vcc, s35, v6
	s_cmp_eq_u64 vcc, exec
	s_cselect_b64 s[8:9], -1, 0
	s_andn2_b64 vcc, exec, s[10:11]
	v_add_u32_e32 v210, 0, v5
	s_cbranch_vccnz .LBB0_832
	s_waitcnt vmcnt(0)
	ds_write_b128 v215, v[114:117] offset:16384
	ds_write_b128 v216, v[118:121] offset:16384
	ds_write_b128 v210, v[122:125] offset:49152
	ds_write_b128 v210, v[126:129] offset:57344

; __device__ __forceinline__ void finishSM(f32x16& p0, f32x16& p1, float alpha, float& l_reg, bf16x8& pa0, bf16x8& pa1, bf16x8& pa2, bf16x8& pa3) {
;     for (int r = 0; r < 16; ++r) p1[r] = __builtin_amdgcn_exp2f(p1[r]);
;     float ps = 0; for (int r = 0; r < 16; ++r) ps += p0[r]; for (int r = 0; r < 16; ++r) ps += p1[r];
;     { auto rr = __builtin_amdgcn_permlane32_swap(__float_as_uint(ps), __float_as_uint(ps), false, false);
;       ps = __uint_as_float(rr[0]) + __uint_as_float(rr[1]); }
;     l_reg = l_reg * alpha + ps;
.LBB0_843:
	v_add_f32_e32 v222, v3, v16
	v_max_f32_e32 v3, v99, v99
	v_max_f32_e32 v4, v98, v98
	v_max_f32_e32 v3, v4, v3
	v_max3_f32 v3, v3, v100, v101
	v_max3_f32 v3, v3, v102, v103
	v_max3_f32 v3, v3, v104, v105
	v_max3_f32 v3, v3, v106, v107
	v_max3_f32 v3, v3, v108, v109
	v_max3_f32 v3, v3, v110, v111
	v_max3_f32 v3, v3, v112, v113
	v_max3_f32 v3, v3, v82, v83
	v_max3_f32 v3, v3, v84, v85
	v_max3_f32 v3, v3, v86, v87
	v_max3_f32 v3, v3, v88, v89
	v_max3_f32 v3, v3, v90, v91
	v_max3_f32 v3, v3, v92, v93
	v_max3_f32 v3, v3, v94, v95
	v_max3_f32 v3, v3, v96, v97
	v_mov_b32_e32 v4, v3
	s_nop 1
	v_permlane32_swap_b32_e32 v3, v4
	v_max_f32_e32 v4, v4, v4
	v_max_f32_e32 v3, v3, v3
	v_max_f32_e32 v3, v3, v4
	v_max_f32_e32 v5, v195, v195
	v_fmac_f32_e32 v222, v194, v196
	v_max_f32_e32 v194, v5, v3
	v_sub_f32_e32 v4, v3, v195
	v_sub_f32_e32 v3, v195, v194
	v_mul_f32_e32 v3, 0x3e0293ee, v3
	v_mul_f32_e32 v4, 0x3db504f3, v4
	v_exp_f32_e32 v3, v3
	v_cmp_ge_f32_e32 vcc, s35, v4
	s_cmp_eq_u64 vcc, exec
	s_cselect_b64 s[10:11], -1, 0
	v_cndmask_b32_e64 v198, v3, 1.0, s[10:11]
	s_barrier
	s_waitcnt vmcnt(0)
	v_cmp_gt_f32_e32 vcc, 1.0, v198
	v_cmp_neq_f32_e64 s[12:13], 0, v222
	s_and_b64 vcc, vcc, s[12:13]
	ds_write_b128 v215, v[178:181]
	ds_write_b128 v216, v[182:185]
	ds_write_b128 v210, v[186:189] offset:32768
	ds_write_b128 v210, v[190:193] offset:40960
	s_cbranch_vccz .LBB0_845
	v_pk_mul_f32 v[80:81], v[80:81], v[198:199] op_sel_hi:[1,0]
	v_pk_mul_f32 v[78:79], v[78:79], v[198:199] op_sel_hi:[1,0]
	v_pk_mul_f32 v[76:77], v[76:77], v[198:199] op_sel_hi:[1,0]
	v_pk_mul_f32 v[74:75], v[74:75], v[198:199] op_sel_hi:[1,0]
	v_pk_mul_f32 v[72:73], v[72:73], v[198:199] op_sel_hi:[1,0]
	v_pk_mul_f32 v[70:71], v[70:71], v[198:199] op_sel_hi:[1,0]
	v_pk_mul_f32 v[68:69], v[68:69], v[198:199] op_sel_hi:[1,0]
	v_pk_mul_f32 v[66:67], v[66:67], v[198:199] op_sel_hi:[1,0]
	v_pk_mul_f32 v[64:65], v[64:65], v[198:199] op_sel_hi:[1,0]
	v_pk_mul_f32 v[62:63], v[62:63], v[198:199] op_sel_hi:[1,0]
	v_pk_mul_f32 v[60:61], v[60:61], v[198:199] op_sel_hi:[1,0]
	v_pk_mul_f32 v[58:59], v[58:59], v[198:199] op_sel_hi:[1,0]
	v_pk_mul_f32 v[56:57], v[56:57], v[198:199] op_sel_hi:[1,0]
	v_pk_mul_f32 v[54:55], v[54:55], v[198:199] op_sel_hi:[1,0]
	v_pk_mul_f32 v[52:53], v[52:53], v[198:199] op_sel_hi:[1,0]
	v_pk_mul_f32 v[50:51], v[50:51], v[198:199] op_sel_hi:[1,0]
	v_pk_mul_f32 v[48:49], v[48:49], v[198:199] op_sel_hi:[1,0]
	v_pk_mul_f32 v[46:47], v[46:47], v[198:199] op_sel_hi:[1,0]
	v_pk_mul_f32 v[44:45], v[44:45], v[198:199] op_sel_hi:[1,0]
	v_pk_mul_f32 v[42:43], v[42:43], v[198:199] op_sel_hi:[1,0]
	v_pk_mul_f32 v[40:41], v[40:41], v[198:199] op_sel_hi:[1,0]
	v_pk_mul_f32 v[38:39], v[38:39], v[198:199] op_sel_hi:[1,0]
	v_pk_mul_f32 v[36:37], v[36:37], v[198:199] op_sel_hi:[1,0]
	v_pk_mul_f32 v[34:35], v[34:35], v[198:199] op_sel_hi:[1,0]
	v_pk_mul_f32 v[32:33], v[32:33], v[198:199] op_sel_hi:[1,0]
	v_pk_mul_f32 v[30:31], v[30:31], v[198:199] op_sel_hi:[1,0]
	v_pk_mul_f32 v[28:29], v[28:29], v[198:199] op_sel_hi:[1,0]
	v_pk_mul_f32 v[26:27], v[26:27], v[198:199] op_sel_hi:[1,0]
	v_pk_mul_f32 v[24:25], v[24:25], v[198:199] op_sel_hi:[1,0]
	v_pk_mul_f32 v[22:23], v[22:23], v[198:199] op_sel_hi:[1,0]
	v_pk_mul_f32 v[20:21], v[20:21], v[198:199] op_sel_hi:[1,0]
	v_pk_mul_f32 v[18:19], v[18:19], v[198:199] op_sel_hi:[1,0]

.LBB0_855:
	v_max_f32_e32 v4, v131, v131
	v_max_f32_e32 v5, v130, v130
	v_max_f32_e32 v4, v5, v4
	v_max3_f32 v4, v4, v132, v133
	v_max3_f32 v4, v4, v134, v135
	v_max3_f32 v4, v4, v136, v137
	v_max3_f32 v4, v4, v138, v139
	v_max3_f32 v4, v4, v140, v141
	v_max3_f32 v4, v4, v142, v143
	v_max3_f32 v4, v4, v144, v145
	v_max3_f32 v4, v4, v114, v115
	v_max3_f32 v4, v4, v116, v117
	v_max3_f32 v4, v4, v118, v119
	v_max3_f32 v4, v4, v120, v121
	v_max3_f32 v4, v4, v122, v123
	v_max3_f32 v4, v4, v124, v125
	v_max3_f32 v4, v4, v126, v127
	v_max3_f32 v4, v4, v128, v129
	v_mov_b32_e32 v5, v4
	s_nop 1
	v_permlane32_swap_b32_e32 v4, v5
	v_max_f32_e32 v5, v5, v5
	v_max_f32_e32 v4, v4, v4
	v_max_f32_e32 v4, v4, v5
	v_sub_f32_e32 v5, v4, v3
	v_mul_f32_e32 v5, 0x3db504f3, v5
	v_cmp_ge_f32_e32 vcc, s35, v5
	s_cmp_eq_u64 vcc, exec
	s_cselect_b64 s[8:9], -1, 0
	s_andn2_b64 vcc, exec, s[12:13]
	s_barrier
	s_cbranch_vccnz .LBB0_857
	s_waitcnt vmcnt(0)
	ds_write_b128 v215, v[178:181] offset:16384
	ds_write_b128 v216, v[182:185] offset:16384
	ds_write_b128 v210, v[186:189] offset:49152
	ds_write_b128 v210, v[190:193] offset:57344

; #define SBAR() __builtin_amdgcn_sched_barrier(0)
; __device__ __forceinline__ unsigned cvtpk(float lo, float hi) { unsigned r; asm volatile("v_cvt_pk_bf16_f32 %0, %1, %2" : "=v"(r) : "v"(lo), "v"(hi)); return r; }
; #define VMW() asm volatile("s_waitcnt vmcnt(0)" ::: "memory")
; #define ATT_G __attribute__((address_space(1)))
; #define SWRITE_HK(bf) do { *(bf16x8*)(K_lds + (bf) * SHM_K + kws) = S.st_k0; *(bf16x8*)(K_lds + (bf) * SHM_K + kws + 32 * 256) = S.st_k1; \
;                            if constexpr (PE) *(bf16x8*)(lds + OFF_KPE + (bf) * SHM_KPE + pws) = S.st_kp; } while (0)
; template <bool PE, bool SK, bool LSE, bool EARLY>
; __device__ __forceinline__ void swa_block(const BlockRef& cur, const BlockRef& nxt, const Prm& P, char* lds, Seam<PE>& S) {
;     ...
;     SBAR();
;     VMW(); SWRITE_HK(0);
;     if constexpr (PE) {
; #pragma unroll
;         for (int d0 = 0; d0 < 4; ++d0) *(bf16x8*)(lds + OFF_QPE + wid * 4096 + d0 * 1024 + lane * 16) = qpn[d0];
;     }
;     SBAR();
;     { const float rl = __builtin_amdgcn_rcpf(l_reg);
;       ATT_G char* ob = (ATT_G char*)cur.O + (unsigned)(((wid * QBLK + r32) * P.os + 8 * hi) * 2);
; #pragma unroll
;       for (int d0 = 0; d0 < 4; ++d0)
; #pragma unroll
;         for (int j = 0; j < 2; ++j) {
;             const unsigned ax = cvtpk(o[d0][8 * j + 0] * rl, o[d0][8 * j + 1] * rl), ay = cvtpk(o[d0][8 * j + 2] * rl, o[d0][8 * j + 3] * rl);
;             const unsigned bx = cvtpk(o[d0][8 * j + 4] * rl, o[d0][8 * j + 5] * rl), by = cvtpk(o[d0][8 * j + 6] * rl, o[d0][8 * j + 7] * rl);
;             auto rx = __builtin_amdgcn_permlane32_swap(ax, bx, false, false); auto ry = __builtin_amdgcn_permlane32_swap(ay, by, false, false);
;             const u32x4 w = {rx[0], ry[0], rx[1], ry[1]};
;             *(ATT_G u32x4*)(ob + d0 * 64 + j * 32) = w; } }
;     if constexpr (LSE) { if (hi == 0) *(ATT_G float*)((ATT_G char*)cur.Lse + (unsigned)((wid * QBLK + r32) * P.lses) * 4u) = m_reg * P.scale + __logf(l_reg); }
.LBB0_876:
	s_waitcnt vmcnt(0)
	ds_write_b128 v210, v[122:125] offset:32768
	ds_write_b128 v210, v[126:129] offset:40960
	v_rcp_f32_e32 v10, v17
	v_lshl_add_u64 v[8:9], s[62:63], 0, v[200:201]
	v_cmp_gt_u32_e32 vcc, 32, v199
	v_mul_f32_e32 v4, v66, v10
	v_mul_f32_e32 v5, v67, v10
	v_mul_f32_e32 v6, v68, v10
	v_cvt_pk_bf16_f32 v4, v4, v5
	v_mul_f32_e32 v5, v69, v10
	v_cvt_pk_bf16_f32 v5, v6, v5
	v_mul_f32_e32 v6, v70, v10
	v_mul_f32_e32 v7, v71, v10
	v_cvt_pk_bf16_f32 v6, v6, v7
	v_mul_f32_e32 v7, v72, v10
	v_mul_f32_e32 v11, v73, v10
	v_cvt_pk_bf16_f32 v7, v7, v11
	v_permlane32_swap_b32_e32 v4, v6
	v_permlane32_swap_b32_e32 v5, v7
	global_store_dwordx4 v[8:9], v[4:7], off
	v_mul_f32_e32 v11, v81, v10
	s_nop 0
	v_mul_f32_e32 v4, v74, v10
	v_mul_f32_e32 v5, v75, v10
	v_cvt_pk_bf16_f32 v4, v4, v5
	v_mul_f32_e32 v5, v76, v10
	v_mul_f32_e32 v6, v77, v10
	v_cvt_pk_bf16_f32 v5, v5, v6
	v_mul_f32_e32 v6, v78, v10
	v_mul_f32_e32 v7, v79, v10
	v_cvt_pk_bf16_f32 v6, v6, v7
	v_mul_f32_e32 v7, v80, v10
	v_cvt_pk_bf16_f32 v7, v7, v11
	v_permlane32_swap_b32_e32 v4, v6
	s_nop 0
	v_permlane32_swap_b32_e32 v5, v7
	global_store_dwordx4 v[8:9], v[4:7], off offset:32
	v_mul_f32_e32 v11, v57, v10
	s_nop 0
	v_mul_f32_e32 v4, v50, v10
	v_mul_f32_e32 v5, v51, v10
	v_cvt_pk_bf16_f32 v4, v4, v5
	v_mul_f32_e32 v5, v52, v10
	v_mul_f32_e32 v6, v53, v10
	v_cvt_pk_bf16_f32 v5, v5, v6
	v_mul_f32_e32 v6, v54, v10
	v_mul_f32_e32 v7, v55, v10
	v_cvt_pk_bf16_f32 v6, v6, v7
	v_mul_f32_e32 v7, v56, v10
	v_cvt_pk_bf16_f32 v7, v7, v11
	v_permlane32_swap_b32_e32 v4, v6
	s_nop 0
	v_permlane32_swap_b32_e32 v5, v7
	global_store_dwordx4 v[8:9], v[4:7], off offset:64
	v_mul_f32_e32 v11, v65, v10
	s_nop 0
	v_mul_f32_e32 v4, v58, v10
	v_mul_f32_e32 v5, v59, v10
	v_cvt_pk_bf16_f32 v4, v4, v5
	v_mul_f32_e32 v5, v60, v10
	v_mul_f32_e32 v6, v61, v10
	v_cvt_pk_bf16_f32 v5, v5, v6
	v_mul_f32_e32 v6, v62, v10
	v_mul_f32_e32 v7, v63, v10
	v_cvt_pk_bf16_f32 v6, v6, v7
	v_mul_f32_e32 v7, v64, v10
	v_cvt_pk_bf16_f32 v7, v7, v11
	v_permlane32_swap_b32_e32 v4, v6
	s_nop 0
	v_permlane32_swap_b32_e32 v5, v7
	global_store_dwordx4 v[8:9], v[4:7], off offset:96
	v_mul_f32_e32 v11, v41, v10
	s_nop 0
	v_mul_f32_e32 v4, v34, v10
	v_mul_f32_e32 v5, v35, v10
	v_cvt_pk_bf16_f32 v4, v4, v5
	v_mul_f32_e32 v5, v36, v10
	v_mul_f32_e32 v6, v37, v10
	v_cvt_pk_bf16_f32 v5, v5, v6
	v_mul_f32_e32 v6, v38, v10
	v_mul_f32_e32 v7, v39, v10
	v_cvt_pk_bf16_f32 v6, v6, v7
	v_mul_f32_e32 v7, v40, v10
	v_cvt_pk_bf16_f32 v7, v7, v11
	v_permlane32_swap_b32_e32 v4, v6
	s_nop 0
	v_permlane32_swap_b32_e32 v5, v7
	global_store_dwordx4 v[8:9], v[4:7], off offset:128
	v_mul_f32_e32 v11, v49, v10
	s_nop 0
	v_mul_f32_e32 v4, v42, v10
	v_mul_f32_e32 v5, v43, v10
	v_cvt_pk_bf16_f32 v4, v4, v5
	v_mul_f32_e32 v5, v44, v10
	v_mul_f32_e32 v6, v45, v10
	v_cvt_pk_bf16_f32 v5, v5, v6
	v_mul_f32_e32 v6, v46, v10
	v_mul_f32_e32 v7, v47, v10
	v_cvt_pk_bf16_f32 v6, v6, v7
	v_mul_f32_e32 v7, v48, v10
	v_cvt_pk_bf16_f32 v7, v7, v11
	v_permlane32_swap_b32_e32 v4, v6
	s_nop 0
	v_permlane32_swap_b32_e32 v5, v7
	global_store_dwordx4 v[8:9], v[4:7], off offset:160
	v_mul_f32_e32 v11, v25, v10
	s_nop 0
	v_mul_f32_e32 v4, v18, v10
	v_mul_f32_e32 v5, v19, v10
	v_cvt_pk_bf16_f32 v4, v4, v5
	v_mul_f32_e32 v5, v20, v10
	v_mul_f32_e32 v6, v21, v10
	v_cvt_pk_bf16_f32 v5, v5, v6
	v_mul_f32_e32 v6, v22, v10
	v_mul_f32_e32 v7, v23, v10
	v_cvt_pk_bf16_f32 v6, v6, v7
	v_mul_f32_e32 v7, v24, v10
	v_cvt_pk_bf16_f32 v7, v7, v11
	v_permlane32_swap_b32_e32 v4, v6
	s_nop 0
	v_permlane32_swap_b32_e32 v5, v7
	global_store_dwordx4 v[8:9], v[4:7], off offset:192
	s_nop 1
	v_mul_f32_e32 v4, v26, v10
	v_mul_f32_e32 v5, v27, v10
	v_cvt_pk_bf16_f32 v4, v4, v5
	v_mul_f32_e32 v5, v28, v10
	v_mul_f32_e32 v6, v29, v10
	v_cvt_pk_bf16_f32 v5, v5, v6
	v_mul_f32_e32 v6, v30, v10
	v_mul_f32_e32 v7, v31, v10
	v_cvt_pk_bf16_f32 v6, v6, v7
	v_mul_f32_e32 v7, v32, v10
	v_mul_f32_e32 v10, v33, v10
	v_cvt_pk_bf16_f32 v7, v7, v10
	v_permlane32_swap_b32_e32 v4, v6
	v_permlane32_swap_b32_e32 v5, v7
	global_store_dwordx4 v[8:9], v[4:7], off offset:224
	s_and_saveexec_b64 s[10:11], vcc
	s_cbranch_execz .LBB0_819
	s_mov_b32 s1, 0x800000
	v_cmp_gt_f32_e32 vcc, s1, v17
	s_mov_b32 s1, 0x3f317217
	v_lshlrev_b32_e32 v3, 2, v3
	v_cndmask_b32_e64 v4, 0, 32, vcc
	v_ldexp_f32 v4, v17, v4
	v_log_f32_e32 v4, v4
	s_nop 0
	v_mul_f32_e32 v5, 0x3f317217, v4
	v_fma_f32 v5, v4, s1, -v5
	v_fmac_f32_e32 v5, 0x3377d1cf, v4
	s_mov_b32 s1, 0x7f800000
	v_fmac_f32_e32 v5, 0x3f317217, v4
	v_cmp_lt_f32_e64 s[8:9], |v4|, s1
	s_nop 1
	v_cndmask_b32_e64 v4, v4, v5, s[8:9]
	v_mov_b32_e32 v5, 0x41b17218
	v_cndmask_b32_e32 v5, 0, v5, vcc
	v_sub_f32_e32 v4, v4, v5
	v_fmac_f32_e32 v4, 0x3db504f3, v195
	global_store_dword v3, v4, s[96:97]
	s_branch .LBB0_819

; #define PG8_STAGE(bufoff, gbase, voff) do { _Pragma("unroll") for (int _i = 0; _i < 2; ++_i) \
;         __builtin_amdgcn_global_load_lds((const unsigned*)((const char*)(gbase) + (voff)[_i]), (PG8_LAS unsigned*)(lds + (bufoff) + ldsw + _i * 8192), 16, 0, 0); } while (0)
; #define PG8_LDA(dst, b, h) do { _Pragma("unroll") for (int m = 0; m < 4; ++m) _Pragma("unroll") for (int k = 0; k < 2; ++k) dst[m][k] = *(const PG8_LAS bf16x8*)(lds + PG8_SA(b, h) + aoff + m * 2048 + k * 1024); } while (0)
; #define PG8_LDB(dst, b, h) do { _Pragma("unroll") for (int n = 0; n < 2; ++n) _Pragma("unroll") for (int k = 0; k < 2; ++k) dst[n][k] = *(const PG8_LAS bf16x8*)(lds + PG8_SB(b, h) + boff + n * 2048 + k * 1024); } while (0)
; #define PG8_MMA(ai, bj, At, Bt) do { __builtin_amdgcn_s_setprio(1); _Pragma("unroll") for (int m = 0; m < 4; ++m) _Pragma("unroll") for (int n = 0; n < 2; ++n) _Pragma("unroll") for (int k = 0; k < 2; ++k) \
;         acc[ai][bj][m][n] = __builtin_amdgcn_mfma_f32_16x16x32_bf16(Bt[n][k], At[m][k], acc[ai][bj][m][n], 0, 0, 0); __builtin_amdgcn_s_setprio(0); } while (0)
; #define PG8_WAIT_V(n) asm volatile("s_waitcnt vmcnt(" #n ")" ::: "memory")
; #define PG8_WAIT_L(n) asm volatile("s_waitcnt lgkmcnt(" #n ")" ::: "memory")
; #define PG8_BAR __builtin_amdgcn_s_barrier()
; #define PG8_SCHED __builtin_amdgcn_sched_barrier(0)
;     ...
;             PG8_LDB(B0, 0, 0); PG8_LDB(B1, 0, 1); PG8_SCHED; PG8_LDA(At, 0, 0); PG8_STAGE(PG8_SA(1, 1), a1 + hstep, voffA);
;             PG8_WAIT_V(8); PG8_WAIT_L(0); PG8_BAR; PG8_MMA(0, 0, At, B0); PG8_MMA(0, 1, At, B1); PG8_BAR; PG8_SCHED;
;             PG8_LDA(At, 0, 1); PG8_STAGE(PG8_SB(0, 0), b2, voffB); PG8_STAGE(PG8_SB(0, 1), b2 + hstep, voffB); PG8_STAGE(PG8_SA(0, 0), a2, voffA);
;             PG8_WAIT_V(8); PG8_WAIT_L(0); PG8_BAR; PG8_MMA(1, 0, At, B0); PG8_MMA(1, 1, At, B1); PG8_BAR; PG8_SCHED;
;             PG8_LDB(B0, 1, 0); PG8_LDB(B1, 1, 1); PG8_SCHED; PG8_LDA(At, 1, 0); PG8_STAGE(PG8_SA(0, 1), a2 + hstep, voffA);
;             PG8_WAIT_V(8); PG8_WAIT_L(0); PG8_BAR; PG8_MMA(0, 0, At, B0); PG8_MMA(0, 1, At, B1); PG8_BAR; PG8_SCHED;
;             PG8_LDA(At, 1, 1); PG8_STAGE(PG8_SB(1, 0), b3, voffB); PG8_STAGE(PG8_SB(1, 1), b3 + hstep, voffB); PG8_STAGE(PG8_SA(1, 0), a3, voffA);
;             PG8_WAIT_V(8); PG8_WAIT_L(0); PG8_BAR; PG8_MMA(1, 0, At, B0); PG8_MMA(1, 1, At, B1); PG8_BAR; PG8_SCHED;
.LBB0_998:
	s_add_u32 s48, s68, 0xfff80080
	s_addc_u32 s49, s69, -1
	s_add_i32 s81, 0, 0x10000
	s_cmp_eq_u32 s79, 28
	s_cselect_b32 s77, s51, s49
	s_cselect_b32 s76, s59, s48
	s_cselect_b32 s71, s25, s78
	s_cselect_b32 s70, s73, s75
	s_add_i32 s48, 0, 0x14000
	ds_read_b128 v[108:111], v251
	ds_read_b128 v[112:115], v251 offset:1024
	ds_read_b128 v[128:131], v251 offset:2048
	ds_read_b128 v[136:139], v251 offset:3072
	ds_read_b128 v[148:151], v251 offset:16384
	ds_read_b128 v[152:155], v251 offset:17408
	ds_read_b128 v[156:159], v251 offset:18432
	ds_read_b128 v[160:163], v251 offset:19456
	v_lshl_add_u64 v[198:199], s[68:69], 0, v[196:197]
	s_add_i32 m0, s6, 0xc000
	ds_read_b128 v[164:167], v234
	ds_read_b128 v[168:171], v234 offset:1024
	ds_read_b128 v[172:175], v234 offset:2048
	ds_read_b128 v[176:179], v234 offset:3072
	ds_read_b128 v[180:183], v234 offset:4096
	ds_read_b128 v[184:187], v234 offset:5120
	ds_read_b128 v[206:209], v234 offset:6144
	ds_read_b128 v[210:213], v234 offset:7168
	global_load_lds_dwordx4 v[198:199], off
	s_add_i32 m0, s6, 0xe000
	v_lshl_add_u64 v[198:199], s[68:69], 0, v[194:195]
	global_load_lds_dwordx4 v[198:199], off
	s_waitcnt vmcnt(8) lgkmcnt(0)
	s_setprio 1
	s_barrier
	v_mfma_f32_16x16x32_bf16 v[144:147], v[108:111], v[164:167], v[144:147]
	v_mfma_f32_16x16x32_bf16 v[140:143], v[128:131], v[164:167], v[140:143]
	v_mfma_f32_16x16x32_bf16 v[120:123], v[108:111], v[172:175], v[120:123]
	v_mfma_f32_16x16x32_bf16 v[116:119], v[128:131], v[172:175], v[116:119]
	v_mfma_f32_16x16x32_bf16 v[96:99], v[108:111], v[180:183], v[96:99]
	v_mfma_f32_16x16x32_bf16 v[92:95], v[128:131], v[180:183], v[92:95]
	v_mfma_f32_16x16x32_bf16 v[80:83], v[108:111], v[206:209], v[80:83]
	v_mfma_f32_16x16x32_bf16 v[76:79], v[128:131], v[206:209], v[76:79]
	v_mfma_f32_16x16x32_bf16 v[144:147], v[112:115], v[168:171], v[144:147]
	v_mfma_f32_16x16x32_bf16 v[140:143], v[136:139], v[168:171], v[140:143]
	v_mfma_f32_16x16x32_bf16 v[120:123], v[112:115], v[176:179], v[120:123]
	v_mfma_f32_16x16x32_bf16 v[116:119], v[136:139], v[176:179], v[116:119]
	v_mfma_f32_16x16x32_bf16 v[96:99], v[112:115], v[184:187], v[96:99]
	v_mfma_f32_16x16x32_bf16 v[92:95], v[136:139], v[184:187], v[92:95]
	v_mfma_f32_16x16x32_bf16 v[80:83], v[112:115], v[210:213], v[80:83]
	v_mfma_f32_16x16x32_bf16 v[76:79], v[136:139], v[210:213], v[76:79]
	v_mfma_f32_16x16x32_bf16 v[132:135], v[148:151], v[164:167], v[132:135]
	v_mfma_f32_16x16x32_bf16 v[124:127], v[156:159], v[164:167], v[124:127]
	v_mfma_f32_16x16x32_bf16 v[104:107], v[148:151], v[172:175], v[104:107]
	v_mfma_f32_16x16x32_bf16 v[100:103], v[156:159], v[172:175], v[100:103]
	v_mfma_f32_16x16x32_bf16 v[88:91], v[148:151], v[180:183], v[88:91]
	v_mfma_f32_16x16x32_bf16 v[84:87], v[156:159], v[180:183], v[84:87]
	v_mfma_f32_16x16x32_bf16 v[72:75], v[148:151], v[206:209], v[72:75]
	v_mfma_f32_16x16x32_bf16 v[68:71], v[156:159], v[206:209], v[68:71]
	v_mfma_f32_16x16x32_bf16 v[132:135], v[152:155], v[168:171], v[132:135]
	v_mfma_f32_16x16x32_bf16 v[124:127], v[160:163], v[168:171], v[124:127]
	v_mfma_f32_16x16x32_bf16 v[104:107], v[152:155], v[176:179], v[104:107]
	v_mfma_f32_16x16x32_bf16 v[100:103], v[160:163], v[176:179], v[100:103]
	v_mfma_f32_16x16x32_bf16 v[88:91], v[152:155], v[184:187], v[88:91]
	v_mfma_f32_16x16x32_bf16 v[84:87], v[160:163], v[184:187], v[84:87]
	v_mfma_f32_16x16x32_bf16 v[72:75], v[152:155], v[210:213], v[72:75]
	v_mfma_f32_16x16x32_bf16 v[68:71], v[160:163], v[210:213], v[68:71]
	s_barrier
	s_setprio 0
	s_add_i32 s49, s81, s5
	v_lshl_add_u64 v[198:199], s[70:71], 0, v[200:201]
	s_mov_b32 m0, s49
	ds_read_b128 v[164:167], v234 offset:16384
	ds_read_b128 v[168:171], v234 offset:17408
	ds_read_b128 v[172:175], v234 offset:18432
	ds_read_b128 v[176:179], v234 offset:19456
	ds_read_b128 v[180:183], v234 offset:20480
	ds_read_b128 v[184:187], v234 offset:21504
	ds_read_b128 v[206:209], v234 offset:22528
	ds_read_b128 v[210:213], v234 offset:23552
	global_load_lds_dwordx4 v[198:199], off
	s_add_i32 m0, s49, 0x2000
	s_add_u32 s84, s70, 0x80000
	v_lshl_add_u64 v[214:215], s[70:71], 0, v[188:189]
	s_addc_u32 s85, s71, 0
	s_add_i32 s48, s48, s5
	global_load_lds_dwordx4 v[214:215], off
	v_lshl_add_u64 v[216:217], s[84:85], 0, v[200:201]
	s_mov_b32 m0, s48
	v_lshl_add_u64 v[218:219], s[76:77], 0, v[190:191]
	global_load_lds_dwordx4 v[216:217], off
	s_add_i32 m0, s48, 0x2000
	v_lshl_add_u64 v[216:217], s[84:85], 0, v[188:189]
	global_load_lds_dwordx4 v[216:217], off
	s_mov_b32 m0, s6
	v_lshl_add_u64 v[216:217], s[76:77], 0, v[192:193]
	global_load_lds_dwordx4 v[216:217], off
	s_mov_b32 m0, s20
	s_nop 0
	global_load_lds_dwordx4 v[218:219], off
	s_waitcnt vmcnt(8) lgkmcnt(0)
	s_setprio 1
	s_barrier
; #define PG8_STAGE(bufoff, gbase, voff) do { _Pragma("unroll") for (int _i = 0; _i < 2; ++_i) \
;         __builtin_amdgcn_global_load_lds((const unsigned*)((const char*)(gbase) + (voff)[_i]), (PG8_LAS unsigned*)(lds + (bufoff) + ldsw + _i * 8192), 16, 0, 0); } while (0)
; #define PG8_LDA(dst, b, h) do { _Pragma("unroll") for (int m = 0; m < 4; ++m) _Pragma("unroll") for (int k = 0; k < 2; ++k) dst[m][k] = *(const PG8_LAS bf16x8*)(lds + PG8_SA(b, h) + aoff + m * 2048 + k * 1024); } while (0)
; #define PG8_LDB(dst, b, h) do { _Pragma("unroll") for (int n = 0; n < 2; ++n) _Pragma("unroll") for (int k = 0; k < 2; ++k) dst[n][k] = *(const PG8_LAS bf16x8*)(lds + PG8_SB(b, h) + boff + n * 2048 + k * 1024); } while (0)
; #define PG8_MMA(ai, bj, At, Bt) do { __builtin_amdgcn_s_setprio(1); _Pragma("unroll") for (int m = 0; m < 4; ++m) _Pragma("unroll") for (int n = 0; n < 2; ++n) _Pragma("unroll") for (int k = 0; k < 2; ++k) \
;         acc[ai][bj][m][n] = __builtin_amdgcn_mfma_f32_16x16x32_bf16(Bt[n][k], At[m][k], acc[ai][bj][m][n], 0, 0, 0); __builtin_amdgcn_s_setprio(0); } while (0)
; #define PG8_WAIT_V(n) asm volatile("s_waitcnt vmcnt(" #n ")" ::: "memory")
; #define PG8_WAIT_L(n) asm volatile("s_waitcnt lgkmcnt(" #n ")" ::: "memory")
; #define PG8_BAR __builtin_amdgcn_s_barrier()
; #define PG8_SCHED __builtin_amdgcn_sched_barrier(0)
;     ...
;             PG8_WAIT_V(8); PG8_WAIT_L(0); PG8_BAR; PG8_MMA(1, 0, At, B0); PG8_MMA(1, 1, At, B1); PG8_BAR; PG8_SCHED;
;             PG8_LDB(B0, 1, 0); PG8_LDB(B1, 1, 1); PG8_SCHED; PG8_LDA(At, 1, 0); PG8_STAGE(PG8_SA(0, 1), a2 + hstep, voffA);
;             PG8_WAIT_V(8); PG8_WAIT_L(0); PG8_BAR; PG8_MMA(0, 0, At, B0); PG8_MMA(0, 1, At, B1); PG8_BAR; PG8_SCHED;
;             PG8_LDA(At, 1, 1); PG8_STAGE(PG8_SB(1, 0), b3, voffB); PG8_STAGE(PG8_SB(1, 1), b3 + hstep, voffB); PG8_STAGE(PG8_SA(1, 0), a3, voffA);
	v_mfma_f32_16x16x32_bf16 v[64:67], v[108:111], v[164:167], v[64:67]
	v_mfma_f32_16x16x32_bf16 v[60:63], v[128:131], v[164:167], v[60:63]
	v_mfma_f32_16x16x32_bf16 v[48:51], v[108:111], v[172:175], v[48:51]
	v_mfma_f32_16x16x32_bf16 v[44:47], v[128:131], v[172:175], v[44:47]
	v_mfma_f32_16x16x32_bf16 v[32:35], v[108:111], v[180:183], v[32:35]
	v_mfma_f32_16x16x32_bf16 v[28:31], v[128:131], v[180:183], v[28:31]
	v_mfma_f32_16x16x32_bf16 v[16:19], v[108:111], v[206:209], v[16:19]
	v_mfma_f32_16x16x32_bf16 v[12:15], v[128:131], v[206:209], v[12:15]
	v_mfma_f32_16x16x32_bf16 v[64:67], v[112:115], v[168:171], v[64:67]
	v_mfma_f32_16x16x32_bf16 v[60:63], v[136:139], v[168:171], v[60:63]
	v_mfma_f32_16x16x32_bf16 v[48:51], v[112:115], v[176:179], v[48:51]
	v_mfma_f32_16x16x32_bf16 v[44:47], v[136:139], v[176:179], v[44:47]
	v_mfma_f32_16x16x32_bf16 v[32:35], v[112:115], v[184:187], v[32:35]
	v_mfma_f32_16x16x32_bf16 v[28:31], v[136:139], v[184:187], v[28:31]
	v_mfma_f32_16x16x32_bf16 v[16:19], v[112:115], v[210:213], v[16:19]
	v_mfma_f32_16x16x32_bf16 v[12:15], v[136:139], v[210:213], v[12:15]
	v_mfma_f32_16x16x32_bf16 v[56:59], v[148:151], v[164:167], v[56:59]
	v_mfma_f32_16x16x32_bf16 v[52:55], v[156:159], v[164:167], v[52:55]
	v_mfma_f32_16x16x32_bf16 v[40:43], v[148:151], v[172:175], v[40:43]
	v_mfma_f32_16x16x32_bf16 v[36:39], v[156:159], v[172:175], v[36:39]
	v_mfma_f32_16x16x32_bf16 v[24:27], v[148:151], v[180:183], v[24:27]
	v_mfma_f32_16x16x32_bf16 v[20:23], v[156:159], v[180:183], v[20:23]
	v_mfma_f32_16x16x32_bf16 v[8:11], v[148:151], v[206:209], v[8:11]
	v_mfma_f32_16x16x32_bf16 v[4:7], v[156:159], v[206:209], v[4:7]
	v_mfma_f32_16x16x32_bf16 v[56:59], v[152:155], v[168:171], v[56:59]
	v_mfma_f32_16x16x32_bf16 v[52:55], v[160:163], v[168:171], v[52:55]
	v_mfma_f32_16x16x32_bf16 v[40:43], v[152:155], v[176:179], v[40:43]
	v_mfma_f32_16x16x32_bf16 v[36:39], v[160:163], v[176:179], v[36:39]
	v_mfma_f32_16x16x32_bf16 v[24:27], v[152:155], v[184:187], v[24:27]
	v_mfma_f32_16x16x32_bf16 v[20:23], v[160:163], v[184:187], v[20:23]
	v_mfma_f32_16x16x32_bf16 v[8:11], v[152:155], v[210:213], v[8:11]
	v_mfma_f32_16x16x32_bf16 v[4:7], v[160:163], v[210:213], v[4:7]
	s_barrier
	s_setprio 0
	s_add_i32 s48, 0, 0x18000
	s_add_i32 s49, 0, 0x1c000
	ds_read_b128 v[108:111], v251 offset:32768
	ds_read_b128 v[112:115], v251 offset:33792
	ds_read_b128 v[128:131], v251 offset:34816
	ds_read_b128 v[136:139], v251 offset:35840
	ds_read_b128 v[148:151], v251 offset:49152
	ds_read_b128 v[152:155], v251 offset:50176
	ds_read_b128 v[156:159], v251 offset:51200
	ds_read_b128 v[160:163], v251 offset:52224
	s_add_u32 s76, s76, 0x80000
	s_addc_u32 s77, s77, 0
	s_mov_b32 m0, s21
	v_lshl_add_u64 v[220:221], s[76:77], 0, v[192:193]
	ds_read_b128 v[164:167], v234 offset:32768
	ds_read_b128 v[168:171], v234 offset:33792
	ds_read_b128 v[172:175], v234 offset:34816
	ds_read_b128 v[176:179], v234 offset:35840
	ds_read_b128 v[180:183], v234 offset:36864
	ds_read_b128 v[184:187], v234 offset:37888
	ds_read_b128 v[206:209], v234 offset:38912
	ds_read_b128 v[210:213], v234 offset:39936
	global_load_lds_dwordx4 v[220:221], off
	s_mov_b32 m0, s23
	v_lshl_add_u64 v[220:221], s[76:77], 0, v[190:191]
	global_load_lds_dwordx4 v[220:221], off
	s_waitcnt vmcnt(8) lgkmcnt(0)
	s_setprio 1
	s_barrier
	v_mfma_f32_16x16x32_bf16 v[144:147], v[108:111], v[164:167], v[144:147]
	v_mfma_f32_16x16x32_bf16 v[140:143], v[128:131], v[164:167], v[140:143]
	v_mfma_f32_16x16x32_bf16 v[120:123], v[108:111], v[172:175], v[120:123]
	v_mfma_f32_16x16x32_bf16 v[116:119], v[128:131], v[172:175], v[116:119]
	v_mfma_f32_16x16x32_bf16 v[96:99], v[108:111], v[180:183], v[96:99]
	v_mfma_f32_16x16x32_bf16 v[92:95], v[128:131], v[180:183], v[92:95]
	v_mfma_f32_16x16x32_bf16 v[80:83], v[108:111], v[206:209], v[80:83]
	v_mfma_f32_16x16x32_bf16 v[76:79], v[128:131], v[206:209], v[76:79]
	v_mfma_f32_16x16x32_bf16 v[144:147], v[112:115], v[168:171], v[144:147]
	v_mfma_f32_16x16x32_bf16 v[140:143], v[136:139], v[168:171], v[140:143]
	v_mfma_f32_16x16x32_bf16 v[120:123], v[112:115], v[176:179], v[120:123]
	v_mfma_f32_16x16x32_bf16 v[116:119], v[136:139], v[176:179], v[116:119]
	v_mfma_f32_16x16x32_bf16 v[96:99], v[112:115], v[184:187], v[96:99]
	v_mfma_f32_16x16x32_bf16 v[92:95], v[136:139], v[184:187], v[92:95]
	v_mfma_f32_16x16x32_bf16 v[80:83], v[112:115], v[210:213], v[80:83]
	v_mfma_f32_16x16x32_bf16 v[76:79], v[136:139], v[210:213], v[76:79]
	v_mfma_f32_16x16x32_bf16 v[132:135], v[148:151], v[164:167], v[132:135]
	v_mfma_f32_16x16x32_bf16 v[124:127], v[156:159], v[164:167], v[124:127]
	v_mfma_f32_16x16x32_bf16 v[104:107], v[148:151], v[172:175], v[104:107]
	v_mfma_f32_16x16x32_bf16 v[100:103], v[156:159], v[172:175], v[100:103]
	v_mfma_f32_16x16x32_bf16 v[88:91], v[148:151], v[180:183], v[88:91]
	v_mfma_f32_16x16x32_bf16 v[84:87], v[156:159], v[180:183], v[84:87]
	v_mfma_f32_16x16x32_bf16 v[72:75], v[148:151], v[206:209], v[72:75]
	v_mfma_f32_16x16x32_bf16 v[68:71], v[156:159], v[206:209], v[68:71]
	v_mfma_f32_16x16x32_bf16 v[132:135], v[152:155], v[168:171], v[132:135]
	v_mfma_f32_16x16x32_bf16 v[124:127], v[160:163], v[168:171], v[124:127]
	v_mfma_f32_16x16x32_bf16 v[104:107], v[152:155], v[176:179], v[104:107]
	v_mfma_f32_16x16x32_bf16 v[100:103], v[160:163], v[176:179], v[100:103]
	v_mfma_f32_16x16x32_bf16 v[88:91], v[152:155], v[184:187], v[88:91]
	v_mfma_f32_16x16x32_bf16 v[84:87], v[160:163], v[184:187], v[84:87]
	v_mfma_f32_16x16x32_bf16 v[72:75], v[152:155], v[210:213], v[72:75]
	v_mfma_f32_16x16x32_bf16 v[68:71], v[160:163], v[210:213], v[68:71]
	s_barrier
; #define PG8_STAGE(bufoff, gbase, voff) do { _Pragma("unroll") for (int _i = 0; _i < 2; ++_i) \
;         __builtin_amdgcn_global_load_lds((const unsigned*)((const char*)(gbase) + (voff)[_i]), (PG8_LAS unsigned*)(lds + (bufoff) + ldsw + _i * 8192), 16, 0, 0); } while (0)
; #define PG8_LDA(dst, b, h) do { _Pragma("unroll") for (int m = 0; m < 4; ++m) _Pragma("unroll") for (int k = 0; k < 2; ++k) dst[m][k] = *(const PG8_LAS bf16x8*)(lds + PG8_SA(b, h) + aoff + m * 2048 + k * 1024); } while (0)
; #define PG8_MMA(ai, bj, At, Bt) do { __builtin_amdgcn_s_setprio(1); _Pragma("unroll") for (int m = 0; m < 4; ++m) _Pragma("unroll") for (int n = 0; n < 2; ++n) _Pragma("unroll") for (int k = 0; k < 2; ++k) \
;         acc[ai][bj][m][n] = __builtin_amdgcn_mfma_f32_16x16x32_bf16(Bt[n][k], At[m][k], acc[ai][bj][m][n], 0, 0, 0); __builtin_amdgcn_s_setprio(0); } while (0)
; #define PG8_WAIT_V(n) asm volatile("s_waitcnt vmcnt(" #n ")" ::: "memory")
; #define PG8_WAIT_L(n) asm volatile("s_waitcnt lgkmcnt(" #n ")" ::: "memory")
; #define PG8_BAR __builtin_amdgcn_s_barrier()
; #define PG8_SCHED __builtin_amdgcn_sched_barrier(0)
;     ...
;         for (int t = 0; t < nt; t += 2) {
;             const bool last = (t == nt - 2);
;             const char* a1 = cA + (size_t)(t + 1) * kstep;
;             const char* a2 = last ? nA : cA + (size_t)(t + 2) * kstep; const char* b2 = last ? nB : cB + (size_t)(t + 2) * kstep;
;             const char* a3 = a2 + kstep; const char* b3 = b2 + kstep;
;     ...
;             PG8_LDA(At, 1, 1); PG8_STAGE(PG8_SB(1, 0), b3, voffB); PG8_STAGE(PG8_SB(1, 1), b3 + hstep, voffB); PG8_STAGE(PG8_SA(1, 0), a3, voffA);
;             PG8_WAIT_V(8); PG8_WAIT_L(0); PG8_BAR; PG8_MMA(1, 0, At, B0); PG8_MMA(1, 1, At, B1); PG8_BAR; PG8_SCHED;
	s_setprio 0
	s_add_i32 s48, s48, s5
	v_lshl_add_u64 v[198:199], v[198:199], 0, s[66:67]
	s_mov_b32 m0, s48
	ds_read_b128 v[164:167], v234 offset:49152
	ds_read_b128 v[168:171], v234 offset:50176
	ds_read_b128 v[172:175], v234 offset:51200
	ds_read_b128 v[176:179], v234 offset:52224
	ds_read_b128 v[180:183], v234 offset:53248
	ds_read_b128 v[184:187], v234 offset:54272
	ds_read_b128 v[206:209], v234 offset:55296
	ds_read_b128 v[210:213], v234 offset:56320
	global_load_lds_dwordx4 v[198:199], off
	s_add_i32 m0, s48, 0x2000
	s_add_u32 s70, s70, 0x80080
	v_lshl_add_u64 v[198:199], v[214:215], 0, s[66:67]
	s_addc_u32 s71, s71, 0
	s_add_i32 s48, s49, s5
	global_load_lds_dwordx4 v[198:199], off
	s_mov_b32 m0, s48
	v_lshl_add_u64 v[198:199], s[70:71], 0, v[200:201]
	global_load_lds_dwordx4 v[198:199], off
	s_add_i32 m0, s48, 0x2000
	v_lshl_add_u64 v[198:199], s[70:71], 0, v[188:189]
	global_load_lds_dwordx4 v[198:199], off
	v_lshl_add_u64 v[198:199], v[216:217], 0, s[66:67]
	s_mov_b32 m0, s54
	s_nop 0
	global_load_lds_dwordx4 v[198:199], off
	v_lshl_add_u64 v[198:199], v[218:219], 0, s[66:67]
	s_mov_b32 m0, s55
	s_nop 0
	global_load_lds_dwordx4 v[198:199], off
	s_waitcnt vmcnt(8) lgkmcnt(0)
	s_setprio 1
	s_barrier
	v_mfma_f32_16x16x32_bf16 v[64:67], v[108:111], v[164:167], v[64:67]
	v_mfma_f32_16x16x32_bf16 v[60:63], v[128:131], v[164:167], v[60:63]
	v_mfma_f32_16x16x32_bf16 v[48:51], v[108:111], v[172:175], v[48:51]
	v_mfma_f32_16x16x32_bf16 v[44:47], v[128:131], v[172:175], v[44:47]
	v_mfma_f32_16x16x32_bf16 v[32:35], v[108:111], v[180:183], v[32:35]
	v_mfma_f32_16x16x32_bf16 v[28:31], v[128:131], v[180:183], v[28:31]
	v_mfma_f32_16x16x32_bf16 v[16:19], v[108:111], v[206:209], v[16:19]
	v_mfma_f32_16x16x32_bf16 v[12:15], v[128:131], v[206:209], v[12:15]
	v_mfma_f32_16x16x32_bf16 v[64:67], v[112:115], v[168:171], v[64:67]
	v_mfma_f32_16x16x32_bf16 v[60:63], v[136:139], v[168:171], v[60:63]
	v_mfma_f32_16x16x32_bf16 v[48:51], v[112:115], v[176:179], v[48:51]
	v_mfma_f32_16x16x32_bf16 v[44:47], v[136:139], v[176:179], v[44:47]
	v_mfma_f32_16x16x32_bf16 v[32:35], v[112:115], v[184:187], v[32:35]
	v_mfma_f32_16x16x32_bf16 v[28:31], v[136:139], v[184:187], v[28:31]
	v_mfma_f32_16x16x32_bf16 v[16:19], v[112:115], v[210:213], v[16:19]
	v_mfma_f32_16x16x32_bf16 v[12:15], v[136:139], v[210:213], v[12:15]
	v_mfma_f32_16x16x32_bf16 v[56:59], v[148:151], v[164:167], v[56:59]
	v_mfma_f32_16x16x32_bf16 v[52:55], v[156:159], v[164:167], v[52:55]
	v_mfma_f32_16x16x32_bf16 v[40:43], v[148:151], v[172:175], v[40:43]
	v_mfma_f32_16x16x32_bf16 v[36:39], v[156:159], v[172:175], v[36:39]
	v_mfma_f32_16x16x32_bf16 v[24:27], v[148:151], v[180:183], v[24:27]
	v_mfma_f32_16x16x32_bf16 v[20:23], v[156:159], v[180:183], v[20:23]
	v_mfma_f32_16x16x32_bf16 v[8:11], v[148:151], v[206:209], v[8:11]
	v_mfma_f32_16x16x32_bf16 v[4:7], v[156:159], v[206:209], v[4:7]
	v_mfma_f32_16x16x32_bf16 v[56:59], v[152:155], v[168:171], v[56:59]
	v_mfma_f32_16x16x32_bf16 v[52:55], v[160:163], v[168:171], v[52:55]
	v_mfma_f32_16x16x32_bf16 v[40:43], v[152:155], v[176:179], v[40:43]
	v_mfma_f32_16x16x32_bf16 v[36:39], v[160:163], v[176:179], v[36:39]
	v_mfma_f32_16x16x32_bf16 v[24:27], v[152:155], v[184:187], v[24:27]
	v_mfma_f32_16x16x32_bf16 v[20:23], v[160:163], v[184:187], v[20:23]
	v_mfma_f32_16x16x32_bf16 v[8:11], v[152:155], v[210:213], v[8:11]
	v_mfma_f32_16x16x32_bf16 v[4:7], v[160:163], v[210:213], v[4:7]
	s_barrier
	s_setprio 0
	s_add_i32 s79, s79, 2
	s_add_u32 s75, s75, 0x100
	s_addc_u32 s78, s78, 0
	s_add_u32 s68, s68, 0x100
	s_addc_u32 s69, s69, 0
	s_cmp_gt_u32 s79, 29
	s_cbranch_scc0 .LBB0_998
	s_and_b64 vcc, exec, s[14:15]
	s_cbranch_vccz .LBB0_1001
	s_barrier

; #define PG8_STAGE(bufoff, gbase, voff) do { _Pragma("unroll") for (int _i = 0; _i < 2; ++_i) \
;         __builtin_amdgcn_global_load_lds((const unsigned*)((const char*)(gbase) + (voff)[_i]), (PG8_LAS unsigned*)(lds + (bufoff) + ldsw + _i * 8192), 16, 0, 0); } while (0)
; #define PG8_LDA(dst, b, h) do { _Pragma("unroll") for (int m = 0; m < 4; ++m) _Pragma("unroll") for (int k = 0; k < 2; ++k) dst[m][k] = *(const PG8_LAS bf16x8*)(lds + PG8_SA(b, h) + aoff + m * 2048 + k * 1024); } while (0)
; #define PG8_LDB(dst, b, h) do { _Pragma("unroll") for (int n = 0; n < 2; ++n) _Pragma("unroll") for (int k = 0; k < 2; ++k) dst[n][k] = *(const PG8_LAS bf16x8*)(lds + PG8_SB(b, h) + boff + n * 2048 + k * 1024); } while (0)
; #define PG8_MMA(ai, bj, At, Bt) do { __builtin_amdgcn_s_setprio(1); _Pragma("unroll") for (int m = 0; m < 4; ++m) _Pragma("unroll") for (int n = 0; n < 2; ++n) _Pragma("unroll") for (int k = 0; k < 2; ++k) \
;         acc[ai][bj][m][n] = __builtin_amdgcn_mfma_f32_16x16x32_bf16(Bt[n][k], At[m][k], acc[ai][bj][m][n], 0, 0, 0); __builtin_amdgcn_s_setprio(0); } while (0)
; #define PG8_WAIT_V(n) asm volatile("s_waitcnt vmcnt(" #n ")" ::: "memory")
; #define PG8_WAIT_L(n) asm volatile("s_waitcnt lgkmcnt(" #n ")" ::: "memory")
; #define PG8_BAR __builtin_amdgcn_s_barrier()
; #define PG8_SCHED __builtin_amdgcn_sched_barrier(0)
;     ...
;             PG8_LDB(B0, 0, 0); PG8_LDB(B1, 0, 1); PG8_SCHED; PG8_LDA(At, 0, 0); PG8_STAGE(PG8_SA(1, 1), a1 + hstep, voffA);
;             PG8_WAIT_V(8); PG8_WAIT_L(0); PG8_BAR; PG8_MMA(0, 0, At, B0); PG8_MMA(0, 1, At, B1); PG8_BAR; PG8_SCHED;
;             PG8_LDA(At, 0, 1); PG8_STAGE(PG8_SB(0, 0), b2, voffB); PG8_STAGE(PG8_SB(0, 1), b2 + hstep, voffB); PG8_STAGE(PG8_SA(0, 0), a2, voffA);
;             PG8_WAIT_V(8); PG8_WAIT_L(0); PG8_BAR; PG8_MMA(1, 0, At, B0); PG8_MMA(1, 1, At, B1); PG8_BAR; PG8_SCHED;
;             PG8_LDB(B0, 1, 0); PG8_LDB(B1, 1, 1); PG8_SCHED; PG8_LDA(At, 1, 0); PG8_STAGE(PG8_SA(0, 1), a2 + hstep, voffA);
;             PG8_WAIT_V(8); PG8_WAIT_L(0); PG8_BAR; PG8_MMA(0, 0, At, B0); PG8_MMA(0, 1, At, B1); PG8_BAR; PG8_SCHED;
;             PG8_LDA(At, 1, 1); PG8_STAGE(PG8_SB(1, 0), b3, voffB); PG8_STAGE(PG8_SB(1, 1), b3 + hstep, voffB); PG8_STAGE(PG8_SA(1, 0), a3, voffA);
;             PG8_WAIT_V(8); PG8_WAIT_L(0); PG8_BAR; PG8_MMA(1, 0, At, B0); PG8_MMA(1, 1, At, B1); PG8_BAR; PG8_SCHED;
.LBB0_1086:
	s_add_u32 s10, s8, 0xfff80080
	s_addc_u32 s11, s9, -1
	s_add_i32 s48, 0, 0x10000
	s_cmp_eq_u32 s97, 28
	s_cselect_b32 s13, s69, s11
	s_cselect_b32 s12, s76, s10
	s_cselect_b32 s11, s77, s89
	s_cselect_b32 s10, s82, s83
	s_add_i32 vcc_lo, 0, 0x14000
	ds_read_b128 v[106:109], v251
	ds_read_b128 v[110:113], v251 offset:1024
	ds_read_b128 v[114:117], v251 offset:2048
	ds_read_b128 v[118:121], v251 offset:3072
	ds_read_b128 v[122:125], v251 offset:16384
	ds_read_b128 v[126:129], v251 offset:17408
	ds_read_b128 v[130:133], v251 offset:18432
	ds_read_b128 v[134:137], v251 offset:19456
	v_lshl_add_u64 v[100:101], s[8:9], 0, v[190:191]
	s_add_i32 m0, s1, 0xc000
	ds_read_b128 v[166:169], v222
	ds_read_b128 v[170:173], v222 offset:1024
	ds_read_b128 v[174:177], v222 offset:2048
	ds_read_b128 v[178:181], v222 offset:3072
	ds_read_b128 v[194:197], v222 offset:4096
	ds_read_b128 v[206:209], v222 offset:5120
	ds_read_b128 v[210:213], v222 offset:6144
	ds_read_b128 v[214:217], v222 offset:7168
	global_load_lds_dwordx4 v[100:101], off
	s_add_i32 m0, s1, 0xe000
	v_lshl_add_u64 v[100:101], s[8:9], 0, v[192:193]
	global_load_lds_dwordx4 v[100:101], off
	s_waitcnt vmcnt(8) lgkmcnt(0)
	s_setprio 1
	s_barrier
	v_mfma_f32_16x16x32_bf16 v[4:7], v[106:109], v[166:169], v[4:7]
	v_mfma_f32_16x16x32_bf16 v[72:75], v[114:117], v[166:169], v[72:75]
	v_mfma_f32_16x16x32_bf16 v[162:165], v[106:109], v[174:177], v[162:165]
	v_mfma_f32_16x16x32_bf16 v[60:63], v[114:117], v[174:177], v[60:63]
	v_mfma_f32_16x16x32_bf16 v[158:161], v[106:109], v[194:197], v[158:161]
	v_mfma_f32_16x16x32_bf16 v[56:59], v[114:117], v[194:197], v[56:59]
	v_mfma_f32_16x16x32_bf16 v[96:99], v[106:109], v[210:213], v[96:99]
	v_mfma_f32_16x16x32_bf16 v[76:79], v[114:117], v[210:213], v[76:79]
	v_mfma_f32_16x16x32_bf16 v[4:7], v[110:113], v[170:173], v[4:7]
	v_mfma_f32_16x16x32_bf16 v[72:75], v[118:121], v[170:173], v[72:75]
	v_mfma_f32_16x16x32_bf16 v[162:165], v[110:113], v[178:181], v[162:165]
	v_mfma_f32_16x16x32_bf16 v[60:63], v[118:121], v[178:181], v[60:63]
	v_mfma_f32_16x16x32_bf16 v[158:161], v[110:113], v[206:209], v[158:161]
	v_mfma_f32_16x16x32_bf16 v[56:59], v[118:121], v[206:209], v[56:59]
	v_mfma_f32_16x16x32_bf16 v[96:99], v[110:113], v[214:217], v[96:99]
	v_mfma_f32_16x16x32_bf16 v[76:79], v[118:121], v[214:217], v[76:79]
	v_mfma_f32_16x16x32_bf16 v[8:11], v[122:125], v[166:169], v[8:11]
	v_mfma_f32_16x16x32_bf16 v[64:67], v[130:133], v[166:169], v[64:67]
	v_mfma_f32_16x16x32_bf16 v[154:157], v[122:125], v[174:177], v[154:157]
	v_mfma_f32_16x16x32_bf16 v[52:55], v[130:133], v[174:177], v[52:55]
	v_mfma_f32_16x16x32_bf16 v[150:153], v[122:125], v[194:197], v[150:153]
	v_mfma_f32_16x16x32_bf16 v[48:51], v[130:133], v[194:197], v[48:51]
	v_mfma_f32_16x16x32_bf16 v[92:95], v[122:125], v[210:213], v[92:95]
	v_mfma_f32_16x16x32_bf16 v[68:71], v[130:133], v[210:213], v[68:71]
	v_mfma_f32_16x16x32_bf16 v[8:11], v[126:129], v[170:173], v[8:11]
	v_mfma_f32_16x16x32_bf16 v[64:67], v[134:137], v[170:173], v[64:67]
	v_mfma_f32_16x16x32_bf16 v[154:157], v[126:129], v[178:181], v[154:157]
	v_mfma_f32_16x16x32_bf16 v[52:55], v[134:137], v[178:181], v[52:55]
	v_mfma_f32_16x16x32_bf16 v[150:153], v[126:129], v[206:209], v[150:153]
	v_mfma_f32_16x16x32_bf16 v[48:51], v[134:137], v[206:209], v[48:51]
	v_mfma_f32_16x16x32_bf16 v[92:95], v[126:129], v[214:217], v[92:95]
	v_mfma_f32_16x16x32_bf16 v[68:71], v[134:137], v[214:217], v[68:71]
	s_barrier
	s_setprio 0
	s_add_i32 s48, s48, s0
	v_lshl_add_u64 v[198:199], s[10:11], 0, v[186:187]
	s_mov_b32 m0, s48
	ds_read_b128 v[166:169], v222 offset:16384
	ds_read_b128 v[170:173], v222 offset:17408
	ds_read_b128 v[174:177], v222 offset:18432
	ds_read_b128 v[178:181], v222 offset:19456
	ds_read_b128 v[194:197], v222 offset:20480
	ds_read_b128 v[206:209], v222 offset:21504
	ds_read_b128 v[210:213], v222 offset:22528
	ds_read_b128 v[214:217], v222 offset:23552
	global_load_lds_dwordx4 v[198:199], off
	s_add_i32 m0, s48, 0x2000
	s_add_u32 s48, s10, 0x80000
	v_lshl_add_u64 v[218:219], s[10:11], 0, v[182:183]
	s_addc_u32 s49, s11, 0
	s_add_i32 vcc_lo, vcc_lo, s0
	global_load_lds_dwordx4 v[218:219], off
	v_lshl_add_u64 v[100:101], s[48:49], 0, v[186:187]
	s_mov_b32 m0, vcc_lo
	v_lshl_add_u64 v[224:225], s[12:13], 0, v[188:189]
	global_load_lds_dwordx4 v[100:101], off
	v_lshl_add_u64 v[100:101], s[48:49], 0, v[182:183]
	s_add_i32 m0, vcc_lo, 0x2000
	v_lshl_add_u64 v[232:233], s[12:13], 0, v[184:185]
	global_load_lds_dwordx4 v[100:101], off
	s_mov_b32 m0, s1
	s_nop 0
	global_load_lds_dwordx4 v[224:225], off
	s_mov_b32 m0, s4
	s_nop 0
	global_load_lds_dwordx4 v[232:233], off
	s_waitcnt vmcnt(8) lgkmcnt(0)
	s_setprio 1
	s_barrier
; #define PG8_STAGE(bufoff, gbase, voff) do { _Pragma("unroll") for (int _i = 0; _i < 2; ++_i) \
;         __builtin_amdgcn_global_load_lds((const unsigned*)((const char*)(gbase) + (voff)[_i]), (PG8_LAS unsigned*)(lds + (bufoff) + ldsw + _i * 8192), 16, 0, 0); } while (0)
; #define PG8_LDA(dst, b, h) do { _Pragma("unroll") for (int m = 0; m < 4; ++m) _Pragma("unroll") for (int k = 0; k < 2; ++k) dst[m][k] = *(const PG8_LAS bf16x8*)(lds + PG8_SA(b, h) + aoff + m * 2048 + k * 1024); } while (0)
; #define PG8_LDB(dst, b, h) do { _Pragma("unroll") for (int n = 0; n < 2; ++n) _Pragma("unroll") for (int k = 0; k < 2; ++k) dst[n][k] = *(const PG8_LAS bf16x8*)(lds + PG8_SB(b, h) + boff + n * 2048 + k * 1024); } while (0)
; #define PG8_MMA(ai, bj, At, Bt) do { __builtin_amdgcn_s_setprio(1); _Pragma("unroll") for (int m = 0; m < 4; ++m) _Pragma("unroll") for (int n = 0; n < 2; ++n) _Pragma("unroll") for (int k = 0; k < 2; ++k) \
;         acc[ai][bj][m][n] = __builtin_amdgcn_mfma_f32_16x16x32_bf16(Bt[n][k], At[m][k], acc[ai][bj][m][n], 0, 0, 0); __builtin_amdgcn_s_setprio(0); } while (0)
; #define PG8_WAIT_V(n) asm volatile("s_waitcnt vmcnt(" #n ")" ::: "memory")
; #define PG8_WAIT_L(n) asm volatile("s_waitcnt lgkmcnt(" #n ")" ::: "memory")
; #define PG8_BAR __builtin_amdgcn_s_barrier()
; #define PG8_SCHED __builtin_amdgcn_sched_barrier(0)
;     ...
;             PG8_WAIT_V(8); PG8_WAIT_L(0); PG8_BAR; PG8_MMA(1, 0, At, B0); PG8_MMA(1, 1, At, B1); PG8_BAR; PG8_SCHED;
;             PG8_LDB(B0, 1, 0); PG8_LDB(B1, 1, 1); PG8_SCHED; PG8_LDA(At, 1, 0); PG8_STAGE(PG8_SA(0, 1), a2 + hstep, voffA);
;             PG8_WAIT_V(8); PG8_WAIT_L(0); PG8_BAR; PG8_MMA(0, 0, At, B0); PG8_MMA(0, 1, At, B1); PG8_BAR; PG8_SCHED;
;             PG8_LDA(At, 1, 1); PG8_STAGE(PG8_SB(1, 0), b3, voffB); PG8_STAGE(PG8_SB(1, 1), b3 + hstep, voffB); PG8_STAGE(PG8_SA(1, 0), a3, voffA);
	v_mfma_f32_16x16x32_bf16 v[146:149], v[106:109], v[166:169], v[146:149]
	v_mfma_f32_16x16x32_bf16 v[44:47], v[114:117], v[166:169], v[44:47]
	v_mfma_f32_16x16x32_bf16 v[142:145], v[106:109], v[174:177], v[142:145]
	v_mfma_f32_16x16x32_bf16 v[40:43], v[114:117], v[174:177], v[40:43]
	v_mfma_f32_16x16x32_bf16 v[138:141], v[106:109], v[194:197], v[138:141]
	v_mfma_f32_16x16x32_bf16 v[36:39], v[114:117], v[194:197], v[36:39]
	v_mfma_f32_16x16x32_bf16 v[80:83], v[106:109], v[210:213], v[80:83]
	v_mfma_f32_16x16x32_bf16 v[20:23], v[114:117], v[210:213], v[20:23]
	v_mfma_f32_16x16x32_bf16 v[146:149], v[110:113], v[170:173], v[146:149]
	v_mfma_f32_16x16x32_bf16 v[44:47], v[118:121], v[170:173], v[44:47]
	v_mfma_f32_16x16x32_bf16 v[142:145], v[110:113], v[178:181], v[142:145]
	v_mfma_f32_16x16x32_bf16 v[40:43], v[118:121], v[178:181], v[40:43]
	v_mfma_f32_16x16x32_bf16 v[138:141], v[110:113], v[206:209], v[138:141]
	v_mfma_f32_16x16x32_bf16 v[36:39], v[118:121], v[206:209], v[36:39]
	v_mfma_f32_16x16x32_bf16 v[80:83], v[110:113], v[214:217], v[80:83]
	v_mfma_f32_16x16x32_bf16 v[20:23], v[118:121], v[214:217], v[20:23]
	v_mfma_f32_16x16x32_bf16 v[100:103], v[122:125], v[166:169], v[102:105]
	v_mfma_f32_16x16x32_bf16 v[32:35], v[130:133], v[166:169], v[32:35]
	v_mfma_f32_16x16x32_bf16 v[88:91], v[122:125], v[174:177], v[88:91]
	v_mfma_f32_16x16x32_bf16 v[28:31], v[130:133], v[174:177], v[28:31]
	v_mfma_f32_16x16x32_bf16 v[84:87], v[122:125], v[194:197], v[84:87]
	v_mfma_f32_16x16x32_bf16 v[24:27], v[130:133], v[194:197], v[24:27]
	v_mfma_f32_16x16x32_bf16 v[16:19], v[122:125], v[210:213], v[16:19]
	v_mfma_f32_16x16x32_bf16 v[12:15], v[130:133], v[210:213], v[12:15]
	v_mfma_f32_16x16x32_bf16 v[100:103], v[126:129], v[170:173], v[100:103]
	v_mfma_f32_16x16x32_bf16 v[32:35], v[134:137], v[170:173], v[32:35]
	v_mfma_f32_16x16x32_bf16 v[88:91], v[126:129], v[178:181], v[88:91]
	v_mfma_f32_16x16x32_bf16 v[28:31], v[134:137], v[178:181], v[28:31]
	v_mfma_f32_16x16x32_bf16 v[84:87], v[126:129], v[206:209], v[84:87]
	v_mfma_f32_16x16x32_bf16 v[24:27], v[134:137], v[206:209], v[24:27]
	v_mfma_f32_16x16x32_bf16 v[16:19], v[126:129], v[214:217], v[16:19]
	v_mfma_f32_16x16x32_bf16 v[12:15], v[134:137], v[214:217], v[12:15]
	s_barrier
	s_setprio 0
	s_add_i32 s48, 0, 0x18000
	s_add_i32 s49, 0, 0x1c000
	ds_read_b128 v[104:107], v251 offset:32768
	ds_read_b128 v[108:111], v251 offset:33792
	ds_read_b128 v[112:115], v251 offset:34816
	ds_read_b128 v[116:119], v251 offset:35840
	ds_read_b128 v[120:123], v251 offset:49152
	ds_read_b128 v[124:127], v251 offset:50176
	ds_read_b128 v[128:131], v251 offset:51200
	ds_read_b128 v[132:135], v251 offset:52224
	s_add_u32 s12, s12, 0x80000
	s_addc_u32 s13, s13, 0
	s_mov_b32 m0, s5
	v_lshl_add_u64 v[136:137], s[12:13], 0, v[188:189]
	ds_read_b128 v[166:169], v222 offset:32768
	ds_read_b128 v[170:173], v222 offset:33792
	ds_read_b128 v[174:177], v222 offset:34816
	ds_read_b128 v[178:181], v222 offset:35840
	ds_read_b128 v[194:197], v222 offset:36864
	ds_read_b128 v[206:209], v222 offset:37888
	ds_read_b128 v[210:213], v222 offset:38912
	ds_read_b128 v[214:217], v222 offset:39936
	global_load_lds_dwordx4 v[136:137], off
	s_mov_b32 m0, s44
	v_lshl_add_u64 v[136:137], s[12:13], 0, v[184:185]
	global_load_lds_dwordx4 v[136:137], off
	s_waitcnt vmcnt(8) lgkmcnt(0)
	s_setprio 1
	s_barrier
	v_mfma_f32_16x16x32_bf16 v[4:7], v[104:107], v[166:169], v[4:7]
	v_mfma_f32_16x16x32_bf16 v[72:75], v[112:115], v[166:169], v[72:75]
	v_mfma_f32_16x16x32_bf16 v[162:165], v[104:107], v[174:177], v[162:165]
	v_mfma_f32_16x16x32_bf16 v[60:63], v[112:115], v[174:177], v[60:63]
	v_mfma_f32_16x16x32_bf16 v[158:161], v[104:107], v[194:197], v[158:161]
	v_mfma_f32_16x16x32_bf16 v[56:59], v[112:115], v[194:197], v[56:59]
	v_mfma_f32_16x16x32_bf16 v[96:99], v[104:107], v[210:213], v[96:99]
	v_mfma_f32_16x16x32_bf16 v[76:79], v[112:115], v[210:213], v[76:79]
	v_mfma_f32_16x16x32_bf16 v[4:7], v[108:111], v[170:173], v[4:7]
	v_mfma_f32_16x16x32_bf16 v[72:75], v[116:119], v[170:173], v[72:75]
	v_mfma_f32_16x16x32_bf16 v[162:165], v[108:111], v[178:181], v[162:165]
	v_mfma_f32_16x16x32_bf16 v[60:63], v[116:119], v[178:181], v[60:63]
	v_mfma_f32_16x16x32_bf16 v[158:161], v[108:111], v[206:209], v[158:161]
	v_mfma_f32_16x16x32_bf16 v[56:59], v[116:119], v[206:209], v[56:59]
	v_mfma_f32_16x16x32_bf16 v[96:99], v[108:111], v[214:217], v[96:99]
	v_mfma_f32_16x16x32_bf16 v[76:79], v[116:119], v[214:217], v[76:79]
	v_mfma_f32_16x16x32_bf16 v[8:11], v[120:123], v[166:169], v[8:11]
	v_mfma_f32_16x16x32_bf16 v[64:67], v[128:131], v[166:169], v[64:67]
	v_mfma_f32_16x16x32_bf16 v[154:157], v[120:123], v[174:177], v[154:157]
	v_mfma_f32_16x16x32_bf16 v[52:55], v[128:131], v[174:177], v[52:55]
	v_mfma_f32_16x16x32_bf16 v[150:153], v[120:123], v[194:197], v[150:153]
	v_mfma_f32_16x16x32_bf16 v[48:51], v[128:131], v[194:197], v[48:51]
	v_mfma_f32_16x16x32_bf16 v[92:95], v[120:123], v[210:213], v[92:95]
	v_mfma_f32_16x16x32_bf16 v[68:71], v[128:131], v[210:213], v[68:71]
	v_mfma_f32_16x16x32_bf16 v[8:11], v[124:127], v[170:173], v[8:11]
	v_mfma_f32_16x16x32_bf16 v[64:67], v[132:135], v[170:173], v[64:67]
	v_mfma_f32_16x16x32_bf16 v[154:157], v[124:127], v[178:181], v[154:157]
	v_mfma_f32_16x16x32_bf16 v[52:55], v[132:135], v[178:181], v[52:55]
	v_mfma_f32_16x16x32_bf16 v[150:153], v[124:127], v[206:209], v[150:153]
	v_mfma_f32_16x16x32_bf16 v[48:51], v[132:135], v[206:209], v[48:51]
	v_mfma_f32_16x16x32_bf16 v[92:95], v[124:127], v[214:217], v[92:95]
	v_mfma_f32_16x16x32_bf16 v[68:71], v[132:135], v[214:217], v[68:71]
	s_barrier
; #define PG8_STAGE(bufoff, gbase, voff) do { _Pragma("unroll") for (int _i = 0; _i < 2; ++_i) \
;         __builtin_amdgcn_global_load_lds((const unsigned*)((const char*)(gbase) + (voff)[_i]), (PG8_LAS unsigned*)(lds + (bufoff) + ldsw + _i * 8192), 16, 0, 0); } while (0)
; #define PG8_LDA(dst, b, h) do { _Pragma("unroll") for (int m = 0; m < 4; ++m) _Pragma("unroll") for (int k = 0; k < 2; ++k) dst[m][k] = *(const PG8_LAS bf16x8*)(lds + PG8_SA(b, h) + aoff + m * 2048 + k * 1024); } while (0)
; #define PG8_MMA(ai, bj, At, Bt) do { __builtin_amdgcn_s_setprio(1); _Pragma("unroll") for (int m = 0; m < 4; ++m) _Pragma("unroll") for (int n = 0; n < 2; ++n) _Pragma("unroll") for (int k = 0; k < 2; ++k) \
;         acc[ai][bj][m][n] = __builtin_amdgcn_mfma_f32_16x16x32_bf16(Bt[n][k], At[m][k], acc[ai][bj][m][n], 0, 0, 0); __builtin_amdgcn_s_setprio(0); } while (0)
; #define PG8_WAIT_V(n) asm volatile("s_waitcnt vmcnt(" #n ")" ::: "memory")
; #define PG8_WAIT_L(n) asm volatile("s_waitcnt lgkmcnt(" #n ")" ::: "memory")
; #define PG8_BAR __builtin_amdgcn_s_barrier()
; #define PG8_SCHED __builtin_amdgcn_sched_barrier(0)
;     ...
;         for (int t = 0; t < nt; t += 2) {
;             const bool last = (t == nt - 2);
;             const char* a1 = cA + (size_t)(t + 1) * kstep;
;             const char* a2 = last ? nA : cA + (size_t)(t + 2) * kstep; const char* b2 = last ? nB : cB + (size_t)(t + 2) * kstep;
;             const char* a3 = a2 + kstep; const char* b3 = b2 + kstep;
;     ...
;             PG8_LDA(At, 1, 1); PG8_STAGE(PG8_SB(1, 0), b3, voffB); PG8_STAGE(PG8_SB(1, 1), b3 + hstep, voffB); PG8_STAGE(PG8_SA(1, 0), a3, voffA);
;             PG8_WAIT_V(8); PG8_WAIT_L(0); PG8_BAR; PG8_MMA(1, 0, At, B0); PG8_MMA(1, 1, At, B1); PG8_BAR; PG8_SCHED;
	s_setprio 0
	s_add_i32 s12, s48, s0
	v_lshl_add_u64 v[136:137], v[198:199], 0, s[66:67]
	s_mov_b32 m0, s12
	ds_read_b128 v[166:169], v222 offset:49152
	ds_read_b128 v[170:173], v222 offset:50176
	ds_read_b128 v[174:177], v222 offset:51200
	ds_read_b128 v[178:181], v222 offset:52224
	ds_read_b128 v[194:197], v222 offset:53248
	ds_read_b128 v[206:209], v222 offset:54272
	ds_read_b128 v[210:213], v222 offset:55296
	ds_read_b128 v[214:217], v222 offset:56320
	global_load_lds_dwordx4 v[136:137], off
	s_add_i32 m0, s12, 0x2000
	s_add_u32 s10, s10, 0x80080
	v_lshl_add_u64 v[136:137], v[218:219], 0, s[66:67]
	s_addc_u32 s11, s11, 0
	s_add_i32 s12, s49, s0
	global_load_lds_dwordx4 v[136:137], off
	s_mov_b32 m0, s12
	v_lshl_add_u64 v[136:137], s[10:11], 0, v[186:187]
	global_load_lds_dwordx4 v[136:137], off
	s_add_i32 m0, s12, 0x2000
	v_lshl_add_u64 v[136:137], s[10:11], 0, v[182:183]
	global_load_lds_dwordx4 v[136:137], off
	v_lshl_add_u64 v[136:137], v[224:225], 0, s[66:67]
	s_mov_b32 m0, s42
	s_nop 0
	global_load_lds_dwordx4 v[136:137], off
	v_lshl_add_u64 v[136:137], v[232:233], 0, s[66:67]
	s_mov_b32 m0, s55
	s_nop 0
	global_load_lds_dwordx4 v[136:137], off
	s_waitcnt vmcnt(8) lgkmcnt(0)
	s_setprio 1
	s_barrier
	v_mfma_f32_16x16x32_bf16 v[146:149], v[104:107], v[166:169], v[146:149]
	v_mfma_f32_16x16x32_bf16 v[44:47], v[112:115], v[166:169], v[44:47]
	v_mfma_f32_16x16x32_bf16 v[142:145], v[104:107], v[174:177], v[142:145]
	v_mfma_f32_16x16x32_bf16 v[40:43], v[112:115], v[174:177], v[40:43]
	v_mfma_f32_16x16x32_bf16 v[136:139], v[104:107], v[194:197], v[138:141]
	v_mfma_f32_16x16x32_bf16 v[36:39], v[112:115], v[194:197], v[36:39]
	v_mfma_f32_16x16x32_bf16 v[80:83], v[104:107], v[210:213], v[80:83]
	v_mfma_f32_16x16x32_bf16 v[20:23], v[112:115], v[210:213], v[20:23]
	v_mfma_f32_16x16x32_bf16 v[146:149], v[108:111], v[170:173], v[146:149]
	v_mfma_f32_16x16x32_bf16 v[44:47], v[116:119], v[170:173], v[44:47]
	v_mfma_f32_16x16x32_bf16 v[142:145], v[108:111], v[178:181], v[142:145]
	v_mfma_f32_16x16x32_bf16 v[40:43], v[116:119], v[178:181], v[40:43]
	v_mfma_f32_16x16x32_bf16 v[138:141], v[108:111], v[206:209], v[136:139]
	v_mfma_f32_16x16x32_bf16 v[36:39], v[116:119], v[206:209], v[36:39]
	v_mfma_f32_16x16x32_bf16 v[80:83], v[108:111], v[214:217], v[80:83]
	v_mfma_f32_16x16x32_bf16 v[20:23], v[116:119], v[214:217], v[20:23]
	v_mfma_f32_16x16x32_bf16 v[100:103], v[120:123], v[166:169], v[100:103]
	v_mfma_f32_16x16x32_bf16 v[32:35], v[128:131], v[166:169], v[32:35]
	v_mfma_f32_16x16x32_bf16 v[88:91], v[120:123], v[174:177], v[88:91]
	v_mfma_f32_16x16x32_bf16 v[28:31], v[128:131], v[174:177], v[28:31]
	v_mfma_f32_16x16x32_bf16 v[84:87], v[120:123], v[194:197], v[84:87]
	v_mfma_f32_16x16x32_bf16 v[24:27], v[128:131], v[194:197], v[24:27]
	v_mfma_f32_16x16x32_bf16 v[16:19], v[120:123], v[210:213], v[16:19]
	v_mfma_f32_16x16x32_bf16 v[12:15], v[128:131], v[210:213], v[12:15]
	v_mfma_f32_16x16x32_bf16 v[102:105], v[124:127], v[170:173], v[100:103]
	v_mfma_f32_16x16x32_bf16 v[32:35], v[132:135], v[170:173], v[32:35]
	v_mfma_f32_16x16x32_bf16 v[88:91], v[124:127], v[178:181], v[88:91]
	v_mfma_f32_16x16x32_bf16 v[28:31], v[132:135], v[178:181], v[28:31]
	v_mfma_f32_16x16x32_bf16 v[84:87], v[124:127], v[206:209], v[84:87]
	v_mfma_f32_16x16x32_bf16 v[24:27], v[132:135], v[206:209], v[24:27]
	v_mfma_f32_16x16x32_bf16 v[16:19], v[124:127], v[214:217], v[16:19]
	v_mfma_f32_16x16x32_bf16 v[12:15], v[132:135], v[214:217], v[12:15]
	s_barrier
	s_setprio 0
	s_add_i32 s97, s97, 2
	s_add_u32 s8, s8, 0x100
	s_addc_u32 s9, s9, 0
	s_add_u32 s83, s83, 0x100
	s_addc_u32 s89, s89, 0
	s_cmp_gt_u32 s97, 29
	s_cbranch_scc0 .LBB0_1086
	s_and_b64 vcc, exec, s[70:71]
	s_cbranch_vccz .LBB0_1089
	s_barrier

; #define PG8_STAGE(bufoff, gbase, voff) do { _Pragma("unroll") for (int _i = 0; _i < 2; ++_i) \
;         __builtin_amdgcn_global_load_lds((const unsigned*)((const char*)(gbase) + (voff)[_i]), (PG8_LAS unsigned*)(lds + (bufoff) + ldsw + _i * 8192), 16, 0, 0); } while (0)
; #define PG8_LDA(dst, b, h) do { _Pragma("unroll") for (int m = 0; m < 4; ++m) _Pragma("unroll") for (int k = 0; k < 2; ++k) dst[m][k] = *(const PG8_LAS bf16x8*)(lds + PG8_SA(b, h) + aoff + m * 2048 + k * 1024); } while (0)
; #define PG8_LDB(dst, b, h) do { _Pragma("unroll") for (int n = 0; n < 2; ++n) _Pragma("unroll") for (int k = 0; k < 2; ++k) dst[n][k] = *(const PG8_LAS bf16x8*)(lds + PG8_SB(b, h) + boff + n * 2048 + k * 1024); } while (0)
; #define PG8_MMA(ai, bj, At, Bt) do { __builtin_amdgcn_s_setprio(1); _Pragma("unroll") for (int m = 0; m < 4; ++m) _Pragma("unroll") for (int n = 0; n < 2; ++n) _Pragma("unroll") for (int k = 0; k < 2; ++k) \
;         acc[ai][bj][m][n] = __builtin_amdgcn_mfma_f32_16x16x32_bf16(Bt[n][k], At[m][k], acc[ai][bj][m][n], 0, 0, 0); __builtin_amdgcn_s_setprio(0); } while (0)
; #define PG8_WAIT_V(n) asm volatile("s_waitcnt vmcnt(" #n ")" ::: "memory")
; #define PG8_WAIT_L(n) asm volatile("s_waitcnt lgkmcnt(" #n ")" ::: "memory")
; #define PG8_BAR __builtin_amdgcn_s_barrier()
; #define PG8_SCHED __builtin_amdgcn_sched_barrier(0)
;     ...
;             PG8_LDB(B0, 0, 0); PG8_LDB(B1, 0, 1); PG8_SCHED; PG8_LDA(At, 0, 0); PG8_STAGE(PG8_SA(1, 1), a1 + hstep, voffA);
;             PG8_WAIT_V(8); PG8_WAIT_L(0); PG8_BAR; PG8_MMA(0, 0, At, B0); PG8_MMA(0, 1, At, B1); PG8_BAR; PG8_SCHED;
;             PG8_LDA(At, 0, 1); PG8_STAGE(PG8_SB(0, 0), b2, voffB); PG8_STAGE(PG8_SB(0, 1), b2 + hstep, voffB); PG8_STAGE(PG8_SA(0, 0), a2, voffA);
;             PG8_WAIT_V(8); PG8_WAIT_L(0); PG8_BAR; PG8_MMA(1, 0, At, B0); PG8_MMA(1, 1, At, B1); PG8_BAR; PG8_SCHED;
;             PG8_LDB(B0, 1, 0); PG8_LDB(B1, 1, 1); PG8_SCHED; PG8_LDA(At, 1, 0); PG8_STAGE(PG8_SA(0, 1), a2 + hstep, voffA);
;             PG8_WAIT_V(8); PG8_WAIT_L(0); PG8_BAR; PG8_MMA(0, 0, At, B0); PG8_MMA(0, 1, At, B1); PG8_BAR; PG8_SCHED;
;             PG8_LDA(At, 1, 1); PG8_STAGE(PG8_SB(1, 0), b3, voffB); PG8_STAGE(PG8_SB(1, 1), b3 + hstep, voffB); PG8_STAGE(PG8_SA(1, 0), a3, voffA);
;             PG8_WAIT_V(8); PG8_WAIT_L(0); PG8_BAR; PG8_MMA(1, 0, At, B0); PG8_MMA(1, 1, At, B1); PG8_BAR; PG8_SCHED;
.LBB0_1212:
	s_add_u32 s62, s60, 0x100
	s_addc_u32 s63, s61, 0
	s_add_i32 s48, 0, 0x10000
	s_cmpk_eq_i32 s79, 0x54
	s_cselect_b32 s71, s9, s63
	s_cselect_b32 s70, s8, s62
	s_cselect_b32 s69, s25, s78
	s_cselect_b32 s68, s24, s77
	s_add_i32 s81, 0, 0x14000
	ds_read_b128 v[108:111], v251
	ds_read_b128 v[112:115], v251 offset:1024
	ds_read_b128 v[128:131], v251 offset:2048
	ds_read_b128 v[136:139], v251 offset:3072
	ds_read_b128 v[148:151], v251 offset:16384
	ds_read_b128 v[152:155], v251 offset:17408
	ds_read_b128 v[156:159], v251 offset:18432
	ds_read_b128 v[160:163], v251 offset:19456
	v_lshl_add_u64 v[198:199], s[60:61], 0, v[196:197]
	s_add_i32 m0, s5, 0xc000
	ds_read_b128 v[164:167], v234
	ds_read_b128 v[168:171], v234 offset:1024
	ds_read_b128 v[172:175], v234 offset:2048
	ds_read_b128 v[176:179], v234 offset:3072
	ds_read_b128 v[180:183], v234 offset:4096
	ds_read_b128 v[184:187], v234 offset:5120
	ds_read_b128 v[206:209], v234 offset:6144
	ds_read_b128 v[210:213], v234 offset:7168
	global_load_lds_dwordx4 v[198:199], off
	s_add_i32 m0, s5, 0xe000
	v_lshl_add_u64 v[198:199], s[60:61], 0, v[194:195]
	global_load_lds_dwordx4 v[198:199], off
	s_waitcnt vmcnt(8) lgkmcnt(0)
	s_setprio 1
	s_barrier
	v_mfma_f32_16x16x32_bf16 v[144:147], v[108:111], v[164:167], v[144:147]
	v_mfma_f32_16x16x32_bf16 v[140:143], v[128:131], v[164:167], v[140:143]
	v_mfma_f32_16x16x32_bf16 v[120:123], v[108:111], v[172:175], v[120:123]
	v_mfma_f32_16x16x32_bf16 v[116:119], v[128:131], v[172:175], v[116:119]
	v_mfma_f32_16x16x32_bf16 v[96:99], v[108:111], v[180:183], v[96:99]
	v_mfma_f32_16x16x32_bf16 v[92:95], v[128:131], v[180:183], v[92:95]
	v_mfma_f32_16x16x32_bf16 v[80:83], v[108:111], v[206:209], v[80:83]
	v_mfma_f32_16x16x32_bf16 v[76:79], v[128:131], v[206:209], v[76:79]
	v_mfma_f32_16x16x32_bf16 v[144:147], v[112:115], v[168:171], v[144:147]
	v_mfma_f32_16x16x32_bf16 v[140:143], v[136:139], v[168:171], v[140:143]
	v_mfma_f32_16x16x32_bf16 v[120:123], v[112:115], v[176:179], v[120:123]
	v_mfma_f32_16x16x32_bf16 v[116:119], v[136:139], v[176:179], v[116:119]
	v_mfma_f32_16x16x32_bf16 v[96:99], v[112:115], v[184:187], v[96:99]
	v_mfma_f32_16x16x32_bf16 v[92:95], v[136:139], v[184:187], v[92:95]
	v_mfma_f32_16x16x32_bf16 v[80:83], v[112:115], v[210:213], v[80:83]
	v_mfma_f32_16x16x32_bf16 v[76:79], v[136:139], v[210:213], v[76:79]
	v_mfma_f32_16x16x32_bf16 v[132:135], v[148:151], v[164:167], v[132:135]
	v_mfma_f32_16x16x32_bf16 v[124:127], v[156:159], v[164:167], v[124:127]
	v_mfma_f32_16x16x32_bf16 v[104:107], v[148:151], v[172:175], v[104:107]
	v_mfma_f32_16x16x32_bf16 v[100:103], v[156:159], v[172:175], v[100:103]
	v_mfma_f32_16x16x32_bf16 v[88:91], v[148:151], v[180:183], v[88:91]
	v_mfma_f32_16x16x32_bf16 v[84:87], v[156:159], v[180:183], v[84:87]
	v_mfma_f32_16x16x32_bf16 v[72:75], v[148:151], v[206:209], v[72:75]
	v_mfma_f32_16x16x32_bf16 v[68:71], v[156:159], v[206:209], v[68:71]
	v_mfma_f32_16x16x32_bf16 v[132:135], v[152:155], v[168:171], v[132:135]
	v_mfma_f32_16x16x32_bf16 v[124:127], v[160:163], v[168:171], v[124:127]
	v_mfma_f32_16x16x32_bf16 v[104:107], v[152:155], v[176:179], v[104:107]
	v_mfma_f32_16x16x32_bf16 v[100:103], v[160:163], v[176:179], v[100:103]
	v_mfma_f32_16x16x32_bf16 v[88:91], v[152:155], v[184:187], v[88:91]
	v_mfma_f32_16x16x32_bf16 v[84:87], v[160:163], v[184:187], v[84:87]
	v_mfma_f32_16x16x32_bf16 v[72:75], v[152:155], v[210:213], v[72:75]
	v_mfma_f32_16x16x32_bf16 v[68:71], v[160:163], v[210:213], v[68:71]
	s_barrier
	s_setprio 0
	s_add_i32 s48, s48, s4
	v_lshl_add_u64 v[198:199], s[68:69], 0, v[200:201]
	s_mov_b32 m0, s48
	ds_read_b128 v[164:167], v234 offset:16384
	ds_read_b128 v[168:171], v234 offset:17408
	ds_read_b128 v[172:175], v234 offset:18432
	ds_read_b128 v[176:179], v234 offset:19456
	ds_read_b128 v[180:183], v234 offset:20480
	ds_read_b128 v[184:187], v234 offset:21504
	ds_read_b128 v[206:209], v234 offset:22528
	ds_read_b128 v[210:213], v234 offset:23552
	global_load_lds_dwordx4 v[198:199], off
	s_add_i32 m0, s48, 0x2000
	s_add_u32 s48, s68, 0x160000
	v_lshl_add_u64 v[214:215], s[68:69], 0, v[188:189]
	s_addc_u32 s49, s69, 0
	s_add_i32 s60, s81, s4
	global_load_lds_dwordx4 v[214:215], off
	v_lshl_add_u64 v[216:217], s[48:49], 0, v[200:201]
	s_mov_b32 m0, s60
	v_lshl_add_u64 v[218:219], s[70:71], 0, v[190:191]
	global_load_lds_dwordx4 v[216:217], off
	s_add_i32 m0, s60, 0x2000
	v_lshl_add_u64 v[216:217], s[48:49], 0, v[188:189]
	global_load_lds_dwordx4 v[216:217], off
	s_mov_b32 m0, s5
	v_lshl_add_u64 v[216:217], s[70:71], 0, v[192:193]
	global_load_lds_dwordx4 v[216:217], off
	s_mov_b32 m0, s20
	s_nop 0
	global_load_lds_dwordx4 v[218:219], off
	s_waitcnt vmcnt(8) lgkmcnt(0)
	s_setprio 1
	s_barrier
; #define PG8_STAGE(bufoff, gbase, voff) do { _Pragma("unroll") for (int _i = 0; _i < 2; ++_i) \
;         __builtin_amdgcn_global_load_lds((const unsigned*)((const char*)(gbase) + (voff)[_i]), (PG8_LAS unsigned*)(lds + (bufoff) + ldsw + _i * 8192), 16, 0, 0); } while (0)
; #define PG8_LDA(dst, b, h) do { _Pragma("unroll") for (int m = 0; m < 4; ++m) _Pragma("unroll") for (int k = 0; k < 2; ++k) dst[m][k] = *(const PG8_LAS bf16x8*)(lds + PG8_SA(b, h) + aoff + m * 2048 + k * 1024); } while (0)
; #define PG8_LDB(dst, b, h) do { _Pragma("unroll") for (int n = 0; n < 2; ++n) _Pragma("unroll") for (int k = 0; k < 2; ++k) dst[n][k] = *(const PG8_LAS bf16x8*)(lds + PG8_SB(b, h) + boff + n * 2048 + k * 1024); } while (0)
; #define PG8_MMA(ai, bj, At, Bt) do { __builtin_amdgcn_s_setprio(1); _Pragma("unroll") for (int m = 0; m < 4; ++m) _Pragma("unroll") for (int n = 0; n < 2; ++n) _Pragma("unroll") for (int k = 0; k < 2; ++k) \
;         acc[ai][bj][m][n] = __builtin_amdgcn_mfma_f32_16x16x32_bf16(Bt[n][k], At[m][k], acc[ai][bj][m][n], 0, 0, 0); __builtin_amdgcn_s_setprio(0); } while (0)
; #define PG8_WAIT_V(n) asm volatile("s_waitcnt vmcnt(" #n ")" ::: "memory")
; #define PG8_WAIT_L(n) asm volatile("s_waitcnt lgkmcnt(" #n ")" ::: "memory")
; #define PG8_BAR __builtin_amdgcn_s_barrier()
; #define PG8_SCHED __builtin_amdgcn_sched_barrier(0)
;     ...
;             PG8_WAIT_V(8); PG8_WAIT_L(0); PG8_BAR; PG8_MMA(1, 0, At, B0); PG8_MMA(1, 1, At, B1); PG8_BAR; PG8_SCHED;
;             PG8_LDB(B0, 1, 0); PG8_LDB(B1, 1, 1); PG8_SCHED; PG8_LDA(At, 1, 0); PG8_STAGE(PG8_SA(0, 1), a2 + hstep, voffA);
;             PG8_WAIT_V(8); PG8_WAIT_L(0); PG8_BAR; PG8_MMA(0, 0, At, B0); PG8_MMA(0, 1, At, B1); PG8_BAR; PG8_SCHED;
;             PG8_LDA(At, 1, 1); PG8_STAGE(PG8_SB(1, 0), b3, voffB); PG8_STAGE(PG8_SB(1, 1), b3 + hstep, voffB); PG8_STAGE(PG8_SA(1, 0), a3, voffA);
	v_mfma_f32_16x16x32_bf16 v[64:67], v[108:111], v[164:167], v[64:67]
	v_mfma_f32_16x16x32_bf16 v[60:63], v[128:131], v[164:167], v[60:63]
	v_mfma_f32_16x16x32_bf16 v[48:51], v[108:111], v[172:175], v[48:51]
	v_mfma_f32_16x16x32_bf16 v[44:47], v[128:131], v[172:175], v[44:47]
	v_mfma_f32_16x16x32_bf16 v[32:35], v[108:111], v[180:183], v[32:35]
	v_mfma_f32_16x16x32_bf16 v[28:31], v[128:131], v[180:183], v[28:31]
	v_mfma_f32_16x16x32_bf16 v[16:19], v[108:111], v[206:209], v[16:19]
	v_mfma_f32_16x16x32_bf16 v[12:15], v[128:131], v[206:209], v[12:15]
	v_mfma_f32_16x16x32_bf16 v[64:67], v[112:115], v[168:171], v[64:67]
	v_mfma_f32_16x16x32_bf16 v[60:63], v[136:139], v[168:171], v[60:63]
	v_mfma_f32_16x16x32_bf16 v[48:51], v[112:115], v[176:179], v[48:51]
	v_mfma_f32_16x16x32_bf16 v[44:47], v[136:139], v[176:179], v[44:47]
	v_mfma_f32_16x16x32_bf16 v[32:35], v[112:115], v[184:187], v[32:35]
	v_mfma_f32_16x16x32_bf16 v[28:31], v[136:139], v[184:187], v[28:31]
	v_mfma_f32_16x16x32_bf16 v[16:19], v[112:115], v[210:213], v[16:19]
	v_mfma_f32_16x16x32_bf16 v[12:15], v[136:139], v[210:213], v[12:15]
	v_mfma_f32_16x16x32_bf16 v[56:59], v[148:151], v[164:167], v[56:59]
	v_mfma_f32_16x16x32_bf16 v[52:55], v[156:159], v[164:167], v[52:55]
	v_mfma_f32_16x16x32_bf16 v[40:43], v[148:151], v[172:175], v[40:43]
	v_mfma_f32_16x16x32_bf16 v[36:39], v[156:159], v[172:175], v[36:39]
	v_mfma_f32_16x16x32_bf16 v[24:27], v[148:151], v[180:183], v[24:27]
	v_mfma_f32_16x16x32_bf16 v[20:23], v[156:159], v[180:183], v[20:23]
	v_mfma_f32_16x16x32_bf16 v[8:11], v[148:151], v[206:209], v[8:11]
	v_mfma_f32_16x16x32_bf16 v[4:7], v[156:159], v[206:209], v[4:7]
	v_mfma_f32_16x16x32_bf16 v[56:59], v[152:155], v[168:171], v[56:59]
	v_mfma_f32_16x16x32_bf16 v[52:55], v[160:163], v[168:171], v[52:55]
	v_mfma_f32_16x16x32_bf16 v[40:43], v[152:155], v[176:179], v[40:43]
	v_mfma_f32_16x16x32_bf16 v[36:39], v[160:163], v[176:179], v[36:39]
	v_mfma_f32_16x16x32_bf16 v[24:27], v[152:155], v[184:187], v[24:27]
	v_mfma_f32_16x16x32_bf16 v[20:23], v[160:163], v[184:187], v[20:23]
	v_mfma_f32_16x16x32_bf16 v[8:11], v[152:155], v[210:213], v[8:11]
	v_mfma_f32_16x16x32_bf16 v[4:7], v[160:163], v[210:213], v[4:7]
	s_barrier
	s_setprio 0
	s_add_i32 s60, 0, 0x18000
	s_add_i32 s61, 0, 0x1c000
	ds_read_b128 v[108:111], v251 offset:32768
	ds_read_b128 v[112:115], v251 offset:33792
	ds_read_b128 v[128:131], v251 offset:34816
	ds_read_b128 v[136:139], v251 offset:35840
	ds_read_b128 v[148:151], v251 offset:49152
	ds_read_b128 v[152:155], v251 offset:50176
	ds_read_b128 v[156:159], v251 offset:51200
	ds_read_b128 v[160:163], v251 offset:52224
	s_add_u32 s48, s70, 0x160000
	s_addc_u32 s49, s71, 0
	s_mov_b32 m0, s21
	v_lshl_add_u64 v[220:221], s[48:49], 0, v[192:193]
	ds_read_b128 v[164:167], v234 offset:32768
	ds_read_b128 v[168:171], v234 offset:33792
	ds_read_b128 v[172:175], v234 offset:34816
	ds_read_b128 v[176:179], v234 offset:35840
	ds_read_b128 v[180:183], v234 offset:36864
	ds_read_b128 v[184:187], v234 offset:37888
	ds_read_b128 v[206:209], v234 offset:38912
	ds_read_b128 v[210:213], v234 offset:39936
	global_load_lds_dwordx4 v[220:221], off
	s_mov_b32 m0, s23
	v_lshl_add_u64 v[220:221], s[48:49], 0, v[190:191]
	global_load_lds_dwordx4 v[220:221], off
	s_waitcnt vmcnt(8) lgkmcnt(0)
	s_setprio 1
	s_barrier
	v_mfma_f32_16x16x32_bf16 v[144:147], v[108:111], v[164:167], v[144:147]
	v_mfma_f32_16x16x32_bf16 v[140:143], v[128:131], v[164:167], v[140:143]
	v_mfma_f32_16x16x32_bf16 v[120:123], v[108:111], v[172:175], v[120:123]
	v_mfma_f32_16x16x32_bf16 v[116:119], v[128:131], v[172:175], v[116:119]
	v_mfma_f32_16x16x32_bf16 v[96:99], v[108:111], v[180:183], v[96:99]
	v_mfma_f32_16x16x32_bf16 v[92:95], v[128:131], v[180:183], v[92:95]
	v_mfma_f32_16x16x32_bf16 v[80:83], v[108:111], v[206:209], v[80:83]
	v_mfma_f32_16x16x32_bf16 v[76:79], v[128:131], v[206:209], v[76:79]
	v_mfma_f32_16x16x32_bf16 v[144:147], v[112:115], v[168:171], v[144:147]
	v_mfma_f32_16x16x32_bf16 v[140:143], v[136:139], v[168:171], v[140:143]
	v_mfma_f32_16x16x32_bf16 v[120:123], v[112:115], v[176:179], v[120:123]
	v_mfma_f32_16x16x32_bf16 v[116:119], v[136:139], v[176:179], v[116:119]
	v_mfma_f32_16x16x32_bf16 v[96:99], v[112:115], v[184:187], v[96:99]
	v_mfma_f32_16x16x32_bf16 v[92:95], v[136:139], v[184:187], v[92:95]
	v_mfma_f32_16x16x32_bf16 v[80:83], v[112:115], v[210:213], v[80:83]
	v_mfma_f32_16x16x32_bf16 v[76:79], v[136:139], v[210:213], v[76:79]
	v_mfma_f32_16x16x32_bf16 v[132:135], v[148:151], v[164:167], v[132:135]
	v_mfma_f32_16x16x32_bf16 v[124:127], v[156:159], v[164:167], v[124:127]
	v_mfma_f32_16x16x32_bf16 v[104:107], v[148:151], v[172:175], v[104:107]
	v_mfma_f32_16x16x32_bf16 v[100:103], v[156:159], v[172:175], v[100:103]
	v_mfma_f32_16x16x32_bf16 v[88:91], v[148:151], v[180:183], v[88:91]
	v_mfma_f32_16x16x32_bf16 v[84:87], v[156:159], v[180:183], v[84:87]
	v_mfma_f32_16x16x32_bf16 v[72:75], v[148:151], v[206:209], v[72:75]
	v_mfma_f32_16x16x32_bf16 v[68:71], v[156:159], v[206:209], v[68:71]
	v_mfma_f32_16x16x32_bf16 v[132:135], v[152:155], v[168:171], v[132:135]
	v_mfma_f32_16x16x32_bf16 v[124:127], v[160:163], v[168:171], v[124:127]
	v_mfma_f32_16x16x32_bf16 v[104:107], v[152:155], v[176:179], v[104:107]
	v_mfma_f32_16x16x32_bf16 v[100:103], v[160:163], v[176:179], v[100:103]
	v_mfma_f32_16x16x32_bf16 v[88:91], v[152:155], v[184:187], v[88:91]
	v_mfma_f32_16x16x32_bf16 v[84:87], v[160:163], v[184:187], v[84:87]
	v_mfma_f32_16x16x32_bf16 v[72:75], v[152:155], v[210:213], v[72:75]
	v_mfma_f32_16x16x32_bf16 v[68:71], v[160:163], v[210:213], v[68:71]
	s_barrier
; #define PG8_STAGE(bufoff, gbase, voff) do { _Pragma("unroll") for (int _i = 0; _i < 2; ++_i) \
;         __builtin_amdgcn_global_load_lds((const unsigned*)((const char*)(gbase) + (voff)[_i]), (PG8_LAS unsigned*)(lds + (bufoff) + ldsw + _i * 8192), 16, 0, 0); } while (0)
; #define PG8_LDA(dst, b, h) do { _Pragma("unroll") for (int m = 0; m < 4; ++m) _Pragma("unroll") for (int k = 0; k < 2; ++k) dst[m][k] = *(const PG8_LAS bf16x8*)(lds + PG8_SA(b, h) + aoff + m * 2048 + k * 1024); } while (0)
; #define PG8_MMA(ai, bj, At, Bt) do { __builtin_amdgcn_s_setprio(1); _Pragma("unroll") for (int m = 0; m < 4; ++m) _Pragma("unroll") for (int n = 0; n < 2; ++n) _Pragma("unroll") for (int k = 0; k < 2; ++k) \
;         acc[ai][bj][m][n] = __builtin_amdgcn_mfma_f32_16x16x32_bf16(Bt[n][k], At[m][k], acc[ai][bj][m][n], 0, 0, 0); __builtin_amdgcn_s_setprio(0); } while (0)
; #define PG8_WAIT_V(n) asm volatile("s_waitcnt vmcnt(" #n ")" ::: "memory")
; #define PG8_WAIT_L(n) asm volatile("s_waitcnt lgkmcnt(" #n ")" ::: "memory")
; #define PG8_BAR __builtin_amdgcn_s_barrier()
; #define PG8_SCHED __builtin_amdgcn_sched_barrier(0)
;     ...
;         for (int t = 0; t < nt; t += 2) {
;             const bool last = (t == nt - 2);
;             const char* a1 = cA + (size_t)(t + 1) * kstep;
;             const char* a2 = last ? nA : cA + (size_t)(t + 2) * kstep; const char* b2 = last ? nB : cB + (size_t)(t + 2) * kstep;
;             const char* a3 = a2 + kstep; const char* b3 = b2 + kstep;
;     ...
;             PG8_LDA(At, 1, 1); PG8_STAGE(PG8_SB(1, 0), b3, voffB); PG8_STAGE(PG8_SB(1, 1), b3 + hstep, voffB); PG8_STAGE(PG8_SA(1, 0), a3, voffA);
;             PG8_WAIT_V(8); PG8_WAIT_L(0); PG8_BAR; PG8_MMA(1, 0, At, B0); PG8_MMA(1, 1, At, B1); PG8_BAR; PG8_SCHED;
	s_setprio 0
	s_add_i32 s48, s60, s4
	v_lshl_add_u64 v[198:199], v[198:199], 0, s[66:67]
	s_mov_b32 m0, s48
	ds_read_b128 v[164:167], v234 offset:49152
	ds_read_b128 v[168:171], v234 offset:50176
	ds_read_b128 v[172:175], v234 offset:51200
	ds_read_b128 v[176:179], v234 offset:52224
	ds_read_b128 v[180:183], v234 offset:53248
	ds_read_b128 v[184:187], v234 offset:54272
	ds_read_b128 v[206:209], v234 offset:55296
	ds_read_b128 v[210:213], v234 offset:56320
	global_load_lds_dwordx4 v[198:199], off
	s_add_i32 m0, s48, 0x2000
	s_add_u32 s48, s68, 0x160080
	v_lshl_add_u64 v[198:199], v[214:215], 0, s[66:67]
	s_addc_u32 s49, s69, 0
	s_add_i32 s60, s61, s4
	global_load_lds_dwordx4 v[198:199], off
	s_mov_b32 m0, s60
	v_lshl_add_u64 v[198:199], s[48:49], 0, v[200:201]
	global_load_lds_dwordx4 v[198:199], off
	s_add_i32 m0, s60, 0x2000
	v_lshl_add_u64 v[198:199], s[48:49], 0, v[188:189]
	global_load_lds_dwordx4 v[198:199], off
	v_lshl_add_u64 v[198:199], v[216:217], 0, s[66:67]
	s_mov_b32 m0, s54
	s_nop 0
	global_load_lds_dwordx4 v[198:199], off
	v_lshl_add_u64 v[198:199], v[218:219], 0, s[66:67]
	s_mov_b32 m0, s55
	s_nop 0
	global_load_lds_dwordx4 v[198:199], off
	s_waitcnt vmcnt(8) lgkmcnt(0)
	s_setprio 1
	s_barrier
	v_mfma_f32_16x16x32_bf16 v[64:67], v[108:111], v[164:167], v[64:67]
	v_mfma_f32_16x16x32_bf16 v[60:63], v[128:131], v[164:167], v[60:63]
	v_mfma_f32_16x16x32_bf16 v[48:51], v[108:111], v[172:175], v[48:51]
	v_mfma_f32_16x16x32_bf16 v[44:47], v[128:131], v[172:175], v[44:47]
	v_mfma_f32_16x16x32_bf16 v[32:35], v[108:111], v[180:183], v[32:35]
	v_mfma_f32_16x16x32_bf16 v[28:31], v[128:131], v[180:183], v[28:31]
	v_mfma_f32_16x16x32_bf16 v[16:19], v[108:111], v[206:209], v[16:19]
	v_mfma_f32_16x16x32_bf16 v[12:15], v[128:131], v[206:209], v[12:15]
	v_mfma_f32_16x16x32_bf16 v[64:67], v[112:115], v[168:171], v[64:67]
	v_mfma_f32_16x16x32_bf16 v[60:63], v[136:139], v[168:171], v[60:63]
	v_mfma_f32_16x16x32_bf16 v[48:51], v[112:115], v[176:179], v[48:51]
	v_mfma_f32_16x16x32_bf16 v[44:47], v[136:139], v[176:179], v[44:47]
	v_mfma_f32_16x16x32_bf16 v[32:35], v[112:115], v[184:187], v[32:35]
	v_mfma_f32_16x16x32_bf16 v[28:31], v[136:139], v[184:187], v[28:31]
	v_mfma_f32_16x16x32_bf16 v[16:19], v[112:115], v[210:213], v[16:19]
	v_mfma_f32_16x16x32_bf16 v[12:15], v[136:139], v[210:213], v[12:15]
	v_mfma_f32_16x16x32_bf16 v[56:59], v[148:151], v[164:167], v[56:59]
	v_mfma_f32_16x16x32_bf16 v[52:55], v[156:159], v[164:167], v[52:55]
	v_mfma_f32_16x16x32_bf16 v[40:43], v[148:151], v[172:175], v[40:43]
	v_mfma_f32_16x16x32_bf16 v[36:39], v[156:159], v[172:175], v[36:39]
	v_mfma_f32_16x16x32_bf16 v[24:27], v[148:151], v[180:183], v[24:27]
	v_mfma_f32_16x16x32_bf16 v[20:23], v[156:159], v[180:183], v[20:23]
	v_mfma_f32_16x16x32_bf16 v[8:11], v[148:151], v[206:209], v[8:11]
	v_mfma_f32_16x16x32_bf16 v[4:7], v[156:159], v[206:209], v[4:7]
	v_mfma_f32_16x16x32_bf16 v[56:59], v[152:155], v[168:171], v[56:59]
	v_mfma_f32_16x16x32_bf16 v[52:55], v[160:163], v[168:171], v[52:55]
	v_mfma_f32_16x16x32_bf16 v[40:43], v[152:155], v[176:179], v[40:43]
	v_mfma_f32_16x16x32_bf16 v[36:39], v[160:163], v[176:179], v[36:39]
	v_mfma_f32_16x16x32_bf16 v[24:27], v[152:155], v[184:187], v[24:27]
	v_mfma_f32_16x16x32_bf16 v[20:23], v[160:163], v[184:187], v[20:23]
	v_mfma_f32_16x16x32_bf16 v[8:11], v[152:155], v[210:213], v[8:11]
	v_mfma_f32_16x16x32_bf16 v[4:7], v[160:163], v[210:213], v[4:7]
	s_barrier
	s_setprio 0
	s_add_i32 s79, s79, 2
	s_add_u32 s77, s77, 0x100
	s_addc_u32 s78, s78, 0
	s_cmpk_gt_u32 s79, 0x55
	s_mov_b64 s[60:61], s[62:63]
	s_cbranch_scc0 .LBB0_1212
	s_and_b64 vcc, exec, s[12:13]
	s_cbranch_vccz .LBB0_1215
	s_barrier

; #define PG8_STAGE(bufoff, gbase, voff) do { _Pragma("unroll") for (int _i = 0; _i < 2; ++_i) \
;         __builtin_amdgcn_global_load_lds((const unsigned*)((const char*)(gbase) + (voff)[_i]), (PG8_LAS unsigned*)(lds + (bufoff) + ldsw + _i * 8192), 16, 0, 0); } while (0)
; #define PG8_LDA(dst, b, h) do { _Pragma("unroll") for (int m = 0; m < 4; ++m) _Pragma("unroll") for (int k = 0; k < 2; ++k) dst[m][k] = *(const PG8_LAS bf16x8*)(lds + PG8_SA(b, h) + aoff + m * 2048 + k * 1024); } while (0)
; #define PG8_LDB(dst, b, h) do { _Pragma("unroll") for (int n = 0; n < 2; ++n) _Pragma("unroll") for (int k = 0; k < 2; ++k) dst[n][k] = *(const PG8_LAS bf16x8*)(lds + PG8_SB(b, h) + boff + n * 2048 + k * 1024); } while (0)
; #define PG8_MMA(ai, bj, At, Bt) do { __builtin_amdgcn_s_setprio(1); _Pragma("unroll") for (int m = 0; m < 4; ++m) _Pragma("unroll") for (int n = 0; n < 2; ++n) _Pragma("unroll") for (int k = 0; k < 2; ++k) \
;         acc[ai][bj][m][n] = __builtin_amdgcn_mfma_f32_16x16x32_bf16(Bt[n][k], At[m][k], acc[ai][bj][m][n], 0, 0, 0); __builtin_amdgcn_s_setprio(0); } while (0)
; #define PG8_WAIT_V(n) asm volatile("s_waitcnt vmcnt(" #n ")" ::: "memory")
; #define PG8_WAIT_L(n) asm volatile("s_waitcnt lgkmcnt(" #n ")" ::: "memory")
; #define PG8_BAR __builtin_amdgcn_s_barrier()
; #define PG8_SCHED __builtin_amdgcn_sched_barrier(0)
;     ...
;             PG8_LDB(B0, 0, 0); PG8_LDB(B1, 0, 1); PG8_SCHED; PG8_LDA(At, 0, 0); PG8_STAGE(PG8_SA(1, 1), a1 + hstep, voffA);
;             PG8_WAIT_V(8); PG8_WAIT_L(0); PG8_BAR; PG8_MMA(0, 0, At, B0); PG8_MMA(0, 1, At, B1); PG8_BAR; PG8_SCHED;
;             PG8_LDA(At, 0, 1); PG8_STAGE(PG8_SB(0, 0), b2, voffB); PG8_STAGE(PG8_SB(0, 1), b2 + hstep, voffB); PG8_STAGE(PG8_SA(0, 0), a2, voffA);
;             PG8_WAIT_V(8); PG8_WAIT_L(0); PG8_BAR; PG8_MMA(1, 0, At, B0); PG8_MMA(1, 1, At, B1); PG8_BAR; PG8_SCHED;
;             PG8_LDB(B0, 1, 0); PG8_LDB(B1, 1, 1); PG8_SCHED; PG8_LDA(At, 1, 0); PG8_STAGE(PG8_SA(0, 1), a2 + hstep, voffA);
;             PG8_WAIT_V(8); PG8_WAIT_L(0); PG8_BAR; PG8_MMA(0, 0, At, B0); PG8_MMA(0, 1, At, B1); PG8_BAR; PG8_SCHED;
;             PG8_LDA(At, 1, 1); PG8_STAGE(PG8_SB(1, 0), b3, voffB); PG8_STAGE(PG8_SB(1, 1), b3 + hstep, voffB); PG8_STAGE(PG8_SA(1, 0), a3, voffA);
;             PG8_WAIT_V(8); PG8_WAIT_L(0); PG8_BAR; PG8_MMA(1, 0, At, B0); PG8_MMA(1, 1, At, B1); PG8_BAR; PG8_SCHED;
.LBB0_1254:
	s_add_u32 s60, s50, 0x100
	s_addc_u32 s61, s51, 0
	s_add_i32 s48, 0, 0x10000
	s_cmpk_eq_i32 s77, 0x54
	s_cselect_b32 s69, s7, s61
	s_cselect_b32 s68, s6, s60
	s_cselect_b32 s63, s25, s76
	s_cselect_b32 s62, s24, s75
	s_add_i32 s78, 0, 0x14000
	ds_read_b128 v[108:111], v251
	ds_read_b128 v[112:115], v251 offset:1024
	ds_read_b128 v[128:131], v251 offset:2048
	ds_read_b128 v[136:139], v251 offset:3072
	ds_read_b128 v[148:151], v251 offset:16384
	ds_read_b128 v[152:155], v251 offset:17408
	ds_read_b128 v[156:159], v251 offset:18432
	ds_read_b128 v[160:163], v251 offset:19456
	v_lshl_add_u64 v[198:199], s[50:51], 0, v[196:197]
	s_add_i32 m0, s21, 0xc000
	ds_read_b128 v[164:167], v234
	ds_read_b128 v[168:171], v234 offset:1024
	ds_read_b128 v[172:175], v234 offset:2048
	ds_read_b128 v[176:179], v234 offset:3072
	ds_read_b128 v[180:183], v234 offset:4096
	ds_read_b128 v[184:187], v234 offset:5120
	ds_read_b128 v[206:209], v234 offset:6144
	ds_read_b128 v[210:213], v234 offset:7168
	global_load_lds_dwordx4 v[198:199], off
	s_add_i32 m0, s21, 0xe000
	v_lshl_add_u64 v[198:199], s[50:51], 0, v[194:195]
	global_load_lds_dwordx4 v[198:199], off
	s_waitcnt vmcnt(8) lgkmcnt(0)
	s_setprio 1
	s_barrier
	v_mfma_f32_16x16x32_bf16 v[144:147], v[108:111], v[164:167], v[144:147]
	v_mfma_f32_16x16x32_bf16 v[140:143], v[128:131], v[164:167], v[140:143]
	v_mfma_f32_16x16x32_bf16 v[120:123], v[108:111], v[172:175], v[120:123]
	v_mfma_f32_16x16x32_bf16 v[116:119], v[128:131], v[172:175], v[116:119]
	v_mfma_f32_16x16x32_bf16 v[96:99], v[108:111], v[180:183], v[96:99]
	v_mfma_f32_16x16x32_bf16 v[92:95], v[128:131], v[180:183], v[92:95]
	v_mfma_f32_16x16x32_bf16 v[80:83], v[108:111], v[206:209], v[80:83]
	v_mfma_f32_16x16x32_bf16 v[76:79], v[128:131], v[206:209], v[76:79]
	v_mfma_f32_16x16x32_bf16 v[144:147], v[112:115], v[168:171], v[144:147]
	v_mfma_f32_16x16x32_bf16 v[140:143], v[136:139], v[168:171], v[140:143]
	v_mfma_f32_16x16x32_bf16 v[120:123], v[112:115], v[176:179], v[120:123]
	v_mfma_f32_16x16x32_bf16 v[116:119], v[136:139], v[176:179], v[116:119]
	v_mfma_f32_16x16x32_bf16 v[96:99], v[112:115], v[184:187], v[96:99]
	v_mfma_f32_16x16x32_bf16 v[92:95], v[136:139], v[184:187], v[92:95]
	v_mfma_f32_16x16x32_bf16 v[80:83], v[112:115], v[210:213], v[80:83]
	v_mfma_f32_16x16x32_bf16 v[76:79], v[136:139], v[210:213], v[76:79]
	v_mfma_f32_16x16x32_bf16 v[132:135], v[148:151], v[164:167], v[132:135]
	v_mfma_f32_16x16x32_bf16 v[124:127], v[156:159], v[164:167], v[124:127]
	v_mfma_f32_16x16x32_bf16 v[104:107], v[148:151], v[172:175], v[104:107]
	v_mfma_f32_16x16x32_bf16 v[100:103], v[156:159], v[172:175], v[100:103]
	v_mfma_f32_16x16x32_bf16 v[88:91], v[148:151], v[180:183], v[88:91]
	v_mfma_f32_16x16x32_bf16 v[84:87], v[156:159], v[180:183], v[84:87]
	v_mfma_f32_16x16x32_bf16 v[72:75], v[148:151], v[206:209], v[72:75]
	v_mfma_f32_16x16x32_bf16 v[68:71], v[156:159], v[206:209], v[68:71]
	v_mfma_f32_16x16x32_bf16 v[132:135], v[152:155], v[168:171], v[132:135]
	v_mfma_f32_16x16x32_bf16 v[124:127], v[160:163], v[168:171], v[124:127]
	v_mfma_f32_16x16x32_bf16 v[104:107], v[152:155], v[176:179], v[104:107]
	v_mfma_f32_16x16x32_bf16 v[100:103], v[160:163], v[176:179], v[100:103]
	v_mfma_f32_16x16x32_bf16 v[88:91], v[152:155], v[184:187], v[88:91]
	v_mfma_f32_16x16x32_bf16 v[84:87], v[160:163], v[184:187], v[84:87]
	v_mfma_f32_16x16x32_bf16 v[72:75], v[152:155], v[210:213], v[72:75]
	v_mfma_f32_16x16x32_bf16 v[68:71], v[160:163], v[210:213], v[68:71]
	s_barrier
	s_setprio 0
	s_add_i32 s48, s48, s20
	v_lshl_add_u64 v[198:199], s[62:63], 0, v[200:201]
	s_mov_b32 m0, s48
	ds_read_b128 v[164:167], v234 offset:16384
	ds_read_b128 v[168:171], v234 offset:17408
	ds_read_b128 v[172:175], v234 offset:18432
	ds_read_b128 v[176:179], v234 offset:19456
	ds_read_b128 v[180:183], v234 offset:20480
	ds_read_b128 v[184:187], v234 offset:21504
	ds_read_b128 v[206:209], v234 offset:22528
	ds_read_b128 v[210:213], v234 offset:23552
	global_load_lds_dwordx4 v[198:199], off
	s_add_i32 m0, s48, 0x2000
	s_add_u32 s48, s62, 0x160000
	v_lshl_add_u64 v[214:215], s[62:63], 0, v[188:189]
	s_addc_u32 s49, s63, 0
	s_add_i32 s50, s78, s20
	global_load_lds_dwordx4 v[214:215], off
	v_lshl_add_u64 v[216:217], s[48:49], 0, v[200:201]
	s_mov_b32 m0, s50
	v_lshl_add_u64 v[218:219], s[68:69], 0, v[190:191]
	global_load_lds_dwordx4 v[216:217], off
	s_add_i32 m0, s50, 0x2000
	v_lshl_add_u64 v[216:217], s[48:49], 0, v[188:189]
	global_load_lds_dwordx4 v[216:217], off
	s_mov_b32 m0, s21
	v_lshl_add_u64 v[216:217], s[68:69], 0, v[192:193]
	global_load_lds_dwordx4 v[216:217], off
	s_mov_b32 m0, s23
	s_nop 0
	global_load_lds_dwordx4 v[218:219], off
	s_waitcnt vmcnt(8) lgkmcnt(0)
	s_setprio 1
	s_barrier
; #define PG8_STAGE(bufoff, gbase, voff) do { _Pragma("unroll") for (int _i = 0; _i < 2; ++_i) \
;         __builtin_amdgcn_global_load_lds((const unsigned*)((const char*)(gbase) + (voff)[_i]), (PG8_LAS unsigned*)(lds + (bufoff) + ldsw + _i * 8192), 16, 0, 0); } while (0)
; #define PG8_LDA(dst, b, h) do { _Pragma("unroll") for (int m = 0; m < 4; ++m) _Pragma("unroll") for (int k = 0; k < 2; ++k) dst[m][k] = *(const PG8_LAS bf16x8*)(lds + PG8_SA(b, h) + aoff + m * 2048 + k * 1024); } while (0)
; #define PG8_LDB(dst, b, h) do { _Pragma("unroll") for (int n = 0; n < 2; ++n) _Pragma("unroll") for (int k = 0; k < 2; ++k) dst[n][k] = *(const PG8_LAS bf16x8*)(lds + PG8_SB(b, h) + boff + n * 2048 + k * 1024); } while (0)
; #define PG8_MMA(ai, bj, At, Bt) do { __builtin_amdgcn_s_setprio(1); _Pragma("unroll") for (int m = 0; m < 4; ++m) _Pragma("unroll") for (int n = 0; n < 2; ++n) _Pragma("unroll") for (int k = 0; k < 2; ++k) \
;         acc[ai][bj][m][n] = __builtin_amdgcn_mfma_f32_16x16x32_bf16(Bt[n][k], At[m][k], acc[ai][bj][m][n], 0, 0, 0); __builtin_amdgcn_s_setprio(0); } while (0)
; #define PG8_WAIT_V(n) asm volatile("s_waitcnt vmcnt(" #n ")" ::: "memory")
; #define PG8_WAIT_L(n) asm volatile("s_waitcnt lgkmcnt(" #n ")" ::: "memory")
; #define PG8_BAR __builtin_amdgcn_s_barrier()
; #define PG8_SCHED __builtin_amdgcn_sched_barrier(0)
;     ...
;             PG8_WAIT_V(8); PG8_WAIT_L(0); PG8_BAR; PG8_MMA(1, 0, At, B0); PG8_MMA(1, 1, At, B1); PG8_BAR; PG8_SCHED;
;             PG8_LDB(B0, 1, 0); PG8_LDB(B1, 1, 1); PG8_SCHED; PG8_LDA(At, 1, 0); PG8_STAGE(PG8_SA(0, 1), a2 + hstep, voffA);
;             PG8_WAIT_V(8); PG8_WAIT_L(0); PG8_BAR; PG8_MMA(0, 0, At, B0); PG8_MMA(0, 1, At, B1); PG8_BAR; PG8_SCHED;
;             PG8_LDA(At, 1, 1); PG8_STAGE(PG8_SB(1, 0), b3, voffB); PG8_STAGE(PG8_SB(1, 1), b3 + hstep, voffB); PG8_STAGE(PG8_SA(1, 0), a3, voffA);
	v_mfma_f32_16x16x32_bf16 v[64:67], v[108:111], v[164:167], v[64:67]
	v_mfma_f32_16x16x32_bf16 v[60:63], v[128:131], v[164:167], v[60:63]
	v_mfma_f32_16x16x32_bf16 v[48:51], v[108:111], v[172:175], v[48:51]
	v_mfma_f32_16x16x32_bf16 v[44:47], v[128:131], v[172:175], v[44:47]
	v_mfma_f32_16x16x32_bf16 v[32:35], v[108:111], v[180:183], v[32:35]
	v_mfma_f32_16x16x32_bf16 v[28:31], v[128:131], v[180:183], v[28:31]
	v_mfma_f32_16x16x32_bf16 v[16:19], v[108:111], v[206:209], v[16:19]
	v_mfma_f32_16x16x32_bf16 v[12:15], v[128:131], v[206:209], v[12:15]
	v_mfma_f32_16x16x32_bf16 v[64:67], v[112:115], v[168:171], v[64:67]
	v_mfma_f32_16x16x32_bf16 v[60:63], v[136:139], v[168:171], v[60:63]
	v_mfma_f32_16x16x32_bf16 v[48:51], v[112:115], v[176:179], v[48:51]
	v_mfma_f32_16x16x32_bf16 v[44:47], v[136:139], v[176:179], v[44:47]
	v_mfma_f32_16x16x32_bf16 v[32:35], v[112:115], v[184:187], v[32:35]
	v_mfma_f32_16x16x32_bf16 v[28:31], v[136:139], v[184:187], v[28:31]
	v_mfma_f32_16x16x32_bf16 v[16:19], v[112:115], v[210:213], v[16:19]
	v_mfma_f32_16x16x32_bf16 v[12:15], v[136:139], v[210:213], v[12:15]
	v_mfma_f32_16x16x32_bf16 v[56:59], v[148:151], v[164:167], v[56:59]
	v_mfma_f32_16x16x32_bf16 v[52:55], v[156:159], v[164:167], v[52:55]
	v_mfma_f32_16x16x32_bf16 v[40:43], v[148:151], v[172:175], v[40:43]
	v_mfma_f32_16x16x32_bf16 v[36:39], v[156:159], v[172:175], v[36:39]
	v_mfma_f32_16x16x32_bf16 v[24:27], v[148:151], v[180:183], v[24:27]
	v_mfma_f32_16x16x32_bf16 v[20:23], v[156:159], v[180:183], v[20:23]
	v_mfma_f32_16x16x32_bf16 v[8:11], v[148:151], v[206:209], v[8:11]
	v_mfma_f32_16x16x32_bf16 v[4:7], v[156:159], v[206:209], v[4:7]
	v_mfma_f32_16x16x32_bf16 v[56:59], v[152:155], v[168:171], v[56:59]
	v_mfma_f32_16x16x32_bf16 v[52:55], v[160:163], v[168:171], v[52:55]
	v_mfma_f32_16x16x32_bf16 v[40:43], v[152:155], v[176:179], v[40:43]
	v_mfma_f32_16x16x32_bf16 v[36:39], v[160:163], v[176:179], v[36:39]
	v_mfma_f32_16x16x32_bf16 v[24:27], v[152:155], v[184:187], v[24:27]
	v_mfma_f32_16x16x32_bf16 v[20:23], v[160:163], v[184:187], v[20:23]
	v_mfma_f32_16x16x32_bf16 v[8:11], v[152:155], v[210:213], v[8:11]
	v_mfma_f32_16x16x32_bf16 v[4:7], v[160:163], v[210:213], v[4:7]
	s_barrier
	s_setprio 0
	s_add_i32 s50, 0, 0x18000
	s_add_i32 s51, 0, 0x1c000
	ds_read_b128 v[108:111], v251 offset:32768
	ds_read_b128 v[112:115], v251 offset:33792
	ds_read_b128 v[128:131], v251 offset:34816
	ds_read_b128 v[136:139], v251 offset:35840
	ds_read_b128 v[148:151], v251 offset:49152
	ds_read_b128 v[152:155], v251 offset:50176
	ds_read_b128 v[156:159], v251 offset:51200
	ds_read_b128 v[160:163], v251 offset:52224
	s_add_u32 s48, s68, 0x160000
	s_addc_u32 s49, s69, 0
	s_mov_b32 m0, s42
	v_lshl_add_u64 v[220:221], s[48:49], 0, v[192:193]
	ds_read_b128 v[164:167], v234 offset:32768
	ds_read_b128 v[168:171], v234 offset:33792
	ds_read_b128 v[172:175], v234 offset:34816
	ds_read_b128 v[176:179], v234 offset:35840
	ds_read_b128 v[180:183], v234 offset:36864
	ds_read_b128 v[184:187], v234 offset:37888
	ds_read_b128 v[206:209], v234 offset:38912
	ds_read_b128 v[210:213], v234 offset:39936
	global_load_lds_dwordx4 v[220:221], off
	s_mov_b32 m0, s52
	v_lshl_add_u64 v[220:221], s[48:49], 0, v[190:191]
	global_load_lds_dwordx4 v[220:221], off
	s_waitcnt vmcnt(8) lgkmcnt(0)
	s_setprio 1
	s_barrier
	v_mfma_f32_16x16x32_bf16 v[144:147], v[108:111], v[164:167], v[144:147]
	v_mfma_f32_16x16x32_bf16 v[140:143], v[128:131], v[164:167], v[140:143]
	v_mfma_f32_16x16x32_bf16 v[120:123], v[108:111], v[172:175], v[120:123]
	v_mfma_f32_16x16x32_bf16 v[116:119], v[128:131], v[172:175], v[116:119]
	v_mfma_f32_16x16x32_bf16 v[96:99], v[108:111], v[180:183], v[96:99]
	v_mfma_f32_16x16x32_bf16 v[92:95], v[128:131], v[180:183], v[92:95]
	v_mfma_f32_16x16x32_bf16 v[80:83], v[108:111], v[206:209], v[80:83]
	v_mfma_f32_16x16x32_bf16 v[76:79], v[128:131], v[206:209], v[76:79]
	v_mfma_f32_16x16x32_bf16 v[144:147], v[112:115], v[168:171], v[144:147]
	v_mfma_f32_16x16x32_bf16 v[140:143], v[136:139], v[168:171], v[140:143]
	v_mfma_f32_16x16x32_bf16 v[120:123], v[112:115], v[176:179], v[120:123]
	v_mfma_f32_16x16x32_bf16 v[116:119], v[136:139], v[176:179], v[116:119]
	v_mfma_f32_16x16x32_bf16 v[96:99], v[112:115], v[184:187], v[96:99]
	v_mfma_f32_16x16x32_bf16 v[92:95], v[136:139], v[184:187], v[92:95]
	v_mfma_f32_16x16x32_bf16 v[80:83], v[112:115], v[210:213], v[80:83]
	v_mfma_f32_16x16x32_bf16 v[76:79], v[136:139], v[210:213], v[76:79]
	v_mfma_f32_16x16x32_bf16 v[132:135], v[148:151], v[164:167], v[132:135]
	v_mfma_f32_16x16x32_bf16 v[124:127], v[156:159], v[164:167], v[124:127]
	v_mfma_f32_16x16x32_bf16 v[104:107], v[148:151], v[172:175], v[104:107]
	v_mfma_f32_16x16x32_bf16 v[100:103], v[156:159], v[172:175], v[100:103]
	v_mfma_f32_16x16x32_bf16 v[88:91], v[148:151], v[180:183], v[88:91]
	v_mfma_f32_16x16x32_bf16 v[84:87], v[156:159], v[180:183], v[84:87]
	v_mfma_f32_16x16x32_bf16 v[72:75], v[148:151], v[206:209], v[72:75]
	v_mfma_f32_16x16x32_bf16 v[68:71], v[156:159], v[206:209], v[68:71]
	v_mfma_f32_16x16x32_bf16 v[132:135], v[152:155], v[168:171], v[132:135]
	v_mfma_f32_16x16x32_bf16 v[124:127], v[160:163], v[168:171], v[124:127]
	v_mfma_f32_16x16x32_bf16 v[104:107], v[152:155], v[176:179], v[104:107]
	v_mfma_f32_16x16x32_bf16 v[100:103], v[160:163], v[176:179], v[100:103]
	v_mfma_f32_16x16x32_bf16 v[88:91], v[152:155], v[184:187], v[88:91]
	v_mfma_f32_16x16x32_bf16 v[84:87], v[160:163], v[184:187], v[84:87]
	v_mfma_f32_16x16x32_bf16 v[72:75], v[152:155], v[210:213], v[72:75]
	v_mfma_f32_16x16x32_bf16 v[68:71], v[160:163], v[210:213], v[68:71]
	s_barrier
; #define PG8_STAGE(bufoff, gbase, voff) do { _Pragma("unroll") for (int _i = 0; _i < 2; ++_i) \
;         __builtin_amdgcn_global_load_lds((const unsigned*)((const char*)(gbase) + (voff)[_i]), (PG8_LAS unsigned*)(lds + (bufoff) + ldsw + _i * 8192), 16, 0, 0); } while (0)
; #define PG8_LDA(dst, b, h) do { _Pragma("unroll") for (int m = 0; m < 4; ++m) _Pragma("unroll") for (int k = 0; k < 2; ++k) dst[m][k] = *(const PG8_LAS bf16x8*)(lds + PG8_SA(b, h) + aoff + m * 2048 + k * 1024); } while (0)
; #define PG8_MMA(ai, bj, At, Bt) do { __builtin_amdgcn_s_setprio(1); _Pragma("unroll") for (int m = 0; m < 4; ++m) _Pragma("unroll") for (int n = 0; n < 2; ++n) _Pragma("unroll") for (int k = 0; k < 2; ++k) \
;         acc[ai][bj][m][n] = __builtin_amdgcn_mfma_f32_16x16x32_bf16(Bt[n][k], At[m][k], acc[ai][bj][m][n], 0, 0, 0); __builtin_amdgcn_s_setprio(0); } while (0)
; #define PG8_WAIT_V(n) asm volatile("s_waitcnt vmcnt(" #n ")" ::: "memory")
; #define PG8_WAIT_L(n) asm volatile("s_waitcnt lgkmcnt(" #n ")" ::: "memory")
; #define PG8_BAR __builtin_amdgcn_s_barrier()
; #define PG8_SCHED __builtin_amdgcn_sched_barrier(0)
;     ...
;         for (int t = 0; t < nt; t += 2) {
;             const bool last = (t == nt - 2);
;             const char* a1 = cA + (size_t)(t + 1) * kstep;
;             const char* a2 = last ? nA : cA + (size_t)(t + 2) * kstep; const char* b2 = last ? nB : cB + (size_t)(t + 2) * kstep;
;             const char* a3 = a2 + kstep; const char* b3 = b2 + kstep;
;     ...
;             PG8_LDA(At, 1, 1); PG8_STAGE(PG8_SB(1, 0), b3, voffB); PG8_STAGE(PG8_SB(1, 1), b3 + hstep, voffB); PG8_STAGE(PG8_SA(1, 0), a3, voffA);
;             PG8_WAIT_V(8); PG8_WAIT_L(0); PG8_BAR; PG8_MMA(1, 0, At, B0); PG8_MMA(1, 1, At, B1); PG8_BAR; PG8_SCHED;
	s_setprio 0
	s_add_i32 s48, s50, s20
	v_lshl_add_u64 v[198:199], v[198:199], 0, s[66:67]
	s_mov_b32 m0, s48
	ds_read_b128 v[164:167], v234 offset:49152
	ds_read_b128 v[168:171], v234 offset:50176
	ds_read_b128 v[172:175], v234 offset:51200
	ds_read_b128 v[176:179], v234 offset:52224
	ds_read_b128 v[180:183], v234 offset:53248
	ds_read_b128 v[184:187], v234 offset:54272
	ds_read_b128 v[206:209], v234 offset:55296
	ds_read_b128 v[210:213], v234 offset:56320
	global_load_lds_dwordx4 v[198:199], off
	s_add_i32 m0, s48, 0x2000
	s_add_u32 s48, s62, 0x160080
	v_lshl_add_u64 v[198:199], v[214:215], 0, s[66:67]
	s_addc_u32 s49, s63, 0
	s_add_i32 s50, s51, s20
	global_load_lds_dwordx4 v[198:199], off
	s_mov_b32 m0, s50
	v_lshl_add_u64 v[198:199], s[48:49], 0, v[200:201]
	global_load_lds_dwordx4 v[198:199], off
	s_add_i32 m0, s50, 0x2000
	v_lshl_add_u64 v[198:199], s[48:49], 0, v[188:189]
	global_load_lds_dwordx4 v[198:199], off
	v_lshl_add_u64 v[198:199], v[216:217], 0, s[66:67]
	s_mov_b32 m0, s56
	s_nop 0
	global_load_lds_dwordx4 v[198:199], off
	v_lshl_add_u64 v[198:199], v[218:219], 0, s[66:67]
	s_mov_b32 m0, s58
	s_nop 0
	global_load_lds_dwordx4 v[198:199], off
	s_waitcnt vmcnt(8) lgkmcnt(0)
	s_setprio 1
	s_barrier
	v_mfma_f32_16x16x32_bf16 v[64:67], v[108:111], v[164:167], v[64:67]
	v_mfma_f32_16x16x32_bf16 v[60:63], v[128:131], v[164:167], v[60:63]
	v_mfma_f32_16x16x32_bf16 v[48:51], v[108:111], v[172:175], v[48:51]
	v_mfma_f32_16x16x32_bf16 v[44:47], v[128:131], v[172:175], v[44:47]
	v_mfma_f32_16x16x32_bf16 v[32:35], v[108:111], v[180:183], v[32:35]
	v_mfma_f32_16x16x32_bf16 v[28:31], v[128:131], v[180:183], v[28:31]
	v_mfma_f32_16x16x32_bf16 v[16:19], v[108:111], v[206:209], v[16:19]
	v_mfma_f32_16x16x32_bf16 v[12:15], v[128:131], v[206:209], v[12:15]
	v_mfma_f32_16x16x32_bf16 v[64:67], v[112:115], v[168:171], v[64:67]
	v_mfma_f32_16x16x32_bf16 v[60:63], v[136:139], v[168:171], v[60:63]
	v_mfma_f32_16x16x32_bf16 v[48:51], v[112:115], v[176:179], v[48:51]
	v_mfma_f32_16x16x32_bf16 v[44:47], v[136:139], v[176:179], v[44:47]
	v_mfma_f32_16x16x32_bf16 v[32:35], v[112:115], v[184:187], v[32:35]
	v_mfma_f32_16x16x32_bf16 v[28:31], v[136:139], v[184:187], v[28:31]
	v_mfma_f32_16x16x32_bf16 v[16:19], v[112:115], v[210:213], v[16:19]
	v_mfma_f32_16x16x32_bf16 v[12:15], v[136:139], v[210:213], v[12:15]
	v_mfma_f32_16x16x32_bf16 v[56:59], v[148:151], v[164:167], v[56:59]
	v_mfma_f32_16x16x32_bf16 v[52:55], v[156:159], v[164:167], v[52:55]
	v_mfma_f32_16x16x32_bf16 v[40:43], v[148:151], v[172:175], v[40:43]
	v_mfma_f32_16x16x32_bf16 v[36:39], v[156:159], v[172:175], v[36:39]
	v_mfma_f32_16x16x32_bf16 v[24:27], v[148:151], v[180:183], v[24:27]
	v_mfma_f32_16x16x32_bf16 v[20:23], v[156:159], v[180:183], v[20:23]
	v_mfma_f32_16x16x32_bf16 v[8:11], v[148:151], v[206:209], v[8:11]
	v_mfma_f32_16x16x32_bf16 v[4:7], v[156:159], v[206:209], v[4:7]
	v_mfma_f32_16x16x32_bf16 v[56:59], v[152:155], v[168:171], v[56:59]
	v_mfma_f32_16x16x32_bf16 v[52:55], v[160:163], v[168:171], v[52:55]
	v_mfma_f32_16x16x32_bf16 v[40:43], v[152:155], v[176:179], v[40:43]
	v_mfma_f32_16x16x32_bf16 v[36:39], v[160:163], v[176:179], v[36:39]
	v_mfma_f32_16x16x32_bf16 v[24:27], v[152:155], v[184:187], v[24:27]
	v_mfma_f32_16x16x32_bf16 v[20:23], v[160:163], v[184:187], v[20:23]
	v_mfma_f32_16x16x32_bf16 v[8:11], v[152:155], v[210:213], v[8:11]
	v_mfma_f32_16x16x32_bf16 v[4:7], v[160:163], v[210:213], v[4:7]
	s_barrier
	s_setprio 0
	s_add_i32 s77, s77, 2
	s_add_u32 s75, s75, 0x100
	s_addc_u32 s76, s76, 0
	s_cmpk_gt_u32 s77, 0x55
	s_mov_b64 s[50:51], s[60:61]
	s_cbranch_scc0 .LBB0_1254
	s_and_b64 vcc, exec, s[12:13]
	s_cbranch_vccz .LBB0_1257
	s_barrier
